# K-loops: removed the provably redundant s_waitcnt lgkmcnt(0) that follows each pre-MFMA barrier (the same wait already sits right before the barrier; no LDS op in between)
# baseline (speedup 1.0000x reference)
; #define PG8_STAGE(bufoff, gbase, voff) do { _Pragma("unroll") for (int _i = 0; _i < 2; ++_i) \
;         __builtin_amdgcn_global_load_lds((const unsigned*)((const char*)(gbase) + (voff)[_i]), (PG8_LAS unsigned*)(lds + (bufoff) + ldsw + _i * 8192), 16, 0, 0); } while (0)
; #define PG8_LDA(dst, b, h) do { _Pragma("unroll") for (int m = 0; m < 4; ++m) _Pragma("unroll") for (int k = 0; k < 2; ++k) dst[m][k] = *(const PG8_LAS bf16x8*)(lds + PG8_SA(b, h) + aoff + m * 2048 + k * 1024); } while (0)
; #define PG8_LDB(dst, b, h) do { _Pragma("unroll") for (int n = 0; n < 2; ++n) _Pragma("unroll") for (int k = 0; k < 2; ++k) dst[n][k] = *(const PG8_LAS bf16x8*)(lds + PG8_SB(b, h) + boff + n * 2048 + k * 1024); } while (0)
; #define PG8_MMA(ai, bj, At, Bt) do { __builtin_amdgcn_s_setprio(1); _Pragma("unroll") for (int m = 0; m < 4; ++m) _Pragma("unroll") for (int n = 0; n < 2; ++n) _Pragma("unroll") for (int k = 0; k < 2; ++k) \
;         acc[ai][bj][m][n] = mma16<Epi::F16>(Bt[n][k], At[m][k], acc[ai][bj][m][n]); __builtin_amdgcn_s_setprio(0); } while (0)
; #define PG8_WAIT_V(n) asm volatile("s_waitcnt vmcnt(" #n ")" ::: "memory")
; #define PG8_WAIT_L(n) asm volatile("s_waitcnt lgkmcnt(" #n ")" ::: "memory")
; #define PG8_BAR __builtin_amdgcn_s_barrier()
; #define PG8_SCHED __builtin_amdgcn_sched_barrier(0)
; template <class Epi, class Sched, bool ALIGN_EPI = false, bool SP2 = false>
; __device__ __forceinline__ void gemm_phase(PG8_LAS unsigned char* lds, const Gemm g, const Sched& S, const Epi& E) {
;     ...
;             PG8_LDB(B0, 0, 0); PG8_LDB(B1, 0, 1); PG8_SCHED; PG8_LDA(At, 0, 0); PG8_STAGE(PG8_SA(1, 1), a1 + hstep, voffA);
;             PG8_WAIT_V(8); PG8_WAIT_L(0); PG8_BAR; PG8_MMA(0, 0, At, B0); PG8_MMA(0, 1, At, B1); PG8_BAR; PG8_SCHED;
;             PG8_LDA(At, 0, 1); PG8_STAGE(PG8_SB(0, 0), b2, voffB); PG8_STAGE(PG8_SB(0, 1), b2 + hstep, voffB); PG8_STAGE(PG8_SA(0, 0), a2, voffA);
;             PG8_WAIT_V(8); PG8_WAIT_L(0); PG8_BAR; PG8_MMA(1, 0, At, B0); PG8_MMA(1, 1, At, B1); PG8_BAR; PG8_SCHED;
.Lpeel_k1:
	s_add_u32 s30, s30, 0x80
	s_addc_u32 s31, s31, 0
	s_add_u32 s77, s34, 0x100
	s_addc_u32 s82, s35, 0
	s_mov_b32 s34, 0
	s_add_i32 s84, s34, 2
	s_add_u32 s85, s30, 0x80
	s_addc_u32 s35, s31, 0
	s_add_i32 s92, 0, 0x10000
	s_cmp_eq_u32 s68, s34
	s_cselect_b32 s35, s1, s35
	s_cselect_b32 s34, s0, s85
	v_add_u32_e32 v146, s92, v151
	s_cselect_b32 s97, s57, s82
	s_cselect_b32 s96, s56, s77
	s_add_i32 s85, 0, 0x14000
	ds_read_b128 v[142:145], v146
	ds_read_b128 v[162:165], v146 offset:1024
	ds_read_b128 v[166:169], v146 offset:2048
	ds_read_b128 v[170:173], v146 offset:3072
	v_add_u32_e32 v146, s85, v151
	ds_read_b128 v[174:177], v146
	ds_read_b128 v[178:181], v146 offset:1024
	ds_read_b128 v[182:185], v146 offset:2048
	ds_read_b128 v[186:189], v146 offset:3072
	v_lshl_add_u64 v[148:149], s[30:31], 0, v[138:139]
	s_add_i32 m0, s61, 0xc000
	ds_read_b128 v[190:193], v161
	ds_read_b128 v[194:197], v161 offset:1024
	ds_read_b128 v[198:201], v161 offset:2048
	ds_read_b128 v[202:205], v161 offset:3072
	ds_read_b128 v[212:215], v161 offset:4096
	ds_read_b128 v[216:219], v161 offset:5120
	ds_read_b128 v[220:223], v161 offset:6144
	ds_read_b128 v[224:227], v161 offset:7168
	global_load_lds_dwordx4 v[148:149], off
	v_lshl_add_u64 v[148:149], s[30:31], 0, v[140:141]
	s_add_i32 m0, s61, 0xe000
	s_nop 0
	global_load_lds_dwordx4 v[148:149], off
	s_waitcnt vmcnt(8)
	s_waitcnt lgkmcnt(0)
	s_barrier
	s_setprio 1
	v_mfma_f32_16x16x32_bf16 v[120:123], v[142:145], v[190:193], 0
	v_mfma_f32_16x16x32_bf16 v[116:119], v[166:169], v[190:193], 0
	v_mfma_f32_16x16x32_bf16 v[108:111], v[142:145], v[198:201], 0
	v_mfma_f32_16x16x32_bf16 v[100:103], v[166:169], v[198:201], 0
	v_mfma_f32_16x16x32_bf16 v[92:95], v[142:145], v[212:215], 0
	v_mfma_f32_16x16x32_bf16 v[84:87], v[166:169], v[212:215], 0
	v_mfma_f32_16x16x32_bf16 v[76:79], v[142:145], v[220:223], 0
	v_mfma_f32_16x16x32_bf16 v[68:71], v[166:169], v[220:223], 0
	v_mfma_f32_16x16x32_bf16 v[120:123], v[162:165], v[194:197], v[120:123]
	v_mfma_f32_16x16x32_bf16 v[116:119], v[170:173], v[194:197], v[116:119]
	v_mfma_f32_16x16x32_bf16 v[108:111], v[162:165], v[202:205], v[108:111]
	v_mfma_f32_16x16x32_bf16 v[100:103], v[170:173], v[202:205], v[100:103]
	v_mfma_f32_16x16x32_bf16 v[92:95], v[162:165], v[216:219], v[92:95]
	v_mfma_f32_16x16x32_bf16 v[84:87], v[170:173], v[216:219], v[84:87]
	v_mfma_f32_16x16x32_bf16 v[76:79], v[162:165], v[224:227], v[76:79]
	v_mfma_f32_16x16x32_bf16 v[68:71], v[170:173], v[224:227], v[68:71]
	s_setprio 0
	s_setprio 1
	v_mfma_f32_16x16x32_bf16 v[124:127], v[174:177], v[190:193], 0
	v_mfma_f32_16x16x32_bf16 v[112:115], v[182:185], v[190:193], 0
	v_mfma_f32_16x16x32_bf16 v[104:107], v[174:177], v[198:201], 0
	v_mfma_f32_16x16x32_bf16 v[96:99], v[182:185], v[198:201], 0
	v_mfma_f32_16x16x32_bf16 v[88:91], v[174:177], v[212:215], 0
	v_mfma_f32_16x16x32_bf16 v[80:83], v[182:185], v[212:215], 0
	v_mfma_f32_16x16x32_bf16 v[72:75], v[174:177], v[220:223], 0
	v_mfma_f32_16x16x32_bf16 v[64:67], v[182:185], v[220:223], 0
	v_mfma_f32_16x16x32_bf16 v[124:127], v[178:181], v[194:197], v[124:127]
	v_mfma_f32_16x16x32_bf16 v[112:115], v[186:189], v[194:197], v[112:115]
	v_mfma_f32_16x16x32_bf16 v[104:107], v[178:181], v[202:205], v[104:107]
	v_mfma_f32_16x16x32_bf16 v[96:99], v[186:189], v[202:205], v[96:99]
	v_mfma_f32_16x16x32_bf16 v[88:91], v[178:181], v[216:219], v[88:91]
	v_mfma_f32_16x16x32_bf16 v[80:83], v[186:189], v[216:219], v[80:83]
	v_mfma_f32_16x16x32_bf16 v[72:75], v[178:181], v[224:227], v[72:75]
	v_mfma_f32_16x16x32_bf16 v[64:67], v[186:189], v[224:227], v[64:67]
	s_setprio 0
	s_barrier
	s_add_i32 s92, s92, s11
	v_lshl_add_u64 v[148:149], s[96:97], 0, v[132:133]
	s_mov_b32 m0, s92
	ds_read_b128 v[190:193], v161 offset:16384
	ds_read_b128 v[194:197], v161 offset:17408
	ds_read_b128 v[198:201], v161 offset:18432
	ds_read_b128 v[202:205], v161 offset:19456
	ds_read_b128 v[212:215], v161 offset:20480
	ds_read_b128 v[216:219], v161 offset:21504
	ds_read_b128 v[220:223], v161 offset:22528
	ds_read_b128 v[224:227], v161 offset:23552
	global_load_lds_dwordx4 v[148:149], off
	s_add_i32 m0, s92, 0x2000
	v_lshl_add_u64 v[152:153], s[96:97], 0, v[128:129]
	s_add_u32 s96, s96, s44
	s_addc_u32 s97, s97, s45
	s_add_i32 s85, s85, s11
	global_load_lds_dwordx4 v[152:153], off
	v_lshl_add_u64 v[206:207], s[96:97], 0, v[132:133]
	s_mov_b32 m0, s85
	v_lshl_add_u64 v[228:229], s[96:97], 0, v[128:129]
	global_load_lds_dwordx4 v[206:207], off
	s_add_i32 m0, s85, 0x2000
	v_lshl_add_u64 v[230:231], s[34:35], 0, v[134:135]
	global_load_lds_dwordx4 v[228:229], off
	s_mov_b32 m0, s61
	v_lshl_add_u64 v[232:233], s[34:35], 0, v[130:131]
	global_load_lds_dwordx4 v[230:231], off
	s_mov_b32 m0, s62
	s_nop 0
	global_load_lds_dwordx4 v[232:233], off
	s_waitcnt vmcnt(8)
	s_waitcnt lgkmcnt(0)
	s_barrier
; #define PG8_STAGE(bufoff, gbase, voff) do { _Pragma("unroll") for (int _i = 0; _i < 2; ++_i) \
;         __builtin_amdgcn_global_load_lds((const unsigned*)((const char*)(gbase) + (voff)[_i]), (PG8_LAS unsigned*)(lds + (bufoff) + ldsw + _i * 8192), 16, 0, 0); } while (0)
; #define PG8_LDA(dst, b, h) do { _Pragma("unroll") for (int m = 0; m < 4; ++m) _Pragma("unroll") for (int k = 0; k < 2; ++k) dst[m][k] = *(const PG8_LAS bf16x8*)(lds + PG8_SA(b, h) + aoff + m * 2048 + k * 1024); } while (0)
; #define PG8_LDB(dst, b, h) do { _Pragma("unroll") for (int n = 0; n < 2; ++n) _Pragma("unroll") for (int k = 0; k < 2; ++k) dst[n][k] = *(const PG8_LAS bf16x8*)(lds + PG8_SB(b, h) + boff + n * 2048 + k * 1024); } while (0)
; #define PG8_MMA(ai, bj, At, Bt) do { __builtin_amdgcn_s_setprio(1); _Pragma("unroll") for (int m = 0; m < 4; ++m) _Pragma("unroll") for (int n = 0; n < 2; ++n) _Pragma("unroll") for (int k = 0; k < 2; ++k) \
;         acc[ai][bj][m][n] = mma16<Epi::F16>(Bt[n][k], At[m][k], acc[ai][bj][m][n]); __builtin_amdgcn_s_setprio(0); } while (0)
; #define PG8_WAIT_V(n) asm volatile("s_waitcnt vmcnt(" #n ")" ::: "memory")
; #define PG8_WAIT_L(n) asm volatile("s_waitcnt lgkmcnt(" #n ")" ::: "memory")
; #define PG8_BAR __builtin_amdgcn_s_barrier()
; #define PG8_SCHED __builtin_amdgcn_sched_barrier(0)
; template <class Epi, class Sched, bool ALIGN_EPI = false, bool SP2 = false>
; __device__ __forceinline__ void gemm_phase(PG8_LAS unsigned char* lds, const Gemm g, const Sched& S, const Epi& E) {
;     ...
;             PG8_WAIT_V(8); PG8_WAIT_L(0); PG8_BAR; PG8_MMA(1, 0, At, B0); PG8_MMA(1, 1, At, B1); PG8_BAR; PG8_SCHED;
;             PG8_LDB(B0, 1, 0); PG8_LDB(B1, 1, 1); PG8_SCHED; PG8_LDA(At, 1, 0); PG8_STAGE(PG8_SA(0, 1), a2 + hstep, voffA);
;             PG8_WAIT_V(8); PG8_WAIT_L(0); PG8_BAR; PG8_MMA(0, 0, At, B0); PG8_MMA(0, 1, At, B1); PG8_BAR; PG8_SCHED;
	s_setprio 1
	v_mfma_f32_16x16x32_bf16 v[60:63], v[142:145], v[190:193], 0
	v_mfma_f32_16x16x32_bf16 v[52:55], v[166:169], v[190:193], 0
	v_mfma_f32_16x16x32_bf16 v[44:47], v[142:145], v[198:201], 0
	v_mfma_f32_16x16x32_bf16 v[36:39], v[166:169], v[198:201], 0
	v_mfma_f32_16x16x32_bf16 v[28:31], v[142:145], v[212:215], 0
	v_mfma_f32_16x16x32_bf16 v[20:23], v[166:169], v[212:215], 0
	v_mfma_f32_16x16x32_bf16 v[12:15], v[142:145], v[220:223], 0
	v_mfma_f32_16x16x32_bf16 v[4:7], v[166:169], v[220:223], 0
	v_mfma_f32_16x16x32_bf16 v[60:63], v[162:165], v[194:197], v[60:63]
	v_mfma_f32_16x16x32_bf16 v[52:55], v[170:173], v[194:197], v[52:55]
	v_mfma_f32_16x16x32_bf16 v[44:47], v[162:165], v[202:205], v[44:47]
	v_mfma_f32_16x16x32_bf16 v[36:39], v[170:173], v[202:205], v[36:39]
	v_mfma_f32_16x16x32_bf16 v[28:31], v[162:165], v[216:219], v[28:31]
	v_mfma_f32_16x16x32_bf16 v[20:23], v[170:173], v[216:219], v[20:23]
	v_mfma_f32_16x16x32_bf16 v[12:15], v[162:165], v[224:227], v[12:15]
	v_mfma_f32_16x16x32_bf16 v[4:7], v[170:173], v[224:227], v[4:7]
	s_setprio 0
	s_setprio 1
	v_mfma_f32_16x16x32_bf16 v[56:59], v[174:177], v[190:193], 0
	v_mfma_f32_16x16x32_bf16 v[48:51], v[182:185], v[190:193], 0
	v_mfma_f32_16x16x32_bf16 v[40:43], v[174:177], v[198:201], 0
	v_mfma_f32_16x16x32_bf16 v[32:35], v[182:185], v[198:201], 0
	v_mfma_f32_16x16x32_bf16 v[24:27], v[174:177], v[212:215], 0
	v_mfma_f32_16x16x32_bf16 v[16:19], v[182:185], v[212:215], 0
	v_mfma_f32_16x16x32_bf16 v[8:11], v[174:177], v[220:223], 0
	v_mfma_f32_16x16x32_bf16 v[0:3], v[182:185], v[220:223], 0
	v_mfma_f32_16x16x32_bf16 v[56:59], v[178:181], v[194:197], v[56:59]
	v_mfma_f32_16x16x32_bf16 v[48:51], v[186:189], v[194:197], v[48:51]
	v_mfma_f32_16x16x32_bf16 v[40:43], v[178:181], v[202:205], v[40:43]
	v_mfma_f32_16x16x32_bf16 v[32:35], v[186:189], v[202:205], v[32:35]
	v_mfma_f32_16x16x32_bf16 v[24:27], v[178:181], v[216:219], v[24:27]
	v_mfma_f32_16x16x32_bf16 v[16:19], v[186:189], v[216:219], v[16:19]
	v_mfma_f32_16x16x32_bf16 v[8:11], v[178:181], v[224:227], v[8:11]
	v_mfma_f32_16x16x32_bf16 v[0:3], v[186:189], v[224:227], v[0:3]
	s_setprio 0
	s_barrier
	s_add_i32 s85, 0, 0x18000
	v_add_u32_e32 v146, s85, v151
	s_add_i32 s92, 0, 0x1c000
	ds_read_b128 v[142:145], v146
	ds_read_b128 v[162:165], v146 offset:1024
	ds_read_b128 v[166:169], v146 offset:2048
	ds_read_b128 v[170:173], v146 offset:3072
	v_add_u32_e32 v146, s92, v151
	ds_read_b128 v[174:177], v146
	ds_read_b128 v[178:181], v146 offset:1024
	ds_read_b128 v[182:185], v146 offset:2048
	ds_read_b128 v[186:189], v146 offset:3072
	s_add_u32 s34, s34, s44
	s_addc_u32 s35, s35, s45
	s_mov_b32 m0, s63
	v_lshl_add_u64 v[234:235], s[34:35], 0, v[134:135]
	ds_read_b128 v[190:193], v161 offset:32768
	ds_read_b128 v[194:197], v161 offset:33792
	ds_read_b128 v[198:201], v161 offset:34816
	ds_read_b128 v[202:205], v161 offset:35840
	ds_read_b128 v[212:215], v161 offset:36864
	ds_read_b128 v[216:219], v161 offset:37888
	ds_read_b128 v[220:223], v161 offset:38912
	ds_read_b128 v[224:227], v161 offset:39936
	global_load_lds_dwordx4 v[234:235], off
	v_lshl_add_u64 v[234:235], s[34:35], 0, v[130:131]
	s_mov_b32 m0, s64
	s_nop 0
	global_load_lds_dwordx4 v[234:235], off
	s_waitcnt vmcnt(8)
	s_waitcnt lgkmcnt(0)
	s_barrier
	s_setprio 1
	v_mfma_f32_16x16x32_bf16 v[120:123], v[142:145], v[190:193], v[120:123]
	v_mfma_f32_16x16x32_bf16 v[116:119], v[166:169], v[190:193], v[116:119]
	v_mfma_f32_16x16x32_bf16 v[108:111], v[142:145], v[198:201], v[108:111]
	v_mfma_f32_16x16x32_bf16 v[100:103], v[166:169], v[198:201], v[100:103]
	v_mfma_f32_16x16x32_bf16 v[92:95], v[142:145], v[212:215], v[92:95]
	v_mfma_f32_16x16x32_bf16 v[84:87], v[166:169], v[212:215], v[84:87]
	v_mfma_f32_16x16x32_bf16 v[76:79], v[142:145], v[220:223], v[76:79]
	v_mfma_f32_16x16x32_bf16 v[68:71], v[166:169], v[220:223], v[68:71]
	v_mfma_f32_16x16x32_bf16 v[120:123], v[162:165], v[194:197], v[120:123]
	v_mfma_f32_16x16x32_bf16 v[116:119], v[170:173], v[194:197], v[116:119]
	v_mfma_f32_16x16x32_bf16 v[108:111], v[162:165], v[202:205], v[108:111]
	v_mfma_f32_16x16x32_bf16 v[100:103], v[170:173], v[202:205], v[100:103]
	v_mfma_f32_16x16x32_bf16 v[92:95], v[162:165], v[216:219], v[92:95]
	v_mfma_f32_16x16x32_bf16 v[84:87], v[170:173], v[216:219], v[84:87]
	v_mfma_f32_16x16x32_bf16 v[76:79], v[162:165], v[224:227], v[76:79]
	v_mfma_f32_16x16x32_bf16 v[68:71], v[170:173], v[224:227], v[68:71]
	s_setprio 0
	s_setprio 1
	v_mfma_f32_16x16x32_bf16 v[124:127], v[174:177], v[190:193], v[124:127]
	v_mfma_f32_16x16x32_bf16 v[112:115], v[182:185], v[190:193], v[112:115]
	v_mfma_f32_16x16x32_bf16 v[104:107], v[174:177], v[198:201], v[104:107]
	v_mfma_f32_16x16x32_bf16 v[96:99], v[182:185], v[198:201], v[96:99]
	v_mfma_f32_16x16x32_bf16 v[88:91], v[174:177], v[212:215], v[88:91]
	v_mfma_f32_16x16x32_bf16 v[80:83], v[182:185], v[212:215], v[80:83]
	v_mfma_f32_16x16x32_bf16 v[72:75], v[174:177], v[220:223], v[72:75]
	v_mfma_f32_16x16x32_bf16 v[64:67], v[182:185], v[220:223], v[64:67]
	v_mfma_f32_16x16x32_bf16 v[124:127], v[178:181], v[194:197], v[124:127]
	v_mfma_f32_16x16x32_bf16 v[112:115], v[186:189], v[194:197], v[112:115]
	v_mfma_f32_16x16x32_bf16 v[104:107], v[178:181], v[202:205], v[104:107]
	v_mfma_f32_16x16x32_bf16 v[96:99], v[186:189], v[202:205], v[96:99]
	v_mfma_f32_16x16x32_bf16 v[88:91], v[178:181], v[216:219], v[88:91]
	v_mfma_f32_16x16x32_bf16 v[80:83], v[186:189], v[216:219], v[80:83]
	v_mfma_f32_16x16x32_bf16 v[72:75], v[178:181], v[224:227], v[72:75]
	v_mfma_f32_16x16x32_bf16 v[64:67], v[186:189], v[224:227], v[64:67]
	s_setprio 0
	s_barrier
; #define PG8_STAGE(bufoff, gbase, voff) do { _Pragma("unroll") for (int _i = 0; _i < 2; ++_i) \
;         __builtin_amdgcn_global_load_lds((const unsigned*)((const char*)(gbase) + (voff)[_i]), (PG8_LAS unsigned*)(lds + (bufoff) + ldsw + _i * 8192), 16, 0, 0); } while (0)
; #define PG8_LDA(dst, b, h) do { _Pragma("unroll") for (int m = 0; m < 4; ++m) _Pragma("unroll") for (int k = 0; k < 2; ++k) dst[m][k] = *(const PG8_LAS bf16x8*)(lds + PG8_SA(b, h) + aoff + m * 2048 + k * 1024); } while (0)
; #define PG8_LDB(dst, b, h) do { _Pragma("unroll") for (int n = 0; n < 2; ++n) _Pragma("unroll") for (int k = 0; k < 2; ++k) dst[n][k] = *(const PG8_LAS bf16x8*)(lds + PG8_SB(b, h) + boff + n * 2048 + k * 1024); } while (0)
; template <class Epi, class Sched, bool ALIGN_EPI = false, bool SP2 = false>
; __device__ __forceinline__ void gemm_phase(PG8_LAS unsigned char* lds, const Gemm g, const Sched& S, const Epi& E) {
;     ...
;         for (int t = 0; t < nt; t += 2) {
;             const bool last = (t == nt - 2);
;             const char* a1 = cA + (size_t)(t + 1) * kstep;
;             const char* a2 = last ? nA : cA + (size_t)(t + 2) * kstep; const char* b2 = last ? nB : cB + (size_t)(t + 2) * kstep;
;             const char* a3 = a2 + kstep; const char* b3 = b2 + kstep;
;             if (last && has_next) S.a_ready(nxt);
;             if constexpr (SP2) {
;             PG8_LDB(B0, 0, 0); PG8_LDB(B1, 0, 1); PG8_SCHED; PG8_LDA(At, 0, 0); PG8_STAGE(PG8_SA(1, 1), a1 + hstep, voffA);
;             PG8_WAIT_V(8); PG8_WAIT_L(0); PG8_BAR; PG8_MMA(0, 0, At, B0); PG8_MMA(0, 1, At, B1); PG8_BAR; PG8_SCHED;
;             PG8_LDA(At, 0, 1); PG8_STAGE(PG8_SB(0, 0), b2, voffB); PG8_STAGE(PG8_SB(0, 1), b2 + hstep, voffB); PG8_STAGE(PG8_SA(0, 0), a2, voffA);
;             PG8_WAIT_V(8); PG8_WAIT_L(0); PG8_BAR; PG8_MMA(1, 0, At, B0); PG8_MMA(1, 1, At, B1); PG8_BAR; PG8_SCHED;
;             PG8_LDB(B0, 1, 0); PG8_LDB(B1, 1, 1); PG8_SCHED; PG8_LDA(At, 1, 0); PG8_STAGE(PG8_SA(0, 1), a2 + hstep, voffA);
;             PG8_WAIT_V(8); PG8_WAIT_L(0); PG8_BAR; PG8_MMA(0, 0, At, B0); PG8_MMA(0, 1, At, B1); PG8_BAR; PG8_SCHED;
;             PG8_LDA(At, 1, 1); PG8_STAGE(PG8_SB(1, 0), b3, voffB); PG8_STAGE(PG8_SB(1, 1), b3 + hstep, voffB); PG8_STAGE(PG8_SA(1, 0), a3, voffA);
;             PG8_WAIT_V(8); PG8_WAIT_L(0); PG8_BAR; PG8_MMA(1, 0, At, B0); PG8_MMA(1, 1, At, B1); PG8_BAR; PG8_SCHED;
	s_add_i32 s34, s85, s11
	v_lshl_add_u64 v[148:149], v[148:149], 0, s[20:21]
	s_mov_b32 m0, s34
	ds_read_b128 v[190:193], v161 offset:49152
	ds_read_b128 v[194:197], v161 offset:50176
	ds_read_b128 v[198:201], v161 offset:51200
	ds_read_b128 v[202:205], v161 offset:52224
	ds_read_b128 v[212:215], v161 offset:53248
	ds_read_b128 v[216:219], v161 offset:54272
	ds_read_b128 v[220:223], v161 offset:55296
	ds_read_b128 v[224:227], v161 offset:56320
	global_load_lds_dwordx4 v[148:149], off
	v_lshl_add_u64 v[148:149], v[152:153], 0, s[20:21]
	s_add_i32 m0, s34, 0x2000
	s_add_i32 s34, s92, s11
	global_load_lds_dwordx4 v[148:149], off
	v_lshl_add_u64 v[148:149], v[206:207], 0, s[20:21]
	s_mov_b32 m0, s34
	s_nop 0
	global_load_lds_dwordx4 v[148:149], off
	v_lshl_add_u64 v[148:149], v[228:229], 0, s[20:21]
	s_add_i32 m0, s34, 0x2000
	s_nop 0
	global_load_lds_dwordx4 v[148:149], off
	v_lshl_add_u64 v[148:149], v[230:231], 0, s[20:21]
	s_mov_b32 m0, s65
	s_nop 0
	global_load_lds_dwordx4 v[148:149], off
	v_lshl_add_u64 v[148:149], v[232:233], 0, s[20:21]
	s_mov_b32 m0, s66
	s_nop 0
	global_load_lds_dwordx4 v[148:149], off
	s_waitcnt vmcnt(8)
	s_waitcnt lgkmcnt(0)
	s_barrier
	s_setprio 1
	v_mfma_f32_16x16x32_bf16 v[60:63], v[142:145], v[190:193], v[60:63]
	v_mfma_f32_16x16x32_bf16 v[52:55], v[166:169], v[190:193], v[52:55]
	v_mfma_f32_16x16x32_bf16 v[44:47], v[142:145], v[198:201], v[44:47]
	v_mfma_f32_16x16x32_bf16 v[36:39], v[166:169], v[198:201], v[36:39]
	v_mfma_f32_16x16x32_bf16 v[28:31], v[142:145], v[212:215], v[28:31]
	v_mfma_f32_16x16x32_bf16 v[20:23], v[166:169], v[212:215], v[20:23]
	v_mfma_f32_16x16x32_bf16 v[12:15], v[142:145], v[220:223], v[12:15]
	v_mfma_f32_16x16x32_bf16 v[4:7], v[166:169], v[220:223], v[4:7]
	v_mfma_f32_16x16x32_bf16 v[60:63], v[162:165], v[194:197], v[60:63]
	v_mfma_f32_16x16x32_bf16 v[52:55], v[170:173], v[194:197], v[52:55]
	v_mfma_f32_16x16x32_bf16 v[44:47], v[162:165], v[202:205], v[44:47]
	v_mfma_f32_16x16x32_bf16 v[36:39], v[170:173], v[202:205], v[36:39]
	v_mfma_f32_16x16x32_bf16 v[28:31], v[162:165], v[216:219], v[28:31]
	v_mfma_f32_16x16x32_bf16 v[20:23], v[170:173], v[216:219], v[20:23]
	v_mfma_f32_16x16x32_bf16 v[12:15], v[162:165], v[224:227], v[12:15]
	v_mfma_f32_16x16x32_bf16 v[4:7], v[170:173], v[224:227], v[4:7]
	s_setprio 0
	s_setprio 1
	v_mfma_f32_16x16x32_bf16 v[56:59], v[174:177], v[190:193], v[56:59]
	v_mfma_f32_16x16x32_bf16 v[48:51], v[182:185], v[190:193], v[48:51]
	v_mfma_f32_16x16x32_bf16 v[40:43], v[174:177], v[198:201], v[40:43]
	v_mfma_f32_16x16x32_bf16 v[32:35], v[182:185], v[198:201], v[32:35]
	v_mfma_f32_16x16x32_bf16 v[24:27], v[174:177], v[212:215], v[24:27]
	v_mfma_f32_16x16x32_bf16 v[16:19], v[182:185], v[212:215], v[16:19]
	v_mfma_f32_16x16x32_bf16 v[8:11], v[174:177], v[220:223], v[8:11]
	v_mfma_f32_16x16x32_bf16 v[0:3], v[182:185], v[220:223], v[0:3]
	v_mfma_f32_16x16x32_bf16 v[56:59], v[178:181], v[194:197], v[56:59]
	v_mfma_f32_16x16x32_bf16 v[48:51], v[186:189], v[194:197], v[48:51]
	v_mfma_f32_16x16x32_bf16 v[40:43], v[178:181], v[202:205], v[40:43]
	v_mfma_f32_16x16x32_bf16 v[32:35], v[186:189], v[202:205], v[32:35]
	v_mfma_f32_16x16x32_bf16 v[24:27], v[178:181], v[216:219], v[24:27]
	v_mfma_f32_16x16x32_bf16 v[16:19], v[186:189], v[216:219], v[16:19]
	v_mfma_f32_16x16x32_bf16 v[8:11], v[178:181], v[224:227], v[8:11]
	v_mfma_f32_16x16x32_bf16 v[0:3], v[186:189], v[224:227], v[0:3]
	s_setprio 0
	s_barrier
	s_add_u32 s30, s30, 0x100
	s_addc_u32 s31, s31, 0
	s_add_u32 s77, s77, 0x100
	s_addc_u32 s82, s82, 0
	s_cmp_ge_i32 s84, s67
	s_mov_b32 s34, s84
	s_cbranch_scc0 .LBB0_191
	s_branch .LBB0_192
.LBB0_191:
	s_add_i32 s84, s34, 2
	s_add_u32 s85, s30, 0x80
	s_addc_u32 s35, s31, 0
	s_add_i32 s92, 0, 0x10000
	s_cmp_eq_u32 s68, s34
	s_cselect_b32 s35, s1, s35
	s_cselect_b32 s34, s0, s85
	v_add_u32_e32 v146, s92, v151
	s_cselect_b32 s97, s57, s82
	s_cselect_b32 s96, s56, s77
	s_add_i32 s85, 0, 0x14000
	ds_read_b128 v[142:145], v146
	ds_read_b128 v[162:165], v146 offset:1024
	ds_read_b128 v[166:169], v146 offset:2048
	ds_read_b128 v[170:173], v146 offset:3072
	v_add_u32_e32 v146, s85, v151
	ds_read_b128 v[174:177], v146
	ds_read_b128 v[178:181], v146 offset:1024
	ds_read_b128 v[182:185], v146 offset:2048
	ds_read_b128 v[186:189], v146 offset:3072
	v_lshl_add_u64 v[148:149], s[30:31], 0, v[138:139]
	s_add_i32 m0, s61, 0xc000
	ds_read_b128 v[190:193], v161
	ds_read_b128 v[194:197], v161 offset:1024
	ds_read_b128 v[198:201], v161 offset:2048
	ds_read_b128 v[202:205], v161 offset:3072
	ds_read_b128 v[212:215], v161 offset:4096
	ds_read_b128 v[216:219], v161 offset:5120
	ds_read_b128 v[220:223], v161 offset:6144
	ds_read_b128 v[224:227], v161 offset:7168
	global_load_lds_dwordx4 v[148:149], off
	v_lshl_add_u64 v[148:149], s[30:31], 0, v[140:141]
	s_add_i32 m0, s61, 0xe000
	s_nop 0
	global_load_lds_dwordx4 v[148:149], off
	s_waitcnt vmcnt(8)
	s_waitcnt lgkmcnt(0)
	s_barrier
; #define PG8_STAGE(bufoff, gbase, voff) do { _Pragma("unroll") for (int _i = 0; _i < 2; ++_i) \
;         __builtin_amdgcn_global_load_lds((const unsigned*)((const char*)(gbase) + (voff)[_i]), (PG8_LAS unsigned*)(lds + (bufoff) + ldsw + _i * 8192), 16, 0, 0); } while (0)
; #define PG8_LDA(dst, b, h) do { _Pragma("unroll") for (int m = 0; m < 4; ++m) _Pragma("unroll") for (int k = 0; k < 2; ++k) dst[m][k] = *(const PG8_LAS bf16x8*)(lds + PG8_SA(b, h) + aoff + m * 2048 + k * 1024); } while (0)
; #define PG8_LDB(dst, b, h) do { _Pragma("unroll") for (int n = 0; n < 2; ++n) _Pragma("unroll") for (int k = 0; k < 2; ++k) dst[n][k] = *(const PG8_LAS bf16x8*)(lds + PG8_SB(b, h) + boff + n * 2048 + k * 1024); } while (0)
; #define PG8_MMA(ai, bj, At, Bt) do { __builtin_amdgcn_s_setprio(1); _Pragma("unroll") for (int m = 0; m < 4; ++m) _Pragma("unroll") for (int n = 0; n < 2; ++n) _Pragma("unroll") for (int k = 0; k < 2; ++k) \
;         acc[ai][bj][m][n] = mma16<Epi::F16>(Bt[n][k], At[m][k], acc[ai][bj][m][n]); __builtin_amdgcn_s_setprio(0); } while (0)
; #define PG8_WAIT_V(n) asm volatile("s_waitcnt vmcnt(" #n ")" ::: "memory")
; #define PG8_WAIT_L(n) asm volatile("s_waitcnt lgkmcnt(" #n ")" ::: "memory")
; #define PG8_BAR __builtin_amdgcn_s_barrier()
; #define PG8_SCHED __builtin_amdgcn_sched_barrier(0)
; template <class Epi, class Sched, bool ALIGN_EPI = false, bool SP2 = false>
; __device__ __forceinline__ void gemm_phase(PG8_LAS unsigned char* lds, const Gemm g, const Sched& S, const Epi& E) {
;     ...
;             PG8_LDB(B0, 0, 0); PG8_LDB(B1, 0, 1); PG8_SCHED; PG8_LDA(At, 0, 0); PG8_STAGE(PG8_SA(1, 1), a1 + hstep, voffA);
;             PG8_WAIT_V(8); PG8_WAIT_L(0); PG8_BAR; PG8_MMA(0, 0, At, B0); PG8_MMA(0, 1, At, B1); PG8_BAR; PG8_SCHED;
;             PG8_LDA(At, 0, 1); PG8_STAGE(PG8_SB(0, 0), b2, voffB); PG8_STAGE(PG8_SB(0, 1), b2 + hstep, voffB); PG8_STAGE(PG8_SA(0, 0), a2, voffA);
;             PG8_WAIT_V(8); PG8_WAIT_L(0); PG8_BAR; PG8_MMA(1, 0, At, B0); PG8_MMA(1, 1, At, B1); PG8_BAR; PG8_SCHED;
;             PG8_LDB(B0, 1, 0); PG8_LDB(B1, 1, 1); PG8_SCHED; PG8_LDA(At, 1, 0); PG8_STAGE(PG8_SA(0, 1), a2 + hstep, voffA);
;             PG8_WAIT_V(8); PG8_WAIT_L(0); PG8_BAR; PG8_MMA(0, 0, At, B0); PG8_MMA(0, 1, At, B1); PG8_BAR; PG8_SCHED;
	s_setprio 1
	v_mfma_f32_16x16x32_bf16 v[120:123], v[142:145], v[190:193], v[120:123]
	v_mfma_f32_16x16x32_bf16 v[116:119], v[166:169], v[190:193], v[116:119]
	v_mfma_f32_16x16x32_bf16 v[108:111], v[142:145], v[198:201], v[108:111]
	v_mfma_f32_16x16x32_bf16 v[100:103], v[166:169], v[198:201], v[100:103]
	v_mfma_f32_16x16x32_bf16 v[92:95], v[142:145], v[212:215], v[92:95]
	v_mfma_f32_16x16x32_bf16 v[84:87], v[166:169], v[212:215], v[84:87]
	v_mfma_f32_16x16x32_bf16 v[76:79], v[142:145], v[220:223], v[76:79]
	v_mfma_f32_16x16x32_bf16 v[68:71], v[166:169], v[220:223], v[68:71]
	v_mfma_f32_16x16x32_bf16 v[120:123], v[162:165], v[194:197], v[120:123]
	v_mfma_f32_16x16x32_bf16 v[116:119], v[170:173], v[194:197], v[116:119]
	v_mfma_f32_16x16x32_bf16 v[108:111], v[162:165], v[202:205], v[108:111]
	v_mfma_f32_16x16x32_bf16 v[100:103], v[170:173], v[202:205], v[100:103]
	v_mfma_f32_16x16x32_bf16 v[92:95], v[162:165], v[216:219], v[92:95]
	v_mfma_f32_16x16x32_bf16 v[84:87], v[170:173], v[216:219], v[84:87]
	v_mfma_f32_16x16x32_bf16 v[76:79], v[162:165], v[224:227], v[76:79]
	v_mfma_f32_16x16x32_bf16 v[68:71], v[170:173], v[224:227], v[68:71]
	s_setprio 0
	s_setprio 1
	v_mfma_f32_16x16x32_bf16 v[124:127], v[174:177], v[190:193], v[124:127]
	v_mfma_f32_16x16x32_bf16 v[112:115], v[182:185], v[190:193], v[112:115]
	v_mfma_f32_16x16x32_bf16 v[104:107], v[174:177], v[198:201], v[104:107]
	v_mfma_f32_16x16x32_bf16 v[96:99], v[182:185], v[198:201], v[96:99]
	v_mfma_f32_16x16x32_bf16 v[88:91], v[174:177], v[212:215], v[88:91]
	v_mfma_f32_16x16x32_bf16 v[80:83], v[182:185], v[212:215], v[80:83]
	v_mfma_f32_16x16x32_bf16 v[72:75], v[174:177], v[220:223], v[72:75]
	v_mfma_f32_16x16x32_bf16 v[64:67], v[182:185], v[220:223], v[64:67]
	v_mfma_f32_16x16x32_bf16 v[124:127], v[178:181], v[194:197], v[124:127]
	v_mfma_f32_16x16x32_bf16 v[112:115], v[186:189], v[194:197], v[112:115]
	v_mfma_f32_16x16x32_bf16 v[104:107], v[178:181], v[202:205], v[104:107]
	v_mfma_f32_16x16x32_bf16 v[96:99], v[186:189], v[202:205], v[96:99]
	v_mfma_f32_16x16x32_bf16 v[88:91], v[178:181], v[216:219], v[88:91]
	v_mfma_f32_16x16x32_bf16 v[80:83], v[186:189], v[216:219], v[80:83]
	v_mfma_f32_16x16x32_bf16 v[72:75], v[178:181], v[224:227], v[72:75]
	v_mfma_f32_16x16x32_bf16 v[64:67], v[186:189], v[224:227], v[64:67]
	s_setprio 0
	s_barrier
	s_add_i32 s92, s92, s11
	v_lshl_add_u64 v[148:149], s[96:97], 0, v[132:133]
	s_mov_b32 m0, s92
	ds_read_b128 v[190:193], v161 offset:16384
	ds_read_b128 v[194:197], v161 offset:17408
	ds_read_b128 v[198:201], v161 offset:18432
	ds_read_b128 v[202:205], v161 offset:19456
	ds_read_b128 v[212:215], v161 offset:20480
	ds_read_b128 v[216:219], v161 offset:21504
	ds_read_b128 v[220:223], v161 offset:22528
	ds_read_b128 v[224:227], v161 offset:23552
	global_load_lds_dwordx4 v[148:149], off
	s_add_i32 m0, s92, 0x2000
	v_lshl_add_u64 v[152:153], s[96:97], 0, v[128:129]
	s_add_u32 s96, s96, s44
	s_addc_u32 s97, s97, s45
	s_add_i32 s85, s85, s11
	global_load_lds_dwordx4 v[152:153], off
	v_lshl_add_u64 v[206:207], s[96:97], 0, v[132:133]
	s_mov_b32 m0, s85
	v_lshl_add_u64 v[228:229], s[96:97], 0, v[128:129]
	global_load_lds_dwordx4 v[206:207], off
	s_add_i32 m0, s85, 0x2000
	v_lshl_add_u64 v[230:231], s[34:35], 0, v[134:135]
	global_load_lds_dwordx4 v[228:229], off
	s_mov_b32 m0, s61
	v_lshl_add_u64 v[232:233], s[34:35], 0, v[130:131]
	global_load_lds_dwordx4 v[230:231], off
	s_mov_b32 m0, s62
	s_nop 0
	global_load_lds_dwordx4 v[232:233], off
	s_waitcnt vmcnt(8)
	s_waitcnt lgkmcnt(0)
	s_barrier
	s_setprio 1
	v_mfma_f32_16x16x32_bf16 v[60:63], v[142:145], v[190:193], v[60:63]
	v_mfma_f32_16x16x32_bf16 v[52:55], v[166:169], v[190:193], v[52:55]
	v_mfma_f32_16x16x32_bf16 v[44:47], v[142:145], v[198:201], v[44:47]
	v_mfma_f32_16x16x32_bf16 v[36:39], v[166:169], v[198:201], v[36:39]
	v_mfma_f32_16x16x32_bf16 v[28:31], v[142:145], v[212:215], v[28:31]
	v_mfma_f32_16x16x32_bf16 v[20:23], v[166:169], v[212:215], v[20:23]
	v_mfma_f32_16x16x32_bf16 v[12:15], v[142:145], v[220:223], v[12:15]
	v_mfma_f32_16x16x32_bf16 v[4:7], v[166:169], v[220:223], v[4:7]
	v_mfma_f32_16x16x32_bf16 v[60:63], v[162:165], v[194:197], v[60:63]
	v_mfma_f32_16x16x32_bf16 v[52:55], v[170:173], v[194:197], v[52:55]
	v_mfma_f32_16x16x32_bf16 v[44:47], v[162:165], v[202:205], v[44:47]
	v_mfma_f32_16x16x32_bf16 v[36:39], v[170:173], v[202:205], v[36:39]
	v_mfma_f32_16x16x32_bf16 v[28:31], v[162:165], v[216:219], v[28:31]
	v_mfma_f32_16x16x32_bf16 v[20:23], v[170:173], v[216:219], v[20:23]
	v_mfma_f32_16x16x32_bf16 v[12:15], v[162:165], v[224:227], v[12:15]
	v_mfma_f32_16x16x32_bf16 v[4:7], v[170:173], v[224:227], v[4:7]
	s_setprio 0
	s_setprio 1
	v_mfma_f32_16x16x32_bf16 v[56:59], v[174:177], v[190:193], v[56:59]
	v_mfma_f32_16x16x32_bf16 v[48:51], v[182:185], v[190:193], v[48:51]
	v_mfma_f32_16x16x32_bf16 v[40:43], v[174:177], v[198:201], v[40:43]
	v_mfma_f32_16x16x32_bf16 v[32:35], v[182:185], v[198:201], v[32:35]
	v_mfma_f32_16x16x32_bf16 v[24:27], v[174:177], v[212:215], v[24:27]
	v_mfma_f32_16x16x32_bf16 v[16:19], v[182:185], v[212:215], v[16:19]
	v_mfma_f32_16x16x32_bf16 v[8:11], v[174:177], v[220:223], v[8:11]
	v_mfma_f32_16x16x32_bf16 v[0:3], v[182:185], v[220:223], v[0:3]
	v_mfma_f32_16x16x32_bf16 v[56:59], v[178:181], v[194:197], v[56:59]
	v_mfma_f32_16x16x32_bf16 v[48:51], v[186:189], v[194:197], v[48:51]
	v_mfma_f32_16x16x32_bf16 v[40:43], v[178:181], v[202:205], v[40:43]
	v_mfma_f32_16x16x32_bf16 v[32:35], v[186:189], v[202:205], v[32:35]
	v_mfma_f32_16x16x32_bf16 v[24:27], v[178:181], v[216:219], v[24:27]
	v_mfma_f32_16x16x32_bf16 v[16:19], v[186:189], v[216:219], v[16:19]
	v_mfma_f32_16x16x32_bf16 v[8:11], v[178:181], v[224:227], v[8:11]
	v_mfma_f32_16x16x32_bf16 v[0:3], v[186:189], v[224:227], v[0:3]
	s_setprio 0
	s_barrier
; #define PG8_STAGE(bufoff, gbase, voff) do { _Pragma("unroll") for (int _i = 0; _i < 2; ++_i) \
;         __builtin_amdgcn_global_load_lds((const unsigned*)((const char*)(gbase) + (voff)[_i]), (PG8_LAS unsigned*)(lds + (bufoff) + ldsw + _i * 8192), 16, 0, 0); } while (0)
; #define PG8_LDA(dst, b, h) do { _Pragma("unroll") for (int m = 0; m < 4; ++m) _Pragma("unroll") for (int k = 0; k < 2; ++k) dst[m][k] = *(const PG8_LAS bf16x8*)(lds + PG8_SA(b, h) + aoff + m * 2048 + k * 1024); } while (0)
; #define PG8_LDB(dst, b, h) do { _Pragma("unroll") for (int n = 0; n < 2; ++n) _Pragma("unroll") for (int k = 0; k < 2; ++k) dst[n][k] = *(const PG8_LAS bf16x8*)(lds + PG8_SB(b, h) + boff + n * 2048 + k * 1024); } while (0)
; #define PG8_MMA(ai, bj, At, Bt) do { __builtin_amdgcn_s_setprio(1); _Pragma("unroll") for (int m = 0; m < 4; ++m) _Pragma("unroll") for (int n = 0; n < 2; ++n) _Pragma("unroll") for (int k = 0; k < 2; ++k) \
;         acc[ai][bj][m][n] = mma16<Epi::F16>(Bt[n][k], At[m][k], acc[ai][bj][m][n]); __builtin_amdgcn_s_setprio(0); } while (0)
; #define PG8_WAIT_V(n) asm volatile("s_waitcnt vmcnt(" #n ")" ::: "memory")
; #define PG8_WAIT_L(n) asm volatile("s_waitcnt lgkmcnt(" #n ")" ::: "memory")
; #define PG8_BAR __builtin_amdgcn_s_barrier()
; #define PG8_SCHED __builtin_amdgcn_sched_barrier(0)
; template <class Epi, class Sched, bool ALIGN_EPI = false, bool SP2 = false>
; __device__ __forceinline__ void gemm_phase(PG8_LAS unsigned char* lds, const Gemm g, const Sched& S, const Epi& E) {
;     ...
;             PG8_LDB(B0, 1, 0); PG8_LDB(B1, 1, 1); PG8_SCHED; PG8_LDA(At, 1, 0); PG8_STAGE(PG8_SA(0, 1), a2 + hstep, voffA);
;             PG8_WAIT_V(8); PG8_WAIT_L(0); PG8_BAR; PG8_MMA(0, 0, At, B0); PG8_MMA(0, 1, At, B1); PG8_BAR; PG8_SCHED;
	s_add_i32 s85, 0, 0x18000
	v_add_u32_e32 v146, s85, v151
	s_add_i32 s92, 0, 0x1c000
	ds_read_b128 v[142:145], v146
	ds_read_b128 v[162:165], v146 offset:1024
	ds_read_b128 v[166:169], v146 offset:2048
	ds_read_b128 v[170:173], v146 offset:3072
	v_add_u32_e32 v146, s92, v151
	ds_read_b128 v[174:177], v146
	ds_read_b128 v[178:181], v146 offset:1024
	ds_read_b128 v[182:185], v146 offset:2048
	ds_read_b128 v[186:189], v146 offset:3072
	s_add_u32 s34, s34, s44
	s_addc_u32 s35, s35, s45
	s_mov_b32 m0, s63
	v_lshl_add_u64 v[234:235], s[34:35], 0, v[134:135]
	ds_read_b128 v[190:193], v161 offset:32768
	ds_read_b128 v[194:197], v161 offset:33792
	ds_read_b128 v[198:201], v161 offset:34816
	ds_read_b128 v[202:205], v161 offset:35840
	ds_read_b128 v[212:215], v161 offset:36864
	ds_read_b128 v[216:219], v161 offset:37888
	ds_read_b128 v[220:223], v161 offset:38912
	ds_read_b128 v[224:227], v161 offset:39936
	global_load_lds_dwordx4 v[234:235], off
	v_lshl_add_u64 v[234:235], s[34:35], 0, v[130:131]
	s_mov_b32 m0, s64
	s_nop 0
	global_load_lds_dwordx4 v[234:235], off
	s_waitcnt vmcnt(8)
	s_waitcnt lgkmcnt(0)
	s_barrier
	s_setprio 1
	v_mfma_f32_16x16x32_bf16 v[120:123], v[142:145], v[190:193], v[120:123]
	v_mfma_f32_16x16x32_bf16 v[116:119], v[166:169], v[190:193], v[116:119]
	v_mfma_f32_16x16x32_bf16 v[108:111], v[142:145], v[198:201], v[108:111]
	v_mfma_f32_16x16x32_bf16 v[100:103], v[166:169], v[198:201], v[100:103]
	v_mfma_f32_16x16x32_bf16 v[92:95], v[142:145], v[212:215], v[92:95]
	v_mfma_f32_16x16x32_bf16 v[84:87], v[166:169], v[212:215], v[84:87]
	v_mfma_f32_16x16x32_bf16 v[76:79], v[142:145], v[220:223], v[76:79]
	v_mfma_f32_16x16x32_bf16 v[68:71], v[166:169], v[220:223], v[68:71]
	v_mfma_f32_16x16x32_bf16 v[120:123], v[162:165], v[194:197], v[120:123]
	v_mfma_f32_16x16x32_bf16 v[116:119], v[170:173], v[194:197], v[116:119]
	v_mfma_f32_16x16x32_bf16 v[108:111], v[162:165], v[202:205], v[108:111]
	v_mfma_f32_16x16x32_bf16 v[100:103], v[170:173], v[202:205], v[100:103]
	v_mfma_f32_16x16x32_bf16 v[92:95], v[162:165], v[216:219], v[92:95]
	v_mfma_f32_16x16x32_bf16 v[84:87], v[170:173], v[216:219], v[84:87]
	v_mfma_f32_16x16x32_bf16 v[76:79], v[162:165], v[224:227], v[76:79]
	v_mfma_f32_16x16x32_bf16 v[68:71], v[170:173], v[224:227], v[68:71]
	s_setprio 0
	s_setprio 1
	v_mfma_f32_16x16x32_bf16 v[124:127], v[174:177], v[190:193], v[124:127]
	v_mfma_f32_16x16x32_bf16 v[112:115], v[182:185], v[190:193], v[112:115]
	v_mfma_f32_16x16x32_bf16 v[104:107], v[174:177], v[198:201], v[104:107]
	v_mfma_f32_16x16x32_bf16 v[96:99], v[182:185], v[198:201], v[96:99]
	v_mfma_f32_16x16x32_bf16 v[88:91], v[174:177], v[212:215], v[88:91]
	v_mfma_f32_16x16x32_bf16 v[80:83], v[182:185], v[212:215], v[80:83]
	v_mfma_f32_16x16x32_bf16 v[72:75], v[174:177], v[220:223], v[72:75]
	v_mfma_f32_16x16x32_bf16 v[64:67], v[182:185], v[220:223], v[64:67]
	v_mfma_f32_16x16x32_bf16 v[124:127], v[178:181], v[194:197], v[124:127]
	v_mfma_f32_16x16x32_bf16 v[112:115], v[186:189], v[194:197], v[112:115]
	v_mfma_f32_16x16x32_bf16 v[104:107], v[178:181], v[202:205], v[104:107]
	v_mfma_f32_16x16x32_bf16 v[96:99], v[186:189], v[202:205], v[96:99]
	v_mfma_f32_16x16x32_bf16 v[88:91], v[178:181], v[216:219], v[88:91]
	v_mfma_f32_16x16x32_bf16 v[80:83], v[186:189], v[216:219], v[80:83]
	v_mfma_f32_16x16x32_bf16 v[72:75], v[178:181], v[224:227], v[72:75]
	v_mfma_f32_16x16x32_bf16 v[64:67], v[186:189], v[224:227], v[64:67]
	s_setprio 0
	s_barrier
; #define PG8_STAGE(bufoff, gbase, voff) do { _Pragma("unroll") for (int _i = 0; _i < 2; ++_i) \
;         __builtin_amdgcn_global_load_lds((const unsigned*)((const char*)(gbase) + (voff)[_i]), (PG8_LAS unsigned*)(lds + (bufoff) + ldsw + _i * 8192), 16, 0, 0); } while (0)
; #define PG8_LDA(dst, b, h) do { _Pragma("unroll") for (int m = 0; m < 4; ++m) _Pragma("unroll") for (int k = 0; k < 2; ++k) dst[m][k] = *(const PG8_LAS bf16x8*)(lds + PG8_SA(b, h) + aoff + m * 2048 + k * 1024); } while (0)
; #define PG8_LDB(dst, b, h) do { _Pragma("unroll") for (int n = 0; n < 2; ++n) _Pragma("unroll") for (int k = 0; k < 2; ++k) dst[n][k] = *(const PG8_LAS bf16x8*)(lds + PG8_SB(b, h) + boff + n * 2048 + k * 1024); } while (0)
; template <class Epi, class Sched, bool ALIGN_EPI = false, bool SP2 = false>
; __device__ __forceinline__ void gemm_phase(PG8_LAS unsigned char* lds, const Gemm g, const Sched& S, const Epi& E) {
;     ...
;         for (int t = 0; t < nt; t += 2) {
;             const bool last = (t == nt - 2);
;             const char* a1 = cA + (size_t)(t + 1) * kstep;
;             const char* a2 = last ? nA : cA + (size_t)(t + 2) * kstep; const char* b2 = last ? nB : cB + (size_t)(t + 2) * kstep;
;             const char* a3 = a2 + kstep; const char* b3 = b2 + kstep;
;             if (last && has_next) S.a_ready(nxt);
;             if constexpr (SP2) {
;             PG8_LDB(B0, 0, 0); PG8_LDB(B1, 0, 1); PG8_SCHED; PG8_LDA(At, 0, 0); PG8_STAGE(PG8_SA(1, 1), a1 + hstep, voffA);
;             PG8_WAIT_V(8); PG8_WAIT_L(0); PG8_BAR; PG8_MMA(0, 0, At, B0); PG8_MMA(0, 1, At, B1); PG8_BAR; PG8_SCHED;
;             PG8_LDA(At, 0, 1); PG8_STAGE(PG8_SB(0, 0), b2, voffB); PG8_STAGE(PG8_SB(0, 1), b2 + hstep, voffB); PG8_STAGE(PG8_SA(0, 0), a2, voffA);
;             PG8_WAIT_V(8); PG8_WAIT_L(0); PG8_BAR; PG8_MMA(1, 0, At, B0); PG8_MMA(1, 1, At, B1); PG8_BAR; PG8_SCHED;
;             PG8_LDB(B0, 1, 0); PG8_LDB(B1, 1, 1); PG8_SCHED; PG8_LDA(At, 1, 0); PG8_STAGE(PG8_SA(0, 1), a2 + hstep, voffA);
;             PG8_WAIT_V(8); PG8_WAIT_L(0); PG8_BAR; PG8_MMA(0, 0, At, B0); PG8_MMA(0, 1, At, B1); PG8_BAR; PG8_SCHED;
;             PG8_LDA(At, 1, 1); PG8_STAGE(PG8_SB(1, 0), b3, voffB); PG8_STAGE(PG8_SB(1, 1), b3 + hstep, voffB); PG8_STAGE(PG8_SA(1, 0), a3, voffA);
;             PG8_WAIT_V(8); PG8_WAIT_L(0); PG8_BAR; PG8_MMA(1, 0, At, B0); PG8_MMA(1, 1, At, B1); PG8_BAR; PG8_SCHED;
	s_add_i32 s34, s85, s11
	v_lshl_add_u64 v[148:149], v[148:149], 0, s[20:21]
	s_mov_b32 m0, s34
	ds_read_b128 v[190:193], v161 offset:49152
	ds_read_b128 v[194:197], v161 offset:50176
	ds_read_b128 v[198:201], v161 offset:51200
	ds_read_b128 v[202:205], v161 offset:52224
	ds_read_b128 v[212:215], v161 offset:53248
	ds_read_b128 v[216:219], v161 offset:54272
	ds_read_b128 v[220:223], v161 offset:55296
	ds_read_b128 v[224:227], v161 offset:56320
	global_load_lds_dwordx4 v[148:149], off
	v_lshl_add_u64 v[148:149], v[152:153], 0, s[20:21]
	s_add_i32 m0, s34, 0x2000
	s_add_i32 s34, s92, s11
	global_load_lds_dwordx4 v[148:149], off
	v_lshl_add_u64 v[148:149], v[206:207], 0, s[20:21]
	s_mov_b32 m0, s34
	s_nop 0
	global_load_lds_dwordx4 v[148:149], off
	v_lshl_add_u64 v[148:149], v[228:229], 0, s[20:21]
	s_add_i32 m0, s34, 0x2000
	s_nop 0
	global_load_lds_dwordx4 v[148:149], off
	v_lshl_add_u64 v[148:149], v[230:231], 0, s[20:21]
	s_mov_b32 m0, s65
	s_nop 0
	global_load_lds_dwordx4 v[148:149], off
	v_lshl_add_u64 v[148:149], v[232:233], 0, s[20:21]
	s_mov_b32 m0, s66
	s_nop 0
	global_load_lds_dwordx4 v[148:149], off
	s_waitcnt vmcnt(8)
	s_waitcnt lgkmcnt(0)
	s_barrier
	s_setprio 1
	v_mfma_f32_16x16x32_bf16 v[60:63], v[142:145], v[190:193], v[60:63]
	v_mfma_f32_16x16x32_bf16 v[52:55], v[166:169], v[190:193], v[52:55]
	v_mfma_f32_16x16x32_bf16 v[44:47], v[142:145], v[198:201], v[44:47]
	v_mfma_f32_16x16x32_bf16 v[36:39], v[166:169], v[198:201], v[36:39]
	v_mfma_f32_16x16x32_bf16 v[28:31], v[142:145], v[212:215], v[28:31]
	v_mfma_f32_16x16x32_bf16 v[20:23], v[166:169], v[212:215], v[20:23]
	v_mfma_f32_16x16x32_bf16 v[12:15], v[142:145], v[220:223], v[12:15]
	v_mfma_f32_16x16x32_bf16 v[4:7], v[166:169], v[220:223], v[4:7]
	v_mfma_f32_16x16x32_bf16 v[60:63], v[162:165], v[194:197], v[60:63]
	v_mfma_f32_16x16x32_bf16 v[52:55], v[170:173], v[194:197], v[52:55]
	v_mfma_f32_16x16x32_bf16 v[44:47], v[162:165], v[202:205], v[44:47]
	v_mfma_f32_16x16x32_bf16 v[36:39], v[170:173], v[202:205], v[36:39]
	v_mfma_f32_16x16x32_bf16 v[28:31], v[162:165], v[216:219], v[28:31]
	v_mfma_f32_16x16x32_bf16 v[20:23], v[170:173], v[216:219], v[20:23]
	v_mfma_f32_16x16x32_bf16 v[12:15], v[162:165], v[224:227], v[12:15]
	v_mfma_f32_16x16x32_bf16 v[4:7], v[170:173], v[224:227], v[4:7]
	s_setprio 0
	s_setprio 1
	v_mfma_f32_16x16x32_bf16 v[56:59], v[174:177], v[190:193], v[56:59]
	v_mfma_f32_16x16x32_bf16 v[48:51], v[182:185], v[190:193], v[48:51]
	v_mfma_f32_16x16x32_bf16 v[40:43], v[174:177], v[198:201], v[40:43]
	v_mfma_f32_16x16x32_bf16 v[32:35], v[182:185], v[198:201], v[32:35]
	v_mfma_f32_16x16x32_bf16 v[24:27], v[174:177], v[212:215], v[24:27]
	v_mfma_f32_16x16x32_bf16 v[16:19], v[182:185], v[212:215], v[16:19]
	v_mfma_f32_16x16x32_bf16 v[8:11], v[174:177], v[220:223], v[8:11]
	v_mfma_f32_16x16x32_bf16 v[0:3], v[182:185], v[220:223], v[0:3]
	v_mfma_f32_16x16x32_bf16 v[56:59], v[178:181], v[194:197], v[56:59]
	v_mfma_f32_16x16x32_bf16 v[48:51], v[186:189], v[194:197], v[48:51]
	v_mfma_f32_16x16x32_bf16 v[40:43], v[178:181], v[202:205], v[40:43]
	v_mfma_f32_16x16x32_bf16 v[32:35], v[186:189], v[202:205], v[32:35]
	v_mfma_f32_16x16x32_bf16 v[24:27], v[178:181], v[216:219], v[24:27]
	v_mfma_f32_16x16x32_bf16 v[16:19], v[186:189], v[216:219], v[16:19]
	v_mfma_f32_16x16x32_bf16 v[8:11], v[178:181], v[224:227], v[8:11]
	v_mfma_f32_16x16x32_bf16 v[0:3], v[186:189], v[224:227], v[0:3]
	s_setprio 0
	s_barrier
	s_add_u32 s30, s30, 0x100
	s_addc_u32 s31, s31, 0
	s_add_u32 s77, s77, 0x100
	s_addc_u32 s82, s82, 0
	s_cmp_ge_i32 s84, s67
	s_mov_b32 s34, s84
	s_cbranch_scc0 .LBB0_191

; #define PG8_STAGE(bufoff, gbase, voff) do { _Pragma("unroll") for (int _i = 0; _i < 2; ++_i) \
;         __builtin_amdgcn_global_load_lds((const unsigned*)((const char*)(gbase) + (voff)[_i]), (PG8_LAS unsigned*)(lds + (bufoff) + ldsw + _i * 8192), 16, 0, 0); } while (0)
; #define PG8_LDA(dst, b, h) do { _Pragma("unroll") for (int m = 0; m < 4; ++m) _Pragma("unroll") for (int k = 0; k < 2; ++k) dst[m][k] = *(const PG8_LAS bf16x8*)(lds + PG8_SA(b, h) + aoff + m * 2048 + k * 1024); } while (0)
; #define PG8_LDB(dst, b, h) do { _Pragma("unroll") for (int n = 0; n < 2; ++n) _Pragma("unroll") for (int k = 0; k < 2; ++k) dst[n][k] = *(const PG8_LAS bf16x8*)(lds + PG8_SB(b, h) + boff + n * 2048 + k * 1024); } while (0)
; #define PG8_MMA(ai, bj, At, Bt) do { __builtin_amdgcn_s_setprio(1); _Pragma("unroll") for (int m = 0; m < 4; ++m) _Pragma("unroll") for (int n = 0; n < 2; ++n) _Pragma("unroll") for (int k = 0; k < 2; ++k) \
;         acc[ai][bj][m][n] = mma16<Epi::F16>(Bt[n][k], At[m][k], acc[ai][bj][m][n]); __builtin_amdgcn_s_setprio(0); } while (0)
; #define PG8_WAIT_V(n) asm volatile("s_waitcnt vmcnt(" #n ")" ::: "memory")
; #define PG8_WAIT_L(n) asm volatile("s_waitcnt lgkmcnt(" #n ")" ::: "memory")
; #define PG8_BAR __builtin_amdgcn_s_barrier()
; #define PG8_SCHED __builtin_amdgcn_sched_barrier(0)
; template <class Epi, class Sched, bool ALIGN_EPI = false, bool SP2 = false>
; __device__ __forceinline__ void gemm_phase(PG8_LAS unsigned char* lds, const Gemm g, const Sched& S, const Epi& E) {
;     ...
;             PG8_LDB(B0, 0, 0); PG8_LDB(B1, 0, 1); PG8_SCHED; PG8_LDA(At, 0, 0); PG8_STAGE(PG8_SA(1, 1), a1 + hstep, voffA);
;             PG8_WAIT_V(8); PG8_WAIT_L(0); PG8_BAR; PG8_MMA(0, 0, At, B0); PG8_MMA(0, 1, At, B1); PG8_BAR; PG8_SCHED;
;             PG8_LDA(At, 0, 1); PG8_STAGE(PG8_SB(0, 0), b2, voffB); PG8_STAGE(PG8_SB(0, 1), b2 + hstep, voffB); PG8_STAGE(PG8_SA(0, 0), a2, voffA);
;             PG8_WAIT_V(8); PG8_WAIT_L(0); PG8_BAR; PG8_MMA(1, 0, At, B0); PG8_MMA(1, 1, At, B1); PG8_BAR; PG8_SCHED;
;             PG8_LDB(B0, 1, 0); PG8_LDB(B1, 1, 1); PG8_SCHED; PG8_LDA(At, 1, 0); PG8_STAGE(PG8_SA(0, 1), a2 + hstep, voffA);
;             PG8_WAIT_V(8); PG8_WAIT_L(0); PG8_BAR; PG8_MMA(0, 0, At, B0); PG8_MMA(0, 1, At, B1); PG8_BAR; PG8_SCHED;
.Lpeel_k2:
	s_add_u32 s30, s30, 0x80
	s_addc_u32 s31, s31, 0
	s_add_u32 s29, s34, 0x100
	s_addc_u32 s85, s35, 0
	s_mov_b32 s34, 0
	s_add_i32 s92, s34, 2
	s_add_u32 s96, s30, 0x80
	s_addc_u32 s35, s31, 0
	s_add_i32 vcc_lo, 0, 0x10000
	s_cmp_eq_u32 s65, s34
	s_cselect_b32 s35, s1, s35
	s_cselect_b32 s34, s0, s96
	s_cselect_b32 s97, s61, s85
	s_cselect_b32 s96, s60, s29
	s_add_i32 vcc_hi, 0, 0x14000
	v_add_u32_e32 v150, vcc_lo, v131
	v_add_u32_e32 v166, vcc_hi, v131
	ds_read_b128 v[138:141], v150
	ds_read_b128 v[142:145], v150 offset:1024
	ds_read_b128 v[146:149], v150 offset:2048
	ds_read_b128 v[150:153], v150 offset:3072
	ds_read_b128 v[154:157], v166
	ds_read_b128 v[158:161], v166 offset:1024
	ds_read_b128 v[162:165], v166 offset:2048
	ds_read_b128 v[166:169], v166 offset:3072
	v_lshl_add_u64 v[190:191], s[30:31], 0, v[134:135]
	s_add_i32 m0, s8, 0xc000
	ds_read_b128 v[170:173], v199
	ds_read_b128 v[174:177], v199 offset:1024
	ds_read_b128 v[178:181], v199 offset:2048
	ds_read_b128 v[182:185], v199 offset:3072
	ds_read_b128 v[186:189], v199 offset:4096
	ds_read_b128 v[200:203], v199 offset:5120
	ds_read_b128 v[204:207], v199 offset:6144
	ds_read_b128 v[212:215], v199 offset:7168
	global_load_lds_dwordx4 v[190:191], off
	v_lshl_add_u64 v[190:191], s[30:31], 0, v[136:137]
	s_add_i32 m0, s8, 0xe000
	s_nop 0
	global_load_lds_dwordx4 v[190:191], off
	s_waitcnt vmcnt(8)
	s_waitcnt lgkmcnt(0)
	s_barrier
	s_setprio 1
	v_mfma_f32_16x16x32_bf16 v[120:123], v[138:141], v[170:173], 0
	v_mfma_f32_16x16x32_bf16 v[124:127], v[146:149], v[170:173], 0
	v_mfma_f32_16x16x32_bf16 v[108:111], v[138:141], v[178:181], 0
	v_mfma_f32_16x16x32_bf16 v[104:107], v[146:149], v[178:181], 0
	v_mfma_f32_16x16x32_bf16 v[92:95], v[138:141], v[186:189], 0
	v_mfma_f32_16x16x32_bf16 v[88:91], v[146:149], v[186:189], 0
	v_mfma_f32_16x16x32_bf16 v[76:79], v[138:141], v[204:207], 0
	v_mfma_f32_16x16x32_bf16 v[72:75], v[146:149], v[204:207], 0
	v_mfma_f32_16x16x32_bf16 v[120:123], v[142:145], v[174:177], v[120:123]
	v_mfma_f32_16x16x32_bf16 v[124:127], v[150:153], v[174:177], v[124:127]
	v_mfma_f32_16x16x32_bf16 v[108:111], v[142:145], v[182:185], v[108:111]
	v_mfma_f32_16x16x32_bf16 v[104:107], v[150:153], v[182:185], v[104:107]
	v_mfma_f32_16x16x32_bf16 v[92:95], v[142:145], v[200:203], v[92:95]
	v_mfma_f32_16x16x32_bf16 v[88:91], v[150:153], v[200:203], v[88:91]
	v_mfma_f32_16x16x32_bf16 v[76:79], v[142:145], v[212:215], v[76:79]
	v_mfma_f32_16x16x32_bf16 v[72:75], v[150:153], v[212:215], v[72:75]
	s_setprio 0
	s_setprio 1
	v_mfma_f32_16x16x32_bf16 v[116:119], v[154:157], v[170:173], 0
	v_mfma_f32_16x16x32_bf16 v[112:115], v[162:165], v[170:173], 0
	v_mfma_f32_16x16x32_bf16 v[100:103], v[154:157], v[178:181], 0
	v_mfma_f32_16x16x32_bf16 v[96:99], v[162:165], v[178:181], 0
	v_mfma_f32_16x16x32_bf16 v[84:87], v[154:157], v[186:189], 0
	v_mfma_f32_16x16x32_bf16 v[80:83], v[162:165], v[186:189], 0
	v_mfma_f32_16x16x32_bf16 v[68:71], v[154:157], v[204:207], 0
	v_mfma_f32_16x16x32_bf16 v[64:67], v[162:165], v[204:207], 0
	v_mfma_f32_16x16x32_bf16 v[116:119], v[158:161], v[174:177], v[116:119]
	v_mfma_f32_16x16x32_bf16 v[112:115], v[166:169], v[174:177], v[112:115]
	v_mfma_f32_16x16x32_bf16 v[100:103], v[158:161], v[182:185], v[100:103]
	v_mfma_f32_16x16x32_bf16 v[96:99], v[166:169], v[182:185], v[96:99]
	v_mfma_f32_16x16x32_bf16 v[84:87], v[158:161], v[200:203], v[84:87]
	v_mfma_f32_16x16x32_bf16 v[80:83], v[166:169], v[200:203], v[80:83]
	v_mfma_f32_16x16x32_bf16 v[68:71], v[158:161], v[212:215], v[68:71]
	v_mfma_f32_16x16x32_bf16 v[64:67], v[166:169], v[212:215], v[64:67]
	s_setprio 0
	s_barrier
	s_add_i32 vcc_lo, vcc_lo, s3
	v_lshl_add_u64 v[190:191], s[96:97], 0, v[208:209]
	s_mov_b32 m0, vcc_lo
	ds_read_b128 v[170:173], v199 offset:16384
	ds_read_b128 v[174:177], v199 offset:17408
	ds_read_b128 v[178:181], v199 offset:18432
	ds_read_b128 v[182:185], v199 offset:19456
	ds_read_b128 v[186:189], v199 offset:20480
	ds_read_b128 v[200:203], v199 offset:21504
	ds_read_b128 v[204:207], v199 offset:22528
	ds_read_b128 v[212:215], v199 offset:23552
	global_load_lds_dwordx4 v[190:191], off
	s_add_i32 m0, vcc_lo, 0x2000
	v_lshl_add_u64 v[194:195], s[96:97], 0, v[128:129]
	s_add_u32 s96, s96, s50
	s_addc_u32 s97, s97, s51
	s_add_i32 vcc_lo, vcc_hi, s3
	global_load_lds_dwordx4 v[194:195], off
	v_lshl_add_u64 v[216:217], s[96:97], 0, v[208:209]
	s_mov_b32 m0, vcc_lo
	v_lshl_add_u64 v[218:219], s[96:97], 0, v[128:129]
	global_load_lds_dwordx4 v[216:217], off
	s_add_i32 m0, vcc_lo, 0x2000
	v_lshl_add_u64 v[220:221], s[34:35], 0, v[208:209]
	global_load_lds_dwordx4 v[218:219], off
	s_mov_b32 m0, s8
	v_lshl_add_u64 v[222:223], s[34:35], 0, v[128:129]
	global_load_lds_dwordx4 v[220:221], off
	s_mov_b32 m0, s9
	s_nop 0
	global_load_lds_dwordx4 v[222:223], off
	s_waitcnt vmcnt(8)
	s_waitcnt lgkmcnt(0)
	s_barrier
; #define PG8_STAGE(bufoff, gbase, voff) do { _Pragma("unroll") for (int _i = 0; _i < 2; ++_i) \
;         __builtin_amdgcn_global_load_lds((const unsigned*)((const char*)(gbase) + (voff)[_i]), (PG8_LAS unsigned*)(lds + (bufoff) + ldsw + _i * 8192), 16, 0, 0); } while (0)
; #define PG8_LDA(dst, b, h) do { _Pragma("unroll") for (int m = 0; m < 4; ++m) _Pragma("unroll") for (int k = 0; k < 2; ++k) dst[m][k] = *(const PG8_LAS bf16x8*)(lds + PG8_SA(b, h) + aoff + m * 2048 + k * 1024); } while (0)
; #define PG8_LDB(dst, b, h) do { _Pragma("unroll") for (int n = 0; n < 2; ++n) _Pragma("unroll") for (int k = 0; k < 2; ++k) dst[n][k] = *(const PG8_LAS bf16x8*)(lds + PG8_SB(b, h) + boff + n * 2048 + k * 1024); } while (0)
; #define PG8_MMA(ai, bj, At, Bt) do { __builtin_amdgcn_s_setprio(1); _Pragma("unroll") for (int m = 0; m < 4; ++m) _Pragma("unroll") for (int n = 0; n < 2; ++n) _Pragma("unroll") for (int k = 0; k < 2; ++k) \
;         acc[ai][bj][m][n] = mma16<Epi::F16>(Bt[n][k], At[m][k], acc[ai][bj][m][n]); __builtin_amdgcn_s_setprio(0); } while (0)
; #define PG8_WAIT_V(n) asm volatile("s_waitcnt vmcnt(" #n ")" ::: "memory")
; #define PG8_WAIT_L(n) asm volatile("s_waitcnt lgkmcnt(" #n ")" ::: "memory")
; #define PG8_BAR __builtin_amdgcn_s_barrier()
; #define PG8_SCHED __builtin_amdgcn_sched_barrier(0)
; template <class Epi, class Sched, bool ALIGN_EPI = false, bool SP2 = false>
; __device__ __forceinline__ void gemm_phase(PG8_LAS unsigned char* lds, const Gemm g, const Sched& S, const Epi& E) {
;     ...
;             PG8_WAIT_V(8); PG8_WAIT_L(0); PG8_BAR; PG8_MMA(1, 0, At, B0); PG8_MMA(1, 1, At, B1); PG8_BAR; PG8_SCHED;
;             PG8_LDB(B0, 1, 0); PG8_LDB(B1, 1, 1); PG8_SCHED; PG8_LDA(At, 1, 0); PG8_STAGE(PG8_SA(0, 1), a2 + hstep, voffA);
;             PG8_WAIT_V(8); PG8_WAIT_L(0); PG8_BAR; PG8_MMA(0, 0, At, B0); PG8_MMA(0, 1, At, B1); PG8_BAR; PG8_SCHED;
	s_setprio 1
	v_mfma_f32_16x16x32_bf16 v[60:63], v[138:141], v[170:173], 0
	v_mfma_f32_16x16x32_bf16 v[56:59], v[146:149], v[170:173], 0
	v_mfma_f32_16x16x32_bf16 v[44:47], v[138:141], v[178:181], 0
	v_mfma_f32_16x16x32_bf16 v[40:43], v[146:149], v[178:181], 0
	v_mfma_f32_16x16x32_bf16 v[28:31], v[138:141], v[186:189], 0
	v_mfma_f32_16x16x32_bf16 v[24:27], v[146:149], v[186:189], 0
	v_mfma_f32_16x16x32_bf16 v[12:15], v[138:141], v[204:207], 0
	v_mfma_f32_16x16x32_bf16 v[8:11], v[146:149], v[204:207], 0
	v_mfma_f32_16x16x32_bf16 v[60:63], v[142:145], v[174:177], v[60:63]
	v_mfma_f32_16x16x32_bf16 v[56:59], v[150:153], v[174:177], v[56:59]
	v_mfma_f32_16x16x32_bf16 v[44:47], v[142:145], v[182:185], v[44:47]
	v_mfma_f32_16x16x32_bf16 v[40:43], v[150:153], v[182:185], v[40:43]
	v_mfma_f32_16x16x32_bf16 v[28:31], v[142:145], v[200:203], v[28:31]
	v_mfma_f32_16x16x32_bf16 v[24:27], v[150:153], v[200:203], v[24:27]
	v_mfma_f32_16x16x32_bf16 v[12:15], v[142:145], v[212:215], v[12:15]
	v_mfma_f32_16x16x32_bf16 v[8:11], v[150:153], v[212:215], v[8:11]
	s_setprio 0
	s_setprio 1
	v_mfma_f32_16x16x32_bf16 v[52:55], v[154:157], v[170:173], 0
	v_mfma_f32_16x16x32_bf16 v[48:51], v[162:165], v[170:173], 0
	v_mfma_f32_16x16x32_bf16 v[36:39], v[154:157], v[178:181], 0
	v_mfma_f32_16x16x32_bf16 v[32:35], v[162:165], v[178:181], 0
	v_mfma_f32_16x16x32_bf16 v[20:23], v[154:157], v[186:189], 0
	v_mfma_f32_16x16x32_bf16 v[16:19], v[162:165], v[186:189], 0
	v_mfma_f32_16x16x32_bf16 v[4:7], v[154:157], v[204:207], 0
	v_mfma_f32_16x16x32_bf16 v[0:3], v[162:165], v[204:207], 0
	v_mfma_f32_16x16x32_bf16 v[52:55], v[158:161], v[174:177], v[52:55]
	v_mfma_f32_16x16x32_bf16 v[48:51], v[166:169], v[174:177], v[48:51]
	v_mfma_f32_16x16x32_bf16 v[36:39], v[158:161], v[182:185], v[36:39]
	v_mfma_f32_16x16x32_bf16 v[32:35], v[166:169], v[182:185], v[32:35]
	v_mfma_f32_16x16x32_bf16 v[20:23], v[158:161], v[200:203], v[20:23]
	v_mfma_f32_16x16x32_bf16 v[16:19], v[166:169], v[200:203], v[16:19]
	v_mfma_f32_16x16x32_bf16 v[4:7], v[158:161], v[212:215], v[4:7]
	v_mfma_f32_16x16x32_bf16 v[0:3], v[166:169], v[212:215], v[0:3]
	s_setprio 0
	s_barrier
	s_add_i32 s96, 0, 0x18000
	s_add_i32 s97, 0, 0x1c000
	v_add_u32_e32 v150, s96, v131
	v_add_u32_e32 v166, s97, v131
	ds_read_b128 v[138:141], v150
	ds_read_b128 v[142:145], v150 offset:1024
	ds_read_b128 v[146:149], v150 offset:2048
	ds_read_b128 v[150:153], v150 offset:3072
	ds_read_b128 v[154:157], v166
	ds_read_b128 v[158:161], v166 offset:1024
	ds_read_b128 v[162:165], v166 offset:2048
	ds_read_b128 v[166:169], v166 offset:3072
	s_add_u32 s34, s34, s50
	s_addc_u32 s35, s35, s51
	s_mov_b32 m0, s11
	v_lshl_add_u64 v[224:225], s[34:35], 0, v[208:209]
	ds_read_b128 v[170:173], v199 offset:32768
	ds_read_b128 v[174:177], v199 offset:33792
	ds_read_b128 v[178:181], v199 offset:34816
	ds_read_b128 v[182:185], v199 offset:35840
	ds_read_b128 v[186:189], v199 offset:36864
	ds_read_b128 v[200:203], v199 offset:37888
	ds_read_b128 v[204:207], v199 offset:38912
	ds_read_b128 v[212:215], v199 offset:39936
	global_load_lds_dwordx4 v[224:225], off
	v_lshl_add_u64 v[224:225], s[34:35], 0, v[128:129]
	s_mov_b32 m0, s36
	s_nop 0
	global_load_lds_dwordx4 v[224:225], off
	s_waitcnt vmcnt(8)
	s_waitcnt lgkmcnt(0)
	s_barrier
	s_setprio 1
	v_mfma_f32_16x16x32_bf16 v[120:123], v[138:141], v[170:173], v[120:123]
	v_mfma_f32_16x16x32_bf16 v[124:127], v[146:149], v[170:173], v[124:127]
	v_mfma_f32_16x16x32_bf16 v[108:111], v[138:141], v[178:181], v[108:111]
	v_mfma_f32_16x16x32_bf16 v[104:107], v[146:149], v[178:181], v[104:107]
	v_mfma_f32_16x16x32_bf16 v[92:95], v[138:141], v[186:189], v[92:95]
	v_mfma_f32_16x16x32_bf16 v[88:91], v[146:149], v[186:189], v[88:91]
	v_mfma_f32_16x16x32_bf16 v[76:79], v[138:141], v[204:207], v[76:79]
	v_mfma_f32_16x16x32_bf16 v[72:75], v[146:149], v[204:207], v[72:75]
	v_mfma_f32_16x16x32_bf16 v[120:123], v[142:145], v[174:177], v[120:123]
	v_mfma_f32_16x16x32_bf16 v[124:127], v[150:153], v[174:177], v[124:127]
	v_mfma_f32_16x16x32_bf16 v[108:111], v[142:145], v[182:185], v[108:111]
	v_mfma_f32_16x16x32_bf16 v[104:107], v[150:153], v[182:185], v[104:107]
	v_mfma_f32_16x16x32_bf16 v[92:95], v[142:145], v[200:203], v[92:95]
	v_mfma_f32_16x16x32_bf16 v[88:91], v[150:153], v[200:203], v[88:91]
	v_mfma_f32_16x16x32_bf16 v[76:79], v[142:145], v[212:215], v[76:79]
	v_mfma_f32_16x16x32_bf16 v[72:75], v[150:153], v[212:215], v[72:75]
	s_setprio 0
	s_setprio 1
	v_mfma_f32_16x16x32_bf16 v[116:119], v[154:157], v[170:173], v[116:119]
	v_mfma_f32_16x16x32_bf16 v[112:115], v[162:165], v[170:173], v[112:115]
	v_mfma_f32_16x16x32_bf16 v[100:103], v[154:157], v[178:181], v[100:103]
	v_mfma_f32_16x16x32_bf16 v[96:99], v[162:165], v[178:181], v[96:99]
	v_mfma_f32_16x16x32_bf16 v[84:87], v[154:157], v[186:189], v[84:87]
	v_mfma_f32_16x16x32_bf16 v[80:83], v[162:165], v[186:189], v[80:83]
	v_mfma_f32_16x16x32_bf16 v[68:71], v[154:157], v[204:207], v[68:71]
	v_mfma_f32_16x16x32_bf16 v[64:67], v[162:165], v[204:207], v[64:67]
	v_mfma_f32_16x16x32_bf16 v[116:119], v[158:161], v[174:177], v[116:119]
	v_mfma_f32_16x16x32_bf16 v[112:115], v[166:169], v[174:177], v[112:115]
	v_mfma_f32_16x16x32_bf16 v[100:103], v[158:161], v[182:185], v[100:103]
	v_mfma_f32_16x16x32_bf16 v[96:99], v[166:169], v[182:185], v[96:99]
	v_mfma_f32_16x16x32_bf16 v[84:87], v[158:161], v[200:203], v[84:87]
	v_mfma_f32_16x16x32_bf16 v[80:83], v[166:169], v[200:203], v[80:83]
	v_mfma_f32_16x16x32_bf16 v[68:71], v[158:161], v[212:215], v[68:71]
	v_mfma_f32_16x16x32_bf16 v[64:67], v[166:169], v[212:215], v[64:67]
	s_setprio 0
	s_barrier
; #define PG8_STAGE(bufoff, gbase, voff) do { _Pragma("unroll") for (int _i = 0; _i < 2; ++_i) \
;         __builtin_amdgcn_global_load_lds((const unsigned*)((const char*)(gbase) + (voff)[_i]), (PG8_LAS unsigned*)(lds + (bufoff) + ldsw + _i * 8192), 16, 0, 0); } while (0)
; #define PG8_LDA(dst, b, h) do { _Pragma("unroll") for (int m = 0; m < 4; ++m) _Pragma("unroll") for (int k = 0; k < 2; ++k) dst[m][k] = *(const PG8_LAS bf16x8*)(lds + PG8_SA(b, h) + aoff + m * 2048 + k * 1024); } while (0)
; #define PG8_LDB(dst, b, h) do { _Pragma("unroll") for (int n = 0; n < 2; ++n) _Pragma("unroll") for (int k = 0; k < 2; ++k) dst[n][k] = *(const PG8_LAS bf16x8*)(lds + PG8_SB(b, h) + boff + n * 2048 + k * 1024); } while (0)
; template <class Epi, class Sched, bool ALIGN_EPI = false, bool SP2 = false>
; __device__ __forceinline__ void gemm_phase(PG8_LAS unsigned char* lds, const Gemm g, const Sched& S, const Epi& E) {
;     ...
;         for (int t = 0; t < nt; t += 2) {
;             const bool last = (t == nt - 2);
;             const char* a1 = cA + (size_t)(t + 1) * kstep;
;             const char* a2 = last ? nA : cA + (size_t)(t + 2) * kstep; const char* b2 = last ? nB : cB + (size_t)(t + 2) * kstep;
;             const char* a3 = a2 + kstep; const char* b3 = b2 + kstep;
;             if (last && has_next) S.a_ready(nxt);
;             if constexpr (SP2) {
;             PG8_LDB(B0, 0, 0); PG8_LDB(B1, 0, 1); PG8_SCHED; PG8_LDA(At, 0, 0); PG8_STAGE(PG8_SA(1, 1), a1 + hstep, voffA);
;             PG8_WAIT_V(8); PG8_WAIT_L(0); PG8_BAR; PG8_MMA(0, 0, At, B0); PG8_MMA(0, 1, At, B1); PG8_BAR; PG8_SCHED;
;             PG8_LDA(At, 0, 1); PG8_STAGE(PG8_SB(0, 0), b2, voffB); PG8_STAGE(PG8_SB(0, 1), b2 + hstep, voffB); PG8_STAGE(PG8_SA(0, 0), a2, voffA);
;             PG8_WAIT_V(8); PG8_WAIT_L(0); PG8_BAR; PG8_MMA(1, 0, At, B0); PG8_MMA(1, 1, At, B1); PG8_BAR; PG8_SCHED;
;             PG8_LDB(B0, 1, 0); PG8_LDB(B1, 1, 1); PG8_SCHED; PG8_LDA(At, 1, 0); PG8_STAGE(PG8_SA(0, 1), a2 + hstep, voffA);
;             PG8_WAIT_V(8); PG8_WAIT_L(0); PG8_BAR; PG8_MMA(0, 0, At, B0); PG8_MMA(0, 1, At, B1); PG8_BAR; PG8_SCHED;
;             PG8_LDA(At, 1, 1); PG8_STAGE(PG8_SB(1, 0), b3, voffB); PG8_STAGE(PG8_SB(1, 1), b3 + hstep, voffB); PG8_STAGE(PG8_SA(1, 0), a3, voffA);
;             PG8_WAIT_V(8); PG8_WAIT_L(0); PG8_BAR; PG8_MMA(1, 0, At, B0); PG8_MMA(1, 1, At, B1); PG8_BAR; PG8_SCHED;
	s_add_i32 s34, s96, s3
	v_lshl_add_u64 v[190:191], v[190:191], 0, s[20:21]
	s_mov_b32 m0, s34
	ds_read_b128 v[170:173], v199 offset:49152
	ds_read_b128 v[174:177], v199 offset:50176
	ds_read_b128 v[178:181], v199 offset:51200
	ds_read_b128 v[182:185], v199 offset:52224
	ds_read_b128 v[186:189], v199 offset:53248
	ds_read_b128 v[200:203], v199 offset:54272
	ds_read_b128 v[204:207], v199 offset:55296
	ds_read_b128 v[212:215], v199 offset:56320
	global_load_lds_dwordx4 v[190:191], off
	v_lshl_add_u64 v[190:191], v[194:195], 0, s[20:21]
	s_add_i32 m0, s34, 0x2000
	s_add_i32 s34, s97, s3
	global_load_lds_dwordx4 v[190:191], off
	v_lshl_add_u64 v[190:191], v[216:217], 0, s[20:21]
	s_mov_b32 m0, s34
	s_nop 0
	global_load_lds_dwordx4 v[190:191], off
	v_lshl_add_u64 v[190:191], v[218:219], 0, s[20:21]
	s_add_i32 m0, s34, 0x2000
	s_nop 0
	global_load_lds_dwordx4 v[190:191], off
	v_lshl_add_u64 v[190:191], v[220:221], 0, s[20:21]
	s_mov_b32 m0, s48
	s_nop 0
	global_load_lds_dwordx4 v[190:191], off
	v_lshl_add_u64 v[190:191], v[222:223], 0, s[20:21]
	s_mov_b32 m0, s64
	s_nop 0
	global_load_lds_dwordx4 v[190:191], off
	s_waitcnt vmcnt(8)
	s_waitcnt lgkmcnt(0)
	s_barrier
	s_setprio 1
	v_mfma_f32_16x16x32_bf16 v[60:63], v[138:141], v[170:173], v[60:63]
	v_mfma_f32_16x16x32_bf16 v[56:59], v[146:149], v[170:173], v[56:59]
	v_mfma_f32_16x16x32_bf16 v[44:47], v[138:141], v[178:181], v[44:47]
	v_mfma_f32_16x16x32_bf16 v[40:43], v[146:149], v[178:181], v[40:43]
	v_mfma_f32_16x16x32_bf16 v[28:31], v[138:141], v[186:189], v[28:31]
	v_mfma_f32_16x16x32_bf16 v[24:27], v[146:149], v[186:189], v[24:27]
	v_mfma_f32_16x16x32_bf16 v[12:15], v[138:141], v[204:207], v[12:15]
	v_mfma_f32_16x16x32_bf16 v[8:11], v[146:149], v[204:207], v[8:11]
	v_mfma_f32_16x16x32_bf16 v[60:63], v[142:145], v[174:177], v[60:63]
	v_mfma_f32_16x16x32_bf16 v[56:59], v[150:153], v[174:177], v[56:59]
	v_mfma_f32_16x16x32_bf16 v[44:47], v[142:145], v[182:185], v[44:47]
	v_mfma_f32_16x16x32_bf16 v[40:43], v[150:153], v[182:185], v[40:43]
	v_mfma_f32_16x16x32_bf16 v[28:31], v[142:145], v[200:203], v[28:31]
	v_mfma_f32_16x16x32_bf16 v[24:27], v[150:153], v[200:203], v[24:27]
	v_mfma_f32_16x16x32_bf16 v[12:15], v[142:145], v[212:215], v[12:15]
	v_mfma_f32_16x16x32_bf16 v[8:11], v[150:153], v[212:215], v[8:11]
	s_setprio 0
	s_setprio 1
	v_mfma_f32_16x16x32_bf16 v[52:55], v[154:157], v[170:173], v[52:55]
	v_mfma_f32_16x16x32_bf16 v[48:51], v[162:165], v[170:173], v[48:51]
	v_mfma_f32_16x16x32_bf16 v[36:39], v[154:157], v[178:181], v[36:39]
	v_mfma_f32_16x16x32_bf16 v[32:35], v[162:165], v[178:181], v[32:35]
	v_mfma_f32_16x16x32_bf16 v[20:23], v[154:157], v[186:189], v[20:23]
	v_mfma_f32_16x16x32_bf16 v[16:19], v[162:165], v[186:189], v[16:19]
	v_mfma_f32_16x16x32_bf16 v[4:7], v[154:157], v[204:207], v[4:7]
	v_mfma_f32_16x16x32_bf16 v[0:3], v[162:165], v[204:207], v[0:3]
	v_mfma_f32_16x16x32_bf16 v[52:55], v[158:161], v[174:177], v[52:55]
	v_mfma_f32_16x16x32_bf16 v[48:51], v[166:169], v[174:177], v[48:51]
	v_mfma_f32_16x16x32_bf16 v[36:39], v[158:161], v[182:185], v[36:39]
	v_mfma_f32_16x16x32_bf16 v[32:35], v[166:169], v[182:185], v[32:35]
	v_mfma_f32_16x16x32_bf16 v[20:23], v[158:161], v[200:203], v[20:23]
	v_mfma_f32_16x16x32_bf16 v[16:19], v[166:169], v[200:203], v[16:19]
	v_mfma_f32_16x16x32_bf16 v[4:7], v[158:161], v[212:215], v[4:7]
	v_mfma_f32_16x16x32_bf16 v[0:3], v[166:169], v[212:215], v[0:3]
	s_setprio 0
	s_barrier
	s_add_u32 s30, s30, 0x100
	s_addc_u32 s31, s31, 0
	s_add_u32 s29, s29, 0x100
	s_addc_u32 s85, s85, 0
	s_cmp_ge_i32 s92, s37
	s_mov_b32 s34, s92
	s_cbranch_scc0 .LBB0_312
	s_branch .LBB0_313
.LBB0_312:
	s_add_i32 s92, s34, 2
	s_add_u32 s96, s30, 0x80
	s_addc_u32 s35, s31, 0
	s_add_i32 vcc_lo, 0, 0x10000
	s_cmp_eq_u32 s65, s34
	s_cselect_b32 s35, s1, s35
	s_cselect_b32 s34, s0, s96
	s_cselect_b32 s97, s61, s85
	s_cselect_b32 s96, s60, s29
	s_add_i32 vcc_hi, 0, 0x14000
	v_add_u32_e32 v150, vcc_lo, v131
	v_add_u32_e32 v166, vcc_hi, v131
	ds_read_b128 v[138:141], v150
	ds_read_b128 v[142:145], v150 offset:1024
	ds_read_b128 v[146:149], v150 offset:2048
	ds_read_b128 v[150:153], v150 offset:3072
	ds_read_b128 v[154:157], v166
	ds_read_b128 v[158:161], v166 offset:1024
	ds_read_b128 v[162:165], v166 offset:2048
	ds_read_b128 v[166:169], v166 offset:3072
	v_lshl_add_u64 v[190:191], s[30:31], 0, v[134:135]
	s_add_i32 m0, s8, 0xc000
	ds_read_b128 v[170:173], v199
	ds_read_b128 v[174:177], v199 offset:1024
	ds_read_b128 v[178:181], v199 offset:2048
	ds_read_b128 v[182:185], v199 offset:3072
	ds_read_b128 v[186:189], v199 offset:4096
	ds_read_b128 v[200:203], v199 offset:5120
	ds_read_b128 v[204:207], v199 offset:6144
	ds_read_b128 v[212:215], v199 offset:7168
	global_load_lds_dwordx4 v[190:191], off
	v_lshl_add_u64 v[190:191], s[30:31], 0, v[136:137]
	s_add_i32 m0, s8, 0xe000
	s_nop 0
	global_load_lds_dwordx4 v[190:191], off
	s_waitcnt vmcnt(8)
	s_waitcnt lgkmcnt(0)
	s_barrier
; #define PG8_STAGE(bufoff, gbase, voff) do { _Pragma("unroll") for (int _i = 0; _i < 2; ++_i) \
;         __builtin_amdgcn_global_load_lds((const unsigned*)((const char*)(gbase) + (voff)[_i]), (PG8_LAS unsigned*)(lds + (bufoff) + ldsw + _i * 8192), 16, 0, 0); } while (0)
; #define PG8_LDA(dst, b, h) do { _Pragma("unroll") for (int m = 0; m < 4; ++m) _Pragma("unroll") for (int k = 0; k < 2; ++k) dst[m][k] = *(const PG8_LAS bf16x8*)(lds + PG8_SA(b, h) + aoff + m * 2048 + k * 1024); } while (0)
; #define PG8_LDB(dst, b, h) do { _Pragma("unroll") for (int n = 0; n < 2; ++n) _Pragma("unroll") for (int k = 0; k < 2; ++k) dst[n][k] = *(const PG8_LAS bf16x8*)(lds + PG8_SB(b, h) + boff + n * 2048 + k * 1024); } while (0)
; #define PG8_MMA(ai, bj, At, Bt) do { __builtin_amdgcn_s_setprio(1); _Pragma("unroll") for (int m = 0; m < 4; ++m) _Pragma("unroll") for (int n = 0; n < 2; ++n) _Pragma("unroll") for (int k = 0; k < 2; ++k) \
;         acc[ai][bj][m][n] = mma16<Epi::F16>(Bt[n][k], At[m][k], acc[ai][bj][m][n]); __builtin_amdgcn_s_setprio(0); } while (0)
; #define PG8_WAIT_V(n) asm volatile("s_waitcnt vmcnt(" #n ")" ::: "memory")
; #define PG8_WAIT_L(n) asm volatile("s_waitcnt lgkmcnt(" #n ")" ::: "memory")
; #define PG8_BAR __builtin_amdgcn_s_barrier()
; #define PG8_SCHED __builtin_amdgcn_sched_barrier(0)
; template <class Epi, class Sched, bool ALIGN_EPI = false, bool SP2 = false>
; __device__ __forceinline__ void gemm_phase(PG8_LAS unsigned char* lds, const Gemm g, const Sched& S, const Epi& E) {
;     ...
;             PG8_LDB(B0, 0, 0); PG8_LDB(B1, 0, 1); PG8_SCHED; PG8_LDA(At, 0, 0); PG8_STAGE(PG8_SA(1, 1), a1 + hstep, voffA);
;             PG8_WAIT_V(8); PG8_WAIT_L(0); PG8_BAR; PG8_MMA(0, 0, At, B0); PG8_MMA(0, 1, At, B1); PG8_BAR; PG8_SCHED;
;             PG8_LDA(At, 0, 1); PG8_STAGE(PG8_SB(0, 0), b2, voffB); PG8_STAGE(PG8_SB(0, 1), b2 + hstep, voffB); PG8_STAGE(PG8_SA(0, 0), a2, voffA);
;             PG8_WAIT_V(8); PG8_WAIT_L(0); PG8_BAR; PG8_MMA(1, 0, At, B0); PG8_MMA(1, 1, At, B1); PG8_BAR; PG8_SCHED;
;             PG8_LDB(B0, 1, 0); PG8_LDB(B1, 1, 1); PG8_SCHED; PG8_LDA(At, 1, 0); PG8_STAGE(PG8_SA(0, 1), a2 + hstep, voffA);
;             PG8_WAIT_V(8); PG8_WAIT_L(0); PG8_BAR; PG8_MMA(0, 0, At, B0); PG8_MMA(0, 1, At, B1); PG8_BAR; PG8_SCHED;
	s_setprio 1
	v_mfma_f32_16x16x32_bf16 v[120:123], v[138:141], v[170:173], v[120:123]
	v_mfma_f32_16x16x32_bf16 v[124:127], v[146:149], v[170:173], v[124:127]
	v_mfma_f32_16x16x32_bf16 v[108:111], v[138:141], v[178:181], v[108:111]
	v_mfma_f32_16x16x32_bf16 v[104:107], v[146:149], v[178:181], v[104:107]
	v_mfma_f32_16x16x32_bf16 v[92:95], v[138:141], v[186:189], v[92:95]
	v_mfma_f32_16x16x32_bf16 v[88:91], v[146:149], v[186:189], v[88:91]
	v_mfma_f32_16x16x32_bf16 v[76:79], v[138:141], v[204:207], v[76:79]
	v_mfma_f32_16x16x32_bf16 v[72:75], v[146:149], v[204:207], v[72:75]
	v_mfma_f32_16x16x32_bf16 v[120:123], v[142:145], v[174:177], v[120:123]
	v_mfma_f32_16x16x32_bf16 v[124:127], v[150:153], v[174:177], v[124:127]
	v_mfma_f32_16x16x32_bf16 v[108:111], v[142:145], v[182:185], v[108:111]
	v_mfma_f32_16x16x32_bf16 v[104:107], v[150:153], v[182:185], v[104:107]
	v_mfma_f32_16x16x32_bf16 v[92:95], v[142:145], v[200:203], v[92:95]
	v_mfma_f32_16x16x32_bf16 v[88:91], v[150:153], v[200:203], v[88:91]
	v_mfma_f32_16x16x32_bf16 v[76:79], v[142:145], v[212:215], v[76:79]
	v_mfma_f32_16x16x32_bf16 v[72:75], v[150:153], v[212:215], v[72:75]
	s_setprio 0
	s_setprio 1
	v_mfma_f32_16x16x32_bf16 v[116:119], v[154:157], v[170:173], v[116:119]
	v_mfma_f32_16x16x32_bf16 v[112:115], v[162:165], v[170:173], v[112:115]
	v_mfma_f32_16x16x32_bf16 v[100:103], v[154:157], v[178:181], v[100:103]
	v_mfma_f32_16x16x32_bf16 v[96:99], v[162:165], v[178:181], v[96:99]
	v_mfma_f32_16x16x32_bf16 v[84:87], v[154:157], v[186:189], v[84:87]
	v_mfma_f32_16x16x32_bf16 v[80:83], v[162:165], v[186:189], v[80:83]
	v_mfma_f32_16x16x32_bf16 v[68:71], v[154:157], v[204:207], v[68:71]
	v_mfma_f32_16x16x32_bf16 v[64:67], v[162:165], v[204:207], v[64:67]
	v_mfma_f32_16x16x32_bf16 v[116:119], v[158:161], v[174:177], v[116:119]
	v_mfma_f32_16x16x32_bf16 v[112:115], v[166:169], v[174:177], v[112:115]
	v_mfma_f32_16x16x32_bf16 v[100:103], v[158:161], v[182:185], v[100:103]
	v_mfma_f32_16x16x32_bf16 v[96:99], v[166:169], v[182:185], v[96:99]
	v_mfma_f32_16x16x32_bf16 v[84:87], v[158:161], v[200:203], v[84:87]
	v_mfma_f32_16x16x32_bf16 v[80:83], v[166:169], v[200:203], v[80:83]
	v_mfma_f32_16x16x32_bf16 v[68:71], v[158:161], v[212:215], v[68:71]
	v_mfma_f32_16x16x32_bf16 v[64:67], v[166:169], v[212:215], v[64:67]
	s_setprio 0
	s_barrier
	s_add_i32 vcc_lo, vcc_lo, s3
	v_lshl_add_u64 v[190:191], s[96:97], 0, v[208:209]
	s_mov_b32 m0, vcc_lo
	ds_read_b128 v[170:173], v199 offset:16384
	ds_read_b128 v[174:177], v199 offset:17408
	ds_read_b128 v[178:181], v199 offset:18432
	ds_read_b128 v[182:185], v199 offset:19456
	ds_read_b128 v[186:189], v199 offset:20480
	ds_read_b128 v[200:203], v199 offset:21504
	ds_read_b128 v[204:207], v199 offset:22528
	ds_read_b128 v[212:215], v199 offset:23552
	global_load_lds_dwordx4 v[190:191], off
	s_add_i32 m0, vcc_lo, 0x2000
	v_lshl_add_u64 v[194:195], s[96:97], 0, v[128:129]
	s_add_u32 s96, s96, s50
	s_addc_u32 s97, s97, s51
	s_add_i32 vcc_lo, vcc_hi, s3
	global_load_lds_dwordx4 v[194:195], off
	v_lshl_add_u64 v[216:217], s[96:97], 0, v[208:209]
	s_mov_b32 m0, vcc_lo
	v_lshl_add_u64 v[218:219], s[96:97], 0, v[128:129]
	global_load_lds_dwordx4 v[216:217], off
	s_add_i32 m0, vcc_lo, 0x2000
	v_lshl_add_u64 v[220:221], s[34:35], 0, v[208:209]
	global_load_lds_dwordx4 v[218:219], off
	s_mov_b32 m0, s8
	v_lshl_add_u64 v[222:223], s[34:35], 0, v[128:129]
	global_load_lds_dwordx4 v[220:221], off
	s_mov_b32 m0, s9
	s_nop 0
	global_load_lds_dwordx4 v[222:223], off
	s_waitcnt vmcnt(8)
	s_waitcnt lgkmcnt(0)
	s_barrier
	s_setprio 1
	v_mfma_f32_16x16x32_bf16 v[60:63], v[138:141], v[170:173], v[60:63]
	v_mfma_f32_16x16x32_bf16 v[56:59], v[146:149], v[170:173], v[56:59]
	v_mfma_f32_16x16x32_bf16 v[44:47], v[138:141], v[178:181], v[44:47]
	v_mfma_f32_16x16x32_bf16 v[40:43], v[146:149], v[178:181], v[40:43]
	v_mfma_f32_16x16x32_bf16 v[28:31], v[138:141], v[186:189], v[28:31]
	v_mfma_f32_16x16x32_bf16 v[24:27], v[146:149], v[186:189], v[24:27]
	v_mfma_f32_16x16x32_bf16 v[12:15], v[138:141], v[204:207], v[12:15]
	v_mfma_f32_16x16x32_bf16 v[8:11], v[146:149], v[204:207], v[8:11]
	v_mfma_f32_16x16x32_bf16 v[60:63], v[142:145], v[174:177], v[60:63]
	v_mfma_f32_16x16x32_bf16 v[56:59], v[150:153], v[174:177], v[56:59]
	v_mfma_f32_16x16x32_bf16 v[44:47], v[142:145], v[182:185], v[44:47]
	v_mfma_f32_16x16x32_bf16 v[40:43], v[150:153], v[182:185], v[40:43]
	v_mfma_f32_16x16x32_bf16 v[28:31], v[142:145], v[200:203], v[28:31]
	v_mfma_f32_16x16x32_bf16 v[24:27], v[150:153], v[200:203], v[24:27]
	v_mfma_f32_16x16x32_bf16 v[12:15], v[142:145], v[212:215], v[12:15]
	v_mfma_f32_16x16x32_bf16 v[8:11], v[150:153], v[212:215], v[8:11]
	s_setprio 0
	s_setprio 1
	v_mfma_f32_16x16x32_bf16 v[52:55], v[154:157], v[170:173], v[52:55]
	v_mfma_f32_16x16x32_bf16 v[48:51], v[162:165], v[170:173], v[48:51]
	v_mfma_f32_16x16x32_bf16 v[36:39], v[154:157], v[178:181], v[36:39]
	v_mfma_f32_16x16x32_bf16 v[32:35], v[162:165], v[178:181], v[32:35]
	v_mfma_f32_16x16x32_bf16 v[20:23], v[154:157], v[186:189], v[20:23]
	v_mfma_f32_16x16x32_bf16 v[16:19], v[162:165], v[186:189], v[16:19]
	v_mfma_f32_16x16x32_bf16 v[4:7], v[154:157], v[204:207], v[4:7]
	v_mfma_f32_16x16x32_bf16 v[0:3], v[162:165], v[204:207], v[0:3]
	v_mfma_f32_16x16x32_bf16 v[52:55], v[158:161], v[174:177], v[52:55]
	v_mfma_f32_16x16x32_bf16 v[48:51], v[166:169], v[174:177], v[48:51]
	v_mfma_f32_16x16x32_bf16 v[36:39], v[158:161], v[182:185], v[36:39]
	v_mfma_f32_16x16x32_bf16 v[32:35], v[166:169], v[182:185], v[32:35]
	v_mfma_f32_16x16x32_bf16 v[20:23], v[158:161], v[200:203], v[20:23]
	v_mfma_f32_16x16x32_bf16 v[16:19], v[166:169], v[200:203], v[16:19]
	v_mfma_f32_16x16x32_bf16 v[4:7], v[158:161], v[212:215], v[4:7]
	v_mfma_f32_16x16x32_bf16 v[0:3], v[166:169], v[212:215], v[0:3]
	s_setprio 0
	s_barrier
; #define PG8_STAGE(bufoff, gbase, voff) do { _Pragma("unroll") for (int _i = 0; _i < 2; ++_i) \
;         __builtin_amdgcn_global_load_lds((const unsigned*)((const char*)(gbase) + (voff)[_i]), (PG8_LAS unsigned*)(lds + (bufoff) + ldsw + _i * 8192), 16, 0, 0); } while (0)
; #define PG8_LDA(dst, b, h) do { _Pragma("unroll") for (int m = 0; m < 4; ++m) _Pragma("unroll") for (int k = 0; k < 2; ++k) dst[m][k] = *(const PG8_LAS bf16x8*)(lds + PG8_SA(b, h) + aoff + m * 2048 + k * 1024); } while (0)
; #define PG8_LDB(dst, b, h) do { _Pragma("unroll") for (int n = 0; n < 2; ++n) _Pragma("unroll") for (int k = 0; k < 2; ++k) dst[n][k] = *(const PG8_LAS bf16x8*)(lds + PG8_SB(b, h) + boff + n * 2048 + k * 1024); } while (0)
; #define PG8_MMA(ai, bj, At, Bt) do { __builtin_amdgcn_s_setprio(1); _Pragma("unroll") for (int m = 0; m < 4; ++m) _Pragma("unroll") for (int n = 0; n < 2; ++n) _Pragma("unroll") for (int k = 0; k < 2; ++k) \
;         acc[ai][bj][m][n] = mma16<Epi::F16>(Bt[n][k], At[m][k], acc[ai][bj][m][n]); __builtin_amdgcn_s_setprio(0); } while (0)
; #define PG8_WAIT_V(n) asm volatile("s_waitcnt vmcnt(" #n ")" ::: "memory")
; #define PG8_WAIT_L(n) asm volatile("s_waitcnt lgkmcnt(" #n ")" ::: "memory")
; #define PG8_BAR __builtin_amdgcn_s_barrier()
; #define PG8_SCHED __builtin_amdgcn_sched_barrier(0)
; template <class Epi, class Sched, bool ALIGN_EPI = false, bool SP2 = false>
; __device__ __forceinline__ void gemm_phase(PG8_LAS unsigned char* lds, const Gemm g, const Sched& S, const Epi& E) {
;     ...
;             PG8_LDB(B0, 1, 0); PG8_LDB(B1, 1, 1); PG8_SCHED; PG8_LDA(At, 1, 0); PG8_STAGE(PG8_SA(0, 1), a2 + hstep, voffA);
;             PG8_WAIT_V(8); PG8_WAIT_L(0); PG8_BAR; PG8_MMA(0, 0, At, B0); PG8_MMA(0, 1, At, B1); PG8_BAR; PG8_SCHED;
	s_add_i32 s96, 0, 0x18000
	s_add_i32 s97, 0, 0x1c000
	v_add_u32_e32 v150, s96, v131
	v_add_u32_e32 v166, s97, v131
	ds_read_b128 v[138:141], v150
	ds_read_b128 v[142:145], v150 offset:1024
	ds_read_b128 v[146:149], v150 offset:2048
	ds_read_b128 v[150:153], v150 offset:3072
	ds_read_b128 v[154:157], v166
	ds_read_b128 v[158:161], v166 offset:1024
	ds_read_b128 v[162:165], v166 offset:2048
	ds_read_b128 v[166:169], v166 offset:3072
	s_add_u32 s34, s34, s50
	s_addc_u32 s35, s35, s51
	s_mov_b32 m0, s11
	v_lshl_add_u64 v[224:225], s[34:35], 0, v[208:209]
	ds_read_b128 v[170:173], v199 offset:32768
	ds_read_b128 v[174:177], v199 offset:33792
	ds_read_b128 v[178:181], v199 offset:34816
	ds_read_b128 v[182:185], v199 offset:35840
	ds_read_b128 v[186:189], v199 offset:36864
	ds_read_b128 v[200:203], v199 offset:37888
	ds_read_b128 v[204:207], v199 offset:38912
	ds_read_b128 v[212:215], v199 offset:39936
	global_load_lds_dwordx4 v[224:225], off
	v_lshl_add_u64 v[224:225], s[34:35], 0, v[128:129]
	s_mov_b32 m0, s36
	s_nop 0
	global_load_lds_dwordx4 v[224:225], off
	s_waitcnt vmcnt(8)
	s_waitcnt lgkmcnt(0)
	s_barrier
	s_setprio 1
	v_mfma_f32_16x16x32_bf16 v[120:123], v[138:141], v[170:173], v[120:123]
	v_mfma_f32_16x16x32_bf16 v[124:127], v[146:149], v[170:173], v[124:127]
	v_mfma_f32_16x16x32_bf16 v[108:111], v[138:141], v[178:181], v[108:111]
	v_mfma_f32_16x16x32_bf16 v[104:107], v[146:149], v[178:181], v[104:107]
	v_mfma_f32_16x16x32_bf16 v[92:95], v[138:141], v[186:189], v[92:95]
	v_mfma_f32_16x16x32_bf16 v[88:91], v[146:149], v[186:189], v[88:91]
	v_mfma_f32_16x16x32_bf16 v[76:79], v[138:141], v[204:207], v[76:79]
	v_mfma_f32_16x16x32_bf16 v[72:75], v[146:149], v[204:207], v[72:75]
	v_mfma_f32_16x16x32_bf16 v[120:123], v[142:145], v[174:177], v[120:123]
	v_mfma_f32_16x16x32_bf16 v[124:127], v[150:153], v[174:177], v[124:127]
	v_mfma_f32_16x16x32_bf16 v[108:111], v[142:145], v[182:185], v[108:111]
	v_mfma_f32_16x16x32_bf16 v[104:107], v[150:153], v[182:185], v[104:107]
	v_mfma_f32_16x16x32_bf16 v[92:95], v[142:145], v[200:203], v[92:95]
	v_mfma_f32_16x16x32_bf16 v[88:91], v[150:153], v[200:203], v[88:91]
	v_mfma_f32_16x16x32_bf16 v[76:79], v[142:145], v[212:215], v[76:79]
	v_mfma_f32_16x16x32_bf16 v[72:75], v[150:153], v[212:215], v[72:75]
	s_setprio 0
	s_setprio 1
	v_mfma_f32_16x16x32_bf16 v[116:119], v[154:157], v[170:173], v[116:119]
	v_mfma_f32_16x16x32_bf16 v[112:115], v[162:165], v[170:173], v[112:115]
	v_mfma_f32_16x16x32_bf16 v[100:103], v[154:157], v[178:181], v[100:103]
	v_mfma_f32_16x16x32_bf16 v[96:99], v[162:165], v[178:181], v[96:99]
	v_mfma_f32_16x16x32_bf16 v[84:87], v[154:157], v[186:189], v[84:87]
	v_mfma_f32_16x16x32_bf16 v[80:83], v[162:165], v[186:189], v[80:83]
	v_mfma_f32_16x16x32_bf16 v[68:71], v[154:157], v[204:207], v[68:71]
	v_mfma_f32_16x16x32_bf16 v[64:67], v[162:165], v[204:207], v[64:67]
	v_mfma_f32_16x16x32_bf16 v[116:119], v[158:161], v[174:177], v[116:119]
	v_mfma_f32_16x16x32_bf16 v[112:115], v[166:169], v[174:177], v[112:115]
	v_mfma_f32_16x16x32_bf16 v[100:103], v[158:161], v[182:185], v[100:103]
	v_mfma_f32_16x16x32_bf16 v[96:99], v[166:169], v[182:185], v[96:99]
	v_mfma_f32_16x16x32_bf16 v[84:87], v[158:161], v[200:203], v[84:87]
	v_mfma_f32_16x16x32_bf16 v[80:83], v[166:169], v[200:203], v[80:83]
	v_mfma_f32_16x16x32_bf16 v[68:71], v[158:161], v[212:215], v[68:71]
	v_mfma_f32_16x16x32_bf16 v[64:67], v[166:169], v[212:215], v[64:67]
	s_setprio 0
	s_barrier
; #define PG8_STAGE(bufoff, gbase, voff) do { _Pragma("unroll") for (int _i = 0; _i < 2; ++_i) \
;         __builtin_amdgcn_global_load_lds((const unsigned*)((const char*)(gbase) + (voff)[_i]), (PG8_LAS unsigned*)(lds + (bufoff) + ldsw + _i * 8192), 16, 0, 0); } while (0)
; #define PG8_LDA(dst, b, h) do { _Pragma("unroll") for (int m = 0; m < 4; ++m) _Pragma("unroll") for (int k = 0; k < 2; ++k) dst[m][k] = *(const PG8_LAS bf16x8*)(lds + PG8_SA(b, h) + aoff + m * 2048 + k * 1024); } while (0)
; #define PG8_LDB(dst, b, h) do { _Pragma("unroll") for (int n = 0; n < 2; ++n) _Pragma("unroll") for (int k = 0; k < 2; ++k) dst[n][k] = *(const PG8_LAS bf16x8*)(lds + PG8_SB(b, h) + boff + n * 2048 + k * 1024); } while (0)
; template <class Epi, class Sched, bool ALIGN_EPI = false, bool SP2 = false>
; __device__ __forceinline__ void gemm_phase(PG8_LAS unsigned char* lds, const Gemm g, const Sched& S, const Epi& E) {
;     ...
;         for (int t = 0; t < nt; t += 2) {
;             const bool last = (t == nt - 2);
;             const char* a1 = cA + (size_t)(t + 1) * kstep;
;             const char* a2 = last ? nA : cA + (size_t)(t + 2) * kstep; const char* b2 = last ? nB : cB + (size_t)(t + 2) * kstep;
;             const char* a3 = a2 + kstep; const char* b3 = b2 + kstep;
;             if (last && has_next) S.a_ready(nxt);
;             if constexpr (SP2) {
;             PG8_LDB(B0, 0, 0); PG8_LDB(B1, 0, 1); PG8_SCHED; PG8_LDA(At, 0, 0); PG8_STAGE(PG8_SA(1, 1), a1 + hstep, voffA);
;             PG8_WAIT_V(8); PG8_WAIT_L(0); PG8_BAR; PG8_MMA(0, 0, At, B0); PG8_MMA(0, 1, At, B1); PG8_BAR; PG8_SCHED;
;             PG8_LDA(At, 0, 1); PG8_STAGE(PG8_SB(0, 0), b2, voffB); PG8_STAGE(PG8_SB(0, 1), b2 + hstep, voffB); PG8_STAGE(PG8_SA(0, 0), a2, voffA);
;             PG8_WAIT_V(8); PG8_WAIT_L(0); PG8_BAR; PG8_MMA(1, 0, At, B0); PG8_MMA(1, 1, At, B1); PG8_BAR; PG8_SCHED;
;             PG8_LDB(B0, 1, 0); PG8_LDB(B1, 1, 1); PG8_SCHED; PG8_LDA(At, 1, 0); PG8_STAGE(PG8_SA(0, 1), a2 + hstep, voffA);
;             PG8_WAIT_V(8); PG8_WAIT_L(0); PG8_BAR; PG8_MMA(0, 0, At, B0); PG8_MMA(0, 1, At, B1); PG8_BAR; PG8_SCHED;
;             PG8_LDA(At, 1, 1); PG8_STAGE(PG8_SB(1, 0), b3, voffB); PG8_STAGE(PG8_SB(1, 1), b3 + hstep, voffB); PG8_STAGE(PG8_SA(1, 0), a3, voffA);
;             PG8_WAIT_V(8); PG8_WAIT_L(0); PG8_BAR; PG8_MMA(1, 0, At, B0); PG8_MMA(1, 1, At, B1); PG8_BAR; PG8_SCHED;
	s_add_i32 s34, s96, s3
	v_lshl_add_u64 v[190:191], v[190:191], 0, s[20:21]
	s_mov_b32 m0, s34
	ds_read_b128 v[170:173], v199 offset:49152
	ds_read_b128 v[174:177], v199 offset:50176
	ds_read_b128 v[178:181], v199 offset:51200
	ds_read_b128 v[182:185], v199 offset:52224
	ds_read_b128 v[186:189], v199 offset:53248
	ds_read_b128 v[200:203], v199 offset:54272
	ds_read_b128 v[204:207], v199 offset:55296
	ds_read_b128 v[212:215], v199 offset:56320
	global_load_lds_dwordx4 v[190:191], off
	v_lshl_add_u64 v[190:191], v[194:195], 0, s[20:21]
	s_add_i32 m0, s34, 0x2000
	s_add_i32 s34, s97, s3
	global_load_lds_dwordx4 v[190:191], off
	v_lshl_add_u64 v[190:191], v[216:217], 0, s[20:21]
	s_mov_b32 m0, s34
	s_nop 0
	global_load_lds_dwordx4 v[190:191], off
	v_lshl_add_u64 v[190:191], v[218:219], 0, s[20:21]
	s_add_i32 m0, s34, 0x2000
	s_nop 0
	global_load_lds_dwordx4 v[190:191], off
	v_lshl_add_u64 v[190:191], v[220:221], 0, s[20:21]
	s_mov_b32 m0, s48
	s_nop 0
	global_load_lds_dwordx4 v[190:191], off
	v_lshl_add_u64 v[190:191], v[222:223], 0, s[20:21]
	s_mov_b32 m0, s64
	s_nop 0
	global_load_lds_dwordx4 v[190:191], off
	s_waitcnt vmcnt(8)
	s_waitcnt lgkmcnt(0)
	s_barrier
	s_setprio 1
	v_mfma_f32_16x16x32_bf16 v[60:63], v[138:141], v[170:173], v[60:63]
	v_mfma_f32_16x16x32_bf16 v[56:59], v[146:149], v[170:173], v[56:59]
	v_mfma_f32_16x16x32_bf16 v[44:47], v[138:141], v[178:181], v[44:47]
	v_mfma_f32_16x16x32_bf16 v[40:43], v[146:149], v[178:181], v[40:43]
	v_mfma_f32_16x16x32_bf16 v[28:31], v[138:141], v[186:189], v[28:31]
	v_mfma_f32_16x16x32_bf16 v[24:27], v[146:149], v[186:189], v[24:27]
	v_mfma_f32_16x16x32_bf16 v[12:15], v[138:141], v[204:207], v[12:15]
	v_mfma_f32_16x16x32_bf16 v[8:11], v[146:149], v[204:207], v[8:11]
	v_mfma_f32_16x16x32_bf16 v[60:63], v[142:145], v[174:177], v[60:63]
	v_mfma_f32_16x16x32_bf16 v[56:59], v[150:153], v[174:177], v[56:59]
	v_mfma_f32_16x16x32_bf16 v[44:47], v[142:145], v[182:185], v[44:47]
	v_mfma_f32_16x16x32_bf16 v[40:43], v[150:153], v[182:185], v[40:43]
	v_mfma_f32_16x16x32_bf16 v[28:31], v[142:145], v[200:203], v[28:31]
	v_mfma_f32_16x16x32_bf16 v[24:27], v[150:153], v[200:203], v[24:27]
	v_mfma_f32_16x16x32_bf16 v[12:15], v[142:145], v[212:215], v[12:15]
	v_mfma_f32_16x16x32_bf16 v[8:11], v[150:153], v[212:215], v[8:11]
	s_setprio 0
	s_setprio 1
	v_mfma_f32_16x16x32_bf16 v[52:55], v[154:157], v[170:173], v[52:55]
	v_mfma_f32_16x16x32_bf16 v[48:51], v[162:165], v[170:173], v[48:51]
	v_mfma_f32_16x16x32_bf16 v[36:39], v[154:157], v[178:181], v[36:39]
	v_mfma_f32_16x16x32_bf16 v[32:35], v[162:165], v[178:181], v[32:35]
	v_mfma_f32_16x16x32_bf16 v[20:23], v[154:157], v[186:189], v[20:23]
	v_mfma_f32_16x16x32_bf16 v[16:19], v[162:165], v[186:189], v[16:19]
	v_mfma_f32_16x16x32_bf16 v[4:7], v[154:157], v[204:207], v[4:7]
	v_mfma_f32_16x16x32_bf16 v[0:3], v[162:165], v[204:207], v[0:3]
	v_mfma_f32_16x16x32_bf16 v[52:55], v[158:161], v[174:177], v[52:55]
	v_mfma_f32_16x16x32_bf16 v[48:51], v[166:169], v[174:177], v[48:51]
	v_mfma_f32_16x16x32_bf16 v[36:39], v[158:161], v[182:185], v[36:39]
	v_mfma_f32_16x16x32_bf16 v[32:35], v[166:169], v[182:185], v[32:35]
	v_mfma_f32_16x16x32_bf16 v[20:23], v[158:161], v[200:203], v[20:23]
	v_mfma_f32_16x16x32_bf16 v[16:19], v[166:169], v[200:203], v[16:19]
	v_mfma_f32_16x16x32_bf16 v[4:7], v[158:161], v[212:215], v[4:7]
	v_mfma_f32_16x16x32_bf16 v[0:3], v[166:169], v[212:215], v[0:3]
	s_setprio 0
	s_barrier
	s_add_u32 s30, s30, 0x100
	s_addc_u32 s31, s31, 0
	s_add_u32 s29, s29, 0x100
	s_addc_u32 s85, s85, 0
	s_cmp_ge_i32 s92, s37
	s_mov_b32 s34, s92
	s_cbranch_scc0 .LBB0_312

; #define PG8_STAGE(bufoff, gbase, voff) do { _Pragma("unroll") for (int _i = 0; _i < 2; ++_i) \
;         __builtin_amdgcn_global_load_lds((const unsigned*)((const char*)(gbase) + (voff)[_i]), (PG8_LAS unsigned*)(lds + (bufoff) + ldsw + _i * 8192), 16, 0, 0); } while (0)
; #define PG8_LDA(dst, b, h) do { _Pragma("unroll") for (int m = 0; m < 4; ++m) _Pragma("unroll") for (int k = 0; k < 2; ++k) dst[m][k] = *(const PG8_LAS bf16x8*)(lds + PG8_SA(b, h) + aoff + m * 2048 + k * 1024); } while (0)
; #define PG8_LDB(dst, b, h) do { _Pragma("unroll") for (int n = 0; n < 2; ++n) _Pragma("unroll") for (int k = 0; k < 2; ++k) dst[n][k] = *(const PG8_LAS bf16x8*)(lds + PG8_SB(b, h) + boff + n * 2048 + k * 1024); } while (0)
; #define PG8_MMA(ai, bj, At, Bt) do { __builtin_amdgcn_s_setprio(1); _Pragma("unroll") for (int m = 0; m < 4; ++m) _Pragma("unroll") for (int n = 0; n < 2; ++n) _Pragma("unroll") for (int k = 0; k < 2; ++k) \
;         acc[ai][bj][m][n] = mma16<Epi::F16>(Bt[n][k], At[m][k], acc[ai][bj][m][n]); __builtin_amdgcn_s_setprio(0); } while (0)
; #define PG8_WAIT_V(n) asm volatile("s_waitcnt vmcnt(" #n ")" ::: "memory")
; #define PG8_WAIT_L(n) asm volatile("s_waitcnt lgkmcnt(" #n ")" ::: "memory")
; #define PG8_BAR __builtin_amdgcn_s_barrier()
; #define PG8_SCHED __builtin_amdgcn_sched_barrier(0)
; template <class Epi, class Sched, bool ALIGN_EPI = false, bool SP2 = false>
; __device__ __forceinline__ void gemm_phase(PG8_LAS unsigned char* lds, const Gemm g, const Sched& S, const Epi& E) {
;     ...
;             PG8_LDB(B0, 0, 0); PG8_LDB(B1, 0, 1); PG8_SCHED; PG8_LDA(At, 0, 0); PG8_STAGE(PG8_SA(1, 1), a1 + hstep, voffA);
;             PG8_WAIT_V(8); PG8_WAIT_L(0); PG8_BAR; PG8_MMA(0, 0, At, B0); PG8_MMA(0, 1, At, B1); PG8_BAR; PG8_SCHED;
;             PG8_LDA(At, 0, 1); PG8_STAGE(PG8_SB(0, 0), b2, voffB); PG8_STAGE(PG8_SB(0, 1), b2 + hstep, voffB); PG8_STAGE(PG8_SA(0, 0), a2, voffA);
;             PG8_WAIT_V(8); PG8_WAIT_L(0); PG8_BAR; PG8_MMA(1, 0, At, B0); PG8_MMA(1, 1, At, B1); PG8_BAR; PG8_SCHED;
;             PG8_LDB(B0, 1, 0); PG8_LDB(B1, 1, 1); PG8_SCHED; PG8_LDA(At, 1, 0); PG8_STAGE(PG8_SA(0, 1), a2 + hstep, voffA);
;             PG8_WAIT_V(8); PG8_WAIT_L(0); PG8_BAR; PG8_MMA(0, 0, At, B0); PG8_MMA(0, 1, At, B1); PG8_BAR; PG8_SCHED;
.Lpeel_k3:
	s_add_u32 s30, s30, 0x80
	s_addc_u32 s31, s31, 0
	s_add_u32 s29, s34, 0x100
	s_addc_u32 s85, s35, 0
	s_mov_b32 s34, 0
	s_add_i32 s92, s34, 2
	s_add_u32 s96, s30, 0x80
	s_addc_u32 s35, s31, 0
	s_add_i32 vcc_lo, 0, 0x10000
	s_cmp_eq_u32 s37, s34
	s_cselect_b32 s35, s1, s35
	s_cselect_b32 s34, s0, s96
	s_cselect_b32 s97, s27, s85
	s_cselect_b32 s96, s26, s29
	s_add_i32 vcc_hi, 0, 0x14000
	v_add_u32_e32 v140, vcc_lo, v197
	v_add_u32_e32 v156, vcc_hi, v197
	ds_read_b128 v[128:131], v140
	ds_read_b128 v[132:135], v140 offset:1024
	ds_read_b128 v[136:139], v140 offset:2048
	ds_read_b128 v[140:143], v140 offset:3072
	ds_read_b128 v[144:147], v156
	ds_read_b128 v[148:151], v156 offset:1024
	ds_read_b128 v[152:155], v156 offset:2048
	ds_read_b128 v[156:159], v156 offset:3072
	v_lshl_add_u64 v[204:205], s[30:31], 0, v[200:201]
	s_add_i32 m0, s8, 0xc000
	ds_read_b128 v[160:163], v230
	ds_read_b128 v[164:167], v230 offset:1024
	ds_read_b128 v[168:171], v230 offset:2048
	ds_read_b128 v[172:175], v230 offset:3072
	ds_read_b128 v[176:179], v230 offset:4096
	ds_read_b128 v[180:183], v230 offset:5120
	ds_read_b128 v[184:187], v230 offset:6144
	ds_read_b128 v[188:191], v230 offset:7168
	global_load_lds_dwordx4 v[204:205], off
	v_lshl_add_u64 v[204:205], s[30:31], 0, v[202:203]
	s_add_i32 m0, s8, 0xe000
	s_nop 0
	global_load_lds_dwordx4 v[204:205], off
	s_waitcnt vmcnt(8)
	s_waitcnt lgkmcnt(0)
	s_barrier
	s_setprio 1
	v_mfma_f32_16x16x32_bf16 v[124:127], v[128:131], v[160:163], 0
	v_mfma_f32_16x16x32_bf16 v[120:123], v[136:139], v[160:163], 0
	v_mfma_f32_16x16x32_bf16 v[108:111], v[128:131], v[168:171], 0
	v_mfma_f32_16x16x32_bf16 v[104:107], v[136:139], v[168:171], 0
	v_mfma_f32_16x16x32_bf16 v[92:95], v[128:131], v[176:179], 0
	v_mfma_f32_16x16x32_bf16 v[88:91], v[136:139], v[176:179], 0
	v_mfma_f32_16x16x32_bf16 v[76:79], v[128:131], v[184:187], 0
	v_mfma_f32_16x16x32_bf16 v[72:75], v[136:139], v[184:187], 0
	v_mfma_f32_16x16x32_bf16 v[124:127], v[132:135], v[164:167], v[124:127]
	v_mfma_f32_16x16x32_bf16 v[120:123], v[140:143], v[164:167], v[120:123]
	v_mfma_f32_16x16x32_bf16 v[108:111], v[132:135], v[172:175], v[108:111]
	v_mfma_f32_16x16x32_bf16 v[104:107], v[140:143], v[172:175], v[104:107]
	v_mfma_f32_16x16x32_bf16 v[92:95], v[132:135], v[180:183], v[92:95]
	v_mfma_f32_16x16x32_bf16 v[88:91], v[140:143], v[180:183], v[88:91]
	v_mfma_f32_16x16x32_bf16 v[76:79], v[132:135], v[188:191], v[76:79]
	v_mfma_f32_16x16x32_bf16 v[72:75], v[140:143], v[188:191], v[72:75]
	s_setprio 0
	s_setprio 1
	v_mfma_f32_16x16x32_bf16 v[116:119], v[144:147], v[160:163], 0
	v_mfma_f32_16x16x32_bf16 v[112:115], v[152:155], v[160:163], 0
	v_mfma_f32_16x16x32_bf16 v[100:103], v[144:147], v[168:171], 0
	v_mfma_f32_16x16x32_bf16 v[96:99], v[152:155], v[168:171], 0
	v_mfma_f32_16x16x32_bf16 v[84:87], v[144:147], v[176:179], 0
	v_mfma_f32_16x16x32_bf16 v[80:83], v[152:155], v[176:179], 0
	v_mfma_f32_16x16x32_bf16 v[68:71], v[144:147], v[184:187], 0
	v_mfma_f32_16x16x32_bf16 v[64:67], v[152:155], v[184:187], 0
	v_mfma_f32_16x16x32_bf16 v[116:119], v[148:151], v[164:167], v[116:119]
	v_mfma_f32_16x16x32_bf16 v[112:115], v[156:159], v[164:167], v[112:115]
	v_mfma_f32_16x16x32_bf16 v[100:103], v[148:151], v[172:175], v[100:103]
	v_mfma_f32_16x16x32_bf16 v[96:99], v[156:159], v[172:175], v[96:99]
	v_mfma_f32_16x16x32_bf16 v[84:87], v[148:151], v[180:183], v[84:87]
	v_mfma_f32_16x16x32_bf16 v[80:83], v[156:159], v[180:183], v[80:83]
	v_mfma_f32_16x16x32_bf16 v[68:71], v[148:151], v[188:191], v[68:71]
	v_mfma_f32_16x16x32_bf16 v[64:67], v[156:159], v[188:191], v[64:67]
	s_setprio 0
	s_barrier
	s_add_i32 vcc_lo, vcc_lo, s3
	v_lshl_add_u64 v[204:205], s[96:97], 0, v[208:209]
	s_mov_b32 m0, vcc_lo
	ds_read_b128 v[160:163], v230 offset:16384
	ds_read_b128 v[164:167], v230 offset:17408
	ds_read_b128 v[168:171], v230 offset:18432
	ds_read_b128 v[172:175], v230 offset:19456
	ds_read_b128 v[176:179], v230 offset:20480
	ds_read_b128 v[180:183], v230 offset:21504
	ds_read_b128 v[184:187], v230 offset:22528
	ds_read_b128 v[188:191], v230 offset:23552
	global_load_lds_dwordx4 v[204:205], off
	s_add_i32 m0, vcc_lo, 0x2000
	v_lshl_add_u64 v[206:207], s[96:97], 0, v[194:195]
	s_add_u32 s96, s96, s50
	s_addc_u32 s97, s97, s51
	s_add_i32 vcc_lo, vcc_hi, s3
	global_load_lds_dwordx4 v[206:207], off
	v_lshl_add_u64 v[212:213], s[96:97], 0, v[208:209]
	s_mov_b32 m0, vcc_lo
	v_lshl_add_u64 v[214:215], s[96:97], 0, v[194:195]
	global_load_lds_dwordx4 v[212:213], off
	s_add_i32 m0, vcc_lo, 0x2000
	v_lshl_add_u64 v[216:217], s[34:35], 0, v[208:209]
	global_load_lds_dwordx4 v[214:215], off
	s_mov_b32 m0, s8
	v_lshl_add_u64 v[218:219], s[34:35], 0, v[194:195]
	global_load_lds_dwordx4 v[216:217], off
	s_mov_b32 m0, s9
	s_nop 0
	global_load_lds_dwordx4 v[218:219], off
	s_waitcnt vmcnt(8)
	s_waitcnt lgkmcnt(0)
	s_barrier
; #define PG8_STAGE(bufoff, gbase, voff) do { _Pragma("unroll") for (int _i = 0; _i < 2; ++_i) \
;         __builtin_amdgcn_global_load_lds((const unsigned*)((const char*)(gbase) + (voff)[_i]), (PG8_LAS unsigned*)(lds + (bufoff) + ldsw + _i * 8192), 16, 0, 0); } while (0)
; #define PG8_LDA(dst, b, h) do { _Pragma("unroll") for (int m = 0; m < 4; ++m) _Pragma("unroll") for (int k = 0; k < 2; ++k) dst[m][k] = *(const PG8_LAS bf16x8*)(lds + PG8_SA(b, h) + aoff + m * 2048 + k * 1024); } while (0)
; #define PG8_LDB(dst, b, h) do { _Pragma("unroll") for (int n = 0; n < 2; ++n) _Pragma("unroll") for (int k = 0; k < 2; ++k) dst[n][k] = *(const PG8_LAS bf16x8*)(lds + PG8_SB(b, h) + boff + n * 2048 + k * 1024); } while (0)
; #define PG8_MMA(ai, bj, At, Bt) do { __builtin_amdgcn_s_setprio(1); _Pragma("unroll") for (int m = 0; m < 4; ++m) _Pragma("unroll") for (int n = 0; n < 2; ++n) _Pragma("unroll") for (int k = 0; k < 2; ++k) \
;         acc[ai][bj][m][n] = mma16<Epi::F16>(Bt[n][k], At[m][k], acc[ai][bj][m][n]); __builtin_amdgcn_s_setprio(0); } while (0)
; #define PG8_WAIT_V(n) asm volatile("s_waitcnt vmcnt(" #n ")" ::: "memory")
; #define PG8_WAIT_L(n) asm volatile("s_waitcnt lgkmcnt(" #n ")" ::: "memory")
; #define PG8_BAR __builtin_amdgcn_s_barrier()
; #define PG8_SCHED __builtin_amdgcn_sched_barrier(0)
; template <class Epi, class Sched, bool ALIGN_EPI = false, bool SP2 = false>
; __device__ __forceinline__ void gemm_phase(PG8_LAS unsigned char* lds, const Gemm g, const Sched& S, const Epi& E) {
;     ...
;             PG8_WAIT_V(8); PG8_WAIT_L(0); PG8_BAR; PG8_MMA(1, 0, At, B0); PG8_MMA(1, 1, At, B1); PG8_BAR; PG8_SCHED;
;             PG8_LDB(B0, 1, 0); PG8_LDB(B1, 1, 1); PG8_SCHED; PG8_LDA(At, 1, 0); PG8_STAGE(PG8_SA(0, 1), a2 + hstep, voffA);
;             PG8_WAIT_V(8); PG8_WAIT_L(0); PG8_BAR; PG8_MMA(0, 0, At, B0); PG8_MMA(0, 1, At, B1); PG8_BAR; PG8_SCHED;
	s_setprio 1
	v_mfma_f32_16x16x32_bf16 v[60:63], v[128:131], v[160:163], 0
	v_mfma_f32_16x16x32_bf16 v[56:59], v[136:139], v[160:163], 0
	v_mfma_f32_16x16x32_bf16 v[44:47], v[128:131], v[168:171], 0
	v_mfma_f32_16x16x32_bf16 v[40:43], v[136:139], v[168:171], 0
	v_mfma_f32_16x16x32_bf16 v[28:31], v[128:131], v[176:179], 0
	v_mfma_f32_16x16x32_bf16 v[24:27], v[136:139], v[176:179], 0
	v_mfma_f32_16x16x32_bf16 v[12:15], v[128:131], v[184:187], 0
	v_mfma_f32_16x16x32_bf16 v[8:11], v[136:139], v[184:187], 0
	v_mfma_f32_16x16x32_bf16 v[60:63], v[132:135], v[164:167], v[60:63]
	v_mfma_f32_16x16x32_bf16 v[56:59], v[140:143], v[164:167], v[56:59]
	v_mfma_f32_16x16x32_bf16 v[44:47], v[132:135], v[172:175], v[44:47]
	v_mfma_f32_16x16x32_bf16 v[40:43], v[140:143], v[172:175], v[40:43]
	v_mfma_f32_16x16x32_bf16 v[28:31], v[132:135], v[180:183], v[28:31]
	v_mfma_f32_16x16x32_bf16 v[24:27], v[140:143], v[180:183], v[24:27]
	v_mfma_f32_16x16x32_bf16 v[12:15], v[132:135], v[188:191], v[12:15]
	v_mfma_f32_16x16x32_bf16 v[8:11], v[140:143], v[188:191], v[8:11]
	s_setprio 0
	s_setprio 1
	v_mfma_f32_16x16x32_bf16 v[52:55], v[144:147], v[160:163], 0
	v_mfma_f32_16x16x32_bf16 v[48:51], v[152:155], v[160:163], 0
	v_mfma_f32_16x16x32_bf16 v[36:39], v[144:147], v[168:171], 0
	v_mfma_f32_16x16x32_bf16 v[32:35], v[152:155], v[168:171], 0
	v_mfma_f32_16x16x32_bf16 v[20:23], v[144:147], v[176:179], 0
	v_mfma_f32_16x16x32_bf16 v[16:19], v[152:155], v[176:179], 0
	v_mfma_f32_16x16x32_bf16 v[4:7], v[144:147], v[184:187], 0
	v_mfma_f32_16x16x32_bf16 v[0:3], v[152:155], v[184:187], 0
	v_mfma_f32_16x16x32_bf16 v[52:55], v[148:151], v[164:167], v[52:55]
	v_mfma_f32_16x16x32_bf16 v[48:51], v[156:159], v[164:167], v[48:51]
	v_mfma_f32_16x16x32_bf16 v[36:39], v[148:151], v[172:175], v[36:39]
	v_mfma_f32_16x16x32_bf16 v[32:35], v[156:159], v[172:175], v[32:35]
	v_mfma_f32_16x16x32_bf16 v[20:23], v[148:151], v[180:183], v[20:23]
	v_mfma_f32_16x16x32_bf16 v[16:19], v[156:159], v[180:183], v[16:19]
	v_mfma_f32_16x16x32_bf16 v[4:7], v[148:151], v[188:191], v[4:7]
	v_mfma_f32_16x16x32_bf16 v[0:3], v[156:159], v[188:191], v[0:3]
	s_setprio 0
	s_barrier
	s_add_i32 s96, 0, 0x18000
	s_add_i32 s97, 0, 0x1c000
	v_add_u32_e32 v140, s96, v197
	v_add_u32_e32 v156, s97, v197
	ds_read_b128 v[128:131], v140
	ds_read_b128 v[132:135], v140 offset:1024
	ds_read_b128 v[136:139], v140 offset:2048
	ds_read_b128 v[140:143], v140 offset:3072
	ds_read_b128 v[144:147], v156
	ds_read_b128 v[148:151], v156 offset:1024
	ds_read_b128 v[152:155], v156 offset:2048
	ds_read_b128 v[156:159], v156 offset:3072
	s_add_u32 s34, s34, s50
	s_addc_u32 s35, s35, s51
	s_mov_b32 m0, s11
	v_lshl_add_u64 v[220:221], s[34:35], 0, v[208:209]
	ds_read_b128 v[160:163], v230 offset:32768
	ds_read_b128 v[164:167], v230 offset:33792
	ds_read_b128 v[168:171], v230 offset:34816
	ds_read_b128 v[172:175], v230 offset:35840
	ds_read_b128 v[176:179], v230 offset:36864
	ds_read_b128 v[180:183], v230 offset:37888
	ds_read_b128 v[184:187], v230 offset:38912
	ds_read_b128 v[188:191], v230 offset:39936
	global_load_lds_dwordx4 v[220:221], off
	v_lshl_add_u64 v[220:221], s[34:35], 0, v[194:195]
	s_mov_b32 m0, s36
	s_nop 0
	global_load_lds_dwordx4 v[220:221], off
	s_waitcnt vmcnt(8)
	s_waitcnt lgkmcnt(0)
	s_barrier
	s_setprio 1
	v_mfma_f32_16x16x32_bf16 v[124:127], v[128:131], v[160:163], v[124:127]
	v_mfma_f32_16x16x32_bf16 v[120:123], v[136:139], v[160:163], v[120:123]
	v_mfma_f32_16x16x32_bf16 v[108:111], v[128:131], v[168:171], v[108:111]
	v_mfma_f32_16x16x32_bf16 v[104:107], v[136:139], v[168:171], v[104:107]
	v_mfma_f32_16x16x32_bf16 v[92:95], v[128:131], v[176:179], v[92:95]
	v_mfma_f32_16x16x32_bf16 v[88:91], v[136:139], v[176:179], v[88:91]
	v_mfma_f32_16x16x32_bf16 v[76:79], v[128:131], v[184:187], v[76:79]
	v_mfma_f32_16x16x32_bf16 v[72:75], v[136:139], v[184:187], v[72:75]
	v_mfma_f32_16x16x32_bf16 v[124:127], v[132:135], v[164:167], v[124:127]
	v_mfma_f32_16x16x32_bf16 v[120:123], v[140:143], v[164:167], v[120:123]
	v_mfma_f32_16x16x32_bf16 v[108:111], v[132:135], v[172:175], v[108:111]
	v_mfma_f32_16x16x32_bf16 v[104:107], v[140:143], v[172:175], v[104:107]
	v_mfma_f32_16x16x32_bf16 v[92:95], v[132:135], v[180:183], v[92:95]
	v_mfma_f32_16x16x32_bf16 v[88:91], v[140:143], v[180:183], v[88:91]
	v_mfma_f32_16x16x32_bf16 v[76:79], v[132:135], v[188:191], v[76:79]
	v_mfma_f32_16x16x32_bf16 v[72:75], v[140:143], v[188:191], v[72:75]
	s_setprio 0
	s_setprio 1
	v_mfma_f32_16x16x32_bf16 v[116:119], v[144:147], v[160:163], v[116:119]
	v_mfma_f32_16x16x32_bf16 v[112:115], v[152:155], v[160:163], v[112:115]
	v_mfma_f32_16x16x32_bf16 v[100:103], v[144:147], v[168:171], v[100:103]
	v_mfma_f32_16x16x32_bf16 v[96:99], v[152:155], v[168:171], v[96:99]
	v_mfma_f32_16x16x32_bf16 v[84:87], v[144:147], v[176:179], v[84:87]
	v_mfma_f32_16x16x32_bf16 v[80:83], v[152:155], v[176:179], v[80:83]
	v_mfma_f32_16x16x32_bf16 v[68:71], v[144:147], v[184:187], v[68:71]
	v_mfma_f32_16x16x32_bf16 v[64:67], v[152:155], v[184:187], v[64:67]
	v_mfma_f32_16x16x32_bf16 v[116:119], v[148:151], v[164:167], v[116:119]
	v_mfma_f32_16x16x32_bf16 v[112:115], v[156:159], v[164:167], v[112:115]
	v_mfma_f32_16x16x32_bf16 v[100:103], v[148:151], v[172:175], v[100:103]
	v_mfma_f32_16x16x32_bf16 v[96:99], v[156:159], v[172:175], v[96:99]
	v_mfma_f32_16x16x32_bf16 v[84:87], v[148:151], v[180:183], v[84:87]
	v_mfma_f32_16x16x32_bf16 v[80:83], v[156:159], v[180:183], v[80:83]
	v_mfma_f32_16x16x32_bf16 v[68:71], v[148:151], v[188:191], v[68:71]
	v_mfma_f32_16x16x32_bf16 v[64:67], v[156:159], v[188:191], v[64:67]
	s_setprio 0
	s_barrier
; #define PG8_STAGE(bufoff, gbase, voff) do { _Pragma("unroll") for (int _i = 0; _i < 2; ++_i) \
;         __builtin_amdgcn_global_load_lds((const unsigned*)((const char*)(gbase) + (voff)[_i]), (PG8_LAS unsigned*)(lds + (bufoff) + ldsw + _i * 8192), 16, 0, 0); } while (0)
; #define PG8_LDA(dst, b, h) do { _Pragma("unroll") for (int m = 0; m < 4; ++m) _Pragma("unroll") for (int k = 0; k < 2; ++k) dst[m][k] = *(const PG8_LAS bf16x8*)(lds + PG8_SA(b, h) + aoff + m * 2048 + k * 1024); } while (0)
; #define PG8_LDB(dst, b, h) do { _Pragma("unroll") for (int n = 0; n < 2; ++n) _Pragma("unroll") for (int k = 0; k < 2; ++k) dst[n][k] = *(const PG8_LAS bf16x8*)(lds + PG8_SB(b, h) + boff + n * 2048 + k * 1024); } while (0)
; template <class Epi, class Sched, bool ALIGN_EPI = false, bool SP2 = false>
; __device__ __forceinline__ void gemm_phase(PG8_LAS unsigned char* lds, const Gemm g, const Sched& S, const Epi& E) {
;     ...
;         for (int t = 0; t < nt; t += 2) {
;             const bool last = (t == nt - 2);
;             const char* a1 = cA + (size_t)(t + 1) * kstep;
;             const char* a2 = last ? nA : cA + (size_t)(t + 2) * kstep; const char* b2 = last ? nB : cB + (size_t)(t + 2) * kstep;
;             const char* a3 = a2 + kstep; const char* b3 = b2 + kstep;
;             if (last && has_next) S.a_ready(nxt);
;             if constexpr (SP2) {
;             PG8_LDB(B0, 0, 0); PG8_LDB(B1, 0, 1); PG8_SCHED; PG8_LDA(At, 0, 0); PG8_STAGE(PG8_SA(1, 1), a1 + hstep, voffA);
;             PG8_WAIT_V(8); PG8_WAIT_L(0); PG8_BAR; PG8_MMA(0, 0, At, B0); PG8_MMA(0, 1, At, B1); PG8_BAR; PG8_SCHED;
;             PG8_LDA(At, 0, 1); PG8_STAGE(PG8_SB(0, 0), b2, voffB); PG8_STAGE(PG8_SB(0, 1), b2 + hstep, voffB); PG8_STAGE(PG8_SA(0, 0), a2, voffA);
;             PG8_WAIT_V(8); PG8_WAIT_L(0); PG8_BAR; PG8_MMA(1, 0, At, B0); PG8_MMA(1, 1, At, B1); PG8_BAR; PG8_SCHED;
;             PG8_LDB(B0, 1, 0); PG8_LDB(B1, 1, 1); PG8_SCHED; PG8_LDA(At, 1, 0); PG8_STAGE(PG8_SA(0, 1), a2 + hstep, voffA);
;             PG8_WAIT_V(8); PG8_WAIT_L(0); PG8_BAR; PG8_MMA(0, 0, At, B0); PG8_MMA(0, 1, At, B1); PG8_BAR; PG8_SCHED;
;             PG8_LDA(At, 1, 1); PG8_STAGE(PG8_SB(1, 0), b3, voffB); PG8_STAGE(PG8_SB(1, 1), b3 + hstep, voffB); PG8_STAGE(PG8_SA(1, 0), a3, voffA);
;             PG8_WAIT_V(8); PG8_WAIT_L(0); PG8_BAR; PG8_MMA(1, 0, At, B0); PG8_MMA(1, 1, At, B1); PG8_BAR; PG8_SCHED;
	s_add_i32 s34, s96, s3
	v_lshl_add_u64 v[204:205], v[204:205], 0, s[20:21]
	s_mov_b32 m0, s34
	ds_read_b128 v[160:163], v230 offset:49152
	ds_read_b128 v[164:167], v230 offset:50176
	ds_read_b128 v[168:171], v230 offset:51200
	ds_read_b128 v[172:175], v230 offset:52224
	ds_read_b128 v[176:179], v230 offset:53248
	ds_read_b128 v[180:183], v230 offset:54272
	ds_read_b128 v[184:187], v230 offset:55296
	ds_read_b128 v[188:191], v230 offset:56320
	global_load_lds_dwordx4 v[204:205], off
	v_lshl_add_u64 v[204:205], v[206:207], 0, s[20:21]
	s_add_i32 m0, s34, 0x2000
	s_add_i32 s34, s97, s3
	global_load_lds_dwordx4 v[204:205], off
	v_lshl_add_u64 v[204:205], v[212:213], 0, s[20:21]
	s_mov_b32 m0, s34
	s_nop 0
	global_load_lds_dwordx4 v[204:205], off
	v_lshl_add_u64 v[204:205], v[214:215], 0, s[20:21]
	s_add_i32 m0, s34, 0x2000
	s_nop 0
	global_load_lds_dwordx4 v[204:205], off
	v_lshl_add_u64 v[204:205], v[216:217], 0, s[20:21]
	s_mov_b32 m0, s48
	s_nop 0
	global_load_lds_dwordx4 v[204:205], off
	v_lshl_add_u64 v[204:205], v[218:219], 0, s[20:21]
	s_mov_b32 m0, s49
	s_nop 0
	global_load_lds_dwordx4 v[204:205], off
	s_waitcnt vmcnt(8)
	s_waitcnt lgkmcnt(0)
	s_barrier
	s_setprio 1
	v_mfma_f32_16x16x32_bf16 v[60:63], v[128:131], v[160:163], v[60:63]
	v_mfma_f32_16x16x32_bf16 v[56:59], v[136:139], v[160:163], v[56:59]
	v_mfma_f32_16x16x32_bf16 v[44:47], v[128:131], v[168:171], v[44:47]
	v_mfma_f32_16x16x32_bf16 v[40:43], v[136:139], v[168:171], v[40:43]
	v_mfma_f32_16x16x32_bf16 v[28:31], v[128:131], v[176:179], v[28:31]
	v_mfma_f32_16x16x32_bf16 v[24:27], v[136:139], v[176:179], v[24:27]
	v_mfma_f32_16x16x32_bf16 v[12:15], v[128:131], v[184:187], v[12:15]
	v_mfma_f32_16x16x32_bf16 v[8:11], v[136:139], v[184:187], v[8:11]
	v_mfma_f32_16x16x32_bf16 v[60:63], v[132:135], v[164:167], v[60:63]
	v_mfma_f32_16x16x32_bf16 v[56:59], v[140:143], v[164:167], v[56:59]
	v_mfma_f32_16x16x32_bf16 v[44:47], v[132:135], v[172:175], v[44:47]
	v_mfma_f32_16x16x32_bf16 v[40:43], v[140:143], v[172:175], v[40:43]
	v_mfma_f32_16x16x32_bf16 v[28:31], v[132:135], v[180:183], v[28:31]
	v_mfma_f32_16x16x32_bf16 v[24:27], v[140:143], v[180:183], v[24:27]
	v_mfma_f32_16x16x32_bf16 v[12:15], v[132:135], v[188:191], v[12:15]
	v_mfma_f32_16x16x32_bf16 v[8:11], v[140:143], v[188:191], v[8:11]
	s_setprio 0
	s_setprio 1
	v_mfma_f32_16x16x32_bf16 v[52:55], v[144:147], v[160:163], v[52:55]
	v_mfma_f32_16x16x32_bf16 v[48:51], v[152:155], v[160:163], v[48:51]
	v_mfma_f32_16x16x32_bf16 v[36:39], v[144:147], v[168:171], v[36:39]
	v_mfma_f32_16x16x32_bf16 v[32:35], v[152:155], v[168:171], v[32:35]
	v_mfma_f32_16x16x32_bf16 v[20:23], v[144:147], v[176:179], v[20:23]
	v_mfma_f32_16x16x32_bf16 v[16:19], v[152:155], v[176:179], v[16:19]
	v_mfma_f32_16x16x32_bf16 v[4:7], v[144:147], v[184:187], v[4:7]
	v_mfma_f32_16x16x32_bf16 v[0:3], v[152:155], v[184:187], v[0:3]
	v_mfma_f32_16x16x32_bf16 v[52:55], v[148:151], v[164:167], v[52:55]
	v_mfma_f32_16x16x32_bf16 v[48:51], v[156:159], v[164:167], v[48:51]
	v_mfma_f32_16x16x32_bf16 v[36:39], v[148:151], v[172:175], v[36:39]
	v_mfma_f32_16x16x32_bf16 v[32:35], v[156:159], v[172:175], v[32:35]
	v_mfma_f32_16x16x32_bf16 v[20:23], v[148:151], v[180:183], v[20:23]
	v_mfma_f32_16x16x32_bf16 v[16:19], v[156:159], v[180:183], v[16:19]
	v_mfma_f32_16x16x32_bf16 v[4:7], v[148:151], v[188:191], v[4:7]
	v_mfma_f32_16x16x32_bf16 v[0:3], v[156:159], v[188:191], v[0:3]
	s_setprio 0
	s_barrier
	s_add_u32 s30, s30, 0x100
	s_addc_u32 s31, s31, 0
	s_add_u32 s29, s29, 0x100
	s_addc_u32 s85, s85, 0
	s_cmp_ge_i32 s92, s79
	s_mov_b32 s34, s92
	s_cbranch_scc0 .LBB0_369
	s_branch .LBB0_370
.LBB0_369:
	s_add_i32 s92, s34, 2
	s_add_u32 s96, s30, 0x80
	s_addc_u32 s35, s31, 0
	s_add_i32 vcc_lo, 0, 0x10000
	s_cmp_eq_u32 s37, s34
	s_cselect_b32 s35, s1, s35
	s_cselect_b32 s34, s0, s96
	s_cselect_b32 s97, s27, s85
	s_cselect_b32 s96, s26, s29
	s_add_i32 vcc_hi, 0, 0x14000
	v_add_u32_e32 v140, vcc_lo, v197
	v_add_u32_e32 v156, vcc_hi, v197
	ds_read_b128 v[128:131], v140
	ds_read_b128 v[132:135], v140 offset:1024
	ds_read_b128 v[136:139], v140 offset:2048
	ds_read_b128 v[140:143], v140 offset:3072
	ds_read_b128 v[144:147], v156
	ds_read_b128 v[148:151], v156 offset:1024
	ds_read_b128 v[152:155], v156 offset:2048
	ds_read_b128 v[156:159], v156 offset:3072
	v_lshl_add_u64 v[204:205], s[30:31], 0, v[200:201]
	s_add_i32 m0, s8, 0xc000
	ds_read_b128 v[160:163], v230
	ds_read_b128 v[164:167], v230 offset:1024
	ds_read_b128 v[168:171], v230 offset:2048
	ds_read_b128 v[172:175], v230 offset:3072
	ds_read_b128 v[176:179], v230 offset:4096
	ds_read_b128 v[180:183], v230 offset:5120
	ds_read_b128 v[184:187], v230 offset:6144
	ds_read_b128 v[188:191], v230 offset:7168
	global_load_lds_dwordx4 v[204:205], off
	v_lshl_add_u64 v[204:205], s[30:31], 0, v[202:203]
	s_add_i32 m0, s8, 0xe000
	s_nop 0
	global_load_lds_dwordx4 v[204:205], off
	s_waitcnt vmcnt(8)
	s_waitcnt lgkmcnt(0)
	s_barrier
; #define PG8_STAGE(bufoff, gbase, voff) do { _Pragma("unroll") for (int _i = 0; _i < 2; ++_i) \
;         __builtin_amdgcn_global_load_lds((const unsigned*)((const char*)(gbase) + (voff)[_i]), (PG8_LAS unsigned*)(lds + (bufoff) + ldsw + _i * 8192), 16, 0, 0); } while (0)
; #define PG8_LDA(dst, b, h) do { _Pragma("unroll") for (int m = 0; m < 4; ++m) _Pragma("unroll") for (int k = 0; k < 2; ++k) dst[m][k] = *(const PG8_LAS bf16x8*)(lds + PG8_SA(b, h) + aoff + m * 2048 + k * 1024); } while (0)
; #define PG8_LDB(dst, b, h) do { _Pragma("unroll") for (int n = 0; n < 2; ++n) _Pragma("unroll") for (int k = 0; k < 2; ++k) dst[n][k] = *(const PG8_LAS bf16x8*)(lds + PG8_SB(b, h) + boff + n * 2048 + k * 1024); } while (0)
; #define PG8_MMA(ai, bj, At, Bt) do { __builtin_amdgcn_s_setprio(1); _Pragma("unroll") for (int m = 0; m < 4; ++m) _Pragma("unroll") for (int n = 0; n < 2; ++n) _Pragma("unroll") for (int k = 0; k < 2; ++k) \
;         acc[ai][bj][m][n] = mma16<Epi::F16>(Bt[n][k], At[m][k], acc[ai][bj][m][n]); __builtin_amdgcn_s_setprio(0); } while (0)
; #define PG8_WAIT_V(n) asm volatile("s_waitcnt vmcnt(" #n ")" ::: "memory")
; #define PG8_WAIT_L(n) asm volatile("s_waitcnt lgkmcnt(" #n ")" ::: "memory")
; #define PG8_BAR __builtin_amdgcn_s_barrier()
; #define PG8_SCHED __builtin_amdgcn_sched_barrier(0)
; template <class Epi, class Sched, bool ALIGN_EPI = false, bool SP2 = false>
; __device__ __forceinline__ void gemm_phase(PG8_LAS unsigned char* lds, const Gemm g, const Sched& S, const Epi& E) {
;     ...
;             PG8_LDB(B0, 0, 0); PG8_LDB(B1, 0, 1); PG8_SCHED; PG8_LDA(At, 0, 0); PG8_STAGE(PG8_SA(1, 1), a1 + hstep, voffA);
;             PG8_WAIT_V(8); PG8_WAIT_L(0); PG8_BAR; PG8_MMA(0, 0, At, B0); PG8_MMA(0, 1, At, B1); PG8_BAR; PG8_SCHED;
;             PG8_LDA(At, 0, 1); PG8_STAGE(PG8_SB(0, 0), b2, voffB); PG8_STAGE(PG8_SB(0, 1), b2 + hstep, voffB); PG8_STAGE(PG8_SA(0, 0), a2, voffA);
;             PG8_WAIT_V(8); PG8_WAIT_L(0); PG8_BAR; PG8_MMA(1, 0, At, B0); PG8_MMA(1, 1, At, B1); PG8_BAR; PG8_SCHED;
;             PG8_LDB(B0, 1, 0); PG8_LDB(B1, 1, 1); PG8_SCHED; PG8_LDA(At, 1, 0); PG8_STAGE(PG8_SA(0, 1), a2 + hstep, voffA);
;             PG8_WAIT_V(8); PG8_WAIT_L(0); PG8_BAR; PG8_MMA(0, 0, At, B0); PG8_MMA(0, 1, At, B1); PG8_BAR; PG8_SCHED;
	s_setprio 1
	v_mfma_f32_16x16x32_bf16 v[124:127], v[128:131], v[160:163], v[124:127]
	v_mfma_f32_16x16x32_bf16 v[120:123], v[136:139], v[160:163], v[120:123]
	v_mfma_f32_16x16x32_bf16 v[108:111], v[128:131], v[168:171], v[108:111]
	v_mfma_f32_16x16x32_bf16 v[104:107], v[136:139], v[168:171], v[104:107]
	v_mfma_f32_16x16x32_bf16 v[92:95], v[128:131], v[176:179], v[92:95]
	v_mfma_f32_16x16x32_bf16 v[88:91], v[136:139], v[176:179], v[88:91]
	v_mfma_f32_16x16x32_bf16 v[76:79], v[128:131], v[184:187], v[76:79]
	v_mfma_f32_16x16x32_bf16 v[72:75], v[136:139], v[184:187], v[72:75]
	v_mfma_f32_16x16x32_bf16 v[124:127], v[132:135], v[164:167], v[124:127]
	v_mfma_f32_16x16x32_bf16 v[120:123], v[140:143], v[164:167], v[120:123]
	v_mfma_f32_16x16x32_bf16 v[108:111], v[132:135], v[172:175], v[108:111]
	v_mfma_f32_16x16x32_bf16 v[104:107], v[140:143], v[172:175], v[104:107]
	v_mfma_f32_16x16x32_bf16 v[92:95], v[132:135], v[180:183], v[92:95]
	v_mfma_f32_16x16x32_bf16 v[88:91], v[140:143], v[180:183], v[88:91]
	v_mfma_f32_16x16x32_bf16 v[76:79], v[132:135], v[188:191], v[76:79]
	v_mfma_f32_16x16x32_bf16 v[72:75], v[140:143], v[188:191], v[72:75]
	s_setprio 0
	s_setprio 1
	v_mfma_f32_16x16x32_bf16 v[116:119], v[144:147], v[160:163], v[116:119]
	v_mfma_f32_16x16x32_bf16 v[112:115], v[152:155], v[160:163], v[112:115]
	v_mfma_f32_16x16x32_bf16 v[100:103], v[144:147], v[168:171], v[100:103]
	v_mfma_f32_16x16x32_bf16 v[96:99], v[152:155], v[168:171], v[96:99]
	v_mfma_f32_16x16x32_bf16 v[84:87], v[144:147], v[176:179], v[84:87]
	v_mfma_f32_16x16x32_bf16 v[80:83], v[152:155], v[176:179], v[80:83]
	v_mfma_f32_16x16x32_bf16 v[68:71], v[144:147], v[184:187], v[68:71]
	v_mfma_f32_16x16x32_bf16 v[64:67], v[152:155], v[184:187], v[64:67]
	v_mfma_f32_16x16x32_bf16 v[116:119], v[148:151], v[164:167], v[116:119]
	v_mfma_f32_16x16x32_bf16 v[112:115], v[156:159], v[164:167], v[112:115]
	v_mfma_f32_16x16x32_bf16 v[100:103], v[148:151], v[172:175], v[100:103]
	v_mfma_f32_16x16x32_bf16 v[96:99], v[156:159], v[172:175], v[96:99]
	v_mfma_f32_16x16x32_bf16 v[84:87], v[148:151], v[180:183], v[84:87]
	v_mfma_f32_16x16x32_bf16 v[80:83], v[156:159], v[180:183], v[80:83]
	v_mfma_f32_16x16x32_bf16 v[68:71], v[148:151], v[188:191], v[68:71]
	v_mfma_f32_16x16x32_bf16 v[64:67], v[156:159], v[188:191], v[64:67]
	s_setprio 0
	s_barrier
	s_add_i32 vcc_lo, vcc_lo, s3
	v_lshl_add_u64 v[204:205], s[96:97], 0, v[208:209]
	s_mov_b32 m0, vcc_lo
	ds_read_b128 v[160:163], v230 offset:16384
	ds_read_b128 v[164:167], v230 offset:17408
	ds_read_b128 v[168:171], v230 offset:18432
	ds_read_b128 v[172:175], v230 offset:19456
	ds_read_b128 v[176:179], v230 offset:20480
	ds_read_b128 v[180:183], v230 offset:21504
	ds_read_b128 v[184:187], v230 offset:22528
	ds_read_b128 v[188:191], v230 offset:23552
	global_load_lds_dwordx4 v[204:205], off
	s_add_i32 m0, vcc_lo, 0x2000
	v_lshl_add_u64 v[206:207], s[96:97], 0, v[194:195]
	s_add_u32 s96, s96, s50
	s_addc_u32 s97, s97, s51
	s_add_i32 vcc_lo, vcc_hi, s3
	global_load_lds_dwordx4 v[206:207], off
	v_lshl_add_u64 v[212:213], s[96:97], 0, v[208:209]
	s_mov_b32 m0, vcc_lo
	v_lshl_add_u64 v[214:215], s[96:97], 0, v[194:195]
	global_load_lds_dwordx4 v[212:213], off
	s_add_i32 m0, vcc_lo, 0x2000
	v_lshl_add_u64 v[216:217], s[34:35], 0, v[208:209]
	global_load_lds_dwordx4 v[214:215], off
	s_mov_b32 m0, s8
	v_lshl_add_u64 v[218:219], s[34:35], 0, v[194:195]
	global_load_lds_dwordx4 v[216:217], off
	s_mov_b32 m0, s9
	s_nop 0
	global_load_lds_dwordx4 v[218:219], off
	s_waitcnt vmcnt(8)
	s_waitcnt lgkmcnt(0)
	s_barrier
	s_setprio 1
	v_mfma_f32_16x16x32_bf16 v[60:63], v[128:131], v[160:163], v[60:63]
	v_mfma_f32_16x16x32_bf16 v[56:59], v[136:139], v[160:163], v[56:59]
	v_mfma_f32_16x16x32_bf16 v[44:47], v[128:131], v[168:171], v[44:47]
	v_mfma_f32_16x16x32_bf16 v[40:43], v[136:139], v[168:171], v[40:43]
	v_mfma_f32_16x16x32_bf16 v[28:31], v[128:131], v[176:179], v[28:31]
	v_mfma_f32_16x16x32_bf16 v[24:27], v[136:139], v[176:179], v[24:27]
	v_mfma_f32_16x16x32_bf16 v[12:15], v[128:131], v[184:187], v[12:15]
	v_mfma_f32_16x16x32_bf16 v[8:11], v[136:139], v[184:187], v[8:11]
	v_mfma_f32_16x16x32_bf16 v[60:63], v[132:135], v[164:167], v[60:63]
	v_mfma_f32_16x16x32_bf16 v[56:59], v[140:143], v[164:167], v[56:59]
	v_mfma_f32_16x16x32_bf16 v[44:47], v[132:135], v[172:175], v[44:47]
	v_mfma_f32_16x16x32_bf16 v[40:43], v[140:143], v[172:175], v[40:43]
	v_mfma_f32_16x16x32_bf16 v[28:31], v[132:135], v[180:183], v[28:31]
	v_mfma_f32_16x16x32_bf16 v[24:27], v[140:143], v[180:183], v[24:27]
	v_mfma_f32_16x16x32_bf16 v[12:15], v[132:135], v[188:191], v[12:15]
	v_mfma_f32_16x16x32_bf16 v[8:11], v[140:143], v[188:191], v[8:11]
	s_setprio 0
	s_setprio 1
	v_mfma_f32_16x16x32_bf16 v[52:55], v[144:147], v[160:163], v[52:55]
	v_mfma_f32_16x16x32_bf16 v[48:51], v[152:155], v[160:163], v[48:51]
	v_mfma_f32_16x16x32_bf16 v[36:39], v[144:147], v[168:171], v[36:39]
	v_mfma_f32_16x16x32_bf16 v[32:35], v[152:155], v[168:171], v[32:35]
	v_mfma_f32_16x16x32_bf16 v[20:23], v[144:147], v[176:179], v[20:23]
	v_mfma_f32_16x16x32_bf16 v[16:19], v[152:155], v[176:179], v[16:19]
	v_mfma_f32_16x16x32_bf16 v[4:7], v[144:147], v[184:187], v[4:7]
	v_mfma_f32_16x16x32_bf16 v[0:3], v[152:155], v[184:187], v[0:3]
	v_mfma_f32_16x16x32_bf16 v[52:55], v[148:151], v[164:167], v[52:55]
	v_mfma_f32_16x16x32_bf16 v[48:51], v[156:159], v[164:167], v[48:51]
	v_mfma_f32_16x16x32_bf16 v[36:39], v[148:151], v[172:175], v[36:39]
	v_mfma_f32_16x16x32_bf16 v[32:35], v[156:159], v[172:175], v[32:35]
	v_mfma_f32_16x16x32_bf16 v[20:23], v[148:151], v[180:183], v[20:23]
	v_mfma_f32_16x16x32_bf16 v[16:19], v[156:159], v[180:183], v[16:19]
	v_mfma_f32_16x16x32_bf16 v[4:7], v[148:151], v[188:191], v[4:7]
	v_mfma_f32_16x16x32_bf16 v[0:3], v[156:159], v[188:191], v[0:3]
	s_setprio 0
	s_barrier
; #define PG8_STAGE(bufoff, gbase, voff) do { _Pragma("unroll") for (int _i = 0; _i < 2; ++_i) \
;         __builtin_amdgcn_global_load_lds((const unsigned*)((const char*)(gbase) + (voff)[_i]), (PG8_LAS unsigned*)(lds + (bufoff) + ldsw + _i * 8192), 16, 0, 0); } while (0)
; #define PG8_LDA(dst, b, h) do { _Pragma("unroll") for (int m = 0; m < 4; ++m) _Pragma("unroll") for (int k = 0; k < 2; ++k) dst[m][k] = *(const PG8_LAS bf16x8*)(lds + PG8_SA(b, h) + aoff + m * 2048 + k * 1024); } while (0)
; #define PG8_LDB(dst, b, h) do { _Pragma("unroll") for (int n = 0; n < 2; ++n) _Pragma("unroll") for (int k = 0; k < 2; ++k) dst[n][k] = *(const PG8_LAS bf16x8*)(lds + PG8_SB(b, h) + boff + n * 2048 + k * 1024); } while (0)
; #define PG8_MMA(ai, bj, At, Bt) do { __builtin_amdgcn_s_setprio(1); _Pragma("unroll") for (int m = 0; m < 4; ++m) _Pragma("unroll") for (int n = 0; n < 2; ++n) _Pragma("unroll") for (int k = 0; k < 2; ++k) \
;         acc[ai][bj][m][n] = mma16<Epi::F16>(Bt[n][k], At[m][k], acc[ai][bj][m][n]); __builtin_amdgcn_s_setprio(0); } while (0)
; #define PG8_WAIT_V(n) asm volatile("s_waitcnt vmcnt(" #n ")" ::: "memory")
; #define PG8_WAIT_L(n) asm volatile("s_waitcnt lgkmcnt(" #n ")" ::: "memory")
; #define PG8_BAR __builtin_amdgcn_s_barrier()
; #define PG8_SCHED __builtin_amdgcn_sched_barrier(0)
; template <class Epi, class Sched, bool ALIGN_EPI = false, bool SP2 = false>
; __device__ __forceinline__ void gemm_phase(PG8_LAS unsigned char* lds, const Gemm g, const Sched& S, const Epi& E) {
;     ...
;             PG8_LDB(B0, 1, 0); PG8_LDB(B1, 1, 1); PG8_SCHED; PG8_LDA(At, 1, 0); PG8_STAGE(PG8_SA(0, 1), a2 + hstep, voffA);
;             PG8_WAIT_V(8); PG8_WAIT_L(0); PG8_BAR; PG8_MMA(0, 0, At, B0); PG8_MMA(0, 1, At, B1); PG8_BAR; PG8_SCHED;
	s_add_i32 s96, 0, 0x18000
	s_add_i32 s97, 0, 0x1c000
	v_add_u32_e32 v140, s96, v197
	v_add_u32_e32 v156, s97, v197
	ds_read_b128 v[128:131], v140
	ds_read_b128 v[132:135], v140 offset:1024
	ds_read_b128 v[136:139], v140 offset:2048
	ds_read_b128 v[140:143], v140 offset:3072
	ds_read_b128 v[144:147], v156
	ds_read_b128 v[148:151], v156 offset:1024
	ds_read_b128 v[152:155], v156 offset:2048
	ds_read_b128 v[156:159], v156 offset:3072
	s_add_u32 s34, s34, s50
	s_addc_u32 s35, s35, s51
	s_mov_b32 m0, s11
	v_lshl_add_u64 v[220:221], s[34:35], 0, v[208:209]
	ds_read_b128 v[160:163], v230 offset:32768
	ds_read_b128 v[164:167], v230 offset:33792
	ds_read_b128 v[168:171], v230 offset:34816
	ds_read_b128 v[172:175], v230 offset:35840
	ds_read_b128 v[176:179], v230 offset:36864
	ds_read_b128 v[180:183], v230 offset:37888
	ds_read_b128 v[184:187], v230 offset:38912
	ds_read_b128 v[188:191], v230 offset:39936
	global_load_lds_dwordx4 v[220:221], off
	v_lshl_add_u64 v[220:221], s[34:35], 0, v[194:195]
	s_mov_b32 m0, s36
	s_nop 0
	global_load_lds_dwordx4 v[220:221], off
	s_waitcnt vmcnt(8)
	s_waitcnt lgkmcnt(0)
	s_barrier
	s_setprio 1
	v_mfma_f32_16x16x32_bf16 v[124:127], v[128:131], v[160:163], v[124:127]
	v_mfma_f32_16x16x32_bf16 v[120:123], v[136:139], v[160:163], v[120:123]
	v_mfma_f32_16x16x32_bf16 v[108:111], v[128:131], v[168:171], v[108:111]
	v_mfma_f32_16x16x32_bf16 v[104:107], v[136:139], v[168:171], v[104:107]
	v_mfma_f32_16x16x32_bf16 v[92:95], v[128:131], v[176:179], v[92:95]
	v_mfma_f32_16x16x32_bf16 v[88:91], v[136:139], v[176:179], v[88:91]
	v_mfma_f32_16x16x32_bf16 v[76:79], v[128:131], v[184:187], v[76:79]
	v_mfma_f32_16x16x32_bf16 v[72:75], v[136:139], v[184:187], v[72:75]
	v_mfma_f32_16x16x32_bf16 v[124:127], v[132:135], v[164:167], v[124:127]
	v_mfma_f32_16x16x32_bf16 v[120:123], v[140:143], v[164:167], v[120:123]
	v_mfma_f32_16x16x32_bf16 v[108:111], v[132:135], v[172:175], v[108:111]
	v_mfma_f32_16x16x32_bf16 v[104:107], v[140:143], v[172:175], v[104:107]
	v_mfma_f32_16x16x32_bf16 v[92:95], v[132:135], v[180:183], v[92:95]
	v_mfma_f32_16x16x32_bf16 v[88:91], v[140:143], v[180:183], v[88:91]
	v_mfma_f32_16x16x32_bf16 v[76:79], v[132:135], v[188:191], v[76:79]
	v_mfma_f32_16x16x32_bf16 v[72:75], v[140:143], v[188:191], v[72:75]
	s_setprio 0
	s_setprio 1
	v_mfma_f32_16x16x32_bf16 v[116:119], v[144:147], v[160:163], v[116:119]
	v_mfma_f32_16x16x32_bf16 v[112:115], v[152:155], v[160:163], v[112:115]
	v_mfma_f32_16x16x32_bf16 v[100:103], v[144:147], v[168:171], v[100:103]
	v_mfma_f32_16x16x32_bf16 v[96:99], v[152:155], v[168:171], v[96:99]
	v_mfma_f32_16x16x32_bf16 v[84:87], v[144:147], v[176:179], v[84:87]
	v_mfma_f32_16x16x32_bf16 v[80:83], v[152:155], v[176:179], v[80:83]
	v_mfma_f32_16x16x32_bf16 v[68:71], v[144:147], v[184:187], v[68:71]
	v_mfma_f32_16x16x32_bf16 v[64:67], v[152:155], v[184:187], v[64:67]
	v_mfma_f32_16x16x32_bf16 v[116:119], v[148:151], v[164:167], v[116:119]
	v_mfma_f32_16x16x32_bf16 v[112:115], v[156:159], v[164:167], v[112:115]
	v_mfma_f32_16x16x32_bf16 v[100:103], v[148:151], v[172:175], v[100:103]
	v_mfma_f32_16x16x32_bf16 v[96:99], v[156:159], v[172:175], v[96:99]
	v_mfma_f32_16x16x32_bf16 v[84:87], v[148:151], v[180:183], v[84:87]
	v_mfma_f32_16x16x32_bf16 v[80:83], v[156:159], v[180:183], v[80:83]
	v_mfma_f32_16x16x32_bf16 v[68:71], v[148:151], v[188:191], v[68:71]
	v_mfma_f32_16x16x32_bf16 v[64:67], v[156:159], v[188:191], v[64:67]
	s_setprio 0
	s_barrier
; #define PG8_STAGE(bufoff, gbase, voff) do { _Pragma("unroll") for (int _i = 0; _i < 2; ++_i) \
;         __builtin_amdgcn_global_load_lds((const unsigned*)((const char*)(gbase) + (voff)[_i]), (PG8_LAS unsigned*)(lds + (bufoff) + ldsw + _i * 8192), 16, 0, 0); } while (0)
; #define PG8_LDA(dst, b, h) do { _Pragma("unroll") for (int m = 0; m < 4; ++m) _Pragma("unroll") for (int k = 0; k < 2; ++k) dst[m][k] = *(const PG8_LAS bf16x8*)(lds + PG8_SA(b, h) + aoff + m * 2048 + k * 1024); } while (0)
; #define PG8_LDB(dst, b, h) do { _Pragma("unroll") for (int n = 0; n < 2; ++n) _Pragma("unroll") for (int k = 0; k < 2; ++k) dst[n][k] = *(const PG8_LAS bf16x8*)(lds + PG8_SB(b, h) + boff + n * 2048 + k * 1024); } while (0)
; template <class Epi, class Sched, bool ALIGN_EPI = false, bool SP2 = false>
; __device__ __forceinline__ void gemm_phase(PG8_LAS unsigned char* lds, const Gemm g, const Sched& S, const Epi& E) {
;     ...
;         for (int t = 0; t < nt; t += 2) {
;             const bool last = (t == nt - 2);
;             const char* a1 = cA + (size_t)(t + 1) * kstep;
;             const char* a2 = last ? nA : cA + (size_t)(t + 2) * kstep; const char* b2 = last ? nB : cB + (size_t)(t + 2) * kstep;
;             const char* a3 = a2 + kstep; const char* b3 = b2 + kstep;
;             if (last && has_next) S.a_ready(nxt);
;             if constexpr (SP2) {
;             PG8_LDB(B0, 0, 0); PG8_LDB(B1, 0, 1); PG8_SCHED; PG8_LDA(At, 0, 0); PG8_STAGE(PG8_SA(1, 1), a1 + hstep, voffA);
;             PG8_WAIT_V(8); PG8_WAIT_L(0); PG8_BAR; PG8_MMA(0, 0, At, B0); PG8_MMA(0, 1, At, B1); PG8_BAR; PG8_SCHED;
;             PG8_LDA(At, 0, 1); PG8_STAGE(PG8_SB(0, 0), b2, voffB); PG8_STAGE(PG8_SB(0, 1), b2 + hstep, voffB); PG8_STAGE(PG8_SA(0, 0), a2, voffA);
;             PG8_WAIT_V(8); PG8_WAIT_L(0); PG8_BAR; PG8_MMA(1, 0, At, B0); PG8_MMA(1, 1, At, B1); PG8_BAR; PG8_SCHED;
;             PG8_LDB(B0, 1, 0); PG8_LDB(B1, 1, 1); PG8_SCHED; PG8_LDA(At, 1, 0); PG8_STAGE(PG8_SA(0, 1), a2 + hstep, voffA);
;             PG8_WAIT_V(8); PG8_WAIT_L(0); PG8_BAR; PG8_MMA(0, 0, At, B0); PG8_MMA(0, 1, At, B1); PG8_BAR; PG8_SCHED;
;             PG8_LDA(At, 1, 1); PG8_STAGE(PG8_SB(1, 0), b3, voffB); PG8_STAGE(PG8_SB(1, 1), b3 + hstep, voffB); PG8_STAGE(PG8_SA(1, 0), a3, voffA);
;             PG8_WAIT_V(8); PG8_WAIT_L(0); PG8_BAR; PG8_MMA(1, 0, At, B0); PG8_MMA(1, 1, At, B1); PG8_BAR; PG8_SCHED;
	s_add_i32 s34, s96, s3
	v_lshl_add_u64 v[204:205], v[204:205], 0, s[20:21]
	s_mov_b32 m0, s34
	ds_read_b128 v[160:163], v230 offset:49152
	ds_read_b128 v[164:167], v230 offset:50176
	ds_read_b128 v[168:171], v230 offset:51200
	ds_read_b128 v[172:175], v230 offset:52224
	ds_read_b128 v[176:179], v230 offset:53248
	ds_read_b128 v[180:183], v230 offset:54272
	ds_read_b128 v[184:187], v230 offset:55296
	ds_read_b128 v[188:191], v230 offset:56320
	global_load_lds_dwordx4 v[204:205], off
	v_lshl_add_u64 v[204:205], v[206:207], 0, s[20:21]
	s_add_i32 m0, s34, 0x2000
	s_add_i32 s34, s97, s3
	global_load_lds_dwordx4 v[204:205], off
	v_lshl_add_u64 v[204:205], v[212:213], 0, s[20:21]
	s_mov_b32 m0, s34
	s_nop 0
	global_load_lds_dwordx4 v[204:205], off
	v_lshl_add_u64 v[204:205], v[214:215], 0, s[20:21]
	s_add_i32 m0, s34, 0x2000
	s_nop 0
	global_load_lds_dwordx4 v[204:205], off
	v_lshl_add_u64 v[204:205], v[216:217], 0, s[20:21]
	s_mov_b32 m0, s48
	s_nop 0
	global_load_lds_dwordx4 v[204:205], off
	v_lshl_add_u64 v[204:205], v[218:219], 0, s[20:21]
	s_mov_b32 m0, s49
	s_nop 0
	global_load_lds_dwordx4 v[204:205], off
	s_waitcnt vmcnt(8)
	s_waitcnt lgkmcnt(0)
	s_barrier
	s_setprio 1
	v_mfma_f32_16x16x32_bf16 v[60:63], v[128:131], v[160:163], v[60:63]
	v_mfma_f32_16x16x32_bf16 v[56:59], v[136:139], v[160:163], v[56:59]
	v_mfma_f32_16x16x32_bf16 v[44:47], v[128:131], v[168:171], v[44:47]
	v_mfma_f32_16x16x32_bf16 v[40:43], v[136:139], v[168:171], v[40:43]
	v_mfma_f32_16x16x32_bf16 v[28:31], v[128:131], v[176:179], v[28:31]
	v_mfma_f32_16x16x32_bf16 v[24:27], v[136:139], v[176:179], v[24:27]
	v_mfma_f32_16x16x32_bf16 v[12:15], v[128:131], v[184:187], v[12:15]
	v_mfma_f32_16x16x32_bf16 v[8:11], v[136:139], v[184:187], v[8:11]
	v_mfma_f32_16x16x32_bf16 v[60:63], v[132:135], v[164:167], v[60:63]
	v_mfma_f32_16x16x32_bf16 v[56:59], v[140:143], v[164:167], v[56:59]
	v_mfma_f32_16x16x32_bf16 v[44:47], v[132:135], v[172:175], v[44:47]
	v_mfma_f32_16x16x32_bf16 v[40:43], v[140:143], v[172:175], v[40:43]
	v_mfma_f32_16x16x32_bf16 v[28:31], v[132:135], v[180:183], v[28:31]
	v_mfma_f32_16x16x32_bf16 v[24:27], v[140:143], v[180:183], v[24:27]
	v_mfma_f32_16x16x32_bf16 v[12:15], v[132:135], v[188:191], v[12:15]
	v_mfma_f32_16x16x32_bf16 v[8:11], v[140:143], v[188:191], v[8:11]
	s_setprio 0
	s_setprio 1
	v_mfma_f32_16x16x32_bf16 v[52:55], v[144:147], v[160:163], v[52:55]
	v_mfma_f32_16x16x32_bf16 v[48:51], v[152:155], v[160:163], v[48:51]
	v_mfma_f32_16x16x32_bf16 v[36:39], v[144:147], v[168:171], v[36:39]
	v_mfma_f32_16x16x32_bf16 v[32:35], v[152:155], v[168:171], v[32:35]
	v_mfma_f32_16x16x32_bf16 v[20:23], v[144:147], v[176:179], v[20:23]
	v_mfma_f32_16x16x32_bf16 v[16:19], v[152:155], v[176:179], v[16:19]
	v_mfma_f32_16x16x32_bf16 v[4:7], v[144:147], v[184:187], v[4:7]
	v_mfma_f32_16x16x32_bf16 v[0:3], v[152:155], v[184:187], v[0:3]
	v_mfma_f32_16x16x32_bf16 v[52:55], v[148:151], v[164:167], v[52:55]
	v_mfma_f32_16x16x32_bf16 v[48:51], v[156:159], v[164:167], v[48:51]
	v_mfma_f32_16x16x32_bf16 v[36:39], v[148:151], v[172:175], v[36:39]
	v_mfma_f32_16x16x32_bf16 v[32:35], v[156:159], v[172:175], v[32:35]
	v_mfma_f32_16x16x32_bf16 v[20:23], v[148:151], v[180:183], v[20:23]
	v_mfma_f32_16x16x32_bf16 v[16:19], v[156:159], v[180:183], v[16:19]
	v_mfma_f32_16x16x32_bf16 v[4:7], v[148:151], v[188:191], v[4:7]
	v_mfma_f32_16x16x32_bf16 v[0:3], v[156:159], v[188:191], v[0:3]
	s_setprio 0
	s_barrier
	s_add_u32 s30, s30, 0x100
	s_addc_u32 s31, s31, 0
	s_add_u32 s29, s29, 0x100
	s_addc_u32 s85, s85, 0
	s_cmp_ge_i32 s92, s79
	s_mov_b32 s34, s92
	s_cbranch_scc0 .LBB0_369

; #define PG8_STAGE(bufoff, gbase, voff) do { _Pragma("unroll") for (int _i = 0; _i < 2; ++_i) \
;         __builtin_amdgcn_global_load_lds((const unsigned*)((const char*)(gbase) + (voff)[_i]), (PG8_LAS unsigned*)(lds + (bufoff) + ldsw + _i * 8192), 16, 0, 0); } while (0)
; #define PG8_LDA(dst, b, h) do { _Pragma("unroll") for (int m = 0; m < 4; ++m) _Pragma("unroll") for (int k = 0; k < 2; ++k) dst[m][k] = *(const PG8_LAS bf16x8*)(lds + PG8_SA(b, h) + aoff + m * 2048 + k * 1024); } while (0)
; #define PG8_LDB(dst, b, h) do { _Pragma("unroll") for (int n = 0; n < 2; ++n) _Pragma("unroll") for (int k = 0; k < 2; ++k) dst[n][k] = *(const PG8_LAS bf16x8*)(lds + PG8_SB(b, h) + boff + n * 2048 + k * 1024); } while (0)
; #define PG8_MMA(ai, bj, At, Bt) do { __builtin_amdgcn_s_setprio(1); _Pragma("unroll") for (int m = 0; m < 4; ++m) _Pragma("unroll") for (int n = 0; n < 2; ++n) _Pragma("unroll") for (int k = 0; k < 2; ++k) \
;         acc[ai][bj][m][n] = mma16<Epi::F16>(Bt[n][k], At[m][k], acc[ai][bj][m][n]); __builtin_amdgcn_s_setprio(0); } while (0)
; #define PG8_WAIT_V(n) asm volatile("s_waitcnt vmcnt(" #n ")" ::: "memory")
; #define PG8_WAIT_L(n) asm volatile("s_waitcnt lgkmcnt(" #n ")" ::: "memory")
; #define PG8_BAR __builtin_amdgcn_s_barrier()
; #define PG8_SCHED __builtin_amdgcn_sched_barrier(0)
; template <class Epi, class Sched, bool ALIGN_EPI = false, bool SP2 = false>
; __device__ __forceinline__ void gemm_phase(PG8_LAS unsigned char* lds, const Gemm g, const Sched& S, const Epi& E) {
;     ...
;             PG8_LDB(B0, 0, 0); PG8_LDB(B1, 0, 1); PG8_SCHED; PG8_LDA(At, 0, 0); PG8_STAGE(PG8_SA(1, 1), a1 + hstep, voffA);
;             PG8_WAIT_V(8); PG8_WAIT_L(0); PG8_BAR; PG8_MMA(0, 0, At, B0); PG8_MMA(0, 1, At, B1); PG8_BAR; PG8_SCHED;
;             PG8_LDA(At, 0, 1); PG8_STAGE(PG8_SB(0, 0), b2, voffB); PG8_STAGE(PG8_SB(0, 1), b2 + hstep, voffB); PG8_STAGE(PG8_SA(0, 0), a2, voffA);
;             PG8_WAIT_V(8); PG8_WAIT_L(0); PG8_BAR; PG8_MMA(1, 0, At, B0); PG8_MMA(1, 1, At, B1); PG8_BAR; PG8_SCHED;
;             PG8_LDB(B0, 1, 0); PG8_LDB(B1, 1, 1); PG8_SCHED; PG8_LDA(At, 1, 0); PG8_STAGE(PG8_SA(0, 1), a2 + hstep, voffA);
;             PG8_WAIT_V(8); PG8_WAIT_L(0); PG8_BAR; PG8_MMA(0, 0, At, B0); PG8_MMA(0, 1, At, B1); PG8_BAR; PG8_SCHED;
.Lpeel_k4:
	s_add_u32 s30, s30, 0x80
	s_addc_u32 s31, s31, 0
	s_add_u32 s67, s34, 0x100
	s_addc_u32 s68, s35, 0
	s_mov_b32 s34, 0
	s_add_i32 s69, s34, 2
	s_add_u32 s70, s30, 0x80
	s_addc_u32 s35, s31, 0
	s_add_i32 s72, 0, 0x10000
	s_cmp_eq_u32 s61, s34
	s_cselect_b32 s35, s1, s35
	s_cselect_b32 s34, s0, s70
	v_add_u32_e32 v146, s72, v153
	s_cselect_b32 s71, s55, s68
	s_cselect_b32 s70, s54, s67
	s_add_i32 s73, 0, 0x14000
	ds_read_b128 v[142:145], v146
	ds_read_b128 v[158:161], v146 offset:1024
	ds_read_b128 v[162:165], v146 offset:2048
	ds_read_b128 v[166:169], v146 offset:3072
	v_add_u32_e32 v146, s73, v153
	ds_read_b128 v[170:173], v146
	ds_read_b128 v[174:177], v146 offset:1024
	ds_read_b128 v[178:181], v146 offset:2048
	ds_read_b128 v[182:185], v146 offset:3072
	v_lshl_add_u64 v[146:147], s[30:31], 0, v[138:139]
	s_add_i32 m0, s39, 0xc000
	ds_read_b128 v[186:189], v157
	ds_read_b128 v[190:193], v157 offset:1024
	ds_read_b128 v[194:197], v157 offset:2048
	ds_read_b128 v[198:201], v157 offset:3072
	ds_read_b128 v[202:205], v157 offset:4096
	ds_read_b128 v[212:215], v157 offset:5120
	ds_read_b128 v[216:219], v157 offset:6144
	ds_read_b128 v[220:223], v157 offset:7168
	global_load_lds_dwordx4 v[146:147], off
	v_lshl_add_u64 v[146:147], s[30:31], 0, v[140:141]
	s_add_i32 m0, s39, 0xe000
	s_nop 0
	global_load_lds_dwordx4 v[146:147], off
	s_waitcnt vmcnt(8)
	s_waitcnt lgkmcnt(0)
	s_barrier
	s_setprio 1
	v_mfma_f32_16x16x32_bf16 v[124:127], v[142:145], v[186:189], 0
	v_mfma_f32_16x16x32_bf16 v[120:123], v[162:165], v[186:189], 0
	v_mfma_f32_16x16x32_bf16 v[108:111], v[142:145], v[194:197], 0
	v_mfma_f32_16x16x32_bf16 v[104:107], v[162:165], v[194:197], 0
	v_mfma_f32_16x16x32_bf16 v[92:95], v[142:145], v[202:205], 0
	v_mfma_f32_16x16x32_bf16 v[88:91], v[162:165], v[202:205], 0
	v_mfma_f32_16x16x32_bf16 v[76:79], v[142:145], v[216:219], 0
	v_mfma_f32_16x16x32_bf16 v[72:75], v[162:165], v[216:219], 0
	v_mfma_f32_16x16x32_bf16 v[124:127], v[158:161], v[190:193], v[124:127]
	v_mfma_f32_16x16x32_bf16 v[120:123], v[166:169], v[190:193], v[120:123]
	v_mfma_f32_16x16x32_bf16 v[108:111], v[158:161], v[198:201], v[108:111]
	v_mfma_f32_16x16x32_bf16 v[104:107], v[166:169], v[198:201], v[104:107]
	v_mfma_f32_16x16x32_bf16 v[92:95], v[158:161], v[212:215], v[92:95]
	v_mfma_f32_16x16x32_bf16 v[88:91], v[166:169], v[212:215], v[88:91]
	v_mfma_f32_16x16x32_bf16 v[76:79], v[158:161], v[220:223], v[76:79]
	v_mfma_f32_16x16x32_bf16 v[72:75], v[166:169], v[220:223], v[72:75]
	s_setprio 0
	s_setprio 1
	v_mfma_f32_16x16x32_bf16 v[116:119], v[170:173], v[186:189], 0
	v_mfma_f32_16x16x32_bf16 v[112:115], v[178:181], v[186:189], 0
	v_mfma_f32_16x16x32_bf16 v[100:103], v[170:173], v[194:197], 0
	v_mfma_f32_16x16x32_bf16 v[96:99], v[178:181], v[194:197], 0
	v_mfma_f32_16x16x32_bf16 v[84:87], v[170:173], v[202:205], 0
	v_mfma_f32_16x16x32_bf16 v[80:83], v[178:181], v[202:205], 0
	v_mfma_f32_16x16x32_bf16 v[68:71], v[170:173], v[216:219], 0
	v_mfma_f32_16x16x32_bf16 v[64:67], v[178:181], v[216:219], 0
	v_mfma_f32_16x16x32_bf16 v[116:119], v[174:177], v[190:193], v[116:119]
	v_mfma_f32_16x16x32_bf16 v[112:115], v[182:185], v[190:193], v[112:115]
	v_mfma_f32_16x16x32_bf16 v[100:103], v[174:177], v[198:201], v[100:103]
	v_mfma_f32_16x16x32_bf16 v[96:99], v[182:185], v[198:201], v[96:99]
	v_mfma_f32_16x16x32_bf16 v[84:87], v[174:177], v[212:215], v[84:87]
	v_mfma_f32_16x16x32_bf16 v[80:83], v[182:185], v[212:215], v[80:83]
	v_mfma_f32_16x16x32_bf16 v[68:71], v[174:177], v[220:223], v[68:71]
	v_mfma_f32_16x16x32_bf16 v[64:67], v[182:185], v[220:223], v[64:67]
	s_setprio 0
	s_barrier
	s_add_i32 s72, s72, s7
	v_lshl_add_u64 v[146:147], s[70:71], 0, v[132:133]
	s_mov_b32 m0, s72
	ds_read_b128 v[186:189], v157 offset:16384
	ds_read_b128 v[190:193], v157 offset:17408
	ds_read_b128 v[194:197], v157 offset:18432
	ds_read_b128 v[198:201], v157 offset:19456
	ds_read_b128 v[202:205], v157 offset:20480
	ds_read_b128 v[212:215], v157 offset:21504
	ds_read_b128 v[216:219], v157 offset:22528
	ds_read_b128 v[220:223], v157 offset:23552
	global_load_lds_dwordx4 v[146:147], off
	s_add_i32 m0, s72, 0x2000
	v_lshl_add_u64 v[150:151], s[70:71], 0, v[128:129]
	s_add_u32 s70, s70, s28
	s_addc_u32 s71, s71, s29
	s_add_i32 s72, s73, s7
	global_load_lds_dwordx4 v[150:151], off
	v_lshl_add_u64 v[154:155], s[70:71], 0, v[132:133]
	s_mov_b32 m0, s72
	v_lshl_add_u64 v[206:207], s[70:71], 0, v[128:129]
	global_load_lds_dwordx4 v[154:155], off
	s_add_i32 m0, s72, 0x2000
	v_lshl_add_u64 v[224:225], s[34:35], 0, v[134:135]
	global_load_lds_dwordx4 v[206:207], off
	s_mov_b32 m0, s39
	v_lshl_add_u64 v[226:227], s[34:35], 0, v[130:131]
	global_load_lds_dwordx4 v[224:225], off
	s_mov_b32 m0, s48
	s_nop 0
	global_load_lds_dwordx4 v[226:227], off
	s_waitcnt vmcnt(8)
	s_waitcnt lgkmcnt(0)
	s_barrier
; #define PG8_STAGE(bufoff, gbase, voff) do { _Pragma("unroll") for (int _i = 0; _i < 2; ++_i) \
;         __builtin_amdgcn_global_load_lds((const unsigned*)((const char*)(gbase) + (voff)[_i]), (PG8_LAS unsigned*)(lds + (bufoff) + ldsw + _i * 8192), 16, 0, 0); } while (0)
; #define PG8_LDA(dst, b, h) do { _Pragma("unroll") for (int m = 0; m < 4; ++m) _Pragma("unroll") for (int k = 0; k < 2; ++k) dst[m][k] = *(const PG8_LAS bf16x8*)(lds + PG8_SA(b, h) + aoff + m * 2048 + k * 1024); } while (0)
; #define PG8_LDB(dst, b, h) do { _Pragma("unroll") for (int n = 0; n < 2; ++n) _Pragma("unroll") for (int k = 0; k < 2; ++k) dst[n][k] = *(const PG8_LAS bf16x8*)(lds + PG8_SB(b, h) + boff + n * 2048 + k * 1024); } while (0)
; #define PG8_MMA(ai, bj, At, Bt) do { __builtin_amdgcn_s_setprio(1); _Pragma("unroll") for (int m = 0; m < 4; ++m) _Pragma("unroll") for (int n = 0; n < 2; ++n) _Pragma("unroll") for (int k = 0; k < 2; ++k) \
;         acc[ai][bj][m][n] = mma16<Epi::F16>(Bt[n][k], At[m][k], acc[ai][bj][m][n]); __builtin_amdgcn_s_setprio(0); } while (0)
; #define PG8_WAIT_V(n) asm volatile("s_waitcnt vmcnt(" #n ")" ::: "memory")
; #define PG8_WAIT_L(n) asm volatile("s_waitcnt lgkmcnt(" #n ")" ::: "memory")
; #define PG8_BAR __builtin_amdgcn_s_barrier()
; #define PG8_SCHED __builtin_amdgcn_sched_barrier(0)
; template <class Epi, class Sched, bool ALIGN_EPI = false, bool SP2 = false>
; __device__ __forceinline__ void gemm_phase(PG8_LAS unsigned char* lds, const Gemm g, const Sched& S, const Epi& E) {
;     ...
;             PG8_WAIT_V(8); PG8_WAIT_L(0); PG8_BAR; PG8_MMA(1, 0, At, B0); PG8_MMA(1, 1, At, B1); PG8_BAR; PG8_SCHED;
;             PG8_LDB(B0, 1, 0); PG8_LDB(B1, 1, 1); PG8_SCHED; PG8_LDA(At, 1, 0); PG8_STAGE(PG8_SA(0, 1), a2 + hstep, voffA);
;             PG8_WAIT_V(8); PG8_WAIT_L(0); PG8_BAR; PG8_MMA(0, 0, At, B0); PG8_MMA(0, 1, At, B1); PG8_BAR; PG8_SCHED;
	s_setprio 1
	v_mfma_f32_16x16x32_bf16 v[60:63], v[142:145], v[186:189], 0
	v_mfma_f32_16x16x32_bf16 v[56:59], v[162:165], v[186:189], 0
	v_mfma_f32_16x16x32_bf16 v[44:47], v[142:145], v[194:197], 0
	v_mfma_f32_16x16x32_bf16 v[40:43], v[162:165], v[194:197], 0
	v_mfma_f32_16x16x32_bf16 v[28:31], v[142:145], v[202:205], 0
	v_mfma_f32_16x16x32_bf16 v[24:27], v[162:165], v[202:205], 0
	v_mfma_f32_16x16x32_bf16 v[12:15], v[142:145], v[216:219], 0
	v_mfma_f32_16x16x32_bf16 v[8:11], v[162:165], v[216:219], 0
	v_mfma_f32_16x16x32_bf16 v[60:63], v[158:161], v[190:193], v[60:63]
	v_mfma_f32_16x16x32_bf16 v[56:59], v[166:169], v[190:193], v[56:59]
	v_mfma_f32_16x16x32_bf16 v[44:47], v[158:161], v[198:201], v[44:47]
	v_mfma_f32_16x16x32_bf16 v[40:43], v[166:169], v[198:201], v[40:43]
	v_mfma_f32_16x16x32_bf16 v[28:31], v[158:161], v[212:215], v[28:31]
	v_mfma_f32_16x16x32_bf16 v[24:27], v[166:169], v[212:215], v[24:27]
	v_mfma_f32_16x16x32_bf16 v[12:15], v[158:161], v[220:223], v[12:15]
	v_mfma_f32_16x16x32_bf16 v[8:11], v[166:169], v[220:223], v[8:11]
	s_setprio 0
	s_setprio 1
	v_mfma_f32_16x16x32_bf16 v[52:55], v[170:173], v[186:189], 0
	v_mfma_f32_16x16x32_bf16 v[48:51], v[178:181], v[186:189], 0
	v_mfma_f32_16x16x32_bf16 v[36:39], v[170:173], v[194:197], 0
	v_mfma_f32_16x16x32_bf16 v[32:35], v[178:181], v[194:197], 0
	v_mfma_f32_16x16x32_bf16 v[20:23], v[170:173], v[202:205], 0
	v_mfma_f32_16x16x32_bf16 v[16:19], v[178:181], v[202:205], 0
	v_mfma_f32_16x16x32_bf16 v[4:7], v[170:173], v[216:219], 0
	v_mfma_f32_16x16x32_bf16 v[0:3], v[178:181], v[216:219], 0
	v_mfma_f32_16x16x32_bf16 v[52:55], v[174:177], v[190:193], v[52:55]
	v_mfma_f32_16x16x32_bf16 v[48:51], v[182:185], v[190:193], v[48:51]
	v_mfma_f32_16x16x32_bf16 v[36:39], v[174:177], v[198:201], v[36:39]
	v_mfma_f32_16x16x32_bf16 v[32:35], v[182:185], v[198:201], v[32:35]
	v_mfma_f32_16x16x32_bf16 v[20:23], v[174:177], v[212:215], v[20:23]
	v_mfma_f32_16x16x32_bf16 v[16:19], v[182:185], v[212:215], v[16:19]
	v_mfma_f32_16x16x32_bf16 v[4:7], v[174:177], v[220:223], v[4:7]
	v_mfma_f32_16x16x32_bf16 v[0:3], v[182:185], v[220:223], v[0:3]
	s_setprio 0
	s_barrier
	s_add_i32 s70, 0, 0x18000
	v_add_u32_e32 v148, s70, v153
	s_add_i32 s71, 0, 0x1c000
	ds_read_b128 v[142:145], v148
	ds_read_b128 v[158:161], v148 offset:1024
	ds_read_b128 v[162:165], v148 offset:2048
	ds_read_b128 v[166:169], v148 offset:3072
	v_add_u32_e32 v148, s71, v153
	ds_read_b128 v[170:173], v148
	ds_read_b128 v[174:177], v148 offset:1024
	ds_read_b128 v[178:181], v148 offset:2048
	ds_read_b128 v[182:185], v148 offset:3072
	s_add_u32 s34, s34, s28
	s_addc_u32 s35, s35, s29
	s_mov_b32 m0, s56
	v_lshl_add_u64 v[228:229], s[34:35], 0, v[134:135]
	ds_read_b128 v[186:189], v157 offset:32768
	ds_read_b128 v[190:193], v157 offset:33792
	ds_read_b128 v[194:197], v157 offset:34816
	ds_read_b128 v[198:201], v157 offset:35840
	ds_read_b128 v[202:205], v157 offset:36864
	ds_read_b128 v[212:215], v157 offset:37888
	ds_read_b128 v[216:219], v157 offset:38912
	ds_read_b128 v[220:223], v157 offset:39936
	global_load_lds_dwordx4 v[228:229], off
	v_lshl_add_u64 v[228:229], s[34:35], 0, v[130:131]
	s_mov_b32 m0, s57
	s_nop 0
	global_load_lds_dwordx4 v[228:229], off
	s_waitcnt vmcnt(8)
	s_waitcnt lgkmcnt(0)
	s_barrier
	s_setprio 1
	v_mfma_f32_16x16x32_bf16 v[124:127], v[142:145], v[186:189], v[124:127]
	v_mfma_f32_16x16x32_bf16 v[120:123], v[162:165], v[186:189], v[120:123]
	v_mfma_f32_16x16x32_bf16 v[108:111], v[142:145], v[194:197], v[108:111]
	v_mfma_f32_16x16x32_bf16 v[104:107], v[162:165], v[194:197], v[104:107]
	v_mfma_f32_16x16x32_bf16 v[92:95], v[142:145], v[202:205], v[92:95]
	v_mfma_f32_16x16x32_bf16 v[88:91], v[162:165], v[202:205], v[88:91]
	v_mfma_f32_16x16x32_bf16 v[76:79], v[142:145], v[216:219], v[76:79]
	v_mfma_f32_16x16x32_bf16 v[72:75], v[162:165], v[216:219], v[72:75]
	v_mfma_f32_16x16x32_bf16 v[124:127], v[158:161], v[190:193], v[124:127]
	v_mfma_f32_16x16x32_bf16 v[120:123], v[166:169], v[190:193], v[120:123]
	v_mfma_f32_16x16x32_bf16 v[108:111], v[158:161], v[198:201], v[108:111]
	v_mfma_f32_16x16x32_bf16 v[104:107], v[166:169], v[198:201], v[104:107]
	v_mfma_f32_16x16x32_bf16 v[92:95], v[158:161], v[212:215], v[92:95]
	v_mfma_f32_16x16x32_bf16 v[88:91], v[166:169], v[212:215], v[88:91]
	v_mfma_f32_16x16x32_bf16 v[76:79], v[158:161], v[220:223], v[76:79]
	v_mfma_f32_16x16x32_bf16 v[72:75], v[166:169], v[220:223], v[72:75]
	s_setprio 0
	s_setprio 1
	v_mfma_f32_16x16x32_bf16 v[116:119], v[170:173], v[186:189], v[116:119]
	v_mfma_f32_16x16x32_bf16 v[112:115], v[178:181], v[186:189], v[112:115]
	v_mfma_f32_16x16x32_bf16 v[100:103], v[170:173], v[194:197], v[100:103]
	v_mfma_f32_16x16x32_bf16 v[96:99], v[178:181], v[194:197], v[96:99]
	v_mfma_f32_16x16x32_bf16 v[84:87], v[170:173], v[202:205], v[84:87]
	v_mfma_f32_16x16x32_bf16 v[80:83], v[178:181], v[202:205], v[80:83]
	v_mfma_f32_16x16x32_bf16 v[68:71], v[170:173], v[216:219], v[68:71]
	v_mfma_f32_16x16x32_bf16 v[64:67], v[178:181], v[216:219], v[64:67]
	v_mfma_f32_16x16x32_bf16 v[116:119], v[174:177], v[190:193], v[116:119]
	v_mfma_f32_16x16x32_bf16 v[112:115], v[182:185], v[190:193], v[112:115]
	v_mfma_f32_16x16x32_bf16 v[100:103], v[174:177], v[198:201], v[100:103]
	v_mfma_f32_16x16x32_bf16 v[96:99], v[182:185], v[198:201], v[96:99]
	v_mfma_f32_16x16x32_bf16 v[84:87], v[174:177], v[212:215], v[84:87]
	v_mfma_f32_16x16x32_bf16 v[80:83], v[182:185], v[212:215], v[80:83]
	v_mfma_f32_16x16x32_bf16 v[68:71], v[174:177], v[220:223], v[68:71]
	v_mfma_f32_16x16x32_bf16 v[64:67], v[182:185], v[220:223], v[64:67]
	s_setprio 0
	s_barrier
; #define PG8_STAGE(bufoff, gbase, voff) do { _Pragma("unroll") for (int _i = 0; _i < 2; ++_i) \
;         __builtin_amdgcn_global_load_lds((const unsigned*)((const char*)(gbase) + (voff)[_i]), (PG8_LAS unsigned*)(lds + (bufoff) + ldsw + _i * 8192), 16, 0, 0); } while (0)
; #define PG8_LDA(dst, b, h) do { _Pragma("unroll") for (int m = 0; m < 4; ++m) _Pragma("unroll") for (int k = 0; k < 2; ++k) dst[m][k] = *(const PG8_LAS bf16x8*)(lds + PG8_SA(b, h) + aoff + m * 2048 + k * 1024); } while (0)
; #define PG8_LDB(dst, b, h) do { _Pragma("unroll") for (int n = 0; n < 2; ++n) _Pragma("unroll") for (int k = 0; k < 2; ++k) dst[n][k] = *(const PG8_LAS bf16x8*)(lds + PG8_SB(b, h) + boff + n * 2048 + k * 1024); } while (0)
; template <class Epi, class Sched, bool ALIGN_EPI = false, bool SP2 = false>
; __device__ __forceinline__ void gemm_phase(PG8_LAS unsigned char* lds, const Gemm g, const Sched& S, const Epi& E) {
;     ...
;         for (int t = 0; t < nt; t += 2) {
;             const bool last = (t == nt - 2);
;             const char* a1 = cA + (size_t)(t + 1) * kstep;
;             const char* a2 = last ? nA : cA + (size_t)(t + 2) * kstep; const char* b2 = last ? nB : cB + (size_t)(t + 2) * kstep;
;             const char* a3 = a2 + kstep; const char* b3 = b2 + kstep;
;             if (last && has_next) S.a_ready(nxt);
;             if constexpr (SP2) {
;             PG8_LDB(B0, 0, 0); PG8_LDB(B1, 0, 1); PG8_SCHED; PG8_LDA(At, 0, 0); PG8_STAGE(PG8_SA(1, 1), a1 + hstep, voffA);
;             PG8_WAIT_V(8); PG8_WAIT_L(0); PG8_BAR; PG8_MMA(0, 0, At, B0); PG8_MMA(0, 1, At, B1); PG8_BAR; PG8_SCHED;
;             PG8_LDA(At, 0, 1); PG8_STAGE(PG8_SB(0, 0), b2, voffB); PG8_STAGE(PG8_SB(0, 1), b2 + hstep, voffB); PG8_STAGE(PG8_SA(0, 0), a2, voffA);
;             PG8_WAIT_V(8); PG8_WAIT_L(0); PG8_BAR; PG8_MMA(1, 0, At, B0); PG8_MMA(1, 1, At, B1); PG8_BAR; PG8_SCHED;
;             PG8_LDB(B0, 1, 0); PG8_LDB(B1, 1, 1); PG8_SCHED; PG8_LDA(At, 1, 0); PG8_STAGE(PG8_SA(0, 1), a2 + hstep, voffA);
;             PG8_WAIT_V(8); PG8_WAIT_L(0); PG8_BAR; PG8_MMA(0, 0, At, B0); PG8_MMA(0, 1, At, B1); PG8_BAR; PG8_SCHED;
;             PG8_LDA(At, 1, 1); PG8_STAGE(PG8_SB(1, 0), b3, voffB); PG8_STAGE(PG8_SB(1, 1), b3 + hstep, voffB); PG8_STAGE(PG8_SA(1, 0), a3, voffA);
;             PG8_WAIT_V(8); PG8_WAIT_L(0); PG8_BAR; PG8_MMA(1, 0, At, B0); PG8_MMA(1, 1, At, B1); PG8_BAR; PG8_SCHED;
	s_add_i32 s34, s70, s7
	v_lshl_add_u64 v[146:147], v[146:147], 0, s[20:21]
	s_mov_b32 m0, s34
	ds_read_b128 v[186:189], v157 offset:49152
	ds_read_b128 v[190:193], v157 offset:50176
	ds_read_b128 v[194:197], v157 offset:51200
	ds_read_b128 v[198:201], v157 offset:52224
	ds_read_b128 v[202:205], v157 offset:53248
	ds_read_b128 v[212:215], v157 offset:54272
	ds_read_b128 v[216:219], v157 offset:55296
	ds_read_b128 v[220:223], v157 offset:56320
	global_load_lds_dwordx4 v[146:147], off
	v_lshl_add_u64 v[146:147], v[150:151], 0, s[20:21]
	s_add_i32 m0, s34, 0x2000
	s_add_i32 s34, s71, s7
	global_load_lds_dwordx4 v[146:147], off
	v_lshl_add_u64 v[146:147], v[154:155], 0, s[20:21]
	s_mov_b32 m0, s34
	s_nop 0
	global_load_lds_dwordx4 v[146:147], off
	v_lshl_add_u64 v[146:147], v[206:207], 0, s[20:21]
	s_add_i32 m0, s34, 0x2000
	s_nop 0
	global_load_lds_dwordx4 v[146:147], off
	v_lshl_add_u64 v[146:147], v[224:225], 0, s[20:21]
	s_mov_b32 m0, s58
	s_nop 0
	global_load_lds_dwordx4 v[146:147], off
	v_lshl_add_u64 v[146:147], v[226:227], 0, s[20:21]
	s_mov_b32 m0, s59
	s_nop 0
	global_load_lds_dwordx4 v[146:147], off
	s_waitcnt vmcnt(8)
	s_waitcnt lgkmcnt(0)
	s_barrier
	s_setprio 1
	v_mfma_f32_16x16x32_bf16 v[60:63], v[142:145], v[186:189], v[60:63]
	v_mfma_f32_16x16x32_bf16 v[56:59], v[162:165], v[186:189], v[56:59]
	v_mfma_f32_16x16x32_bf16 v[44:47], v[142:145], v[194:197], v[44:47]
	v_mfma_f32_16x16x32_bf16 v[40:43], v[162:165], v[194:197], v[40:43]
	v_mfma_f32_16x16x32_bf16 v[28:31], v[142:145], v[202:205], v[28:31]
	v_mfma_f32_16x16x32_bf16 v[24:27], v[162:165], v[202:205], v[24:27]
	v_mfma_f32_16x16x32_bf16 v[12:15], v[142:145], v[216:219], v[12:15]
	v_mfma_f32_16x16x32_bf16 v[8:11], v[162:165], v[216:219], v[8:11]
	v_mfma_f32_16x16x32_bf16 v[60:63], v[158:161], v[190:193], v[60:63]
	v_mfma_f32_16x16x32_bf16 v[56:59], v[166:169], v[190:193], v[56:59]
	v_mfma_f32_16x16x32_bf16 v[44:47], v[158:161], v[198:201], v[44:47]
	v_mfma_f32_16x16x32_bf16 v[40:43], v[166:169], v[198:201], v[40:43]
	v_mfma_f32_16x16x32_bf16 v[28:31], v[158:161], v[212:215], v[28:31]
	v_mfma_f32_16x16x32_bf16 v[24:27], v[166:169], v[212:215], v[24:27]
	v_mfma_f32_16x16x32_bf16 v[12:15], v[158:161], v[220:223], v[12:15]
	v_mfma_f32_16x16x32_bf16 v[8:11], v[166:169], v[220:223], v[8:11]
	s_setprio 0
	s_setprio 1
	v_mfma_f32_16x16x32_bf16 v[52:55], v[170:173], v[186:189], v[52:55]
	v_mfma_f32_16x16x32_bf16 v[48:51], v[178:181], v[186:189], v[48:51]
	v_mfma_f32_16x16x32_bf16 v[36:39], v[170:173], v[194:197], v[36:39]
	v_mfma_f32_16x16x32_bf16 v[32:35], v[178:181], v[194:197], v[32:35]
	v_mfma_f32_16x16x32_bf16 v[20:23], v[170:173], v[202:205], v[20:23]
	v_mfma_f32_16x16x32_bf16 v[16:19], v[178:181], v[202:205], v[16:19]
	v_mfma_f32_16x16x32_bf16 v[4:7], v[170:173], v[216:219], v[4:7]
	v_mfma_f32_16x16x32_bf16 v[0:3], v[178:181], v[216:219], v[0:3]
	v_mfma_f32_16x16x32_bf16 v[52:55], v[174:177], v[190:193], v[52:55]
	v_mfma_f32_16x16x32_bf16 v[48:51], v[182:185], v[190:193], v[48:51]
	v_mfma_f32_16x16x32_bf16 v[36:39], v[174:177], v[198:201], v[36:39]
	v_mfma_f32_16x16x32_bf16 v[32:35], v[182:185], v[198:201], v[32:35]
	v_mfma_f32_16x16x32_bf16 v[20:23], v[174:177], v[212:215], v[20:23]
	v_mfma_f32_16x16x32_bf16 v[16:19], v[182:185], v[212:215], v[16:19]
	v_mfma_f32_16x16x32_bf16 v[4:7], v[174:177], v[220:223], v[4:7]
	v_mfma_f32_16x16x32_bf16 v[0:3], v[182:185], v[220:223], v[0:3]
	s_setprio 0
	s_barrier
	s_add_u32 s30, s30, 0x100
	s_addc_u32 s31, s31, 0
	s_add_u32 s67, s67, 0x100
	s_addc_u32 s68, s68, 0
	s_cmp_ge_i32 s69, s60
	s_mov_b32 s34, s69
	s_cbranch_scc0 .LBB0_511
	s_branch .LBB0_512
.LBB0_511:
	s_add_i32 s69, s34, 2
	s_add_u32 s70, s30, 0x80
	s_addc_u32 s35, s31, 0
	s_add_i32 s72, 0, 0x10000
	s_cmp_eq_u32 s61, s34
	s_cselect_b32 s35, s1, s35
	s_cselect_b32 s34, s0, s70
	v_add_u32_e32 v146, s72, v153
	s_cselect_b32 s71, s55, s68
	s_cselect_b32 s70, s54, s67
	s_add_i32 s73, 0, 0x14000
	ds_read_b128 v[142:145], v146
	ds_read_b128 v[158:161], v146 offset:1024
	ds_read_b128 v[162:165], v146 offset:2048
	ds_read_b128 v[166:169], v146 offset:3072
	v_add_u32_e32 v146, s73, v153
	ds_read_b128 v[170:173], v146
	ds_read_b128 v[174:177], v146 offset:1024
	ds_read_b128 v[178:181], v146 offset:2048
	ds_read_b128 v[182:185], v146 offset:3072
	v_lshl_add_u64 v[146:147], s[30:31], 0, v[138:139]
	s_add_i32 m0, s39, 0xc000
	ds_read_b128 v[186:189], v157
	ds_read_b128 v[190:193], v157 offset:1024
	ds_read_b128 v[194:197], v157 offset:2048
	ds_read_b128 v[198:201], v157 offset:3072
	ds_read_b128 v[202:205], v157 offset:4096
	ds_read_b128 v[212:215], v157 offset:5120
	ds_read_b128 v[216:219], v157 offset:6144
	ds_read_b128 v[220:223], v157 offset:7168
	global_load_lds_dwordx4 v[146:147], off
	v_lshl_add_u64 v[146:147], s[30:31], 0, v[140:141]
	s_add_i32 m0, s39, 0xe000
	s_nop 0
	global_load_lds_dwordx4 v[146:147], off
	s_waitcnt vmcnt(8)
	s_waitcnt lgkmcnt(0)
	s_barrier
; #define PG8_STAGE(bufoff, gbase, voff) do { _Pragma("unroll") for (int _i = 0; _i < 2; ++_i) \
;         __builtin_amdgcn_global_load_lds((const unsigned*)((const char*)(gbase) + (voff)[_i]), (PG8_LAS unsigned*)(lds + (bufoff) + ldsw + _i * 8192), 16, 0, 0); } while (0)
; #define PG8_LDA(dst, b, h) do { _Pragma("unroll") for (int m = 0; m < 4; ++m) _Pragma("unroll") for (int k = 0; k < 2; ++k) dst[m][k] = *(const PG8_LAS bf16x8*)(lds + PG8_SA(b, h) + aoff + m * 2048 + k * 1024); } while (0)
; #define PG8_LDB(dst, b, h) do { _Pragma("unroll") for (int n = 0; n < 2; ++n) _Pragma("unroll") for (int k = 0; k < 2; ++k) dst[n][k] = *(const PG8_LAS bf16x8*)(lds + PG8_SB(b, h) + boff + n * 2048 + k * 1024); } while (0)
; #define PG8_MMA(ai, bj, At, Bt) do { __builtin_amdgcn_s_setprio(1); _Pragma("unroll") for (int m = 0; m < 4; ++m) _Pragma("unroll") for (int n = 0; n < 2; ++n) _Pragma("unroll") for (int k = 0; k < 2; ++k) \
;         acc[ai][bj][m][n] = mma16<Epi::F16>(Bt[n][k], At[m][k], acc[ai][bj][m][n]); __builtin_amdgcn_s_setprio(0); } while (0)
; #define PG8_WAIT_V(n) asm volatile("s_waitcnt vmcnt(" #n ")" ::: "memory")
; #define PG8_WAIT_L(n) asm volatile("s_waitcnt lgkmcnt(" #n ")" ::: "memory")
; #define PG8_BAR __builtin_amdgcn_s_barrier()
; #define PG8_SCHED __builtin_amdgcn_sched_barrier(0)
; template <class Epi, class Sched, bool ALIGN_EPI = false, bool SP2 = false>
; __device__ __forceinline__ void gemm_phase(PG8_LAS unsigned char* lds, const Gemm g, const Sched& S, const Epi& E) {
;     ...
;             PG8_LDB(B0, 0, 0); PG8_LDB(B1, 0, 1); PG8_SCHED; PG8_LDA(At, 0, 0); PG8_STAGE(PG8_SA(1, 1), a1 + hstep, voffA);
;             PG8_WAIT_V(8); PG8_WAIT_L(0); PG8_BAR; PG8_MMA(0, 0, At, B0); PG8_MMA(0, 1, At, B1); PG8_BAR; PG8_SCHED;
;             PG8_LDA(At, 0, 1); PG8_STAGE(PG8_SB(0, 0), b2, voffB); PG8_STAGE(PG8_SB(0, 1), b2 + hstep, voffB); PG8_STAGE(PG8_SA(0, 0), a2, voffA);
;             PG8_WAIT_V(8); PG8_WAIT_L(0); PG8_BAR; PG8_MMA(1, 0, At, B0); PG8_MMA(1, 1, At, B1); PG8_BAR; PG8_SCHED;
;             PG8_LDB(B0, 1, 0); PG8_LDB(B1, 1, 1); PG8_SCHED; PG8_LDA(At, 1, 0); PG8_STAGE(PG8_SA(0, 1), a2 + hstep, voffA);
;             PG8_WAIT_V(8); PG8_WAIT_L(0); PG8_BAR; PG8_MMA(0, 0, At, B0); PG8_MMA(0, 1, At, B1); PG8_BAR; PG8_SCHED;
	s_setprio 1
	v_mfma_f32_16x16x32_bf16 v[124:127], v[142:145], v[186:189], v[124:127]
	v_mfma_f32_16x16x32_bf16 v[120:123], v[162:165], v[186:189], v[120:123]
	v_mfma_f32_16x16x32_bf16 v[108:111], v[142:145], v[194:197], v[108:111]
	v_mfma_f32_16x16x32_bf16 v[104:107], v[162:165], v[194:197], v[104:107]
	v_mfma_f32_16x16x32_bf16 v[92:95], v[142:145], v[202:205], v[92:95]
	v_mfma_f32_16x16x32_bf16 v[88:91], v[162:165], v[202:205], v[88:91]
	v_mfma_f32_16x16x32_bf16 v[76:79], v[142:145], v[216:219], v[76:79]
	v_mfma_f32_16x16x32_bf16 v[72:75], v[162:165], v[216:219], v[72:75]
	v_mfma_f32_16x16x32_bf16 v[124:127], v[158:161], v[190:193], v[124:127]
	v_mfma_f32_16x16x32_bf16 v[120:123], v[166:169], v[190:193], v[120:123]
	v_mfma_f32_16x16x32_bf16 v[108:111], v[158:161], v[198:201], v[108:111]
	v_mfma_f32_16x16x32_bf16 v[104:107], v[166:169], v[198:201], v[104:107]
	v_mfma_f32_16x16x32_bf16 v[92:95], v[158:161], v[212:215], v[92:95]
	v_mfma_f32_16x16x32_bf16 v[88:91], v[166:169], v[212:215], v[88:91]
	v_mfma_f32_16x16x32_bf16 v[76:79], v[158:161], v[220:223], v[76:79]
	v_mfma_f32_16x16x32_bf16 v[72:75], v[166:169], v[220:223], v[72:75]
	s_setprio 0
	s_setprio 1
	v_mfma_f32_16x16x32_bf16 v[116:119], v[170:173], v[186:189], v[116:119]
	v_mfma_f32_16x16x32_bf16 v[112:115], v[178:181], v[186:189], v[112:115]
	v_mfma_f32_16x16x32_bf16 v[100:103], v[170:173], v[194:197], v[100:103]
	v_mfma_f32_16x16x32_bf16 v[96:99], v[178:181], v[194:197], v[96:99]
	v_mfma_f32_16x16x32_bf16 v[84:87], v[170:173], v[202:205], v[84:87]
	v_mfma_f32_16x16x32_bf16 v[80:83], v[178:181], v[202:205], v[80:83]
	v_mfma_f32_16x16x32_bf16 v[68:71], v[170:173], v[216:219], v[68:71]
	v_mfma_f32_16x16x32_bf16 v[64:67], v[178:181], v[216:219], v[64:67]
	v_mfma_f32_16x16x32_bf16 v[116:119], v[174:177], v[190:193], v[116:119]
	v_mfma_f32_16x16x32_bf16 v[112:115], v[182:185], v[190:193], v[112:115]
	v_mfma_f32_16x16x32_bf16 v[100:103], v[174:177], v[198:201], v[100:103]
	v_mfma_f32_16x16x32_bf16 v[96:99], v[182:185], v[198:201], v[96:99]
	v_mfma_f32_16x16x32_bf16 v[84:87], v[174:177], v[212:215], v[84:87]
	v_mfma_f32_16x16x32_bf16 v[80:83], v[182:185], v[212:215], v[80:83]
	v_mfma_f32_16x16x32_bf16 v[68:71], v[174:177], v[220:223], v[68:71]
	v_mfma_f32_16x16x32_bf16 v[64:67], v[182:185], v[220:223], v[64:67]
	s_setprio 0
	s_barrier
	s_add_i32 s72, s72, s7
	v_lshl_add_u64 v[146:147], s[70:71], 0, v[132:133]
	s_mov_b32 m0, s72
	ds_read_b128 v[186:189], v157 offset:16384
	ds_read_b128 v[190:193], v157 offset:17408
	ds_read_b128 v[194:197], v157 offset:18432
	ds_read_b128 v[198:201], v157 offset:19456
	ds_read_b128 v[202:205], v157 offset:20480
	ds_read_b128 v[212:215], v157 offset:21504
	ds_read_b128 v[216:219], v157 offset:22528
	ds_read_b128 v[220:223], v157 offset:23552
	global_load_lds_dwordx4 v[146:147], off
	s_add_i32 m0, s72, 0x2000
	v_lshl_add_u64 v[150:151], s[70:71], 0, v[128:129]
	s_add_u32 s70, s70, s28
	s_addc_u32 s71, s71, s29
	s_add_i32 s72, s73, s7
	global_load_lds_dwordx4 v[150:151], off
	v_lshl_add_u64 v[154:155], s[70:71], 0, v[132:133]
	s_mov_b32 m0, s72
	v_lshl_add_u64 v[206:207], s[70:71], 0, v[128:129]
	global_load_lds_dwordx4 v[154:155], off
	s_add_i32 m0, s72, 0x2000
	v_lshl_add_u64 v[224:225], s[34:35], 0, v[134:135]
	global_load_lds_dwordx4 v[206:207], off
	s_mov_b32 m0, s39
	v_lshl_add_u64 v[226:227], s[34:35], 0, v[130:131]
	global_load_lds_dwordx4 v[224:225], off
	s_mov_b32 m0, s48
	s_nop 0
	global_load_lds_dwordx4 v[226:227], off
	s_waitcnt vmcnt(8)
	s_waitcnt lgkmcnt(0)
	s_barrier
	s_setprio 1
	v_mfma_f32_16x16x32_bf16 v[60:63], v[142:145], v[186:189], v[60:63]
	v_mfma_f32_16x16x32_bf16 v[56:59], v[162:165], v[186:189], v[56:59]
	v_mfma_f32_16x16x32_bf16 v[44:47], v[142:145], v[194:197], v[44:47]
	v_mfma_f32_16x16x32_bf16 v[40:43], v[162:165], v[194:197], v[40:43]
	v_mfma_f32_16x16x32_bf16 v[28:31], v[142:145], v[202:205], v[28:31]
	v_mfma_f32_16x16x32_bf16 v[24:27], v[162:165], v[202:205], v[24:27]
	v_mfma_f32_16x16x32_bf16 v[12:15], v[142:145], v[216:219], v[12:15]
	v_mfma_f32_16x16x32_bf16 v[8:11], v[162:165], v[216:219], v[8:11]
	v_mfma_f32_16x16x32_bf16 v[60:63], v[158:161], v[190:193], v[60:63]
	v_mfma_f32_16x16x32_bf16 v[56:59], v[166:169], v[190:193], v[56:59]
	v_mfma_f32_16x16x32_bf16 v[44:47], v[158:161], v[198:201], v[44:47]
	v_mfma_f32_16x16x32_bf16 v[40:43], v[166:169], v[198:201], v[40:43]
	v_mfma_f32_16x16x32_bf16 v[28:31], v[158:161], v[212:215], v[28:31]
	v_mfma_f32_16x16x32_bf16 v[24:27], v[166:169], v[212:215], v[24:27]
	v_mfma_f32_16x16x32_bf16 v[12:15], v[158:161], v[220:223], v[12:15]
	v_mfma_f32_16x16x32_bf16 v[8:11], v[166:169], v[220:223], v[8:11]
	s_setprio 0
	s_setprio 1
	v_mfma_f32_16x16x32_bf16 v[52:55], v[170:173], v[186:189], v[52:55]
	v_mfma_f32_16x16x32_bf16 v[48:51], v[178:181], v[186:189], v[48:51]
	v_mfma_f32_16x16x32_bf16 v[36:39], v[170:173], v[194:197], v[36:39]
	v_mfma_f32_16x16x32_bf16 v[32:35], v[178:181], v[194:197], v[32:35]
	v_mfma_f32_16x16x32_bf16 v[20:23], v[170:173], v[202:205], v[20:23]
	v_mfma_f32_16x16x32_bf16 v[16:19], v[178:181], v[202:205], v[16:19]
	v_mfma_f32_16x16x32_bf16 v[4:7], v[170:173], v[216:219], v[4:7]
	v_mfma_f32_16x16x32_bf16 v[0:3], v[178:181], v[216:219], v[0:3]
	v_mfma_f32_16x16x32_bf16 v[52:55], v[174:177], v[190:193], v[52:55]
	v_mfma_f32_16x16x32_bf16 v[48:51], v[182:185], v[190:193], v[48:51]
	v_mfma_f32_16x16x32_bf16 v[36:39], v[174:177], v[198:201], v[36:39]
	v_mfma_f32_16x16x32_bf16 v[32:35], v[182:185], v[198:201], v[32:35]
	v_mfma_f32_16x16x32_bf16 v[20:23], v[174:177], v[212:215], v[20:23]
	v_mfma_f32_16x16x32_bf16 v[16:19], v[182:185], v[212:215], v[16:19]
	v_mfma_f32_16x16x32_bf16 v[4:7], v[174:177], v[220:223], v[4:7]
	v_mfma_f32_16x16x32_bf16 v[0:3], v[182:185], v[220:223], v[0:3]
	s_setprio 0
	s_barrier
; #define PG8_STAGE(bufoff, gbase, voff) do { _Pragma("unroll") for (int _i = 0; _i < 2; ++_i) \
;         __builtin_amdgcn_global_load_lds((const unsigned*)((const char*)(gbase) + (voff)[_i]), (PG8_LAS unsigned*)(lds + (bufoff) + ldsw + _i * 8192), 16, 0, 0); } while (0)
; #define PG8_LDA(dst, b, h) do { _Pragma("unroll") for (int m = 0; m < 4; ++m) _Pragma("unroll") for (int k = 0; k < 2; ++k) dst[m][k] = *(const PG8_LAS bf16x8*)(lds + PG8_SA(b, h) + aoff + m * 2048 + k * 1024); } while (0)
; #define PG8_LDB(dst, b, h) do { _Pragma("unroll") for (int n = 0; n < 2; ++n) _Pragma("unroll") for (int k = 0; k < 2; ++k) dst[n][k] = *(const PG8_LAS bf16x8*)(lds + PG8_SB(b, h) + boff + n * 2048 + k * 1024); } while (0)
; #define PG8_MMA(ai, bj, At, Bt) do { __builtin_amdgcn_s_setprio(1); _Pragma("unroll") for (int m = 0; m < 4; ++m) _Pragma("unroll") for (int n = 0; n < 2; ++n) _Pragma("unroll") for (int k = 0; k < 2; ++k) \
;         acc[ai][bj][m][n] = mma16<Epi::F16>(Bt[n][k], At[m][k], acc[ai][bj][m][n]); __builtin_amdgcn_s_setprio(0); } while (0)
; #define PG8_WAIT_V(n) asm volatile("s_waitcnt vmcnt(" #n ")" ::: "memory")
; #define PG8_WAIT_L(n) asm volatile("s_waitcnt lgkmcnt(" #n ")" ::: "memory")
; #define PG8_BAR __builtin_amdgcn_s_barrier()
; #define PG8_SCHED __builtin_amdgcn_sched_barrier(0)
; template <class Epi, class Sched, bool ALIGN_EPI = false, bool SP2 = false>
; __device__ __forceinline__ void gemm_phase(PG8_LAS unsigned char* lds, const Gemm g, const Sched& S, const Epi& E) {
;     ...
;             PG8_LDB(B0, 1, 0); PG8_LDB(B1, 1, 1); PG8_SCHED; PG8_LDA(At, 1, 0); PG8_STAGE(PG8_SA(0, 1), a2 + hstep, voffA);
;             PG8_WAIT_V(8); PG8_WAIT_L(0); PG8_BAR; PG8_MMA(0, 0, At, B0); PG8_MMA(0, 1, At, B1); PG8_BAR; PG8_SCHED;
	s_add_i32 s70, 0, 0x18000
	v_add_u32_e32 v148, s70, v153
	s_add_i32 s71, 0, 0x1c000
	ds_read_b128 v[142:145], v148
	ds_read_b128 v[158:161], v148 offset:1024
	ds_read_b128 v[162:165], v148 offset:2048
	ds_read_b128 v[166:169], v148 offset:3072
	v_add_u32_e32 v148, s71, v153
	ds_read_b128 v[170:173], v148
	ds_read_b128 v[174:177], v148 offset:1024
	ds_read_b128 v[178:181], v148 offset:2048
	ds_read_b128 v[182:185], v148 offset:3072
	s_add_u32 s34, s34, s28
	s_addc_u32 s35, s35, s29
	s_mov_b32 m0, s56
	v_lshl_add_u64 v[228:229], s[34:35], 0, v[134:135]
	ds_read_b128 v[186:189], v157 offset:32768
	ds_read_b128 v[190:193], v157 offset:33792
	ds_read_b128 v[194:197], v157 offset:34816
	ds_read_b128 v[198:201], v157 offset:35840
	ds_read_b128 v[202:205], v157 offset:36864
	ds_read_b128 v[212:215], v157 offset:37888
	ds_read_b128 v[216:219], v157 offset:38912
	ds_read_b128 v[220:223], v157 offset:39936
	global_load_lds_dwordx4 v[228:229], off
	v_lshl_add_u64 v[228:229], s[34:35], 0, v[130:131]
	s_mov_b32 m0, s57
	s_nop 0
	global_load_lds_dwordx4 v[228:229], off
	s_waitcnt vmcnt(8)
	s_waitcnt lgkmcnt(0)
	s_barrier
	s_setprio 1
	v_mfma_f32_16x16x32_bf16 v[124:127], v[142:145], v[186:189], v[124:127]
	v_mfma_f32_16x16x32_bf16 v[120:123], v[162:165], v[186:189], v[120:123]
	v_mfma_f32_16x16x32_bf16 v[108:111], v[142:145], v[194:197], v[108:111]
	v_mfma_f32_16x16x32_bf16 v[104:107], v[162:165], v[194:197], v[104:107]
	v_mfma_f32_16x16x32_bf16 v[92:95], v[142:145], v[202:205], v[92:95]
	v_mfma_f32_16x16x32_bf16 v[88:91], v[162:165], v[202:205], v[88:91]
	v_mfma_f32_16x16x32_bf16 v[76:79], v[142:145], v[216:219], v[76:79]
	v_mfma_f32_16x16x32_bf16 v[72:75], v[162:165], v[216:219], v[72:75]
	v_mfma_f32_16x16x32_bf16 v[124:127], v[158:161], v[190:193], v[124:127]
	v_mfma_f32_16x16x32_bf16 v[120:123], v[166:169], v[190:193], v[120:123]
	v_mfma_f32_16x16x32_bf16 v[108:111], v[158:161], v[198:201], v[108:111]
	v_mfma_f32_16x16x32_bf16 v[104:107], v[166:169], v[198:201], v[104:107]
	v_mfma_f32_16x16x32_bf16 v[92:95], v[158:161], v[212:215], v[92:95]
	v_mfma_f32_16x16x32_bf16 v[88:91], v[166:169], v[212:215], v[88:91]
	v_mfma_f32_16x16x32_bf16 v[76:79], v[158:161], v[220:223], v[76:79]
	v_mfma_f32_16x16x32_bf16 v[72:75], v[166:169], v[220:223], v[72:75]
	s_setprio 0
	s_setprio 1
	v_mfma_f32_16x16x32_bf16 v[116:119], v[170:173], v[186:189], v[116:119]
	v_mfma_f32_16x16x32_bf16 v[112:115], v[178:181], v[186:189], v[112:115]
	v_mfma_f32_16x16x32_bf16 v[100:103], v[170:173], v[194:197], v[100:103]
	v_mfma_f32_16x16x32_bf16 v[96:99], v[178:181], v[194:197], v[96:99]
	v_mfma_f32_16x16x32_bf16 v[84:87], v[170:173], v[202:205], v[84:87]
	v_mfma_f32_16x16x32_bf16 v[80:83], v[178:181], v[202:205], v[80:83]
	v_mfma_f32_16x16x32_bf16 v[68:71], v[170:173], v[216:219], v[68:71]
	v_mfma_f32_16x16x32_bf16 v[64:67], v[178:181], v[216:219], v[64:67]
	v_mfma_f32_16x16x32_bf16 v[116:119], v[174:177], v[190:193], v[116:119]
	v_mfma_f32_16x16x32_bf16 v[112:115], v[182:185], v[190:193], v[112:115]
	v_mfma_f32_16x16x32_bf16 v[100:103], v[174:177], v[198:201], v[100:103]
	v_mfma_f32_16x16x32_bf16 v[96:99], v[182:185], v[198:201], v[96:99]
	v_mfma_f32_16x16x32_bf16 v[84:87], v[174:177], v[212:215], v[84:87]
	v_mfma_f32_16x16x32_bf16 v[80:83], v[182:185], v[212:215], v[80:83]
	v_mfma_f32_16x16x32_bf16 v[68:71], v[174:177], v[220:223], v[68:71]
	v_mfma_f32_16x16x32_bf16 v[64:67], v[182:185], v[220:223], v[64:67]
	s_setprio 0
	s_barrier
; #define PG8_STAGE(bufoff, gbase, voff) do { _Pragma("unroll") for (int _i = 0; _i < 2; ++_i) \
;         __builtin_amdgcn_global_load_lds((const unsigned*)((const char*)(gbase) + (voff)[_i]), (PG8_LAS unsigned*)(lds + (bufoff) + ldsw + _i * 8192), 16, 0, 0); } while (0)
; #define PG8_LDA(dst, b, h) do { _Pragma("unroll") for (int m = 0; m < 4; ++m) _Pragma("unroll") for (int k = 0; k < 2; ++k) dst[m][k] = *(const PG8_LAS bf16x8*)(lds + PG8_SA(b, h) + aoff + m * 2048 + k * 1024); } while (0)
; #define PG8_LDB(dst, b, h) do { _Pragma("unroll") for (int n = 0; n < 2; ++n) _Pragma("unroll") for (int k = 0; k < 2; ++k) dst[n][k] = *(const PG8_LAS bf16x8*)(lds + PG8_SB(b, h) + boff + n * 2048 + k * 1024); } while (0)
; template <class Epi, class Sched, bool ALIGN_EPI = false, bool SP2 = false>
; __device__ __forceinline__ void gemm_phase(PG8_LAS unsigned char* lds, const Gemm g, const Sched& S, const Epi& E) {
;     ...
;         for (int t = 0; t < nt; t += 2) {
;             const bool last = (t == nt - 2);
;             const char* a1 = cA + (size_t)(t + 1) * kstep;
;             const char* a2 = last ? nA : cA + (size_t)(t + 2) * kstep; const char* b2 = last ? nB : cB + (size_t)(t + 2) * kstep;
;             const char* a3 = a2 + kstep; const char* b3 = b2 + kstep;
;             if (last && has_next) S.a_ready(nxt);
;             if constexpr (SP2) {
;             PG8_LDB(B0, 0, 0); PG8_LDB(B1, 0, 1); PG8_SCHED; PG8_LDA(At, 0, 0); PG8_STAGE(PG8_SA(1, 1), a1 + hstep, voffA);
;             PG8_WAIT_V(8); PG8_WAIT_L(0); PG8_BAR; PG8_MMA(0, 0, At, B0); PG8_MMA(0, 1, At, B1); PG8_BAR; PG8_SCHED;
;             PG8_LDA(At, 0, 1); PG8_STAGE(PG8_SB(0, 0), b2, voffB); PG8_STAGE(PG8_SB(0, 1), b2 + hstep, voffB); PG8_STAGE(PG8_SA(0, 0), a2, voffA);
;             PG8_WAIT_V(8); PG8_WAIT_L(0); PG8_BAR; PG8_MMA(1, 0, At, B0); PG8_MMA(1, 1, At, B1); PG8_BAR; PG8_SCHED;
;             PG8_LDB(B0, 1, 0); PG8_LDB(B1, 1, 1); PG8_SCHED; PG8_LDA(At, 1, 0); PG8_STAGE(PG8_SA(0, 1), a2 + hstep, voffA);
;             PG8_WAIT_V(8); PG8_WAIT_L(0); PG8_BAR; PG8_MMA(0, 0, At, B0); PG8_MMA(0, 1, At, B1); PG8_BAR; PG8_SCHED;
;             PG8_LDA(At, 1, 1); PG8_STAGE(PG8_SB(1, 0), b3, voffB); PG8_STAGE(PG8_SB(1, 1), b3 + hstep, voffB); PG8_STAGE(PG8_SA(1, 0), a3, voffA);
;             PG8_WAIT_V(8); PG8_WAIT_L(0); PG8_BAR; PG8_MMA(1, 0, At, B0); PG8_MMA(1, 1, At, B1); PG8_BAR; PG8_SCHED;
	s_add_i32 s34, s70, s7
	v_lshl_add_u64 v[146:147], v[146:147], 0, s[20:21]
	s_mov_b32 m0, s34
	ds_read_b128 v[186:189], v157 offset:49152
	ds_read_b128 v[190:193], v157 offset:50176
	ds_read_b128 v[194:197], v157 offset:51200
	ds_read_b128 v[198:201], v157 offset:52224
	ds_read_b128 v[202:205], v157 offset:53248
	ds_read_b128 v[212:215], v157 offset:54272
	ds_read_b128 v[216:219], v157 offset:55296
	ds_read_b128 v[220:223], v157 offset:56320
	global_load_lds_dwordx4 v[146:147], off
	v_lshl_add_u64 v[146:147], v[150:151], 0, s[20:21]
	s_add_i32 m0, s34, 0x2000
	s_add_i32 s34, s71, s7
	global_load_lds_dwordx4 v[146:147], off
	v_lshl_add_u64 v[146:147], v[154:155], 0, s[20:21]
	s_mov_b32 m0, s34
	s_nop 0
	global_load_lds_dwordx4 v[146:147], off
	v_lshl_add_u64 v[146:147], v[206:207], 0, s[20:21]
	s_add_i32 m0, s34, 0x2000
	s_nop 0
	global_load_lds_dwordx4 v[146:147], off
	v_lshl_add_u64 v[146:147], v[224:225], 0, s[20:21]
	s_mov_b32 m0, s58
	s_nop 0
	global_load_lds_dwordx4 v[146:147], off
	v_lshl_add_u64 v[146:147], v[226:227], 0, s[20:21]
	s_mov_b32 m0, s59
	s_nop 0
	global_load_lds_dwordx4 v[146:147], off
	s_waitcnt vmcnt(8)
	s_waitcnt lgkmcnt(0)
	s_barrier
	s_setprio 1
	v_mfma_f32_16x16x32_bf16 v[60:63], v[142:145], v[186:189], v[60:63]
	v_mfma_f32_16x16x32_bf16 v[56:59], v[162:165], v[186:189], v[56:59]
	v_mfma_f32_16x16x32_bf16 v[44:47], v[142:145], v[194:197], v[44:47]
	v_mfma_f32_16x16x32_bf16 v[40:43], v[162:165], v[194:197], v[40:43]
	v_mfma_f32_16x16x32_bf16 v[28:31], v[142:145], v[202:205], v[28:31]
	v_mfma_f32_16x16x32_bf16 v[24:27], v[162:165], v[202:205], v[24:27]
	v_mfma_f32_16x16x32_bf16 v[12:15], v[142:145], v[216:219], v[12:15]
	v_mfma_f32_16x16x32_bf16 v[8:11], v[162:165], v[216:219], v[8:11]
	v_mfma_f32_16x16x32_bf16 v[60:63], v[158:161], v[190:193], v[60:63]
	v_mfma_f32_16x16x32_bf16 v[56:59], v[166:169], v[190:193], v[56:59]
	v_mfma_f32_16x16x32_bf16 v[44:47], v[158:161], v[198:201], v[44:47]
	v_mfma_f32_16x16x32_bf16 v[40:43], v[166:169], v[198:201], v[40:43]
	v_mfma_f32_16x16x32_bf16 v[28:31], v[158:161], v[212:215], v[28:31]
	v_mfma_f32_16x16x32_bf16 v[24:27], v[166:169], v[212:215], v[24:27]
	v_mfma_f32_16x16x32_bf16 v[12:15], v[158:161], v[220:223], v[12:15]
	v_mfma_f32_16x16x32_bf16 v[8:11], v[166:169], v[220:223], v[8:11]
	s_setprio 0
	s_setprio 1
	v_mfma_f32_16x16x32_bf16 v[52:55], v[170:173], v[186:189], v[52:55]
	v_mfma_f32_16x16x32_bf16 v[48:51], v[178:181], v[186:189], v[48:51]
	v_mfma_f32_16x16x32_bf16 v[36:39], v[170:173], v[194:197], v[36:39]
	v_mfma_f32_16x16x32_bf16 v[32:35], v[178:181], v[194:197], v[32:35]
	v_mfma_f32_16x16x32_bf16 v[20:23], v[170:173], v[202:205], v[20:23]
	v_mfma_f32_16x16x32_bf16 v[16:19], v[178:181], v[202:205], v[16:19]
	v_mfma_f32_16x16x32_bf16 v[4:7], v[170:173], v[216:219], v[4:7]
	v_mfma_f32_16x16x32_bf16 v[0:3], v[178:181], v[216:219], v[0:3]
	v_mfma_f32_16x16x32_bf16 v[52:55], v[174:177], v[190:193], v[52:55]
	v_mfma_f32_16x16x32_bf16 v[48:51], v[182:185], v[190:193], v[48:51]
	v_mfma_f32_16x16x32_bf16 v[36:39], v[174:177], v[198:201], v[36:39]
	v_mfma_f32_16x16x32_bf16 v[32:35], v[182:185], v[198:201], v[32:35]
	v_mfma_f32_16x16x32_bf16 v[20:23], v[174:177], v[212:215], v[20:23]
	v_mfma_f32_16x16x32_bf16 v[16:19], v[182:185], v[212:215], v[16:19]
	v_mfma_f32_16x16x32_bf16 v[4:7], v[174:177], v[220:223], v[4:7]
	v_mfma_f32_16x16x32_bf16 v[0:3], v[182:185], v[220:223], v[0:3]
	s_setprio 0
	s_barrier
	s_add_u32 s30, s30, 0x100
	s_addc_u32 s31, s31, 0
	s_add_u32 s67, s67, 0x100
	s_addc_u32 s68, s68, 0
	s_cmp_ge_i32 s69, s60
	s_mov_b32 s34, s69
	s_cbranch_scc0 .LBB0_511

; #define PG8_STAGE(bufoff, gbase, voff) do { _Pragma("unroll") for (int _i = 0; _i < 2; ++_i) \
;         __builtin_amdgcn_global_load_lds((const unsigned*)((const char*)(gbase) + (voff)[_i]), (PG8_LAS unsigned*)(lds + (bufoff) + ldsw + _i * 8192), 16, 0, 0); } while (0)
; #define PG8_LDA(dst, b, h) do { _Pragma("unroll") for (int m = 0; m < 4; ++m) _Pragma("unroll") for (int k = 0; k < 2; ++k) dst[m][k] = *(const PG8_LAS bf16x8*)(lds + PG8_SA(b, h) + aoff + m * 2048 + k * 1024); } while (0)
; #define PG8_LDB(dst, b, h) do { _Pragma("unroll") for (int n = 0; n < 2; ++n) _Pragma("unroll") for (int k = 0; k < 2; ++k) dst[n][k] = *(const PG8_LAS bf16x8*)(lds + PG8_SB(b, h) + boff + n * 2048 + k * 1024); } while (0)
; #define PG8_MMA(ai, bj, At, Bt) do { __builtin_amdgcn_s_setprio(1); _Pragma("unroll") for (int m = 0; m < 4; ++m) _Pragma("unroll") for (int n = 0; n < 2; ++n) _Pragma("unroll") for (int k = 0; k < 2; ++k) \
;         acc[ai][bj][m][n] = mma16<Epi::F16>(Bt[n][k], At[m][k], acc[ai][bj][m][n]); __builtin_amdgcn_s_setprio(0); } while (0)
; #define PG8_WAIT_V(n) asm volatile("s_waitcnt vmcnt(" #n ")" ::: "memory")
; #define PG8_WAIT_L(n) asm volatile("s_waitcnt lgkmcnt(" #n ")" ::: "memory")
; #define PG8_BAR __builtin_amdgcn_s_barrier()
; #define PG8_SCHED __builtin_amdgcn_sched_barrier(0)
; template <class Epi, class Sched, bool ALIGN_EPI = false, bool SP2 = false>
; __device__ __forceinline__ void gemm_phase(PG8_LAS unsigned char* lds, const Gemm g, const Sched& S, const Epi& E) {
;     ...
;             PG8_LDB(B0, 0, 0); PG8_LDB(B1, 0, 1); PG8_SCHED; PG8_LDA(At, 0, 0); PG8_STAGE(PG8_SA(1, 1), a1 + hstep, voffA);
;             PG8_WAIT_V(8); PG8_WAIT_L(0); PG8_BAR; PG8_MMA(0, 0, At, B0); PG8_MMA(0, 1, At, B1); PG8_BAR; PG8_SCHED;
;             PG8_LDA(At, 0, 1); PG8_STAGE(PG8_SB(0, 0), b2, voffB); PG8_STAGE(PG8_SB(0, 1), b2 + hstep, voffB); PG8_STAGE(PG8_SA(0, 0), a2, voffA);
;             PG8_WAIT_V(8); PG8_WAIT_L(0); PG8_BAR; PG8_MMA(1, 0, At, B0); PG8_MMA(1, 1, At, B1); PG8_BAR; PG8_SCHED;
;             PG8_LDB(B0, 1, 0); PG8_LDB(B1, 1, 1); PG8_SCHED; PG8_LDA(At, 1, 0); PG8_STAGE(PG8_SA(0, 1), a2 + hstep, voffA);
;             PG8_WAIT_V(8); PG8_WAIT_L(0); PG8_BAR; PG8_MMA(0, 0, At, B0); PG8_MMA(0, 1, At, B1); PG8_BAR; PG8_SCHED;
.Lpeel_k5:
	s_add_u32 s30, s30, 0x80
	s_addc_u32 s31, s31, 0
	s_add_u32 s29, s34, 0x100
	s_addc_u32 s73, s35, 0
	s_mov_b32 s34, 0
	s_add_i32 s77, s34, 2
	s_add_u32 s82, s30, 0x80
	s_addc_u32 s35, s31, 0
	s_add_i32 s92, 0, 0x10000
	s_cmp_eq_u32 s48, s34
	s_cselect_b32 s35, s1, s35
	s_cselect_b32 s34, s0, s82
	v_add_u32_e32 v131, s92, v133
	s_cselect_b32 s85, s61, s73
	s_cselect_b32 s84, s60, s29
	s_add_i32 s82, 0, 0x14000
	ds_read_b128 v[140:143], v131
	ds_read_b128 v[144:147], v131 offset:1024
	ds_read_b128 v[148:151], v131 offset:2048
	ds_read_b128 v[152:155], v131 offset:3072
	v_add_u32_e32 v131, s82, v133
	ds_read_b128 v[156:159], v131
	ds_read_b128 v[160:163], v131 offset:1024
	ds_read_b128 v[164:167], v131 offset:2048
	ds_read_b128 v[168:171], v131 offset:3072
	v_lshl_add_u64 v[212:213], s[30:31], 0, v[136:137]
	s_add_i32 m0, s8, 0xc000
	ds_read_b128 v[172:175], v199
	ds_read_b128 v[176:179], v199 offset:1024
	ds_read_b128 v[180:183], v199 offset:2048
	ds_read_b128 v[184:187], v199 offset:3072
	ds_read_b128 v[188:191], v199 offset:4096
	ds_read_b128 v[192:195], v199 offset:5120
	ds_read_b128 v[200:203], v199 offset:6144
	ds_read_b128 v[204:207], v199 offset:7168
	global_load_lds_dwordx4 v[212:213], off
	v_lshl_add_u64 v[212:213], s[30:31], 0, v[138:139]
	s_add_i32 m0, s8, 0xe000
	s_nop 0
	global_load_lds_dwordx4 v[212:213], off
	s_waitcnt vmcnt(8)
	s_waitcnt lgkmcnt(0)
	s_barrier
	s_setprio 1
	v_mfma_f32_16x16x32_bf16 v[120:123], v[140:143], v[172:175], 0
	v_mfma_f32_16x16x32_bf16 v[124:127], v[148:151], v[172:175], 0
	v_mfma_f32_16x16x32_bf16 v[108:111], v[140:143], v[180:183], 0
	v_mfma_f32_16x16x32_bf16 v[104:107], v[148:151], v[180:183], 0
	v_mfma_f32_16x16x32_bf16 v[92:95], v[140:143], v[188:191], 0
	v_mfma_f32_16x16x32_bf16 v[88:91], v[148:151], v[188:191], 0
	v_mfma_f32_16x16x32_bf16 v[76:79], v[140:143], v[200:203], 0
	v_mfma_f32_16x16x32_bf16 v[72:75], v[148:151], v[200:203], 0
	v_mfma_f32_16x16x32_bf16 v[120:123], v[144:147], v[176:179], v[120:123]
	v_mfma_f32_16x16x32_bf16 v[124:127], v[152:155], v[176:179], v[124:127]
	v_mfma_f32_16x16x32_bf16 v[108:111], v[144:147], v[184:187], v[108:111]
	v_mfma_f32_16x16x32_bf16 v[104:107], v[152:155], v[184:187], v[104:107]
	v_mfma_f32_16x16x32_bf16 v[92:95], v[144:147], v[192:195], v[92:95]
	v_mfma_f32_16x16x32_bf16 v[88:91], v[152:155], v[192:195], v[88:91]
	v_mfma_f32_16x16x32_bf16 v[76:79], v[144:147], v[204:207], v[76:79]
	v_mfma_f32_16x16x32_bf16 v[72:75], v[152:155], v[204:207], v[72:75]
	s_setprio 0
	s_setprio 1
	v_mfma_f32_16x16x32_bf16 v[116:119], v[156:159], v[172:175], 0
	v_mfma_f32_16x16x32_bf16 v[112:115], v[164:167], v[172:175], 0
	v_mfma_f32_16x16x32_bf16 v[100:103], v[156:159], v[180:183], 0
	v_mfma_f32_16x16x32_bf16 v[96:99], v[164:167], v[180:183], 0
	v_mfma_f32_16x16x32_bf16 v[84:87], v[156:159], v[188:191], 0
	v_mfma_f32_16x16x32_bf16 v[80:83], v[164:167], v[188:191], 0
	v_mfma_f32_16x16x32_bf16 v[68:71], v[156:159], v[200:203], 0
	v_mfma_f32_16x16x32_bf16 v[64:67], v[164:167], v[200:203], 0
	v_mfma_f32_16x16x32_bf16 v[116:119], v[160:163], v[176:179], v[116:119]
	v_mfma_f32_16x16x32_bf16 v[112:115], v[168:171], v[176:179], v[112:115]
	v_mfma_f32_16x16x32_bf16 v[100:103], v[160:163], v[184:187], v[100:103]
	v_mfma_f32_16x16x32_bf16 v[96:99], v[168:171], v[184:187], v[96:99]
	v_mfma_f32_16x16x32_bf16 v[84:87], v[160:163], v[192:195], v[84:87]
	v_mfma_f32_16x16x32_bf16 v[80:83], v[168:171], v[192:195], v[80:83]
	v_mfma_f32_16x16x32_bf16 v[68:71], v[160:163], v[204:207], v[68:71]
	v_mfma_f32_16x16x32_bf16 v[64:67], v[168:171], v[204:207], v[64:67]
	s_setprio 0
	s_barrier
	s_add_i32 s92, s92, s7
	v_lshl_add_u64 v[212:213], s[84:85], 0, v[208:209]
	s_mov_b32 m0, s92
	ds_read_b128 v[172:175], v199 offset:16384
	ds_read_b128 v[176:179], v199 offset:17408
	ds_read_b128 v[180:183], v199 offset:18432
	ds_read_b128 v[184:187], v199 offset:19456
	ds_read_b128 v[188:191], v199 offset:20480
	ds_read_b128 v[192:195], v199 offset:21504
	ds_read_b128 v[200:203], v199 offset:22528
	ds_read_b128 v[204:207], v199 offset:23552
	global_load_lds_dwordx4 v[212:213], off
	s_add_i32 m0, s92, 0x2000
	v_lshl_add_u64 v[214:215], s[84:85], 0, v[128:129]
	s_add_u32 s84, s84, s50
	s_addc_u32 s85, s85, s51
	s_add_i32 s82, s82, s7
	global_load_lds_dwordx4 v[214:215], off
	v_lshl_add_u64 v[216:217], s[84:85], 0, v[208:209]
	s_mov_b32 m0, s82
	v_lshl_add_u64 v[218:219], s[84:85], 0, v[128:129]
	global_load_lds_dwordx4 v[216:217], off
	s_add_i32 m0, s82, 0x2000
	v_lshl_add_u64 v[220:221], s[34:35], 0, v[208:209]
	global_load_lds_dwordx4 v[218:219], off
	s_mov_b32 m0, s8
	v_lshl_add_u64 v[222:223], s[34:35], 0, v[128:129]
	global_load_lds_dwordx4 v[220:221], off
	s_mov_b32 m0, s9
	s_nop 0
	global_load_lds_dwordx4 v[222:223], off
	s_waitcnt vmcnt(8)
	s_waitcnt lgkmcnt(0)
	s_barrier
; #define PG8_STAGE(bufoff, gbase, voff) do { _Pragma("unroll") for (int _i = 0; _i < 2; ++_i) \
;         __builtin_amdgcn_global_load_lds((const unsigned*)((const char*)(gbase) + (voff)[_i]), (PG8_LAS unsigned*)(lds + (bufoff) + ldsw + _i * 8192), 16, 0, 0); } while (0)
; #define PG8_LDA(dst, b, h) do { _Pragma("unroll") for (int m = 0; m < 4; ++m) _Pragma("unroll") for (int k = 0; k < 2; ++k) dst[m][k] = *(const PG8_LAS bf16x8*)(lds + PG8_SA(b, h) + aoff + m * 2048 + k * 1024); } while (0)
; #define PG8_LDB(dst, b, h) do { _Pragma("unroll") for (int n = 0; n < 2; ++n) _Pragma("unroll") for (int k = 0; k < 2; ++k) dst[n][k] = *(const PG8_LAS bf16x8*)(lds + PG8_SB(b, h) + boff + n * 2048 + k * 1024); } while (0)
; #define PG8_MMA(ai, bj, At, Bt) do { __builtin_amdgcn_s_setprio(1); _Pragma("unroll") for (int m = 0; m < 4; ++m) _Pragma("unroll") for (int n = 0; n < 2; ++n) _Pragma("unroll") for (int k = 0; k < 2; ++k) \
;         acc[ai][bj][m][n] = mma16<Epi::F16>(Bt[n][k], At[m][k], acc[ai][bj][m][n]); __builtin_amdgcn_s_setprio(0); } while (0)
; #define PG8_WAIT_V(n) asm volatile("s_waitcnt vmcnt(" #n ")" ::: "memory")
; #define PG8_WAIT_L(n) asm volatile("s_waitcnt lgkmcnt(" #n ")" ::: "memory")
; #define PG8_BAR __builtin_amdgcn_s_barrier()
; #define PG8_SCHED __builtin_amdgcn_sched_barrier(0)
; template <class Epi, class Sched, bool ALIGN_EPI = false, bool SP2 = false>
; __device__ __forceinline__ void gemm_phase(PG8_LAS unsigned char* lds, const Gemm g, const Sched& S, const Epi& E) {
;     ...
;             PG8_WAIT_V(8); PG8_WAIT_L(0); PG8_BAR; PG8_MMA(1, 0, At, B0); PG8_MMA(1, 1, At, B1); PG8_BAR; PG8_SCHED;
;             PG8_LDB(B0, 1, 0); PG8_LDB(B1, 1, 1); PG8_SCHED; PG8_LDA(At, 1, 0); PG8_STAGE(PG8_SA(0, 1), a2 + hstep, voffA);
;             PG8_WAIT_V(8); PG8_WAIT_L(0); PG8_BAR; PG8_MMA(0, 0, At, B0); PG8_MMA(0, 1, At, B1); PG8_BAR; PG8_SCHED;
	s_setprio 1
	v_mfma_f32_16x16x32_bf16 v[60:63], v[140:143], v[172:175], 0
	v_mfma_f32_16x16x32_bf16 v[56:59], v[148:151], v[172:175], 0
	v_mfma_f32_16x16x32_bf16 v[44:47], v[140:143], v[180:183], 0
	v_mfma_f32_16x16x32_bf16 v[40:43], v[148:151], v[180:183], 0
	v_mfma_f32_16x16x32_bf16 v[28:31], v[140:143], v[188:191], 0
	v_mfma_f32_16x16x32_bf16 v[24:27], v[148:151], v[188:191], 0
	v_mfma_f32_16x16x32_bf16 v[12:15], v[140:143], v[200:203], 0
	v_mfma_f32_16x16x32_bf16 v[8:11], v[148:151], v[200:203], 0
	v_mfma_f32_16x16x32_bf16 v[60:63], v[144:147], v[176:179], v[60:63]
	v_mfma_f32_16x16x32_bf16 v[56:59], v[152:155], v[176:179], v[56:59]
	v_mfma_f32_16x16x32_bf16 v[44:47], v[144:147], v[184:187], v[44:47]
	v_mfma_f32_16x16x32_bf16 v[40:43], v[152:155], v[184:187], v[40:43]
	v_mfma_f32_16x16x32_bf16 v[28:31], v[144:147], v[192:195], v[28:31]
	v_mfma_f32_16x16x32_bf16 v[24:27], v[152:155], v[192:195], v[24:27]
	v_mfma_f32_16x16x32_bf16 v[12:15], v[144:147], v[204:207], v[12:15]
	v_mfma_f32_16x16x32_bf16 v[8:11], v[152:155], v[204:207], v[8:11]
	s_setprio 0
	s_setprio 1
	v_mfma_f32_16x16x32_bf16 v[52:55], v[156:159], v[172:175], 0
	v_mfma_f32_16x16x32_bf16 v[48:51], v[164:167], v[172:175], 0
	v_mfma_f32_16x16x32_bf16 v[36:39], v[156:159], v[180:183], 0
	v_mfma_f32_16x16x32_bf16 v[32:35], v[164:167], v[180:183], 0
	v_mfma_f32_16x16x32_bf16 v[20:23], v[156:159], v[188:191], 0
	v_mfma_f32_16x16x32_bf16 v[16:19], v[164:167], v[188:191], 0
	v_mfma_f32_16x16x32_bf16 v[4:7], v[156:159], v[200:203], 0
	v_mfma_f32_16x16x32_bf16 v[0:3], v[164:167], v[200:203], 0
	v_mfma_f32_16x16x32_bf16 v[52:55], v[160:163], v[176:179], v[52:55]
	v_mfma_f32_16x16x32_bf16 v[48:51], v[168:171], v[176:179], v[48:51]
	v_mfma_f32_16x16x32_bf16 v[36:39], v[160:163], v[184:187], v[36:39]
	v_mfma_f32_16x16x32_bf16 v[32:35], v[168:171], v[184:187], v[32:35]
	v_mfma_f32_16x16x32_bf16 v[20:23], v[160:163], v[192:195], v[20:23]
	v_mfma_f32_16x16x32_bf16 v[16:19], v[168:171], v[192:195], v[16:19]
	v_mfma_f32_16x16x32_bf16 v[4:7], v[160:163], v[204:207], v[4:7]
	v_mfma_f32_16x16x32_bf16 v[0:3], v[168:171], v[204:207], v[0:3]
	s_setprio 0
	s_barrier
	s_add_i32 s82, 0, 0x18000
	v_add_u32_e32 v131, s82, v133
	s_add_i32 s84, 0, 0x1c000
	ds_read_b128 v[140:143], v131
	ds_read_b128 v[144:147], v131 offset:1024
	ds_read_b128 v[148:151], v131 offset:2048
	ds_read_b128 v[152:155], v131 offset:3072
	v_add_u32_e32 v131, s84, v133
	ds_read_b128 v[156:159], v131
	ds_read_b128 v[160:163], v131 offset:1024
	ds_read_b128 v[164:167], v131 offset:2048
	ds_read_b128 v[168:171], v131 offset:3072
	s_add_u32 s34, s34, s50
	s_addc_u32 s35, s35, s51
	s_mov_b32 m0, s11
	v_lshl_add_u64 v[224:225], s[34:35], 0, v[208:209]
	ds_read_b128 v[172:175], v199 offset:32768
	ds_read_b128 v[176:179], v199 offset:33792
	ds_read_b128 v[180:183], v199 offset:34816
	ds_read_b128 v[184:187], v199 offset:35840
	ds_read_b128 v[188:191], v199 offset:36864
	ds_read_b128 v[192:195], v199 offset:37888
	ds_read_b128 v[200:203], v199 offset:38912
	ds_read_b128 v[204:207], v199 offset:39936
	global_load_lds_dwordx4 v[224:225], off
	v_lshl_add_u64 v[224:225], s[34:35], 0, v[128:129]
	s_mov_b32 m0, s36
	s_nop 0
	global_load_lds_dwordx4 v[224:225], off
	s_waitcnt vmcnt(8)
	s_waitcnt lgkmcnt(0)
	s_barrier
	s_setprio 1
	v_mfma_f32_16x16x32_bf16 v[120:123], v[140:143], v[172:175], v[120:123]
	v_mfma_f32_16x16x32_bf16 v[124:127], v[148:151], v[172:175], v[124:127]
	v_mfma_f32_16x16x32_bf16 v[108:111], v[140:143], v[180:183], v[108:111]
	v_mfma_f32_16x16x32_bf16 v[104:107], v[148:151], v[180:183], v[104:107]
	v_mfma_f32_16x16x32_bf16 v[92:95], v[140:143], v[188:191], v[92:95]
	v_mfma_f32_16x16x32_bf16 v[88:91], v[148:151], v[188:191], v[88:91]
	v_mfma_f32_16x16x32_bf16 v[76:79], v[140:143], v[200:203], v[76:79]
	v_mfma_f32_16x16x32_bf16 v[72:75], v[148:151], v[200:203], v[72:75]
	v_mfma_f32_16x16x32_bf16 v[120:123], v[144:147], v[176:179], v[120:123]
	v_mfma_f32_16x16x32_bf16 v[124:127], v[152:155], v[176:179], v[124:127]
	v_mfma_f32_16x16x32_bf16 v[108:111], v[144:147], v[184:187], v[108:111]
	v_mfma_f32_16x16x32_bf16 v[104:107], v[152:155], v[184:187], v[104:107]
	v_mfma_f32_16x16x32_bf16 v[92:95], v[144:147], v[192:195], v[92:95]
	v_mfma_f32_16x16x32_bf16 v[88:91], v[152:155], v[192:195], v[88:91]
	v_mfma_f32_16x16x32_bf16 v[76:79], v[144:147], v[204:207], v[76:79]
	v_mfma_f32_16x16x32_bf16 v[72:75], v[152:155], v[204:207], v[72:75]
	s_setprio 0
	s_setprio 1
	v_mfma_f32_16x16x32_bf16 v[116:119], v[156:159], v[172:175], v[116:119]
	v_mfma_f32_16x16x32_bf16 v[112:115], v[164:167], v[172:175], v[112:115]
	v_mfma_f32_16x16x32_bf16 v[100:103], v[156:159], v[180:183], v[100:103]
	v_mfma_f32_16x16x32_bf16 v[96:99], v[164:167], v[180:183], v[96:99]
	v_mfma_f32_16x16x32_bf16 v[84:87], v[156:159], v[188:191], v[84:87]
	v_mfma_f32_16x16x32_bf16 v[80:83], v[164:167], v[188:191], v[80:83]
	v_mfma_f32_16x16x32_bf16 v[68:71], v[156:159], v[200:203], v[68:71]
	v_mfma_f32_16x16x32_bf16 v[64:67], v[164:167], v[200:203], v[64:67]
	v_mfma_f32_16x16x32_bf16 v[116:119], v[160:163], v[176:179], v[116:119]
	v_mfma_f32_16x16x32_bf16 v[112:115], v[168:171], v[176:179], v[112:115]
	v_mfma_f32_16x16x32_bf16 v[100:103], v[160:163], v[184:187], v[100:103]
	v_mfma_f32_16x16x32_bf16 v[96:99], v[168:171], v[184:187], v[96:99]
	v_mfma_f32_16x16x32_bf16 v[84:87], v[160:163], v[192:195], v[84:87]
	v_mfma_f32_16x16x32_bf16 v[80:83], v[168:171], v[192:195], v[80:83]
	v_mfma_f32_16x16x32_bf16 v[68:71], v[160:163], v[204:207], v[68:71]
	v_mfma_f32_16x16x32_bf16 v[64:67], v[168:171], v[204:207], v[64:67]
	s_setprio 0
	s_barrier
; #define PG8_STAGE(bufoff, gbase, voff) do { _Pragma("unroll") for (int _i = 0; _i < 2; ++_i) \
;         __builtin_amdgcn_global_load_lds((const unsigned*)((const char*)(gbase) + (voff)[_i]), (PG8_LAS unsigned*)(lds + (bufoff) + ldsw + _i * 8192), 16, 0, 0); } while (0)
; #define PG8_LDA(dst, b, h) do { _Pragma("unroll") for (int m = 0; m < 4; ++m) _Pragma("unroll") for (int k = 0; k < 2; ++k) dst[m][k] = *(const PG8_LAS bf16x8*)(lds + PG8_SA(b, h) + aoff + m * 2048 + k * 1024); } while (0)
; #define PG8_LDB(dst, b, h) do { _Pragma("unroll") for (int n = 0; n < 2; ++n) _Pragma("unroll") for (int k = 0; k < 2; ++k) dst[n][k] = *(const PG8_LAS bf16x8*)(lds + PG8_SB(b, h) + boff + n * 2048 + k * 1024); } while (0)
; template <class Epi, class Sched, bool ALIGN_EPI = false, bool SP2 = false>
; __device__ __forceinline__ void gemm_phase(PG8_LAS unsigned char* lds, const Gemm g, const Sched& S, const Epi& E) {
;     ...
;         for (int t = 0; t < nt; t += 2) {
;             const bool last = (t == nt - 2);
;             const char* a1 = cA + (size_t)(t + 1) * kstep;
;             const char* a2 = last ? nA : cA + (size_t)(t + 2) * kstep; const char* b2 = last ? nB : cB + (size_t)(t + 2) * kstep;
;             const char* a3 = a2 + kstep; const char* b3 = b2 + kstep;
;             if (last && has_next) S.a_ready(nxt);
;             if constexpr (SP2) {
;             PG8_LDB(B0, 0, 0); PG8_LDB(B1, 0, 1); PG8_SCHED; PG8_LDA(At, 0, 0); PG8_STAGE(PG8_SA(1, 1), a1 + hstep, voffA);
;             PG8_WAIT_V(8); PG8_WAIT_L(0); PG8_BAR; PG8_MMA(0, 0, At, B0); PG8_MMA(0, 1, At, B1); PG8_BAR; PG8_SCHED;
;             PG8_LDA(At, 0, 1); PG8_STAGE(PG8_SB(0, 0), b2, voffB); PG8_STAGE(PG8_SB(0, 1), b2 + hstep, voffB); PG8_STAGE(PG8_SA(0, 0), a2, voffA);
;             PG8_WAIT_V(8); PG8_WAIT_L(0); PG8_BAR; PG8_MMA(1, 0, At, B0); PG8_MMA(1, 1, At, B1); PG8_BAR; PG8_SCHED;
;             PG8_LDB(B0, 1, 0); PG8_LDB(B1, 1, 1); PG8_SCHED; PG8_LDA(At, 1, 0); PG8_STAGE(PG8_SA(0, 1), a2 + hstep, voffA);
;             PG8_WAIT_V(8); PG8_WAIT_L(0); PG8_BAR; PG8_MMA(0, 0, At, B0); PG8_MMA(0, 1, At, B1); PG8_BAR; PG8_SCHED;
;             PG8_LDA(At, 1, 1); PG8_STAGE(PG8_SB(1, 0), b3, voffB); PG8_STAGE(PG8_SB(1, 1), b3 + hstep, voffB); PG8_STAGE(PG8_SA(1, 0), a3, voffA);
;             PG8_WAIT_V(8); PG8_WAIT_L(0); PG8_BAR; PG8_MMA(1, 0, At, B0); PG8_MMA(1, 1, At, B1); PG8_BAR; PG8_SCHED;
	s_add_i32 s34, s82, s7
	v_lshl_add_u64 v[212:213], v[212:213], 0, s[20:21]
	s_mov_b32 m0, s34
	ds_read_b128 v[172:175], v199 offset:49152
	ds_read_b128 v[176:179], v199 offset:50176
	ds_read_b128 v[180:183], v199 offset:51200
	ds_read_b128 v[184:187], v199 offset:52224
	ds_read_b128 v[188:191], v199 offset:53248
	ds_read_b128 v[192:195], v199 offset:54272
	ds_read_b128 v[200:203], v199 offset:55296
	ds_read_b128 v[204:207], v199 offset:56320
	global_load_lds_dwordx4 v[212:213], off
	v_lshl_add_u64 v[212:213], v[214:215], 0, s[20:21]
	s_add_i32 m0, s34, 0x2000
	s_add_i32 s34, s84, s7
	global_load_lds_dwordx4 v[212:213], off
	v_lshl_add_u64 v[212:213], v[216:217], 0, s[20:21]
	s_mov_b32 m0, s34
	s_nop 0
	global_load_lds_dwordx4 v[212:213], off
	v_lshl_add_u64 v[212:213], v[218:219], 0, s[20:21]
	s_add_i32 m0, s34, 0x2000
	s_nop 0
	global_load_lds_dwordx4 v[212:213], off
	v_lshl_add_u64 v[212:213], v[220:221], 0, s[20:21]
	s_mov_b32 m0, s37
	s_nop 0
	global_load_lds_dwordx4 v[212:213], off
	v_lshl_add_u64 v[212:213], v[222:223], 0, s[20:21]
	s_mov_b32 m0, s38
	s_nop 0
	global_load_lds_dwordx4 v[212:213], off
	s_waitcnt vmcnt(8)
	s_waitcnt lgkmcnt(0)
	s_barrier
	s_setprio 1
	v_mfma_f32_16x16x32_bf16 v[60:63], v[140:143], v[172:175], v[60:63]
	v_mfma_f32_16x16x32_bf16 v[56:59], v[148:151], v[172:175], v[56:59]
	v_mfma_f32_16x16x32_bf16 v[44:47], v[140:143], v[180:183], v[44:47]
	v_mfma_f32_16x16x32_bf16 v[40:43], v[148:151], v[180:183], v[40:43]
	v_mfma_f32_16x16x32_bf16 v[28:31], v[140:143], v[188:191], v[28:31]
	v_mfma_f32_16x16x32_bf16 v[24:27], v[148:151], v[188:191], v[24:27]
	v_mfma_f32_16x16x32_bf16 v[12:15], v[140:143], v[200:203], v[12:15]
	v_mfma_f32_16x16x32_bf16 v[8:11], v[148:151], v[200:203], v[8:11]
	v_mfma_f32_16x16x32_bf16 v[60:63], v[144:147], v[176:179], v[60:63]
	v_mfma_f32_16x16x32_bf16 v[56:59], v[152:155], v[176:179], v[56:59]
	v_mfma_f32_16x16x32_bf16 v[44:47], v[144:147], v[184:187], v[44:47]
	v_mfma_f32_16x16x32_bf16 v[40:43], v[152:155], v[184:187], v[40:43]
	v_mfma_f32_16x16x32_bf16 v[28:31], v[144:147], v[192:195], v[28:31]
	v_mfma_f32_16x16x32_bf16 v[24:27], v[152:155], v[192:195], v[24:27]
	v_mfma_f32_16x16x32_bf16 v[12:15], v[144:147], v[204:207], v[12:15]
	v_mfma_f32_16x16x32_bf16 v[8:11], v[152:155], v[204:207], v[8:11]
	s_setprio 0
	s_setprio 1
	v_mfma_f32_16x16x32_bf16 v[52:55], v[156:159], v[172:175], v[52:55]
	v_mfma_f32_16x16x32_bf16 v[48:51], v[164:167], v[172:175], v[48:51]
	v_mfma_f32_16x16x32_bf16 v[36:39], v[156:159], v[180:183], v[36:39]
	v_mfma_f32_16x16x32_bf16 v[32:35], v[164:167], v[180:183], v[32:35]
	v_mfma_f32_16x16x32_bf16 v[20:23], v[156:159], v[188:191], v[20:23]
	v_mfma_f32_16x16x32_bf16 v[16:19], v[164:167], v[188:191], v[16:19]
	v_mfma_f32_16x16x32_bf16 v[4:7], v[156:159], v[200:203], v[4:7]
	v_mfma_f32_16x16x32_bf16 v[0:3], v[164:167], v[200:203], v[0:3]
	v_mfma_f32_16x16x32_bf16 v[52:55], v[160:163], v[176:179], v[52:55]
	v_mfma_f32_16x16x32_bf16 v[48:51], v[168:171], v[176:179], v[48:51]
	v_mfma_f32_16x16x32_bf16 v[36:39], v[160:163], v[184:187], v[36:39]
	v_mfma_f32_16x16x32_bf16 v[32:35], v[168:171], v[184:187], v[32:35]
	v_mfma_f32_16x16x32_bf16 v[20:23], v[160:163], v[192:195], v[20:23]
	v_mfma_f32_16x16x32_bf16 v[16:19], v[168:171], v[192:195], v[16:19]
	v_mfma_f32_16x16x32_bf16 v[4:7], v[160:163], v[204:207], v[4:7]
	v_mfma_f32_16x16x32_bf16 v[0:3], v[168:171], v[204:207], v[0:3]
	s_setprio 0
	s_barrier
	s_add_u32 s30, s30, 0x100
	s_addc_u32 s31, s31, 0
	s_add_u32 s29, s29, 0x100
	s_addc_u32 s73, s73, 0
	s_cmp_ge_i32 s77, s39
	s_mov_b32 s34, s77
	s_cbranch_scc0 .LBB0_757
	s_branch .LBB0_758
.LBB0_757:
	s_add_i32 s77, s34, 2
	s_add_u32 s82, s30, 0x80
	s_addc_u32 s35, s31, 0
	s_add_i32 s92, 0, 0x10000
	s_cmp_eq_u32 s48, s34
	s_cselect_b32 s35, s1, s35
	s_cselect_b32 s34, s0, s82
	v_add_u32_e32 v131, s92, v133
	s_cselect_b32 s85, s61, s73
	s_cselect_b32 s84, s60, s29
	s_add_i32 s82, 0, 0x14000
	ds_read_b128 v[140:143], v131
	ds_read_b128 v[144:147], v131 offset:1024
	ds_read_b128 v[148:151], v131 offset:2048
	ds_read_b128 v[152:155], v131 offset:3072
	v_add_u32_e32 v131, s82, v133
	ds_read_b128 v[156:159], v131
	ds_read_b128 v[160:163], v131 offset:1024
	ds_read_b128 v[164:167], v131 offset:2048
	ds_read_b128 v[168:171], v131 offset:3072
	v_lshl_add_u64 v[212:213], s[30:31], 0, v[136:137]
	s_add_i32 m0, s8, 0xc000
	ds_read_b128 v[172:175], v199
	ds_read_b128 v[176:179], v199 offset:1024
	ds_read_b128 v[180:183], v199 offset:2048
	ds_read_b128 v[184:187], v199 offset:3072
	ds_read_b128 v[188:191], v199 offset:4096
	ds_read_b128 v[192:195], v199 offset:5120
	ds_read_b128 v[200:203], v199 offset:6144
	ds_read_b128 v[204:207], v199 offset:7168
	global_load_lds_dwordx4 v[212:213], off
	v_lshl_add_u64 v[212:213], s[30:31], 0, v[138:139]
	s_add_i32 m0, s8, 0xe000
	s_nop 0
	global_load_lds_dwordx4 v[212:213], off
	s_waitcnt vmcnt(8)
	s_waitcnt lgkmcnt(0)
	s_barrier
; #define PG8_STAGE(bufoff, gbase, voff) do { _Pragma("unroll") for (int _i = 0; _i < 2; ++_i) \
;         __builtin_amdgcn_global_load_lds((const unsigned*)((const char*)(gbase) + (voff)[_i]), (PG8_LAS unsigned*)(lds + (bufoff) + ldsw + _i * 8192), 16, 0, 0); } while (0)
; #define PG8_LDA(dst, b, h) do { _Pragma("unroll") for (int m = 0; m < 4; ++m) _Pragma("unroll") for (int k = 0; k < 2; ++k) dst[m][k] = *(const PG8_LAS bf16x8*)(lds + PG8_SA(b, h) + aoff + m * 2048 + k * 1024); } while (0)
; #define PG8_LDB(dst, b, h) do { _Pragma("unroll") for (int n = 0; n < 2; ++n) _Pragma("unroll") for (int k = 0; k < 2; ++k) dst[n][k] = *(const PG8_LAS bf16x8*)(lds + PG8_SB(b, h) + boff + n * 2048 + k * 1024); } while (0)
; #define PG8_MMA(ai, bj, At, Bt) do { __builtin_amdgcn_s_setprio(1); _Pragma("unroll") for (int m = 0; m < 4; ++m) _Pragma("unroll") for (int n = 0; n < 2; ++n) _Pragma("unroll") for (int k = 0; k < 2; ++k) \
;         acc[ai][bj][m][n] = mma16<Epi::F16>(Bt[n][k], At[m][k], acc[ai][bj][m][n]); __builtin_amdgcn_s_setprio(0); } while (0)
; #define PG8_WAIT_V(n) asm volatile("s_waitcnt vmcnt(" #n ")" ::: "memory")
; #define PG8_WAIT_L(n) asm volatile("s_waitcnt lgkmcnt(" #n ")" ::: "memory")
; #define PG8_BAR __builtin_amdgcn_s_barrier()
; #define PG8_SCHED __builtin_amdgcn_sched_barrier(0)
; template <class Epi, class Sched, bool ALIGN_EPI = false, bool SP2 = false>
; __device__ __forceinline__ void gemm_phase(PG8_LAS unsigned char* lds, const Gemm g, const Sched& S, const Epi& E) {
;     ...
;             PG8_LDB(B0, 0, 0); PG8_LDB(B1, 0, 1); PG8_SCHED; PG8_LDA(At, 0, 0); PG8_STAGE(PG8_SA(1, 1), a1 + hstep, voffA);
;             PG8_WAIT_V(8); PG8_WAIT_L(0); PG8_BAR; PG8_MMA(0, 0, At, B0); PG8_MMA(0, 1, At, B1); PG8_BAR; PG8_SCHED;
;             PG8_LDA(At, 0, 1); PG8_STAGE(PG8_SB(0, 0), b2, voffB); PG8_STAGE(PG8_SB(0, 1), b2 + hstep, voffB); PG8_STAGE(PG8_SA(0, 0), a2, voffA);
;             PG8_WAIT_V(8); PG8_WAIT_L(0); PG8_BAR; PG8_MMA(1, 0, At, B0); PG8_MMA(1, 1, At, B1); PG8_BAR; PG8_SCHED;
	s_setprio 1
	v_mfma_f32_16x16x32_bf16 v[120:123], v[140:143], v[172:175], v[120:123]
	v_mfma_f32_16x16x32_bf16 v[124:127], v[148:151], v[172:175], v[124:127]
	v_mfma_f32_16x16x32_bf16 v[108:111], v[140:143], v[180:183], v[108:111]
	v_mfma_f32_16x16x32_bf16 v[104:107], v[148:151], v[180:183], v[104:107]
	v_mfma_f32_16x16x32_bf16 v[92:95], v[140:143], v[188:191], v[92:95]
	v_mfma_f32_16x16x32_bf16 v[88:91], v[148:151], v[188:191], v[88:91]
	v_mfma_f32_16x16x32_bf16 v[76:79], v[140:143], v[200:203], v[76:79]
	v_mfma_f32_16x16x32_bf16 v[72:75], v[148:151], v[200:203], v[72:75]
	v_mfma_f32_16x16x32_bf16 v[120:123], v[144:147], v[176:179], v[120:123]
	v_mfma_f32_16x16x32_bf16 v[124:127], v[152:155], v[176:179], v[124:127]
	v_mfma_f32_16x16x32_bf16 v[108:111], v[144:147], v[184:187], v[108:111]
	v_mfma_f32_16x16x32_bf16 v[104:107], v[152:155], v[184:187], v[104:107]
	v_mfma_f32_16x16x32_bf16 v[92:95], v[144:147], v[192:195], v[92:95]
	v_mfma_f32_16x16x32_bf16 v[88:91], v[152:155], v[192:195], v[88:91]
	v_mfma_f32_16x16x32_bf16 v[76:79], v[144:147], v[204:207], v[76:79]
	v_mfma_f32_16x16x32_bf16 v[72:75], v[152:155], v[204:207], v[72:75]
	s_setprio 0
	s_setprio 1
	v_mfma_f32_16x16x32_bf16 v[116:119], v[156:159], v[172:175], v[116:119]
	v_mfma_f32_16x16x32_bf16 v[112:115], v[164:167], v[172:175], v[112:115]
	v_mfma_f32_16x16x32_bf16 v[100:103], v[156:159], v[180:183], v[100:103]
	v_mfma_f32_16x16x32_bf16 v[96:99], v[164:167], v[180:183], v[96:99]
	v_mfma_f32_16x16x32_bf16 v[84:87], v[156:159], v[188:191], v[84:87]
	v_mfma_f32_16x16x32_bf16 v[80:83], v[164:167], v[188:191], v[80:83]
	v_mfma_f32_16x16x32_bf16 v[68:71], v[156:159], v[200:203], v[68:71]
	v_mfma_f32_16x16x32_bf16 v[64:67], v[164:167], v[200:203], v[64:67]
	v_mfma_f32_16x16x32_bf16 v[116:119], v[160:163], v[176:179], v[116:119]
	v_mfma_f32_16x16x32_bf16 v[112:115], v[168:171], v[176:179], v[112:115]
	v_mfma_f32_16x16x32_bf16 v[100:103], v[160:163], v[184:187], v[100:103]
	v_mfma_f32_16x16x32_bf16 v[96:99], v[168:171], v[184:187], v[96:99]
	v_mfma_f32_16x16x32_bf16 v[84:87], v[160:163], v[192:195], v[84:87]
	v_mfma_f32_16x16x32_bf16 v[80:83], v[168:171], v[192:195], v[80:83]
	v_mfma_f32_16x16x32_bf16 v[68:71], v[160:163], v[204:207], v[68:71]
	v_mfma_f32_16x16x32_bf16 v[64:67], v[168:171], v[204:207], v[64:67]
	s_setprio 0
	s_barrier
	s_add_i32 s92, s92, s7
	v_lshl_add_u64 v[212:213], s[84:85], 0, v[208:209]
	s_mov_b32 m0, s92
	ds_read_b128 v[172:175], v199 offset:16384
	ds_read_b128 v[176:179], v199 offset:17408
	ds_read_b128 v[180:183], v199 offset:18432
	ds_read_b128 v[184:187], v199 offset:19456
	ds_read_b128 v[188:191], v199 offset:20480
	ds_read_b128 v[192:195], v199 offset:21504
	ds_read_b128 v[200:203], v199 offset:22528
	ds_read_b128 v[204:207], v199 offset:23552
	global_load_lds_dwordx4 v[212:213], off
	s_add_i32 m0, s92, 0x2000
	v_lshl_add_u64 v[214:215], s[84:85], 0, v[128:129]
	s_add_u32 s84, s84, s50
	s_addc_u32 s85, s85, s51
	s_add_i32 s82, s82, s7
	global_load_lds_dwordx4 v[214:215], off
	v_lshl_add_u64 v[216:217], s[84:85], 0, v[208:209]
	s_mov_b32 m0, s82
	v_lshl_add_u64 v[218:219], s[84:85], 0, v[128:129]
	global_load_lds_dwordx4 v[216:217], off
	s_add_i32 m0, s82, 0x2000
	v_lshl_add_u64 v[220:221], s[34:35], 0, v[208:209]
	global_load_lds_dwordx4 v[218:219], off
	s_mov_b32 m0, s8
	v_lshl_add_u64 v[222:223], s[34:35], 0, v[128:129]
	global_load_lds_dwordx4 v[220:221], off
	s_mov_b32 m0, s9
	s_nop 0
	global_load_lds_dwordx4 v[222:223], off
	s_waitcnt vmcnt(8)
	s_waitcnt lgkmcnt(0)
	s_barrier
	s_setprio 1
	v_mfma_f32_16x16x32_bf16 v[60:63], v[140:143], v[172:175], v[60:63]
	v_mfma_f32_16x16x32_bf16 v[56:59], v[148:151], v[172:175], v[56:59]
	v_mfma_f32_16x16x32_bf16 v[44:47], v[140:143], v[180:183], v[44:47]
	v_mfma_f32_16x16x32_bf16 v[40:43], v[148:151], v[180:183], v[40:43]
	v_mfma_f32_16x16x32_bf16 v[28:31], v[140:143], v[188:191], v[28:31]
	v_mfma_f32_16x16x32_bf16 v[24:27], v[148:151], v[188:191], v[24:27]
	v_mfma_f32_16x16x32_bf16 v[12:15], v[140:143], v[200:203], v[12:15]
	v_mfma_f32_16x16x32_bf16 v[8:11], v[148:151], v[200:203], v[8:11]
	v_mfma_f32_16x16x32_bf16 v[60:63], v[144:147], v[176:179], v[60:63]
	v_mfma_f32_16x16x32_bf16 v[56:59], v[152:155], v[176:179], v[56:59]
	v_mfma_f32_16x16x32_bf16 v[44:47], v[144:147], v[184:187], v[44:47]
	v_mfma_f32_16x16x32_bf16 v[40:43], v[152:155], v[184:187], v[40:43]
	v_mfma_f32_16x16x32_bf16 v[28:31], v[144:147], v[192:195], v[28:31]
	v_mfma_f32_16x16x32_bf16 v[24:27], v[152:155], v[192:195], v[24:27]
	v_mfma_f32_16x16x32_bf16 v[12:15], v[144:147], v[204:207], v[12:15]
	v_mfma_f32_16x16x32_bf16 v[8:11], v[152:155], v[204:207], v[8:11]
	s_setprio 0
	s_setprio 1
	v_mfma_f32_16x16x32_bf16 v[52:55], v[156:159], v[172:175], v[52:55]
	v_mfma_f32_16x16x32_bf16 v[48:51], v[164:167], v[172:175], v[48:51]
	v_mfma_f32_16x16x32_bf16 v[36:39], v[156:159], v[180:183], v[36:39]
	v_mfma_f32_16x16x32_bf16 v[32:35], v[164:167], v[180:183], v[32:35]
	v_mfma_f32_16x16x32_bf16 v[20:23], v[156:159], v[188:191], v[20:23]
	v_mfma_f32_16x16x32_bf16 v[16:19], v[164:167], v[188:191], v[16:19]
	v_mfma_f32_16x16x32_bf16 v[4:7], v[156:159], v[200:203], v[4:7]
	v_mfma_f32_16x16x32_bf16 v[0:3], v[164:167], v[200:203], v[0:3]
	v_mfma_f32_16x16x32_bf16 v[52:55], v[160:163], v[176:179], v[52:55]
	v_mfma_f32_16x16x32_bf16 v[48:51], v[168:171], v[176:179], v[48:51]
	v_mfma_f32_16x16x32_bf16 v[36:39], v[160:163], v[184:187], v[36:39]
	v_mfma_f32_16x16x32_bf16 v[32:35], v[168:171], v[184:187], v[32:35]
	v_mfma_f32_16x16x32_bf16 v[20:23], v[160:163], v[192:195], v[20:23]
	v_mfma_f32_16x16x32_bf16 v[16:19], v[168:171], v[192:195], v[16:19]
	v_mfma_f32_16x16x32_bf16 v[4:7], v[160:163], v[204:207], v[4:7]
	v_mfma_f32_16x16x32_bf16 v[0:3], v[168:171], v[204:207], v[0:3]
	s_setprio 0
	s_barrier
; #define PG8_STAGE(bufoff, gbase, voff) do { _Pragma("unroll") for (int _i = 0; _i < 2; ++_i) \
;         __builtin_amdgcn_global_load_lds((const unsigned*)((const char*)(gbase) + (voff)[_i]), (PG8_LAS unsigned*)(lds + (bufoff) + ldsw + _i * 8192), 16, 0, 0); } while (0)
; #define PG8_LDA(dst, b, h) do { _Pragma("unroll") for (int m = 0; m < 4; ++m) _Pragma("unroll") for (int k = 0; k < 2; ++k) dst[m][k] = *(const PG8_LAS bf16x8*)(lds + PG8_SA(b, h) + aoff + m * 2048 + k * 1024); } while (0)
; #define PG8_LDB(dst, b, h) do { _Pragma("unroll") for (int n = 0; n < 2; ++n) _Pragma("unroll") for (int k = 0; k < 2; ++k) dst[n][k] = *(const PG8_LAS bf16x8*)(lds + PG8_SB(b, h) + boff + n * 2048 + k * 1024); } while (0)
; #define PG8_MMA(ai, bj, At, Bt) do { __builtin_amdgcn_s_setprio(1); _Pragma("unroll") for (int m = 0; m < 4; ++m) _Pragma("unroll") for (int n = 0; n < 2; ++n) _Pragma("unroll") for (int k = 0; k < 2; ++k) \
;         acc[ai][bj][m][n] = mma16<Epi::F16>(Bt[n][k], At[m][k], acc[ai][bj][m][n]); __builtin_amdgcn_s_setprio(0); } while (0)
; #define PG8_WAIT_V(n) asm volatile("s_waitcnt vmcnt(" #n ")" ::: "memory")
; #define PG8_WAIT_L(n) asm volatile("s_waitcnt lgkmcnt(" #n ")" ::: "memory")
; #define PG8_BAR __builtin_amdgcn_s_barrier()
; #define PG8_SCHED __builtin_amdgcn_sched_barrier(0)
; template <class Epi, class Sched, bool ALIGN_EPI = false, bool SP2 = false>
; __device__ __forceinline__ void gemm_phase(PG8_LAS unsigned char* lds, const Gemm g, const Sched& S, const Epi& E) {
;     ...
;             PG8_LDB(B0, 1, 0); PG8_LDB(B1, 1, 1); PG8_SCHED; PG8_LDA(At, 1, 0); PG8_STAGE(PG8_SA(0, 1), a2 + hstep, voffA);
;             PG8_WAIT_V(8); PG8_WAIT_L(0); PG8_BAR; PG8_MMA(0, 0, At, B0); PG8_MMA(0, 1, At, B1); PG8_BAR; PG8_SCHED;
	s_add_i32 s82, 0, 0x18000
	v_add_u32_e32 v131, s82, v133
	s_add_i32 s84, 0, 0x1c000
	ds_read_b128 v[140:143], v131
	ds_read_b128 v[144:147], v131 offset:1024
	ds_read_b128 v[148:151], v131 offset:2048
	ds_read_b128 v[152:155], v131 offset:3072
	v_add_u32_e32 v131, s84, v133
	ds_read_b128 v[156:159], v131
	ds_read_b128 v[160:163], v131 offset:1024
	ds_read_b128 v[164:167], v131 offset:2048
	ds_read_b128 v[168:171], v131 offset:3072
	s_add_u32 s34, s34, s50
	s_addc_u32 s35, s35, s51
	s_mov_b32 m0, s11
	v_lshl_add_u64 v[224:225], s[34:35], 0, v[208:209]
	ds_read_b128 v[172:175], v199 offset:32768
	ds_read_b128 v[176:179], v199 offset:33792
	ds_read_b128 v[180:183], v199 offset:34816
	ds_read_b128 v[184:187], v199 offset:35840
	ds_read_b128 v[188:191], v199 offset:36864
	ds_read_b128 v[192:195], v199 offset:37888
	ds_read_b128 v[200:203], v199 offset:38912
	ds_read_b128 v[204:207], v199 offset:39936
	global_load_lds_dwordx4 v[224:225], off
	v_lshl_add_u64 v[224:225], s[34:35], 0, v[128:129]
	s_mov_b32 m0, s36
	s_nop 0
	global_load_lds_dwordx4 v[224:225], off
	s_waitcnt vmcnt(8)
	s_waitcnt lgkmcnt(0)
	s_barrier
	s_setprio 1
	v_mfma_f32_16x16x32_bf16 v[120:123], v[140:143], v[172:175], v[120:123]
	v_mfma_f32_16x16x32_bf16 v[124:127], v[148:151], v[172:175], v[124:127]
	v_mfma_f32_16x16x32_bf16 v[108:111], v[140:143], v[180:183], v[108:111]
	v_mfma_f32_16x16x32_bf16 v[104:107], v[148:151], v[180:183], v[104:107]
	v_mfma_f32_16x16x32_bf16 v[92:95], v[140:143], v[188:191], v[92:95]
	v_mfma_f32_16x16x32_bf16 v[88:91], v[148:151], v[188:191], v[88:91]
	v_mfma_f32_16x16x32_bf16 v[76:79], v[140:143], v[200:203], v[76:79]
	v_mfma_f32_16x16x32_bf16 v[72:75], v[148:151], v[200:203], v[72:75]
	v_mfma_f32_16x16x32_bf16 v[120:123], v[144:147], v[176:179], v[120:123]
	v_mfma_f32_16x16x32_bf16 v[124:127], v[152:155], v[176:179], v[124:127]
	v_mfma_f32_16x16x32_bf16 v[108:111], v[144:147], v[184:187], v[108:111]
	v_mfma_f32_16x16x32_bf16 v[104:107], v[152:155], v[184:187], v[104:107]
	v_mfma_f32_16x16x32_bf16 v[92:95], v[144:147], v[192:195], v[92:95]
	v_mfma_f32_16x16x32_bf16 v[88:91], v[152:155], v[192:195], v[88:91]
	v_mfma_f32_16x16x32_bf16 v[76:79], v[144:147], v[204:207], v[76:79]
	v_mfma_f32_16x16x32_bf16 v[72:75], v[152:155], v[204:207], v[72:75]
	s_setprio 0
	s_setprio 1
	v_mfma_f32_16x16x32_bf16 v[116:119], v[156:159], v[172:175], v[116:119]
	v_mfma_f32_16x16x32_bf16 v[112:115], v[164:167], v[172:175], v[112:115]
	v_mfma_f32_16x16x32_bf16 v[100:103], v[156:159], v[180:183], v[100:103]
	v_mfma_f32_16x16x32_bf16 v[96:99], v[164:167], v[180:183], v[96:99]
	v_mfma_f32_16x16x32_bf16 v[84:87], v[156:159], v[188:191], v[84:87]
	v_mfma_f32_16x16x32_bf16 v[80:83], v[164:167], v[188:191], v[80:83]
	v_mfma_f32_16x16x32_bf16 v[68:71], v[156:159], v[200:203], v[68:71]
	v_mfma_f32_16x16x32_bf16 v[64:67], v[164:167], v[200:203], v[64:67]
	v_mfma_f32_16x16x32_bf16 v[116:119], v[160:163], v[176:179], v[116:119]
	v_mfma_f32_16x16x32_bf16 v[112:115], v[168:171], v[176:179], v[112:115]
	v_mfma_f32_16x16x32_bf16 v[100:103], v[160:163], v[184:187], v[100:103]
	v_mfma_f32_16x16x32_bf16 v[96:99], v[168:171], v[184:187], v[96:99]
	v_mfma_f32_16x16x32_bf16 v[84:87], v[160:163], v[192:195], v[84:87]
	v_mfma_f32_16x16x32_bf16 v[80:83], v[168:171], v[192:195], v[80:83]
	v_mfma_f32_16x16x32_bf16 v[68:71], v[160:163], v[204:207], v[68:71]
	v_mfma_f32_16x16x32_bf16 v[64:67], v[168:171], v[204:207], v[64:67]
	s_setprio 0
	s_barrier
; #define PG8_STAGE(bufoff, gbase, voff) do { _Pragma("unroll") for (int _i = 0; _i < 2; ++_i) \
;         __builtin_amdgcn_global_load_lds((const unsigned*)((const char*)(gbase) + (voff)[_i]), (PG8_LAS unsigned*)(lds + (bufoff) + ldsw + _i * 8192), 16, 0, 0); } while (0)
; #define PG8_LDA(dst, b, h) do { _Pragma("unroll") for (int m = 0; m < 4; ++m) _Pragma("unroll") for (int k = 0; k < 2; ++k) dst[m][k] = *(const PG8_LAS bf16x8*)(lds + PG8_SA(b, h) + aoff + m * 2048 + k * 1024); } while (0)
; #define PG8_MMA(ai, bj, At, Bt) do { __builtin_amdgcn_s_setprio(1); _Pragma("unroll") for (int m = 0; m < 4; ++m) _Pragma("unroll") for (int n = 0; n < 2; ++n) _Pragma("unroll") for (int k = 0; k < 2; ++k) \
;         acc[ai][bj][m][n] = mma16<Epi::F16>(Bt[n][k], At[m][k], acc[ai][bj][m][n]); __builtin_amdgcn_s_setprio(0); } while (0)
; #define PG8_WAIT_V(n) asm volatile("s_waitcnt vmcnt(" #n ")" ::: "memory")
; #define PG8_WAIT_L(n) asm volatile("s_waitcnt lgkmcnt(" #n ")" ::: "memory")
; #define PG8_BAR __builtin_amdgcn_s_barrier()
; #define PG8_SCHED __builtin_amdgcn_sched_barrier(0)
; template <class Epi, class Sched, bool ALIGN_EPI = false, bool SP2 = false>
; __device__ __forceinline__ void gemm_phase(PG8_LAS unsigned char* lds, const Gemm g, const Sched& S, const Epi& E) {
;     ...
;         for (int t = 0; t < nt; t += 2) {
;             const bool last = (t == nt - 2);
;             const char* a1 = cA + (size_t)(t + 1) * kstep;
;             const char* a2 = last ? nA : cA + (size_t)(t + 2) * kstep; const char* b2 = last ? nB : cB + (size_t)(t + 2) * kstep;
;     ...
;             PG8_LDA(At, 1, 1); PG8_STAGE(PG8_SB(1, 0), b3, voffB); PG8_STAGE(PG8_SB(1, 1), b3 + hstep, voffB); PG8_STAGE(PG8_SA(1, 0), a3, voffA);
;             PG8_WAIT_V(8); PG8_WAIT_L(0); PG8_BAR; PG8_MMA(1, 0, At, B0); PG8_MMA(1, 1, At, B1); PG8_BAR; PG8_SCHED;
	s_add_i32 s34, s82, s7
	v_lshl_add_u64 v[212:213], v[212:213], 0, s[20:21]
	s_mov_b32 m0, s34
	ds_read_b128 v[172:175], v199 offset:49152
	ds_read_b128 v[176:179], v199 offset:50176
	ds_read_b128 v[180:183], v199 offset:51200
	ds_read_b128 v[184:187], v199 offset:52224
	ds_read_b128 v[188:191], v199 offset:53248
	ds_read_b128 v[192:195], v199 offset:54272
	ds_read_b128 v[200:203], v199 offset:55296
	ds_read_b128 v[204:207], v199 offset:56320
	global_load_lds_dwordx4 v[212:213], off
	v_lshl_add_u64 v[212:213], v[214:215], 0, s[20:21]
	s_add_i32 m0, s34, 0x2000
	s_add_i32 s34, s84, s7
	global_load_lds_dwordx4 v[212:213], off
	v_lshl_add_u64 v[212:213], v[216:217], 0, s[20:21]
	s_mov_b32 m0, s34
	s_nop 0
	global_load_lds_dwordx4 v[212:213], off
	v_lshl_add_u64 v[212:213], v[218:219], 0, s[20:21]
	s_add_i32 m0, s34, 0x2000
	s_nop 0
	global_load_lds_dwordx4 v[212:213], off
	v_lshl_add_u64 v[212:213], v[220:221], 0, s[20:21]
	s_mov_b32 m0, s37
	s_nop 0
	global_load_lds_dwordx4 v[212:213], off
	v_lshl_add_u64 v[212:213], v[222:223], 0, s[20:21]
	s_mov_b32 m0, s38
	s_nop 0
	global_load_lds_dwordx4 v[212:213], off
	s_waitcnt vmcnt(8)
	s_waitcnt lgkmcnt(0)
	s_barrier
	s_setprio 1
	v_mfma_f32_16x16x32_bf16 v[60:63], v[140:143], v[172:175], v[60:63]
	v_mfma_f32_16x16x32_bf16 v[56:59], v[148:151], v[172:175], v[56:59]
	v_mfma_f32_16x16x32_bf16 v[44:47], v[140:143], v[180:183], v[44:47]
	v_mfma_f32_16x16x32_bf16 v[40:43], v[148:151], v[180:183], v[40:43]
	v_mfma_f32_16x16x32_bf16 v[28:31], v[140:143], v[188:191], v[28:31]
	v_mfma_f32_16x16x32_bf16 v[24:27], v[148:151], v[188:191], v[24:27]
	v_mfma_f32_16x16x32_bf16 v[12:15], v[140:143], v[200:203], v[12:15]
	v_mfma_f32_16x16x32_bf16 v[8:11], v[148:151], v[200:203], v[8:11]
	v_mfma_f32_16x16x32_bf16 v[60:63], v[144:147], v[176:179], v[60:63]
	v_mfma_f32_16x16x32_bf16 v[56:59], v[152:155], v[176:179], v[56:59]
	v_mfma_f32_16x16x32_bf16 v[44:47], v[144:147], v[184:187], v[44:47]
	v_mfma_f32_16x16x32_bf16 v[40:43], v[152:155], v[184:187], v[40:43]
	v_mfma_f32_16x16x32_bf16 v[28:31], v[144:147], v[192:195], v[28:31]
	v_mfma_f32_16x16x32_bf16 v[24:27], v[152:155], v[192:195], v[24:27]
	v_mfma_f32_16x16x32_bf16 v[12:15], v[144:147], v[204:207], v[12:15]
	v_mfma_f32_16x16x32_bf16 v[8:11], v[152:155], v[204:207], v[8:11]
	s_setprio 0
	s_setprio 1
	v_mfma_f32_16x16x32_bf16 v[52:55], v[156:159], v[172:175], v[52:55]
	v_mfma_f32_16x16x32_bf16 v[48:51], v[164:167], v[172:175], v[48:51]
	v_mfma_f32_16x16x32_bf16 v[36:39], v[156:159], v[180:183], v[36:39]
	v_mfma_f32_16x16x32_bf16 v[32:35], v[164:167], v[180:183], v[32:35]
	v_mfma_f32_16x16x32_bf16 v[20:23], v[156:159], v[188:191], v[20:23]
	v_mfma_f32_16x16x32_bf16 v[16:19], v[164:167], v[188:191], v[16:19]
	v_mfma_f32_16x16x32_bf16 v[4:7], v[156:159], v[200:203], v[4:7]
	v_mfma_f32_16x16x32_bf16 v[0:3], v[164:167], v[200:203], v[0:3]
	v_mfma_f32_16x16x32_bf16 v[52:55], v[160:163], v[176:179], v[52:55]
	v_mfma_f32_16x16x32_bf16 v[48:51], v[168:171], v[176:179], v[48:51]
	v_mfma_f32_16x16x32_bf16 v[36:39], v[160:163], v[184:187], v[36:39]
	v_mfma_f32_16x16x32_bf16 v[32:35], v[168:171], v[184:187], v[32:35]
	v_mfma_f32_16x16x32_bf16 v[20:23], v[160:163], v[192:195], v[20:23]
	v_mfma_f32_16x16x32_bf16 v[16:19], v[168:171], v[192:195], v[16:19]
	v_mfma_f32_16x16x32_bf16 v[4:7], v[160:163], v[204:207], v[4:7]
	v_mfma_f32_16x16x32_bf16 v[0:3], v[168:171], v[204:207], v[0:3]
	s_setprio 0
	s_barrier
	s_add_u32 s30, s30, 0x100
	s_addc_u32 s31, s31, 0
	s_add_u32 s29, s29, 0x100
	s_addc_u32 s73, s73, 0
	s_cmp_ge_i32 s77, s39
	s_mov_b32 s34, s77
	s_cbranch_scc0 .LBB0_757

; #define PG8_STAGE(bufoff, gbase, voff) do { _Pragma("unroll") for (int _i = 0; _i < 2; ++_i) \
;         __builtin_amdgcn_global_load_lds((const unsigned*)((const char*)(gbase) + (voff)[_i]), (PG8_LAS unsigned*)(lds + (bufoff) + ldsw + _i * 8192), 16, 0, 0); } while (0)
; #define PG8_LDA(dst, b, h) do { _Pragma("unroll") for (int m = 0; m < 4; ++m) _Pragma("unroll") for (int k = 0; k < 2; ++k) dst[m][k] = *(const PG8_LAS bf16x8*)(lds + PG8_SA(b, h) + aoff + m * 2048 + k * 1024); } while (0)
; #define PG8_LDB(dst, b, h) do { _Pragma("unroll") for (int n = 0; n < 2; ++n) _Pragma("unroll") for (int k = 0; k < 2; ++k) dst[n][k] = *(const PG8_LAS bf16x8*)(lds + PG8_SB(b, h) + boff + n * 2048 + k * 1024); } while (0)
; #define PG8_MMA(ai, bj, At, Bt) do { __builtin_amdgcn_s_setprio(1); _Pragma("unroll") for (int m = 0; m < 4; ++m) _Pragma("unroll") for (int n = 0; n < 2; ++n) _Pragma("unroll") for (int k = 0; k < 2; ++k) \
;         acc[ai][bj][m][n] = mma16<Epi::F16>(Bt[n][k], At[m][k], acc[ai][bj][m][n]); __builtin_amdgcn_s_setprio(0); } while (0)
; #define PG8_WAIT_V(n) asm volatile("s_waitcnt vmcnt(" #n ")" ::: "memory")
; #define PG8_WAIT_L(n) asm volatile("s_waitcnt lgkmcnt(" #n ")" ::: "memory")
; #define PG8_BAR __builtin_amdgcn_s_barrier()
; #define PG8_SCHED __builtin_amdgcn_sched_barrier(0)
; template <class Epi, class Sched, bool ALIGN_EPI = false, bool SP2 = false>
; __device__ __forceinline__ void gemm_phase(PG8_LAS unsigned char* lds, const Gemm g, const Sched& S, const Epi& E) {
;     ...
;         for (int t = 0; t < nt; t += 2) {
;             const bool last = (t == nt - 2);
;             const char* a1 = cA + (size_t)(t + 1) * kstep;
;             const char* a2 = last ? nA : cA + (size_t)(t + 2) * kstep; const char* b2 = last ? nB : cB + (size_t)(t + 2) * kstep;
;             const char* a3 = a2 + kstep; const char* b3 = b2 + kstep;
;             if (last && has_next) S.a_ready(nxt);
;             if constexpr (SP2) {
;             PG8_LDB(B0, 0, 0); PG8_LDB(B1, 0, 1); PG8_SCHED; PG8_LDA(At, 0, 0); PG8_STAGE(PG8_SA(1, 1), a1 + hstep, voffA);
;             PG8_WAIT_V(8); PG8_WAIT_L(0); PG8_BAR; PG8_MMA(0, 0, At, B0); PG8_MMA(0, 1, At, B1); PG8_BAR; PG8_SCHED;
;             PG8_LDA(At, 0, 1); PG8_STAGE(PG8_SB(0, 0), b2, voffB); PG8_STAGE(PG8_SB(0, 1), b2 + hstep, voffB); PG8_STAGE(PG8_SA(0, 0), a2, voffA);
.Lpeel_k6:
	s_add_u32 s28, s28, 0x80
	s_addc_u32 s29, s29, 0
	s_add_u32 s34, s30, 0x100
	s_addc_u32 s35, s31, 0
	s_mov_b32 s30, 0
	s_add_i32 s43, s30, 2
	s_add_u32 s44, s28, 0x80
	s_addc_u32 s31, s29, 0
	s_add_i32 s68, 0, 0x10000
	s_cmp_eq_u32 s85, s30
	s_cselect_b32 s31, s1, s31
	s_cselect_b32 s30, s0, s44
	s_cselect_b32 s45, s67, s35
	s_cselect_b32 s44, s66, s34
	s_add_i32 s69, 0, 0x14000
	v_add_u32_e32 v160, s68, v170
	v_add_u32_e32 v168, s69, v170
	ds_read_b128 v[148:151], v160
	ds_read_b128 v[152:155], v160 offset:1024
	ds_read_b128 v[156:159], v160 offset:2048
	ds_read_b128 v[160:163], v160 offset:3072
	ds_read_b128 v[164:167], v168
	ds_read_b128 v[172:175], v168 offset:1024
	ds_read_b128 v[176:179], v168 offset:2048
	ds_read_b128 v[180:183], v168 offset:3072
	v_lshl_add_u64 v[168:169], s[28:29], 0, v[144:145]
	s_add_i32 m0, s72, 0xc000
	ds_read_b128 v[184:187], v171
	ds_read_b128 v[188:191], v171 offset:1024
	ds_read_b128 v[192:195], v171 offset:2048
	ds_read_b128 v[196:199], v171 offset:3072
	ds_read_b128 v[200:203], v171 offset:4096
	ds_read_b128 v[204:207], v171 offset:5120
	ds_read_b128 v[212:215], v171 offset:6144
	ds_read_b128 v[216:219], v171 offset:7168
	global_load_lds_dwordx4 v[168:169], off
	v_lshl_add_u64 v[168:169], s[28:29], 0, v[146:147]
	s_add_i32 m0, s72, 0xe000
	s_nop 0
	global_load_lds_dwordx4 v[168:169], off
	s_waitcnt vmcnt(8)
	s_waitcnt lgkmcnt(0)
	s_barrier
	s_setprio 1
	v_mfma_f32_16x16x32_bf16 v[124:127], v[148:151], v[184:187], 0
	v_mfma_f32_16x16x32_bf16 v[120:123], v[156:159], v[184:187], 0
	v_mfma_f32_16x16x32_bf16 v[108:111], v[148:151], v[192:195], 0
	v_mfma_f32_16x16x32_bf16 v[104:107], v[156:159], v[192:195], 0
	v_mfma_f32_16x16x32_bf16 v[92:95], v[148:151], v[200:203], 0
	v_mfma_f32_16x16x32_bf16 v[88:91], v[156:159], v[200:203], 0
	v_mfma_f32_16x16x32_bf16 v[76:79], v[148:151], v[212:215], 0
	v_mfma_f32_16x16x32_bf16 v[72:75], v[156:159], v[212:215], 0
	v_mfma_f32_16x16x32_bf16 v[124:127], v[152:155], v[188:191], v[124:127]
	v_mfma_f32_16x16x32_bf16 v[120:123], v[160:163], v[188:191], v[120:123]
	v_mfma_f32_16x16x32_bf16 v[108:111], v[152:155], v[196:199], v[108:111]
	v_mfma_f32_16x16x32_bf16 v[104:107], v[160:163], v[196:199], v[104:107]
	v_mfma_f32_16x16x32_bf16 v[92:95], v[152:155], v[204:207], v[92:95]
	v_mfma_f32_16x16x32_bf16 v[88:91], v[160:163], v[204:207], v[88:91]
	v_mfma_f32_16x16x32_bf16 v[76:79], v[152:155], v[216:219], v[76:79]
	v_mfma_f32_16x16x32_bf16 v[72:75], v[160:163], v[216:219], v[72:75]
	s_setprio 0
	s_setprio 1
	v_mfma_f32_16x16x32_bf16 v[116:119], v[164:167], v[184:187], 0
	v_mfma_f32_16x16x32_bf16 v[112:115], v[176:179], v[184:187], 0
	v_mfma_f32_16x16x32_bf16 v[100:103], v[164:167], v[192:195], 0
	v_mfma_f32_16x16x32_bf16 v[96:99], v[176:179], v[192:195], 0
	v_mfma_f32_16x16x32_bf16 v[84:87], v[164:167], v[200:203], 0
	v_mfma_f32_16x16x32_bf16 v[80:83], v[176:179], v[200:203], 0
	v_mfma_f32_16x16x32_bf16 v[68:71], v[164:167], v[212:215], 0
	v_mfma_f32_16x16x32_bf16 v[64:67], v[176:179], v[212:215], 0
	v_mfma_f32_16x16x32_bf16 v[116:119], v[172:175], v[188:191], v[116:119]
	v_mfma_f32_16x16x32_bf16 v[112:115], v[180:183], v[188:191], v[112:115]
	v_mfma_f32_16x16x32_bf16 v[100:103], v[172:175], v[196:199], v[100:103]
	v_mfma_f32_16x16x32_bf16 v[96:99], v[180:183], v[196:199], v[96:99]
	v_mfma_f32_16x16x32_bf16 v[84:87], v[172:175], v[204:207], v[84:87]
	v_mfma_f32_16x16x32_bf16 v[80:83], v[180:183], v[204:207], v[80:83]
	v_mfma_f32_16x16x32_bf16 v[68:71], v[172:175], v[216:219], v[68:71]
	v_mfma_f32_16x16x32_bf16 v[64:67], v[180:183], v[216:219], v[64:67]
	s_setprio 0
	s_barrier
	s_add_i32 s68, s68, s71
	v_lshl_add_u64 v[168:169], s[44:45], 0, v[128:129]
	s_mov_b32 m0, s68
	ds_read_b128 v[184:187], v171 offset:16384
	ds_read_b128 v[188:191], v171 offset:17408
	ds_read_b128 v[192:195], v171 offset:18432
	ds_read_b128 v[196:199], v171 offset:19456
	ds_read_b128 v[200:203], v171 offset:20480
	ds_read_b128 v[204:207], v171 offset:21504
	ds_read_b128 v[212:215], v171 offset:22528
	ds_read_b128 v[216:219], v171 offset:23552
	global_load_lds_dwordx4 v[168:169], off
	s_add_i32 m0, s68, 0x2000
	v_lshl_add_u64 v[220:221], s[44:45], 0, v[130:131]
	s_add_u32 s44, s44, s50
	s_addc_u32 s45, s45, s51
	s_add_i32 s68, s69, s71
	global_load_lds_dwordx4 v[220:221], off
	v_lshl_add_u64 v[222:223], s[44:45], 0, v[128:129]
	s_mov_b32 m0, s68
	v_lshl_add_u64 v[224:225], s[44:45], 0, v[130:131]
	global_load_lds_dwordx4 v[222:223], off
	s_add_i32 m0, s68, 0x2000
	v_lshl_add_u64 v[226:227], s[30:31], 0, v[128:129]
	global_load_lds_dwordx4 v[224:225], off
	s_mov_b32 m0, s72
	v_lshl_add_u64 v[228:229], s[30:31], 0, v[130:131]
	global_load_lds_dwordx4 v[226:227], off
	s_mov_b32 m0, s73
	s_nop 0
	global_load_lds_dwordx4 v[228:229], off
	s_waitcnt vmcnt(8)
	s_waitcnt lgkmcnt(0)
	s_barrier
; #define PG8_STAGE(bufoff, gbase, voff) do { _Pragma("unroll") for (int _i = 0; _i < 2; ++_i) \
;         __builtin_amdgcn_global_load_lds((const unsigned*)((const char*)(gbase) + (voff)[_i]), (PG8_LAS unsigned*)(lds + (bufoff) + ldsw + _i * 8192), 16, 0, 0); } while (0)
; #define PG8_LDA(dst, b, h) do { _Pragma("unroll") for (int m = 0; m < 4; ++m) _Pragma("unroll") for (int k = 0; k < 2; ++k) dst[m][k] = *(const PG8_LAS bf16x8*)(lds + PG8_SA(b, h) + aoff + m * 2048 + k * 1024); } while (0)
; #define PG8_LDB(dst, b, h) do { _Pragma("unroll") for (int n = 0; n < 2; ++n) _Pragma("unroll") for (int k = 0; k < 2; ++k) dst[n][k] = *(const PG8_LAS bf16x8*)(lds + PG8_SB(b, h) + boff + n * 2048 + k * 1024); } while (0)
; #define PG8_MMA(ai, bj, At, Bt) do { __builtin_amdgcn_s_setprio(1); _Pragma("unroll") for (int m = 0; m < 4; ++m) _Pragma("unroll") for (int n = 0; n < 2; ++n) _Pragma("unroll") for (int k = 0; k < 2; ++k) \
;         acc[ai][bj][m][n] = mma16<Epi::F16>(Bt[n][k], At[m][k], acc[ai][bj][m][n]); __builtin_amdgcn_s_setprio(0); } while (0)
; #define PG8_WAIT_V(n) asm volatile("s_waitcnt vmcnt(" #n ")" ::: "memory")
; #define PG8_WAIT_L(n) asm volatile("s_waitcnt lgkmcnt(" #n ")" ::: "memory")
; #define PG8_BAR __builtin_amdgcn_s_barrier()
; #define PG8_SCHED __builtin_amdgcn_sched_barrier(0)
; template <class Epi, class Sched, bool ALIGN_EPI = false, bool SP2 = false>
; __device__ __forceinline__ void gemm_phase(PG8_LAS unsigned char* lds, const Gemm g, const Sched& S, const Epi& E) {
;     ...
;             PG8_WAIT_V(8); PG8_WAIT_L(0); PG8_BAR; PG8_MMA(1, 0, At, B0); PG8_MMA(1, 1, At, B1); PG8_BAR; PG8_SCHED;
;             PG8_LDB(B0, 1, 0); PG8_LDB(B1, 1, 1); PG8_SCHED; PG8_LDA(At, 1, 0); PG8_STAGE(PG8_SA(0, 1), a2 + hstep, voffA);
;             PG8_WAIT_V(8); PG8_WAIT_L(0); PG8_BAR; PG8_MMA(0, 0, At, B0); PG8_MMA(0, 1, At, B1); PG8_BAR; PG8_SCHED;
	s_setprio 1
	v_mfma_f32_16x16x32_bf16 v[60:63], v[148:151], v[184:187], 0
	v_mfma_f32_16x16x32_bf16 v[56:59], v[156:159], v[184:187], 0
	v_mfma_f32_16x16x32_bf16 v[44:47], v[148:151], v[192:195], 0
	v_mfma_f32_16x16x32_bf16 v[40:43], v[156:159], v[192:195], 0
	v_mfma_f32_16x16x32_bf16 v[28:31], v[148:151], v[200:203], 0
	v_mfma_f32_16x16x32_bf16 v[24:27], v[156:159], v[200:203], 0
	v_mfma_f32_16x16x32_bf16 v[12:15], v[148:151], v[212:215], 0
	v_mfma_f32_16x16x32_bf16 v[8:11], v[156:159], v[212:215], 0
	v_mfma_f32_16x16x32_bf16 v[60:63], v[152:155], v[188:191], v[60:63]
	v_mfma_f32_16x16x32_bf16 v[56:59], v[160:163], v[188:191], v[56:59]
	v_mfma_f32_16x16x32_bf16 v[44:47], v[152:155], v[196:199], v[44:47]
	v_mfma_f32_16x16x32_bf16 v[40:43], v[160:163], v[196:199], v[40:43]
	v_mfma_f32_16x16x32_bf16 v[28:31], v[152:155], v[204:207], v[28:31]
	v_mfma_f32_16x16x32_bf16 v[24:27], v[160:163], v[204:207], v[24:27]
	v_mfma_f32_16x16x32_bf16 v[12:15], v[152:155], v[216:219], v[12:15]
	v_mfma_f32_16x16x32_bf16 v[8:11], v[160:163], v[216:219], v[8:11]
	s_setprio 0
	s_setprio 1
	v_mfma_f32_16x16x32_bf16 v[52:55], v[164:167], v[184:187], 0
	v_mfma_f32_16x16x32_bf16 v[48:51], v[176:179], v[184:187], 0
	v_mfma_f32_16x16x32_bf16 v[36:39], v[164:167], v[192:195], 0
	v_mfma_f32_16x16x32_bf16 v[32:35], v[176:179], v[192:195], 0
	v_mfma_f32_16x16x32_bf16 v[20:23], v[164:167], v[200:203], 0
	v_mfma_f32_16x16x32_bf16 v[16:19], v[176:179], v[200:203], 0
	v_mfma_f32_16x16x32_bf16 v[4:7], v[164:167], v[212:215], 0
	v_mfma_f32_16x16x32_bf16 v[0:3], v[176:179], v[212:215], 0
	v_mfma_f32_16x16x32_bf16 v[52:55], v[172:175], v[188:191], v[52:55]
	v_mfma_f32_16x16x32_bf16 v[48:51], v[180:183], v[188:191], v[48:51]
	v_mfma_f32_16x16x32_bf16 v[36:39], v[172:175], v[196:199], v[36:39]
	v_mfma_f32_16x16x32_bf16 v[32:35], v[180:183], v[196:199], v[32:35]
	v_mfma_f32_16x16x32_bf16 v[20:23], v[172:175], v[204:207], v[20:23]
	v_mfma_f32_16x16x32_bf16 v[16:19], v[180:183], v[204:207], v[16:19]
	v_mfma_f32_16x16x32_bf16 v[4:7], v[172:175], v[216:219], v[4:7]
	v_mfma_f32_16x16x32_bf16 v[0:3], v[180:183], v[216:219], v[0:3]
	s_setprio 0
	s_barrier
	s_add_i32 s44, 0, 0x18000
	s_add_i32 s45, 0, 0x1c000
	v_add_u32_e32 v160, s44, v170
	v_add_u32_e32 v180, s45, v170
	ds_read_b128 v[148:151], v160
	ds_read_b128 v[152:155], v160 offset:1024
	ds_read_b128 v[156:159], v160 offset:2048
	ds_read_b128 v[160:163], v160 offset:3072
	ds_read_b128 v[164:167], v180
	ds_read_b128 v[172:175], v180 offset:1024
	ds_read_b128 v[176:179], v180 offset:2048
	ds_read_b128 v[180:183], v180 offset:3072
	s_add_u32 s30, s30, s50
	s_addc_u32 s31, s31, s51
	s_mov_b32 m0, s7
	v_lshl_add_u64 v[230:231], s[30:31], 0, v[128:129]
	ds_read_b128 v[184:187], v171 offset:32768
	ds_read_b128 v[188:191], v171 offset:33792
	ds_read_b128 v[192:195], v171 offset:34816
	ds_read_b128 v[196:199], v171 offset:35840
	ds_read_b128 v[200:203], v171 offset:36864
	ds_read_b128 v[204:207], v171 offset:37888
	ds_read_b128 v[212:215], v171 offset:38912
	ds_read_b128 v[216:219], v171 offset:39936
	global_load_lds_dwordx4 v[230:231], off
	v_lshl_add_u64 v[230:231], s[30:31], 0, v[130:131]
	s_mov_b32 m0, s8
	s_nop 0
	global_load_lds_dwordx4 v[230:231], off
	s_waitcnt vmcnt(8)
	s_waitcnt lgkmcnt(0)
	s_barrier
	s_setprio 1
	v_mfma_f32_16x16x32_bf16 v[124:127], v[148:151], v[184:187], v[124:127]
	v_mfma_f32_16x16x32_bf16 v[120:123], v[156:159], v[184:187], v[120:123]
	v_mfma_f32_16x16x32_bf16 v[108:111], v[148:151], v[192:195], v[108:111]
	v_mfma_f32_16x16x32_bf16 v[104:107], v[156:159], v[192:195], v[104:107]
	v_mfma_f32_16x16x32_bf16 v[92:95], v[148:151], v[200:203], v[92:95]
	v_mfma_f32_16x16x32_bf16 v[88:91], v[156:159], v[200:203], v[88:91]
	v_mfma_f32_16x16x32_bf16 v[76:79], v[148:151], v[212:215], v[76:79]
	v_mfma_f32_16x16x32_bf16 v[72:75], v[156:159], v[212:215], v[72:75]
	v_mfma_f32_16x16x32_bf16 v[124:127], v[152:155], v[188:191], v[124:127]
	v_mfma_f32_16x16x32_bf16 v[120:123], v[160:163], v[188:191], v[120:123]
	v_mfma_f32_16x16x32_bf16 v[108:111], v[152:155], v[196:199], v[108:111]
	v_mfma_f32_16x16x32_bf16 v[104:107], v[160:163], v[196:199], v[104:107]
	v_mfma_f32_16x16x32_bf16 v[92:95], v[152:155], v[204:207], v[92:95]
	v_mfma_f32_16x16x32_bf16 v[88:91], v[160:163], v[204:207], v[88:91]
	v_mfma_f32_16x16x32_bf16 v[76:79], v[152:155], v[216:219], v[76:79]
	v_mfma_f32_16x16x32_bf16 v[72:75], v[160:163], v[216:219], v[72:75]
	s_setprio 0
	s_setprio 1
	v_mfma_f32_16x16x32_bf16 v[116:119], v[164:167], v[184:187], v[116:119]
	v_mfma_f32_16x16x32_bf16 v[112:115], v[176:179], v[184:187], v[112:115]
	v_mfma_f32_16x16x32_bf16 v[100:103], v[164:167], v[192:195], v[100:103]
	v_mfma_f32_16x16x32_bf16 v[96:99], v[176:179], v[192:195], v[96:99]
	v_mfma_f32_16x16x32_bf16 v[84:87], v[164:167], v[200:203], v[84:87]
	v_mfma_f32_16x16x32_bf16 v[80:83], v[176:179], v[200:203], v[80:83]
	v_mfma_f32_16x16x32_bf16 v[68:71], v[164:167], v[212:215], v[68:71]
	v_mfma_f32_16x16x32_bf16 v[64:67], v[176:179], v[212:215], v[64:67]
	v_mfma_f32_16x16x32_bf16 v[116:119], v[172:175], v[188:191], v[116:119]
	v_mfma_f32_16x16x32_bf16 v[112:115], v[180:183], v[188:191], v[112:115]
	v_mfma_f32_16x16x32_bf16 v[100:103], v[172:175], v[196:199], v[100:103]
	v_mfma_f32_16x16x32_bf16 v[96:99], v[180:183], v[196:199], v[96:99]
	v_mfma_f32_16x16x32_bf16 v[84:87], v[172:175], v[204:207], v[84:87]
	v_mfma_f32_16x16x32_bf16 v[80:83], v[180:183], v[204:207], v[80:83]
	v_mfma_f32_16x16x32_bf16 v[68:71], v[172:175], v[216:219], v[68:71]
	v_mfma_f32_16x16x32_bf16 v[64:67], v[180:183], v[216:219], v[64:67]
	s_setprio 0
	s_barrier
; #define PG8_STAGE(bufoff, gbase, voff) do { _Pragma("unroll") for (int _i = 0; _i < 2; ++_i) \
;         __builtin_amdgcn_global_load_lds((const unsigned*)((const char*)(gbase) + (voff)[_i]), (PG8_LAS unsigned*)(lds + (bufoff) + ldsw + _i * 8192), 16, 0, 0); } while (0)
; #define PG8_LDA(dst, b, h) do { _Pragma("unroll") for (int m = 0; m < 4; ++m) _Pragma("unroll") for (int k = 0; k < 2; ++k) dst[m][k] = *(const PG8_LAS bf16x8*)(lds + PG8_SA(b, h) + aoff + m * 2048 + k * 1024); } while (0)
; #define PG8_LDB(dst, b, h) do { _Pragma("unroll") for (int n = 0; n < 2; ++n) _Pragma("unroll") for (int k = 0; k < 2; ++k) dst[n][k] = *(const PG8_LAS bf16x8*)(lds + PG8_SB(b, h) + boff + n * 2048 + k * 1024); } while (0)
; #define PG8_MMA(ai, bj, At, Bt) do { __builtin_amdgcn_s_setprio(1); _Pragma("unroll") for (int m = 0; m < 4; ++m) _Pragma("unroll") for (int n = 0; n < 2; ++n) _Pragma("unroll") for (int k = 0; k < 2; ++k) \
;         acc[ai][bj][m][n] = mma16<Epi::F16>(Bt[n][k], At[m][k], acc[ai][bj][m][n]); __builtin_amdgcn_s_setprio(0); } while (0)
; #define PG8_WAIT_V(n) asm volatile("s_waitcnt vmcnt(" #n ")" ::: "memory")
; #define PG8_WAIT_L(n) asm volatile("s_waitcnt lgkmcnt(" #n ")" ::: "memory")
; template <class Epi, class Sched, bool ALIGN_EPI = false, bool SP2 = false>
; __device__ __forceinline__ void gemm_phase(PG8_LAS unsigned char* lds, const Gemm g, const Sched& S, const Epi& E) {
;     ...
;         for (int t = 0; t < nt; t += 2) {
;             const bool last = (t == nt - 2);
;             const char* a1 = cA + (size_t)(t + 1) * kstep;
;             const char* a2 = last ? nA : cA + (size_t)(t + 2) * kstep; const char* b2 = last ? nB : cB + (size_t)(t + 2) * kstep;
;             const char* a3 = a2 + kstep; const char* b3 = b2 + kstep;
;             if (last && has_next) S.a_ready(nxt);
;             if constexpr (SP2) {
;             PG8_LDB(B0, 0, 0); PG8_LDB(B1, 0, 1); PG8_SCHED; PG8_LDA(At, 0, 0); PG8_STAGE(PG8_SA(1, 1), a1 + hstep, voffA);
;             PG8_WAIT_V(8); PG8_WAIT_L(0); PG8_BAR; PG8_MMA(0, 0, At, B0); PG8_MMA(0, 1, At, B1); PG8_BAR; PG8_SCHED;
;     ...
;             PG8_LDA(At, 1, 1); PG8_STAGE(PG8_SB(1, 0), b3, voffB); PG8_STAGE(PG8_SB(1, 1), b3 + hstep, voffB); PG8_STAGE(PG8_SA(1, 0), a3, voffA);
;             PG8_WAIT_V(8); PG8_WAIT_L(0); PG8_BAR; PG8_MMA(1, 0, At, B0); PG8_MMA(1, 1, At, B1); PG8_BAR; PG8_SCHED;
	s_add_i32 s30, s44, s71
	v_lshl_add_u64 v[168:169], v[168:169], 0, s[20:21]
	s_mov_b32 m0, s30
	ds_read_b128 v[184:187], v171 offset:49152
	ds_read_b128 v[188:191], v171 offset:50176
	ds_read_b128 v[192:195], v171 offset:51200
	ds_read_b128 v[196:199], v171 offset:52224
	ds_read_b128 v[200:203], v171 offset:53248
	ds_read_b128 v[204:207], v171 offset:54272
	ds_read_b128 v[212:215], v171 offset:55296
	ds_read_b128 v[216:219], v171 offset:56320
	global_load_lds_dwordx4 v[168:169], off
	v_lshl_add_u64 v[168:169], v[220:221], 0, s[20:21]
	s_add_i32 m0, s30, 0x2000
	s_add_i32 s30, s45, s71
	global_load_lds_dwordx4 v[168:169], off
	v_lshl_add_u64 v[168:169], v[222:223], 0, s[20:21]
	s_mov_b32 m0, s30
	s_nop 0
	global_load_lds_dwordx4 v[168:169], off
	v_lshl_add_u64 v[168:169], v[224:225], 0, s[20:21]
	s_add_i32 m0, s30, 0x2000
	s_nop 0
	global_load_lds_dwordx4 v[168:169], off
	v_lshl_add_u64 v[168:169], v[226:227], 0, s[20:21]
	s_mov_b32 m0, s9
	s_nop 0
	global_load_lds_dwordx4 v[168:169], off
	v_lshl_add_u64 v[168:169], v[228:229], 0, s[20:21]
	s_mov_b32 m0, s84
	s_nop 0
	global_load_lds_dwordx4 v[168:169], off
	s_waitcnt vmcnt(8)
	s_waitcnt lgkmcnt(0)
	s_barrier
	s_setprio 1
	v_mfma_f32_16x16x32_bf16 v[60:63], v[148:151], v[184:187], v[60:63]
	v_mfma_f32_16x16x32_bf16 v[56:59], v[156:159], v[184:187], v[56:59]
	v_mfma_f32_16x16x32_bf16 v[44:47], v[148:151], v[192:195], v[44:47]
	v_mfma_f32_16x16x32_bf16 v[40:43], v[156:159], v[192:195], v[40:43]
	v_mfma_f32_16x16x32_bf16 v[28:31], v[148:151], v[200:203], v[28:31]
	v_mfma_f32_16x16x32_bf16 v[24:27], v[156:159], v[200:203], v[24:27]
	v_mfma_f32_16x16x32_bf16 v[12:15], v[148:151], v[212:215], v[12:15]
	v_mfma_f32_16x16x32_bf16 v[8:11], v[156:159], v[212:215], v[8:11]
	v_mfma_f32_16x16x32_bf16 v[60:63], v[152:155], v[188:191], v[60:63]
	v_mfma_f32_16x16x32_bf16 v[56:59], v[160:163], v[188:191], v[56:59]
	v_mfma_f32_16x16x32_bf16 v[44:47], v[152:155], v[196:199], v[44:47]
	v_mfma_f32_16x16x32_bf16 v[40:43], v[160:163], v[196:199], v[40:43]
	v_mfma_f32_16x16x32_bf16 v[28:31], v[152:155], v[204:207], v[28:31]
	v_mfma_f32_16x16x32_bf16 v[24:27], v[160:163], v[204:207], v[24:27]
	v_mfma_f32_16x16x32_bf16 v[12:15], v[152:155], v[216:219], v[12:15]
	v_mfma_f32_16x16x32_bf16 v[8:11], v[160:163], v[216:219], v[8:11]
	s_setprio 0
	s_setprio 1
	v_mfma_f32_16x16x32_bf16 v[52:55], v[164:167], v[184:187], v[52:55]
	v_mfma_f32_16x16x32_bf16 v[48:51], v[176:179], v[184:187], v[48:51]
	v_mfma_f32_16x16x32_bf16 v[36:39], v[164:167], v[192:195], v[36:39]
	v_mfma_f32_16x16x32_bf16 v[32:35], v[176:179], v[192:195], v[32:35]
	v_mfma_f32_16x16x32_bf16 v[20:23], v[164:167], v[200:203], v[20:23]
	v_mfma_f32_16x16x32_bf16 v[16:19], v[176:179], v[200:203], v[16:19]
	v_mfma_f32_16x16x32_bf16 v[4:7], v[164:167], v[212:215], v[4:7]
	v_mfma_f32_16x16x32_bf16 v[0:3], v[176:179], v[212:215], v[0:3]
	v_mfma_f32_16x16x32_bf16 v[52:55], v[172:175], v[188:191], v[52:55]
	v_mfma_f32_16x16x32_bf16 v[48:51], v[180:183], v[188:191], v[48:51]
	v_mfma_f32_16x16x32_bf16 v[36:39], v[172:175], v[196:199], v[36:39]
	v_mfma_f32_16x16x32_bf16 v[32:35], v[180:183], v[196:199], v[32:35]
	v_mfma_f32_16x16x32_bf16 v[20:23], v[172:175], v[204:207], v[20:23]
	v_mfma_f32_16x16x32_bf16 v[16:19], v[180:183], v[204:207], v[16:19]
	v_mfma_f32_16x16x32_bf16 v[4:7], v[172:175], v[216:219], v[4:7]
	v_mfma_f32_16x16x32_bf16 v[0:3], v[180:183], v[216:219], v[0:3]
	s_setprio 0
	s_barrier
	s_add_u32 s28, s28, 0x100
	s_addc_u32 s29, s29, 0
	s_add_u32 s34, s34, 0x100
	s_addc_u32 s35, s35, 0
	s_cmp_ge_i32 s43, s96
	s_mov_b32 s30, s43
	s_cbranch_scc0 .LBB0_901
	s_branch .LBB0_902
.LBB0_901:
	s_add_i32 s43, s30, 2
	s_add_u32 s44, s28, 0x80
	s_addc_u32 s31, s29, 0
	s_add_i32 s68, 0, 0x10000
	s_cmp_eq_u32 s85, s30
	s_cselect_b32 s31, s1, s31
	s_cselect_b32 s30, s0, s44
	s_cselect_b32 s45, s67, s35
	s_cselect_b32 s44, s66, s34
	s_add_i32 s69, 0, 0x14000
	v_add_u32_e32 v160, s68, v170
	v_add_u32_e32 v168, s69, v170
	ds_read_b128 v[148:151], v160
	ds_read_b128 v[152:155], v160 offset:1024
	ds_read_b128 v[156:159], v160 offset:2048
	ds_read_b128 v[160:163], v160 offset:3072
	ds_read_b128 v[164:167], v168
	ds_read_b128 v[172:175], v168 offset:1024
	ds_read_b128 v[176:179], v168 offset:2048
	ds_read_b128 v[180:183], v168 offset:3072
	v_lshl_add_u64 v[168:169], s[28:29], 0, v[144:145]
	s_add_i32 m0, s72, 0xc000
	ds_read_b128 v[184:187], v171
	ds_read_b128 v[188:191], v171 offset:1024
	ds_read_b128 v[192:195], v171 offset:2048
	ds_read_b128 v[196:199], v171 offset:3072
	ds_read_b128 v[200:203], v171 offset:4096
	ds_read_b128 v[204:207], v171 offset:5120
	ds_read_b128 v[212:215], v171 offset:6144
	ds_read_b128 v[216:219], v171 offset:7168
	global_load_lds_dwordx4 v[168:169], off
	v_lshl_add_u64 v[168:169], s[28:29], 0, v[146:147]
	s_add_i32 m0, s72, 0xe000
	s_nop 0
	global_load_lds_dwordx4 v[168:169], off
	s_waitcnt vmcnt(8)
	s_waitcnt lgkmcnt(0)
	s_barrier
; #define PG8_STAGE(bufoff, gbase, voff) do { _Pragma("unroll") for (int _i = 0; _i < 2; ++_i) \
;         __builtin_amdgcn_global_load_lds((const unsigned*)((const char*)(gbase) + (voff)[_i]), (PG8_LAS unsigned*)(lds + (bufoff) + ldsw + _i * 8192), 16, 0, 0); } while (0)
; #define PG8_LDA(dst, b, h) do { _Pragma("unroll") for (int m = 0; m < 4; ++m) _Pragma("unroll") for (int k = 0; k < 2; ++k) dst[m][k] = *(const PG8_LAS bf16x8*)(lds + PG8_SA(b, h) + aoff + m * 2048 + k * 1024); } while (0)
; #define PG8_LDB(dst, b, h) do { _Pragma("unroll") for (int n = 0; n < 2; ++n) _Pragma("unroll") for (int k = 0; k < 2; ++k) dst[n][k] = *(const PG8_LAS bf16x8*)(lds + PG8_SB(b, h) + boff + n * 2048 + k * 1024); } while (0)
; #define PG8_MMA(ai, bj, At, Bt) do { __builtin_amdgcn_s_setprio(1); _Pragma("unroll") for (int m = 0; m < 4; ++m) _Pragma("unroll") for (int n = 0; n < 2; ++n) _Pragma("unroll") for (int k = 0; k < 2; ++k) \
;         acc[ai][bj][m][n] = mma16<Epi::F16>(Bt[n][k], At[m][k], acc[ai][bj][m][n]); __builtin_amdgcn_s_setprio(0); } while (0)
; #define PG8_WAIT_V(n) asm volatile("s_waitcnt vmcnt(" #n ")" ::: "memory")
; #define PG8_WAIT_L(n) asm volatile("s_waitcnt lgkmcnt(" #n ")" ::: "memory")
; #define PG8_BAR __builtin_amdgcn_s_barrier()
; #define PG8_SCHED __builtin_amdgcn_sched_barrier(0)
; template <class Epi, class Sched, bool ALIGN_EPI = false, bool SP2 = false>
; __device__ __forceinline__ void gemm_phase(PG8_LAS unsigned char* lds, const Gemm g, const Sched& S, const Epi& E) {
;     ...
;             PG8_WAIT_V(8); PG8_WAIT_L(0); PG8_BAR; PG8_MMA(0, 0, At, B0); PG8_MMA(0, 1, At, B1); PG8_BAR; PG8_SCHED;
;             PG8_LDA(At, 0, 1); PG8_STAGE(PG8_SB(0, 0), b2, voffB); PG8_STAGE(PG8_SB(0, 1), b2 + hstep, voffB); PG8_STAGE(PG8_SA(0, 0), a2, voffA);
;             PG8_WAIT_V(8); PG8_WAIT_L(0); PG8_BAR; PG8_MMA(1, 0, At, B0); PG8_MMA(1, 1, At, B1); PG8_BAR; PG8_SCHED;
;             PG8_LDB(B0, 1, 0); PG8_LDB(B1, 1, 1); PG8_SCHED; PG8_LDA(At, 1, 0); PG8_STAGE(PG8_SA(0, 1), a2 + hstep, voffA);
;             PG8_WAIT_V(8); PG8_WAIT_L(0); PG8_BAR; PG8_MMA(0, 0, At, B0); PG8_MMA(0, 1, At, B1); PG8_BAR; PG8_SCHED;
;             PG8_LDA(At, 1, 1); PG8_STAGE(PG8_SB(1, 0), b3, voffB); PG8_STAGE(PG8_SB(1, 1), b3 + hstep, voffB); PG8_STAGE(PG8_SA(1, 0), a3, voffA);
	s_setprio 1
	v_mfma_f32_16x16x32_bf16 v[124:127], v[148:151], v[184:187], v[124:127]
	v_mfma_f32_16x16x32_bf16 v[120:123], v[156:159], v[184:187], v[120:123]
	v_mfma_f32_16x16x32_bf16 v[108:111], v[148:151], v[192:195], v[108:111]
	v_mfma_f32_16x16x32_bf16 v[104:107], v[156:159], v[192:195], v[104:107]
	v_mfma_f32_16x16x32_bf16 v[92:95], v[148:151], v[200:203], v[92:95]
	v_mfma_f32_16x16x32_bf16 v[88:91], v[156:159], v[200:203], v[88:91]
	v_mfma_f32_16x16x32_bf16 v[76:79], v[148:151], v[212:215], v[76:79]
	v_mfma_f32_16x16x32_bf16 v[72:75], v[156:159], v[212:215], v[72:75]
	v_mfma_f32_16x16x32_bf16 v[124:127], v[152:155], v[188:191], v[124:127]
	v_mfma_f32_16x16x32_bf16 v[120:123], v[160:163], v[188:191], v[120:123]
	v_mfma_f32_16x16x32_bf16 v[108:111], v[152:155], v[196:199], v[108:111]
	v_mfma_f32_16x16x32_bf16 v[104:107], v[160:163], v[196:199], v[104:107]
	v_mfma_f32_16x16x32_bf16 v[92:95], v[152:155], v[204:207], v[92:95]
	v_mfma_f32_16x16x32_bf16 v[88:91], v[160:163], v[204:207], v[88:91]
	v_mfma_f32_16x16x32_bf16 v[76:79], v[152:155], v[216:219], v[76:79]
	v_mfma_f32_16x16x32_bf16 v[72:75], v[160:163], v[216:219], v[72:75]
	s_setprio 0
	s_setprio 1
	v_mfma_f32_16x16x32_bf16 v[116:119], v[164:167], v[184:187], v[116:119]
	v_mfma_f32_16x16x32_bf16 v[112:115], v[176:179], v[184:187], v[112:115]
	v_mfma_f32_16x16x32_bf16 v[100:103], v[164:167], v[192:195], v[100:103]
	v_mfma_f32_16x16x32_bf16 v[96:99], v[176:179], v[192:195], v[96:99]
	v_mfma_f32_16x16x32_bf16 v[84:87], v[164:167], v[200:203], v[84:87]
	v_mfma_f32_16x16x32_bf16 v[80:83], v[176:179], v[200:203], v[80:83]
	v_mfma_f32_16x16x32_bf16 v[68:71], v[164:167], v[212:215], v[68:71]
	v_mfma_f32_16x16x32_bf16 v[64:67], v[176:179], v[212:215], v[64:67]
	v_mfma_f32_16x16x32_bf16 v[116:119], v[172:175], v[188:191], v[116:119]
	v_mfma_f32_16x16x32_bf16 v[112:115], v[180:183], v[188:191], v[112:115]
	v_mfma_f32_16x16x32_bf16 v[100:103], v[172:175], v[196:199], v[100:103]
	v_mfma_f32_16x16x32_bf16 v[96:99], v[180:183], v[196:199], v[96:99]
	v_mfma_f32_16x16x32_bf16 v[84:87], v[172:175], v[204:207], v[84:87]
	v_mfma_f32_16x16x32_bf16 v[80:83], v[180:183], v[204:207], v[80:83]
	v_mfma_f32_16x16x32_bf16 v[68:71], v[172:175], v[216:219], v[68:71]
	v_mfma_f32_16x16x32_bf16 v[64:67], v[180:183], v[216:219], v[64:67]
	s_setprio 0
	s_barrier
	s_add_i32 s68, s68, s71
	v_lshl_add_u64 v[168:169], s[44:45], 0, v[128:129]
	s_mov_b32 m0, s68
	ds_read_b128 v[184:187], v171 offset:16384
	ds_read_b128 v[188:191], v171 offset:17408
	ds_read_b128 v[192:195], v171 offset:18432
	ds_read_b128 v[196:199], v171 offset:19456
	ds_read_b128 v[200:203], v171 offset:20480
	ds_read_b128 v[204:207], v171 offset:21504
	ds_read_b128 v[212:215], v171 offset:22528
	ds_read_b128 v[216:219], v171 offset:23552
	global_load_lds_dwordx4 v[168:169], off
	s_add_i32 m0, s68, 0x2000
	v_lshl_add_u64 v[220:221], s[44:45], 0, v[130:131]
	s_add_u32 s44, s44, s50
	s_addc_u32 s45, s45, s51
	s_add_i32 s68, s69, s71
	global_load_lds_dwordx4 v[220:221], off
	v_lshl_add_u64 v[222:223], s[44:45], 0, v[128:129]
	s_mov_b32 m0, s68
	v_lshl_add_u64 v[224:225], s[44:45], 0, v[130:131]
	global_load_lds_dwordx4 v[222:223], off
	s_add_i32 m0, s68, 0x2000
	v_lshl_add_u64 v[226:227], s[30:31], 0, v[128:129]
	global_load_lds_dwordx4 v[224:225], off
	s_mov_b32 m0, s72
	v_lshl_add_u64 v[228:229], s[30:31], 0, v[130:131]
	global_load_lds_dwordx4 v[226:227], off
	s_mov_b32 m0, s73
	s_nop 0
	global_load_lds_dwordx4 v[228:229], off
	s_waitcnt vmcnt(8)
	s_waitcnt lgkmcnt(0)
	s_barrier
	s_setprio 1
	v_mfma_f32_16x16x32_bf16 v[60:63], v[148:151], v[184:187], v[60:63]
	v_mfma_f32_16x16x32_bf16 v[56:59], v[156:159], v[184:187], v[56:59]
	v_mfma_f32_16x16x32_bf16 v[44:47], v[148:151], v[192:195], v[44:47]
	v_mfma_f32_16x16x32_bf16 v[40:43], v[156:159], v[192:195], v[40:43]
	v_mfma_f32_16x16x32_bf16 v[28:31], v[148:151], v[200:203], v[28:31]
	v_mfma_f32_16x16x32_bf16 v[24:27], v[156:159], v[200:203], v[24:27]
	v_mfma_f32_16x16x32_bf16 v[12:15], v[148:151], v[212:215], v[12:15]
	v_mfma_f32_16x16x32_bf16 v[8:11], v[156:159], v[212:215], v[8:11]
	v_mfma_f32_16x16x32_bf16 v[60:63], v[152:155], v[188:191], v[60:63]
	v_mfma_f32_16x16x32_bf16 v[56:59], v[160:163], v[188:191], v[56:59]
	v_mfma_f32_16x16x32_bf16 v[44:47], v[152:155], v[196:199], v[44:47]
	v_mfma_f32_16x16x32_bf16 v[40:43], v[160:163], v[196:199], v[40:43]
	v_mfma_f32_16x16x32_bf16 v[28:31], v[152:155], v[204:207], v[28:31]
	v_mfma_f32_16x16x32_bf16 v[24:27], v[160:163], v[204:207], v[24:27]
	v_mfma_f32_16x16x32_bf16 v[12:15], v[152:155], v[216:219], v[12:15]
	v_mfma_f32_16x16x32_bf16 v[8:11], v[160:163], v[216:219], v[8:11]
	s_setprio 0
	s_setprio 1
	v_mfma_f32_16x16x32_bf16 v[52:55], v[164:167], v[184:187], v[52:55]
	v_mfma_f32_16x16x32_bf16 v[48:51], v[176:179], v[184:187], v[48:51]
	v_mfma_f32_16x16x32_bf16 v[36:39], v[164:167], v[192:195], v[36:39]
	v_mfma_f32_16x16x32_bf16 v[32:35], v[176:179], v[192:195], v[32:35]
	v_mfma_f32_16x16x32_bf16 v[20:23], v[164:167], v[200:203], v[20:23]
	v_mfma_f32_16x16x32_bf16 v[16:19], v[176:179], v[200:203], v[16:19]
	v_mfma_f32_16x16x32_bf16 v[4:7], v[164:167], v[212:215], v[4:7]
	v_mfma_f32_16x16x32_bf16 v[0:3], v[176:179], v[212:215], v[0:3]
	v_mfma_f32_16x16x32_bf16 v[52:55], v[172:175], v[188:191], v[52:55]
	v_mfma_f32_16x16x32_bf16 v[48:51], v[180:183], v[188:191], v[48:51]
	v_mfma_f32_16x16x32_bf16 v[36:39], v[172:175], v[196:199], v[36:39]
	v_mfma_f32_16x16x32_bf16 v[32:35], v[180:183], v[196:199], v[32:35]
	v_mfma_f32_16x16x32_bf16 v[20:23], v[172:175], v[204:207], v[20:23]
	v_mfma_f32_16x16x32_bf16 v[16:19], v[180:183], v[204:207], v[16:19]
	v_mfma_f32_16x16x32_bf16 v[4:7], v[172:175], v[216:219], v[4:7]
	v_mfma_f32_16x16x32_bf16 v[0:3], v[180:183], v[216:219], v[0:3]
	s_setprio 0
	s_barrier
; #define PG8_STAGE(bufoff, gbase, voff) do { _Pragma("unroll") for (int _i = 0; _i < 2; ++_i) \
;         __builtin_amdgcn_global_load_lds((const unsigned*)((const char*)(gbase) + (voff)[_i]), (PG8_LAS unsigned*)(lds + (bufoff) + ldsw + _i * 8192), 16, 0, 0); } while (0)
; #define PG8_LDA(dst, b, h) do { _Pragma("unroll") for (int m = 0; m < 4; ++m) _Pragma("unroll") for (int k = 0; k < 2; ++k) dst[m][k] = *(const PG8_LAS bf16x8*)(lds + PG8_SA(b, h) + aoff + m * 2048 + k * 1024); } while (0)
; #define PG8_LDB(dst, b, h) do { _Pragma("unroll") for (int n = 0; n < 2; ++n) _Pragma("unroll") for (int k = 0; k < 2; ++k) dst[n][k] = *(const PG8_LAS bf16x8*)(lds + PG8_SB(b, h) + boff + n * 2048 + k * 1024); } while (0)
; #define PG8_MMA(ai, bj, At, Bt) do { __builtin_amdgcn_s_setprio(1); _Pragma("unroll") for (int m = 0; m < 4; ++m) _Pragma("unroll") for (int n = 0; n < 2; ++n) _Pragma("unroll") for (int k = 0; k < 2; ++k) \
;         acc[ai][bj][m][n] = mma16<Epi::F16>(Bt[n][k], At[m][k], acc[ai][bj][m][n]); __builtin_amdgcn_s_setprio(0); } while (0)
; #define PG8_WAIT_V(n) asm volatile("s_waitcnt vmcnt(" #n ")" ::: "memory")
; #define PG8_WAIT_L(n) asm volatile("s_waitcnt lgkmcnt(" #n ")" ::: "memory")
; #define PG8_BAR __builtin_amdgcn_s_barrier()
; #define PG8_SCHED __builtin_amdgcn_sched_barrier(0)
; template <class Epi, class Sched, bool ALIGN_EPI = false, bool SP2 = false>
; __device__ __forceinline__ void gemm_phase(PG8_LAS unsigned char* lds, const Gemm g, const Sched& S, const Epi& E) {
;     ...
;             PG8_LDB(B0, 1, 0); PG8_LDB(B1, 1, 1); PG8_SCHED; PG8_LDA(At, 1, 0); PG8_STAGE(PG8_SA(0, 1), a2 + hstep, voffA);
;             PG8_WAIT_V(8); PG8_WAIT_L(0); PG8_BAR; PG8_MMA(0, 0, At, B0); PG8_MMA(0, 1, At, B1); PG8_BAR; PG8_SCHED;
;             PG8_LDA(At, 1, 1); PG8_STAGE(PG8_SB(1, 0), b3, voffB); PG8_STAGE(PG8_SB(1, 1), b3 + hstep, voffB); PG8_STAGE(PG8_SA(1, 0), a3, voffA);
;             PG8_WAIT_V(8); PG8_WAIT_L(0); PG8_BAR; PG8_MMA(1, 0, At, B0); PG8_MMA(1, 1, At, B1); PG8_BAR; PG8_SCHED;
	s_add_i32 s44, 0, 0x18000
	s_add_i32 s45, 0, 0x1c000
	v_add_u32_e32 v160, s44, v170
	v_add_u32_e32 v180, s45, v170
	ds_read_b128 v[148:151], v160
	ds_read_b128 v[152:155], v160 offset:1024
	ds_read_b128 v[156:159], v160 offset:2048
	ds_read_b128 v[160:163], v160 offset:3072
	ds_read_b128 v[164:167], v180
	ds_read_b128 v[172:175], v180 offset:1024
	ds_read_b128 v[176:179], v180 offset:2048
	ds_read_b128 v[180:183], v180 offset:3072
	s_add_u32 s30, s30, s50
	s_addc_u32 s31, s31, s51
	s_mov_b32 m0, s7
	v_lshl_add_u64 v[230:231], s[30:31], 0, v[128:129]
	ds_read_b128 v[184:187], v171 offset:32768
	ds_read_b128 v[188:191], v171 offset:33792
	ds_read_b128 v[192:195], v171 offset:34816
	ds_read_b128 v[196:199], v171 offset:35840
	ds_read_b128 v[200:203], v171 offset:36864
	ds_read_b128 v[204:207], v171 offset:37888
	ds_read_b128 v[212:215], v171 offset:38912
	ds_read_b128 v[216:219], v171 offset:39936
	global_load_lds_dwordx4 v[230:231], off
	v_lshl_add_u64 v[230:231], s[30:31], 0, v[130:131]
	s_mov_b32 m0, s8
	s_nop 0
	global_load_lds_dwordx4 v[230:231], off
	s_waitcnt vmcnt(8)
	s_waitcnt lgkmcnt(0)
	s_barrier
	s_setprio 1
	v_mfma_f32_16x16x32_bf16 v[124:127], v[148:151], v[184:187], v[124:127]
	v_mfma_f32_16x16x32_bf16 v[120:123], v[156:159], v[184:187], v[120:123]
	v_mfma_f32_16x16x32_bf16 v[108:111], v[148:151], v[192:195], v[108:111]
	v_mfma_f32_16x16x32_bf16 v[104:107], v[156:159], v[192:195], v[104:107]
	v_mfma_f32_16x16x32_bf16 v[92:95], v[148:151], v[200:203], v[92:95]
	v_mfma_f32_16x16x32_bf16 v[88:91], v[156:159], v[200:203], v[88:91]
	v_mfma_f32_16x16x32_bf16 v[76:79], v[148:151], v[212:215], v[76:79]
	v_mfma_f32_16x16x32_bf16 v[72:75], v[156:159], v[212:215], v[72:75]
	v_mfma_f32_16x16x32_bf16 v[124:127], v[152:155], v[188:191], v[124:127]
	v_mfma_f32_16x16x32_bf16 v[120:123], v[160:163], v[188:191], v[120:123]
	v_mfma_f32_16x16x32_bf16 v[108:111], v[152:155], v[196:199], v[108:111]
	v_mfma_f32_16x16x32_bf16 v[104:107], v[160:163], v[196:199], v[104:107]
	v_mfma_f32_16x16x32_bf16 v[92:95], v[152:155], v[204:207], v[92:95]
	v_mfma_f32_16x16x32_bf16 v[88:91], v[160:163], v[204:207], v[88:91]
	v_mfma_f32_16x16x32_bf16 v[76:79], v[152:155], v[216:219], v[76:79]
	v_mfma_f32_16x16x32_bf16 v[72:75], v[160:163], v[216:219], v[72:75]
	s_setprio 0
	s_setprio 1
	v_mfma_f32_16x16x32_bf16 v[116:119], v[164:167], v[184:187], v[116:119]
	v_mfma_f32_16x16x32_bf16 v[112:115], v[176:179], v[184:187], v[112:115]
	v_mfma_f32_16x16x32_bf16 v[100:103], v[164:167], v[192:195], v[100:103]
	v_mfma_f32_16x16x32_bf16 v[96:99], v[176:179], v[192:195], v[96:99]
	v_mfma_f32_16x16x32_bf16 v[84:87], v[164:167], v[200:203], v[84:87]
	v_mfma_f32_16x16x32_bf16 v[80:83], v[176:179], v[200:203], v[80:83]
	v_mfma_f32_16x16x32_bf16 v[68:71], v[164:167], v[212:215], v[68:71]
	v_mfma_f32_16x16x32_bf16 v[64:67], v[176:179], v[212:215], v[64:67]
	v_mfma_f32_16x16x32_bf16 v[116:119], v[172:175], v[188:191], v[116:119]
	v_mfma_f32_16x16x32_bf16 v[112:115], v[180:183], v[188:191], v[112:115]
	v_mfma_f32_16x16x32_bf16 v[100:103], v[172:175], v[196:199], v[100:103]
	v_mfma_f32_16x16x32_bf16 v[96:99], v[180:183], v[196:199], v[96:99]
	v_mfma_f32_16x16x32_bf16 v[84:87], v[172:175], v[204:207], v[84:87]
	v_mfma_f32_16x16x32_bf16 v[80:83], v[180:183], v[204:207], v[80:83]
	v_mfma_f32_16x16x32_bf16 v[68:71], v[172:175], v[216:219], v[68:71]
	v_mfma_f32_16x16x32_bf16 v[64:67], v[180:183], v[216:219], v[64:67]
	s_setprio 0
	s_barrier
	s_add_i32 s30, s44, s71
	v_lshl_add_u64 v[168:169], v[168:169], 0, s[20:21]
	s_mov_b32 m0, s30
	ds_read_b128 v[184:187], v171 offset:49152
	ds_read_b128 v[188:191], v171 offset:50176
	ds_read_b128 v[192:195], v171 offset:51200
	ds_read_b128 v[196:199], v171 offset:52224
	ds_read_b128 v[200:203], v171 offset:53248
	ds_read_b128 v[204:207], v171 offset:54272
	ds_read_b128 v[212:215], v171 offset:55296
	ds_read_b128 v[216:219], v171 offset:56320
	global_load_lds_dwordx4 v[168:169], off
	v_lshl_add_u64 v[168:169], v[220:221], 0, s[20:21]
	s_add_i32 m0, s30, 0x2000
	s_add_i32 s30, s45, s71
	global_load_lds_dwordx4 v[168:169], off
	v_lshl_add_u64 v[168:169], v[222:223], 0, s[20:21]
	s_mov_b32 m0, s30
	s_nop 0
	global_load_lds_dwordx4 v[168:169], off
	v_lshl_add_u64 v[168:169], v[224:225], 0, s[20:21]
	s_add_i32 m0, s30, 0x2000
	s_nop 0
	global_load_lds_dwordx4 v[168:169], off
	v_lshl_add_u64 v[168:169], v[226:227], 0, s[20:21]
	s_mov_b32 m0, s9
	s_nop 0
	global_load_lds_dwordx4 v[168:169], off
	v_lshl_add_u64 v[168:169], v[228:229], 0, s[20:21]
	s_mov_b32 m0, s84
	s_nop 0
	global_load_lds_dwordx4 v[168:169], off
	s_waitcnt vmcnt(8)
	s_waitcnt lgkmcnt(0)
	s_barrier
	s_setprio 1
	v_mfma_f32_16x16x32_bf16 v[60:63], v[148:151], v[184:187], v[60:63]
	v_mfma_f32_16x16x32_bf16 v[56:59], v[156:159], v[184:187], v[56:59]
	v_mfma_f32_16x16x32_bf16 v[44:47], v[148:151], v[192:195], v[44:47]
	v_mfma_f32_16x16x32_bf16 v[40:43], v[156:159], v[192:195], v[40:43]
	v_mfma_f32_16x16x32_bf16 v[28:31], v[148:151], v[200:203], v[28:31]
	v_mfma_f32_16x16x32_bf16 v[24:27], v[156:159], v[200:203], v[24:27]
	v_mfma_f32_16x16x32_bf16 v[12:15], v[148:151], v[212:215], v[12:15]
	v_mfma_f32_16x16x32_bf16 v[8:11], v[156:159], v[212:215], v[8:11]
	v_mfma_f32_16x16x32_bf16 v[60:63], v[152:155], v[188:191], v[60:63]
	v_mfma_f32_16x16x32_bf16 v[56:59], v[160:163], v[188:191], v[56:59]
	v_mfma_f32_16x16x32_bf16 v[44:47], v[152:155], v[196:199], v[44:47]
	v_mfma_f32_16x16x32_bf16 v[40:43], v[160:163], v[196:199], v[40:43]
	v_mfma_f32_16x16x32_bf16 v[28:31], v[152:155], v[204:207], v[28:31]
	v_mfma_f32_16x16x32_bf16 v[24:27], v[160:163], v[204:207], v[24:27]
	v_mfma_f32_16x16x32_bf16 v[12:15], v[152:155], v[216:219], v[12:15]
	v_mfma_f32_16x16x32_bf16 v[8:11], v[160:163], v[216:219], v[8:11]
	s_setprio 0
	s_setprio 1
	v_mfma_f32_16x16x32_bf16 v[52:55], v[164:167], v[184:187], v[52:55]
	v_mfma_f32_16x16x32_bf16 v[48:51], v[176:179], v[184:187], v[48:51]
	v_mfma_f32_16x16x32_bf16 v[36:39], v[164:167], v[192:195], v[36:39]
	v_mfma_f32_16x16x32_bf16 v[32:35], v[176:179], v[192:195], v[32:35]
	v_mfma_f32_16x16x32_bf16 v[20:23], v[164:167], v[200:203], v[20:23]
	v_mfma_f32_16x16x32_bf16 v[16:19], v[176:179], v[200:203], v[16:19]
	v_mfma_f32_16x16x32_bf16 v[4:7], v[164:167], v[212:215], v[4:7]
	v_mfma_f32_16x16x32_bf16 v[0:3], v[176:179], v[212:215], v[0:3]
	v_mfma_f32_16x16x32_bf16 v[52:55], v[172:175], v[188:191], v[52:55]
	v_mfma_f32_16x16x32_bf16 v[48:51], v[180:183], v[188:191], v[48:51]
	v_mfma_f32_16x16x32_bf16 v[36:39], v[172:175], v[196:199], v[36:39]
	v_mfma_f32_16x16x32_bf16 v[32:35], v[180:183], v[196:199], v[32:35]
	v_mfma_f32_16x16x32_bf16 v[20:23], v[172:175], v[204:207], v[20:23]
	v_mfma_f32_16x16x32_bf16 v[16:19], v[180:183], v[204:207], v[16:19]
	v_mfma_f32_16x16x32_bf16 v[4:7], v[172:175], v[216:219], v[4:7]
	v_mfma_f32_16x16x32_bf16 v[0:3], v[180:183], v[216:219], v[0:3]
	s_setprio 0
	s_barrier
	s_add_u32 s28, s28, 0x100
	s_addc_u32 s29, s29, 0
	s_add_u32 s34, s34, 0x100
	s_addc_u32 s35, s35, 0
	s_cmp_ge_i32 s43, s96
	s_mov_b32 s30, s43
	s_cbranch_scc0 .LBB0_901

; #define PG8_STAGE(bufoff, gbase, voff) do { _Pragma("unroll") for (int _i = 0; _i < 2; ++_i) \
;         __builtin_amdgcn_global_load_lds((const unsigned*)((const char*)(gbase) + (voff)[_i]), (PG8_LAS unsigned*)(lds + (bufoff) + ldsw + _i * 8192), 16, 0, 0); } while (0)
; #define PG8_LDA(dst, b, h) do { _Pragma("unroll") for (int m = 0; m < 4; ++m) _Pragma("unroll") for (int k = 0; k < 2; ++k) dst[m][k] = *(const PG8_LAS bf16x8*)(lds + PG8_SA(b, h) + aoff + m * 2048 + k * 1024); } while (0)
; #define PG8_LDB(dst, b, h) do { _Pragma("unroll") for (int n = 0; n < 2; ++n) _Pragma("unroll") for (int k = 0; k < 2; ++k) dst[n][k] = *(const PG8_LAS bf16x8*)(lds + PG8_SB(b, h) + boff + n * 2048 + k * 1024); } while (0)
; #define PG8_MMA(ai, bj, At, Bt) do { __builtin_amdgcn_s_setprio(1); _Pragma("unroll") for (int m = 0; m < 4; ++m) _Pragma("unroll") for (int n = 0; n < 2; ++n) _Pragma("unroll") for (int k = 0; k < 2; ++k) \
;         acc[ai][bj][m][n] = mma16<Epi::F16>(Bt[n][k], At[m][k], acc[ai][bj][m][n]); __builtin_amdgcn_s_setprio(0); } while (0)
; #define PG8_WAIT_V(n) asm volatile("s_waitcnt vmcnt(" #n ")" ::: "memory")
; #define PG8_WAIT_L(n) asm volatile("s_waitcnt lgkmcnt(" #n ")" ::: "memory")
; #define PG8_BAR __builtin_amdgcn_s_barrier()
; #define PG8_SCHED __builtin_amdgcn_sched_barrier(0)
; template <class Epi, class Sched, bool ALIGN_EPI = false, bool SP2 = false>
; __device__ __forceinline__ void gemm_phase(PG8_LAS unsigned char* lds, const Gemm g, const Sched& S, const Epi& E) {
;     ...
;         for (int t = 0; t < nt; t += 2) {
;             const bool last = (t == nt - 2);
;             const char* a1 = cA + (size_t)(t + 1) * kstep;
;             const char* a2 = last ? nA : cA + (size_t)(t + 2) * kstep; const char* b2 = last ? nB : cB + (size_t)(t + 2) * kstep;
;             const char* a3 = a2 + kstep; const char* b3 = b2 + kstep;
;             if (last && has_next) S.a_ready(nxt);
;             if constexpr (SP2) {
;             PG8_LDB(B0, 0, 0); PG8_LDB(B1, 0, 1); PG8_SCHED; PG8_LDA(At, 0, 0); PG8_STAGE(PG8_SA(1, 1), a1 + hstep, voffA);
;             PG8_WAIT_V(8); PG8_WAIT_L(0); PG8_BAR; PG8_MMA(0, 0, At, B0); PG8_MMA(0, 1, At, B1); PG8_BAR; PG8_SCHED;
;             PG8_LDA(At, 0, 1); PG8_STAGE(PG8_SB(0, 0), b2, voffB); PG8_STAGE(PG8_SB(0, 1), b2 + hstep, voffB); PG8_STAGE(PG8_SA(0, 0), a2, voffA);
.Lpeel_k7:
	s_add_u32 s30, s30, 0x80
	s_addc_u32 s31, s31, 0
	s_add_u32 s69, s34, 0x100
	s_addc_u32 s70, s35, 0
	s_mov_b32 s34, 0
	s_add_i32 s71, s34, 2
	s_add_u32 s72, s30, 0x80
	s_addc_u32 s35, s31, 0
	s_add_i32 s77, 0, 0x10000
	s_cmp_eq_u32 s65, s34
	s_cselect_b32 s35, s1, s35
	s_cselect_b32 s34, s0, s72
	s_cselect_b32 s73, s55, s70
	s_cselect_b32 s72, s54, s69
	s_add_i32 s82, 0, 0x14000
	v_add_u32_e32 v140, s77, v191
	v_add_u32_e32 v156, s82, v191
	ds_read_b128 v[128:131], v140
	ds_read_b128 v[132:135], v140 offset:1024
	ds_read_b128 v[136:139], v140 offset:2048
	ds_read_b128 v[140:143], v140 offset:3072
	ds_read_b128 v[144:147], v156
	ds_read_b128 v[148:151], v156 offset:1024
	ds_read_b128 v[152:155], v156 offset:2048
	ds_read_b128 v[156:159], v156 offset:3072
	v_lshl_add_u64 v[192:193], s[30:31], 0, v[182:183]
	s_add_i32 m0, s48, 0xc000
	ds_read_b128 v[160:163], v195
	ds_read_b128 v[164:167], v195 offset:1024
	ds_read_b128 v[168:171], v195 offset:2048
	ds_read_b128 v[172:175], v195 offset:3072
	ds_read_b128 v[186:189], v195 offset:4096
	ds_read_b128 v[196:199], v195 offset:5120
	ds_read_b128 v[200:203], v195 offset:6144
	ds_read_b128 v[204:207], v195 offset:7168
	global_load_lds_dwordx4 v[192:193], off
	v_lshl_add_u64 v[192:193], s[30:31], 0, v[184:185]
	s_add_i32 m0, s48, 0xe000
	s_nop 0
	global_load_lds_dwordx4 v[192:193], off
	s_waitcnt vmcnt(8)
	s_waitcnt lgkmcnt(0)
	s_barrier
	s_setprio 1
	v_mfma_f32_16x16x32_bf16 v[124:127], v[128:131], v[160:163], 0
	v_mfma_f32_16x16x32_bf16 v[120:123], v[136:139], v[160:163], 0
	v_mfma_f32_16x16x32_bf16 v[108:111], v[128:131], v[168:171], 0
	v_mfma_f32_16x16x32_bf16 v[104:107], v[136:139], v[168:171], 0
	v_mfma_f32_16x16x32_bf16 v[92:95], v[128:131], v[186:189], 0
	v_mfma_f32_16x16x32_bf16 v[88:91], v[136:139], v[186:189], 0
	v_mfma_f32_16x16x32_bf16 v[76:79], v[128:131], v[200:203], 0
	v_mfma_f32_16x16x32_bf16 v[72:75], v[136:139], v[200:203], 0
	v_mfma_f32_16x16x32_bf16 v[124:127], v[132:135], v[164:167], v[124:127]
	v_mfma_f32_16x16x32_bf16 v[120:123], v[140:143], v[164:167], v[120:123]
	v_mfma_f32_16x16x32_bf16 v[108:111], v[132:135], v[172:175], v[108:111]
	v_mfma_f32_16x16x32_bf16 v[104:107], v[140:143], v[172:175], v[104:107]
	v_mfma_f32_16x16x32_bf16 v[92:95], v[132:135], v[196:199], v[92:95]
	v_mfma_f32_16x16x32_bf16 v[88:91], v[140:143], v[196:199], v[88:91]
	v_mfma_f32_16x16x32_bf16 v[76:79], v[132:135], v[204:207], v[76:79]
	v_mfma_f32_16x16x32_bf16 v[72:75], v[140:143], v[204:207], v[72:75]
	s_setprio 0
	s_setprio 1
	v_mfma_f32_16x16x32_bf16 v[116:119], v[144:147], v[160:163], 0
	v_mfma_f32_16x16x32_bf16 v[112:115], v[152:155], v[160:163], 0
	v_mfma_f32_16x16x32_bf16 v[100:103], v[144:147], v[168:171], 0
	v_mfma_f32_16x16x32_bf16 v[96:99], v[152:155], v[168:171], 0
	v_mfma_f32_16x16x32_bf16 v[84:87], v[144:147], v[186:189], 0
	v_mfma_f32_16x16x32_bf16 v[80:83], v[152:155], v[186:189], 0
	v_mfma_f32_16x16x32_bf16 v[68:71], v[144:147], v[200:203], 0
	v_mfma_f32_16x16x32_bf16 v[64:67], v[152:155], v[200:203], 0
	v_mfma_f32_16x16x32_bf16 v[116:119], v[148:151], v[164:167], v[116:119]
	v_mfma_f32_16x16x32_bf16 v[112:115], v[156:159], v[164:167], v[112:115]
	v_mfma_f32_16x16x32_bf16 v[100:103], v[148:151], v[172:175], v[100:103]
	v_mfma_f32_16x16x32_bf16 v[96:99], v[156:159], v[172:175], v[96:99]
	v_mfma_f32_16x16x32_bf16 v[84:87], v[148:151], v[196:199], v[84:87]
	v_mfma_f32_16x16x32_bf16 v[80:83], v[156:159], v[196:199], v[80:83]
	v_mfma_f32_16x16x32_bf16 v[68:71], v[148:151], v[204:207], v[68:71]
	v_mfma_f32_16x16x32_bf16 v[64:67], v[156:159], v[204:207], v[64:67]
	s_setprio 0
	s_barrier
	s_add_i32 s77, s77, s3
	v_lshl_add_u64 v[192:193], s[72:73], 0, v[178:179]
	s_mov_b32 m0, s77
	ds_read_b128 v[160:163], v195 offset:16384
	ds_read_b128 v[164:167], v195 offset:17408
	ds_read_b128 v[168:171], v195 offset:18432
	ds_read_b128 v[172:175], v195 offset:19456
	ds_read_b128 v[186:189], v195 offset:20480
	ds_read_b128 v[196:199], v195 offset:21504
	ds_read_b128 v[200:203], v195 offset:22528
	ds_read_b128 v[204:207], v195 offset:23552
	global_load_lds_dwordx4 v[192:193], off
	s_add_i32 m0, s77, 0x2000
	v_lshl_add_u64 v[212:213], s[72:73], 0, v[176:177]
	s_add_u32 s72, s72, s42
	s_addc_u32 s73, s73, s43
	s_add_i32 s77, s82, s3
	global_load_lds_dwordx4 v[212:213], off
	v_lshl_add_u64 v[214:215], s[72:73], 0, v[178:179]
	s_mov_b32 m0, s77
	v_lshl_add_u64 v[216:217], s[72:73], 0, v[176:177]
	global_load_lds_dwordx4 v[214:215], off
	s_add_i32 m0, s77, 0x2000
	v_lshl_add_u64 v[218:219], s[34:35], 0, v[178:179]
	global_load_lds_dwordx4 v[216:217], off
	s_mov_b32 m0, s48
	v_lshl_add_u64 v[220:221], s[34:35], 0, v[176:177]
	global_load_lds_dwordx4 v[218:219], off
	s_mov_b32 m0, s56
	s_nop 0
	global_load_lds_dwordx4 v[220:221], off
	s_waitcnt vmcnt(8)
	s_waitcnt lgkmcnt(0)
	s_barrier
; #define PG8_STAGE(bufoff, gbase, voff) do { _Pragma("unroll") for (int _i = 0; _i < 2; ++_i) \
;         __builtin_amdgcn_global_load_lds((const unsigned*)((const char*)(gbase) + (voff)[_i]), (PG8_LAS unsigned*)(lds + (bufoff) + ldsw + _i * 8192), 16, 0, 0); } while (0)
; #define PG8_LDA(dst, b, h) do { _Pragma("unroll") for (int m = 0; m < 4; ++m) _Pragma("unroll") for (int k = 0; k < 2; ++k) dst[m][k] = *(const PG8_LAS bf16x8*)(lds + PG8_SA(b, h) + aoff + m * 2048 + k * 1024); } while (0)
; #define PG8_LDB(dst, b, h) do { _Pragma("unroll") for (int n = 0; n < 2; ++n) _Pragma("unroll") for (int k = 0; k < 2; ++k) dst[n][k] = *(const PG8_LAS bf16x8*)(lds + PG8_SB(b, h) + boff + n * 2048 + k * 1024); } while (0)
; #define PG8_MMA(ai, bj, At, Bt) do { __builtin_amdgcn_s_setprio(1); _Pragma("unroll") for (int m = 0; m < 4; ++m) _Pragma("unroll") for (int n = 0; n < 2; ++n) _Pragma("unroll") for (int k = 0; k < 2; ++k) \
;         acc[ai][bj][m][n] = mma16<Epi::F16>(Bt[n][k], At[m][k], acc[ai][bj][m][n]); __builtin_amdgcn_s_setprio(0); } while (0)
; #define PG8_WAIT_V(n) asm volatile("s_waitcnt vmcnt(" #n ")" ::: "memory")
; #define PG8_WAIT_L(n) asm volatile("s_waitcnt lgkmcnt(" #n ")" ::: "memory")
; #define PG8_BAR __builtin_amdgcn_s_barrier()
; #define PG8_SCHED __builtin_amdgcn_sched_barrier(0)
; template <class Epi, class Sched, bool ALIGN_EPI = false, bool SP2 = false>
; __device__ __forceinline__ void gemm_phase(PG8_LAS unsigned char* lds, const Gemm g, const Sched& S, const Epi& E) {
;     ...
;             PG8_WAIT_V(8); PG8_WAIT_L(0); PG8_BAR; PG8_MMA(1, 0, At, B0); PG8_MMA(1, 1, At, B1); PG8_BAR; PG8_SCHED;
;             PG8_LDB(B0, 1, 0); PG8_LDB(B1, 1, 1); PG8_SCHED; PG8_LDA(At, 1, 0); PG8_STAGE(PG8_SA(0, 1), a2 + hstep, voffA);
;             PG8_WAIT_V(8); PG8_WAIT_L(0); PG8_BAR; PG8_MMA(0, 0, At, B0); PG8_MMA(0, 1, At, B1); PG8_BAR; PG8_SCHED;
	s_setprio 1
	v_mfma_f32_16x16x32_bf16 v[60:63], v[128:131], v[160:163], 0
	v_mfma_f32_16x16x32_bf16 v[56:59], v[136:139], v[160:163], 0
	v_mfma_f32_16x16x32_bf16 v[44:47], v[128:131], v[168:171], 0
	v_mfma_f32_16x16x32_bf16 v[40:43], v[136:139], v[168:171], 0
	v_mfma_f32_16x16x32_bf16 v[28:31], v[128:131], v[186:189], 0
	v_mfma_f32_16x16x32_bf16 v[24:27], v[136:139], v[186:189], 0
	v_mfma_f32_16x16x32_bf16 v[12:15], v[128:131], v[200:203], 0
	v_mfma_f32_16x16x32_bf16 v[8:11], v[136:139], v[200:203], 0
	v_mfma_f32_16x16x32_bf16 v[60:63], v[132:135], v[164:167], v[60:63]
	v_mfma_f32_16x16x32_bf16 v[56:59], v[140:143], v[164:167], v[56:59]
	v_mfma_f32_16x16x32_bf16 v[44:47], v[132:135], v[172:175], v[44:47]
	v_mfma_f32_16x16x32_bf16 v[40:43], v[140:143], v[172:175], v[40:43]
	v_mfma_f32_16x16x32_bf16 v[28:31], v[132:135], v[196:199], v[28:31]
	v_mfma_f32_16x16x32_bf16 v[24:27], v[140:143], v[196:199], v[24:27]
	v_mfma_f32_16x16x32_bf16 v[12:15], v[132:135], v[204:207], v[12:15]
	v_mfma_f32_16x16x32_bf16 v[8:11], v[140:143], v[204:207], v[8:11]
	s_setprio 0
	s_setprio 1
	v_mfma_f32_16x16x32_bf16 v[52:55], v[144:147], v[160:163], 0
	v_mfma_f32_16x16x32_bf16 v[48:51], v[152:155], v[160:163], 0
	v_mfma_f32_16x16x32_bf16 v[36:39], v[144:147], v[168:171], 0
	v_mfma_f32_16x16x32_bf16 v[32:35], v[152:155], v[168:171], 0
	v_mfma_f32_16x16x32_bf16 v[20:23], v[144:147], v[186:189], 0
	v_mfma_f32_16x16x32_bf16 v[16:19], v[152:155], v[186:189], 0
	v_mfma_f32_16x16x32_bf16 v[4:7], v[144:147], v[200:203], 0
	v_mfma_f32_16x16x32_bf16 v[0:3], v[152:155], v[200:203], 0
	v_mfma_f32_16x16x32_bf16 v[52:55], v[148:151], v[164:167], v[52:55]
	v_mfma_f32_16x16x32_bf16 v[48:51], v[156:159], v[164:167], v[48:51]
	v_mfma_f32_16x16x32_bf16 v[36:39], v[148:151], v[172:175], v[36:39]
	v_mfma_f32_16x16x32_bf16 v[32:35], v[156:159], v[172:175], v[32:35]
	v_mfma_f32_16x16x32_bf16 v[20:23], v[148:151], v[196:199], v[20:23]
	v_mfma_f32_16x16x32_bf16 v[16:19], v[156:159], v[196:199], v[16:19]
	v_mfma_f32_16x16x32_bf16 v[4:7], v[148:151], v[204:207], v[4:7]
	v_mfma_f32_16x16x32_bf16 v[0:3], v[156:159], v[204:207], v[0:3]
	s_setprio 0
	s_barrier
	s_add_i32 s72, 0, 0x18000
	s_add_i32 s73, 0, 0x1c000
	v_add_u32_e32 v140, s72, v191
	v_add_u32_e32 v156, s73, v191
	ds_read_b128 v[128:131], v140
	ds_read_b128 v[132:135], v140 offset:1024
	ds_read_b128 v[136:139], v140 offset:2048
	ds_read_b128 v[140:143], v140 offset:3072
	ds_read_b128 v[144:147], v156
	ds_read_b128 v[148:151], v156 offset:1024
	ds_read_b128 v[152:155], v156 offset:2048
	ds_read_b128 v[156:159], v156 offset:3072
	s_add_u32 s34, s34, s42
	s_addc_u32 s35, s35, s43
	s_mov_b32 m0, s57
	v_lshl_add_u64 v[222:223], s[34:35], 0, v[178:179]
	ds_read_b128 v[160:163], v195 offset:32768
	ds_read_b128 v[164:167], v195 offset:33792
	ds_read_b128 v[168:171], v195 offset:34816
	ds_read_b128 v[172:175], v195 offset:35840
	ds_read_b128 v[186:189], v195 offset:36864
	ds_read_b128 v[196:199], v195 offset:37888
	ds_read_b128 v[200:203], v195 offset:38912
	ds_read_b128 v[204:207], v195 offset:39936
	global_load_lds_dwordx4 v[222:223], off
	v_lshl_add_u64 v[222:223], s[34:35], 0, v[176:177]
	s_mov_b32 m0, s59
	s_nop 0
	global_load_lds_dwordx4 v[222:223], off
	s_waitcnt vmcnt(8)
	s_waitcnt lgkmcnt(0)
	s_barrier
	s_setprio 1
	v_mfma_f32_16x16x32_bf16 v[124:127], v[128:131], v[160:163], v[124:127]
	v_mfma_f32_16x16x32_bf16 v[120:123], v[136:139], v[160:163], v[120:123]
	v_mfma_f32_16x16x32_bf16 v[108:111], v[128:131], v[168:171], v[108:111]
	v_mfma_f32_16x16x32_bf16 v[104:107], v[136:139], v[168:171], v[104:107]
	v_mfma_f32_16x16x32_bf16 v[92:95], v[128:131], v[186:189], v[92:95]
	v_mfma_f32_16x16x32_bf16 v[88:91], v[136:139], v[186:189], v[88:91]
	v_mfma_f32_16x16x32_bf16 v[76:79], v[128:131], v[200:203], v[76:79]
	v_mfma_f32_16x16x32_bf16 v[72:75], v[136:139], v[200:203], v[72:75]
	v_mfma_f32_16x16x32_bf16 v[124:127], v[132:135], v[164:167], v[124:127]
	v_mfma_f32_16x16x32_bf16 v[120:123], v[140:143], v[164:167], v[120:123]
	v_mfma_f32_16x16x32_bf16 v[108:111], v[132:135], v[172:175], v[108:111]
	v_mfma_f32_16x16x32_bf16 v[104:107], v[140:143], v[172:175], v[104:107]
	v_mfma_f32_16x16x32_bf16 v[92:95], v[132:135], v[196:199], v[92:95]
	v_mfma_f32_16x16x32_bf16 v[88:91], v[140:143], v[196:199], v[88:91]
	v_mfma_f32_16x16x32_bf16 v[76:79], v[132:135], v[204:207], v[76:79]
	v_mfma_f32_16x16x32_bf16 v[72:75], v[140:143], v[204:207], v[72:75]
	s_setprio 0
	s_setprio 1
	v_mfma_f32_16x16x32_bf16 v[116:119], v[144:147], v[160:163], v[116:119]
	v_mfma_f32_16x16x32_bf16 v[112:115], v[152:155], v[160:163], v[112:115]
	v_mfma_f32_16x16x32_bf16 v[100:103], v[144:147], v[168:171], v[100:103]
	v_mfma_f32_16x16x32_bf16 v[96:99], v[152:155], v[168:171], v[96:99]
	v_mfma_f32_16x16x32_bf16 v[84:87], v[144:147], v[186:189], v[84:87]
	v_mfma_f32_16x16x32_bf16 v[80:83], v[152:155], v[186:189], v[80:83]
	v_mfma_f32_16x16x32_bf16 v[68:71], v[144:147], v[200:203], v[68:71]
	v_mfma_f32_16x16x32_bf16 v[64:67], v[152:155], v[200:203], v[64:67]
	v_mfma_f32_16x16x32_bf16 v[116:119], v[148:151], v[164:167], v[116:119]
	v_mfma_f32_16x16x32_bf16 v[112:115], v[156:159], v[164:167], v[112:115]
	v_mfma_f32_16x16x32_bf16 v[100:103], v[148:151], v[172:175], v[100:103]
	v_mfma_f32_16x16x32_bf16 v[96:99], v[156:159], v[172:175], v[96:99]
	v_mfma_f32_16x16x32_bf16 v[84:87], v[148:151], v[196:199], v[84:87]
	v_mfma_f32_16x16x32_bf16 v[80:83], v[156:159], v[196:199], v[80:83]
	v_mfma_f32_16x16x32_bf16 v[68:71], v[148:151], v[204:207], v[68:71]
	v_mfma_f32_16x16x32_bf16 v[64:67], v[156:159], v[204:207], v[64:67]
	s_setprio 0
	s_barrier
; #define PG8_STAGE(bufoff, gbase, voff) do { _Pragma("unroll") for (int _i = 0; _i < 2; ++_i) \
;         __builtin_amdgcn_global_load_lds((const unsigned*)((const char*)(gbase) + (voff)[_i]), (PG8_LAS unsigned*)(lds + (bufoff) + ldsw + _i * 8192), 16, 0, 0); } while (0)
; #define PG8_LDA(dst, b, h) do { _Pragma("unroll") for (int m = 0; m < 4; ++m) _Pragma("unroll") for (int k = 0; k < 2; ++k) dst[m][k] = *(const PG8_LAS bf16x8*)(lds + PG8_SA(b, h) + aoff + m * 2048 + k * 1024); } while (0)
; #define PG8_LDB(dst, b, h) do { _Pragma("unroll") for (int n = 0; n < 2; ++n) _Pragma("unroll") for (int k = 0; k < 2; ++k) dst[n][k] = *(const PG8_LAS bf16x8*)(lds + PG8_SB(b, h) + boff + n * 2048 + k * 1024); } while (0)
; #define PG8_MMA(ai, bj, At, Bt) do { __builtin_amdgcn_s_setprio(1); _Pragma("unroll") for (int m = 0; m < 4; ++m) _Pragma("unroll") for (int n = 0; n < 2; ++n) _Pragma("unroll") for (int k = 0; k < 2; ++k) \
;         acc[ai][bj][m][n] = mma16<Epi::F16>(Bt[n][k], At[m][k], acc[ai][bj][m][n]); __builtin_amdgcn_s_setprio(0); } while (0)
; #define PG8_WAIT_V(n) asm volatile("s_waitcnt vmcnt(" #n ")" ::: "memory")
; #define PG8_WAIT_L(n) asm volatile("s_waitcnt lgkmcnt(" #n ")" ::: "memory")
; template <class Epi, class Sched, bool ALIGN_EPI = false, bool SP2 = false>
; __device__ __forceinline__ void gemm_phase(PG8_LAS unsigned char* lds, const Gemm g, const Sched& S, const Epi& E) {
;     ...
;         for (int t = 0; t < nt; t += 2) {
;             const bool last = (t == nt - 2);
;             const char* a1 = cA + (size_t)(t + 1) * kstep;
;             const char* a2 = last ? nA : cA + (size_t)(t + 2) * kstep; const char* b2 = last ? nB : cB + (size_t)(t + 2) * kstep;
;             const char* a3 = a2 + kstep; const char* b3 = b2 + kstep;
;             if (last && has_next) S.a_ready(nxt);
;             if constexpr (SP2) {
;             PG8_LDB(B0, 0, 0); PG8_LDB(B1, 0, 1); PG8_SCHED; PG8_LDA(At, 0, 0); PG8_STAGE(PG8_SA(1, 1), a1 + hstep, voffA);
;             PG8_WAIT_V(8); PG8_WAIT_L(0); PG8_BAR; PG8_MMA(0, 0, At, B0); PG8_MMA(0, 1, At, B1); PG8_BAR; PG8_SCHED;
;     ...
;             PG8_LDA(At, 1, 1); PG8_STAGE(PG8_SB(1, 0), b3, voffB); PG8_STAGE(PG8_SB(1, 1), b3 + hstep, voffB); PG8_STAGE(PG8_SA(1, 0), a3, voffA);
;             PG8_WAIT_V(8); PG8_WAIT_L(0); PG8_BAR; PG8_MMA(1, 0, At, B0); PG8_MMA(1, 1, At, B1); PG8_BAR; PG8_SCHED;
	s_add_i32 s34, s72, s3
	v_lshl_add_u64 v[192:193], v[192:193], 0, s[20:21]
	s_mov_b32 m0, s34
	ds_read_b128 v[160:163], v195 offset:49152
	ds_read_b128 v[164:167], v195 offset:50176
	ds_read_b128 v[168:171], v195 offset:51200
	ds_read_b128 v[172:175], v195 offset:52224
	ds_read_b128 v[186:189], v195 offset:53248
	ds_read_b128 v[196:199], v195 offset:54272
	ds_read_b128 v[200:203], v195 offset:55296
	ds_read_b128 v[204:207], v195 offset:56320
	global_load_lds_dwordx4 v[192:193], off
	v_lshl_add_u64 v[192:193], v[212:213], 0, s[20:21]
	s_add_i32 m0, s34, 0x2000
	s_add_i32 s34, s73, s3
	global_load_lds_dwordx4 v[192:193], off
	v_lshl_add_u64 v[192:193], v[214:215], 0, s[20:21]
	s_mov_b32 m0, s34
	s_nop 0
	global_load_lds_dwordx4 v[192:193], off
	v_lshl_add_u64 v[192:193], v[216:217], 0, s[20:21]
	s_add_i32 m0, s34, 0x2000
	s_nop 0
	global_load_lds_dwordx4 v[192:193], off
	v_lshl_add_u64 v[192:193], v[218:219], 0, s[20:21]
	s_mov_b32 m0, s63
	s_nop 0
	global_load_lds_dwordx4 v[192:193], off
	v_lshl_add_u64 v[192:193], v[220:221], 0, s[20:21]
	s_mov_b32 m0, s64
	s_nop 0
	global_load_lds_dwordx4 v[192:193], off
	s_waitcnt vmcnt(8)
	s_waitcnt lgkmcnt(0)
	s_barrier
	s_setprio 1
	v_mfma_f32_16x16x32_bf16 v[60:63], v[128:131], v[160:163], v[60:63]
	v_mfma_f32_16x16x32_bf16 v[56:59], v[136:139], v[160:163], v[56:59]
	v_mfma_f32_16x16x32_bf16 v[44:47], v[128:131], v[168:171], v[44:47]
	v_mfma_f32_16x16x32_bf16 v[40:43], v[136:139], v[168:171], v[40:43]
	v_mfma_f32_16x16x32_bf16 v[28:31], v[128:131], v[186:189], v[28:31]
	v_mfma_f32_16x16x32_bf16 v[24:27], v[136:139], v[186:189], v[24:27]
	v_mfma_f32_16x16x32_bf16 v[12:15], v[128:131], v[200:203], v[12:15]
	v_mfma_f32_16x16x32_bf16 v[8:11], v[136:139], v[200:203], v[8:11]
	v_mfma_f32_16x16x32_bf16 v[60:63], v[132:135], v[164:167], v[60:63]
	v_mfma_f32_16x16x32_bf16 v[56:59], v[140:143], v[164:167], v[56:59]
	v_mfma_f32_16x16x32_bf16 v[44:47], v[132:135], v[172:175], v[44:47]
	v_mfma_f32_16x16x32_bf16 v[40:43], v[140:143], v[172:175], v[40:43]
	v_mfma_f32_16x16x32_bf16 v[28:31], v[132:135], v[196:199], v[28:31]
	v_mfma_f32_16x16x32_bf16 v[24:27], v[140:143], v[196:199], v[24:27]
	v_mfma_f32_16x16x32_bf16 v[12:15], v[132:135], v[204:207], v[12:15]
	v_mfma_f32_16x16x32_bf16 v[8:11], v[140:143], v[204:207], v[8:11]
	s_setprio 0
	s_setprio 1
	v_mfma_f32_16x16x32_bf16 v[52:55], v[144:147], v[160:163], v[52:55]
	v_mfma_f32_16x16x32_bf16 v[48:51], v[152:155], v[160:163], v[48:51]
	v_mfma_f32_16x16x32_bf16 v[36:39], v[144:147], v[168:171], v[36:39]
	v_mfma_f32_16x16x32_bf16 v[32:35], v[152:155], v[168:171], v[32:35]
	v_mfma_f32_16x16x32_bf16 v[20:23], v[144:147], v[186:189], v[20:23]
	v_mfma_f32_16x16x32_bf16 v[16:19], v[152:155], v[186:189], v[16:19]
	v_mfma_f32_16x16x32_bf16 v[4:7], v[144:147], v[200:203], v[4:7]
	v_mfma_f32_16x16x32_bf16 v[0:3], v[152:155], v[200:203], v[0:3]
	v_mfma_f32_16x16x32_bf16 v[52:55], v[148:151], v[164:167], v[52:55]
	v_mfma_f32_16x16x32_bf16 v[48:51], v[156:159], v[164:167], v[48:51]
	v_mfma_f32_16x16x32_bf16 v[36:39], v[148:151], v[172:175], v[36:39]
	v_mfma_f32_16x16x32_bf16 v[32:35], v[156:159], v[172:175], v[32:35]
	v_mfma_f32_16x16x32_bf16 v[20:23], v[148:151], v[196:199], v[20:23]
	v_mfma_f32_16x16x32_bf16 v[16:19], v[156:159], v[196:199], v[16:19]
	v_mfma_f32_16x16x32_bf16 v[4:7], v[148:151], v[204:207], v[4:7]
	v_mfma_f32_16x16x32_bf16 v[0:3], v[156:159], v[204:207], v[0:3]
	s_setprio 0
	s_barrier
	s_add_u32 s30, s30, 0x100
	s_addc_u32 s31, s31, 0
	s_add_u32 s69, s69, 0x100
	s_addc_u32 s70, s70, 0
	s_cmp_ge_i32 s71, s60
	s_mov_b32 s34, s71
	s_cbranch_scc0 .LBB0_1147
	s_branch .LBB0_1148
.LBB0_1147:
	s_add_i32 s71, s34, 2
	s_add_u32 s72, s30, 0x80
	s_addc_u32 s35, s31, 0
	s_add_i32 s77, 0, 0x10000
	s_cmp_eq_u32 s65, s34
	s_cselect_b32 s35, s1, s35
	s_cselect_b32 s34, s0, s72
	s_cselect_b32 s73, s55, s70
	s_cselect_b32 s72, s54, s69
	s_add_i32 s82, 0, 0x14000
	v_add_u32_e32 v140, s77, v191
	v_add_u32_e32 v156, s82, v191
	ds_read_b128 v[128:131], v140
	ds_read_b128 v[132:135], v140 offset:1024
	ds_read_b128 v[136:139], v140 offset:2048
	ds_read_b128 v[140:143], v140 offset:3072
	ds_read_b128 v[144:147], v156
	ds_read_b128 v[148:151], v156 offset:1024
	ds_read_b128 v[152:155], v156 offset:2048
	ds_read_b128 v[156:159], v156 offset:3072
	v_lshl_add_u64 v[192:193], s[30:31], 0, v[182:183]
	s_add_i32 m0, s48, 0xc000
	ds_read_b128 v[160:163], v195
	ds_read_b128 v[164:167], v195 offset:1024
	ds_read_b128 v[168:171], v195 offset:2048
	ds_read_b128 v[172:175], v195 offset:3072
	ds_read_b128 v[186:189], v195 offset:4096
	ds_read_b128 v[196:199], v195 offset:5120
	ds_read_b128 v[200:203], v195 offset:6144
	ds_read_b128 v[204:207], v195 offset:7168
	global_load_lds_dwordx4 v[192:193], off
	v_lshl_add_u64 v[192:193], s[30:31], 0, v[184:185]
	s_add_i32 m0, s48, 0xe000
	s_nop 0
	global_load_lds_dwordx4 v[192:193], off
	s_waitcnt vmcnt(8)
	s_waitcnt lgkmcnt(0)
	s_barrier
; #define PG8_STAGE(bufoff, gbase, voff) do { _Pragma("unroll") for (int _i = 0; _i < 2; ++_i) \
;         __builtin_amdgcn_global_load_lds((const unsigned*)((const char*)(gbase) + (voff)[_i]), (PG8_LAS unsigned*)(lds + (bufoff) + ldsw + _i * 8192), 16, 0, 0); } while (0)
; #define PG8_LDA(dst, b, h) do { _Pragma("unroll") for (int m = 0; m < 4; ++m) _Pragma("unroll") for (int k = 0; k < 2; ++k) dst[m][k] = *(const PG8_LAS bf16x8*)(lds + PG8_SA(b, h) + aoff + m * 2048 + k * 1024); } while (0)
; #define PG8_LDB(dst, b, h) do { _Pragma("unroll") for (int n = 0; n < 2; ++n) _Pragma("unroll") for (int k = 0; k < 2; ++k) dst[n][k] = *(const PG8_LAS bf16x8*)(lds + PG8_SB(b, h) + boff + n * 2048 + k * 1024); } while (0)
; #define PG8_MMA(ai, bj, At, Bt) do { __builtin_amdgcn_s_setprio(1); _Pragma("unroll") for (int m = 0; m < 4; ++m) _Pragma("unroll") for (int n = 0; n < 2; ++n) _Pragma("unroll") for (int k = 0; k < 2; ++k) \
;         acc[ai][bj][m][n] = mma16<Epi::F16>(Bt[n][k], At[m][k], acc[ai][bj][m][n]); __builtin_amdgcn_s_setprio(0); } while (0)
; #define PG8_WAIT_V(n) asm volatile("s_waitcnt vmcnt(" #n ")" ::: "memory")
; #define PG8_WAIT_L(n) asm volatile("s_waitcnt lgkmcnt(" #n ")" ::: "memory")
; #define PG8_BAR __builtin_amdgcn_s_barrier()
; #define PG8_SCHED __builtin_amdgcn_sched_barrier(0)
; template <class Epi, class Sched, bool ALIGN_EPI = false, bool SP2 = false>
; __device__ __forceinline__ void gemm_phase(PG8_LAS unsigned char* lds, const Gemm g, const Sched& S, const Epi& E) {
;     ...
;             PG8_WAIT_V(8); PG8_WAIT_L(0); PG8_BAR; PG8_MMA(0, 0, At, B0); PG8_MMA(0, 1, At, B1); PG8_BAR; PG8_SCHED;
;             PG8_LDA(At, 0, 1); PG8_STAGE(PG8_SB(0, 0), b2, voffB); PG8_STAGE(PG8_SB(0, 1), b2 + hstep, voffB); PG8_STAGE(PG8_SA(0, 0), a2, voffA);
;             PG8_WAIT_V(8); PG8_WAIT_L(0); PG8_BAR; PG8_MMA(1, 0, At, B0); PG8_MMA(1, 1, At, B1); PG8_BAR; PG8_SCHED;
;             PG8_LDB(B0, 1, 0); PG8_LDB(B1, 1, 1); PG8_SCHED; PG8_LDA(At, 1, 0); PG8_STAGE(PG8_SA(0, 1), a2 + hstep, voffA);
;             PG8_WAIT_V(8); PG8_WAIT_L(0); PG8_BAR; PG8_MMA(0, 0, At, B0); PG8_MMA(0, 1, At, B1); PG8_BAR; PG8_SCHED;
;             PG8_LDA(At, 1, 1); PG8_STAGE(PG8_SB(1, 0), b3, voffB); PG8_STAGE(PG8_SB(1, 1), b3 + hstep, voffB); PG8_STAGE(PG8_SA(1, 0), a3, voffA);
	s_setprio 1
	v_mfma_f32_16x16x32_bf16 v[124:127], v[128:131], v[160:163], v[124:127]
	v_mfma_f32_16x16x32_bf16 v[120:123], v[136:139], v[160:163], v[120:123]
	v_mfma_f32_16x16x32_bf16 v[108:111], v[128:131], v[168:171], v[108:111]
	v_mfma_f32_16x16x32_bf16 v[104:107], v[136:139], v[168:171], v[104:107]
	v_mfma_f32_16x16x32_bf16 v[92:95], v[128:131], v[186:189], v[92:95]
	v_mfma_f32_16x16x32_bf16 v[88:91], v[136:139], v[186:189], v[88:91]
	v_mfma_f32_16x16x32_bf16 v[76:79], v[128:131], v[200:203], v[76:79]
	v_mfma_f32_16x16x32_bf16 v[72:75], v[136:139], v[200:203], v[72:75]
	v_mfma_f32_16x16x32_bf16 v[124:127], v[132:135], v[164:167], v[124:127]
	v_mfma_f32_16x16x32_bf16 v[120:123], v[140:143], v[164:167], v[120:123]
	v_mfma_f32_16x16x32_bf16 v[108:111], v[132:135], v[172:175], v[108:111]
	v_mfma_f32_16x16x32_bf16 v[104:107], v[140:143], v[172:175], v[104:107]
	v_mfma_f32_16x16x32_bf16 v[92:95], v[132:135], v[196:199], v[92:95]
	v_mfma_f32_16x16x32_bf16 v[88:91], v[140:143], v[196:199], v[88:91]
	v_mfma_f32_16x16x32_bf16 v[76:79], v[132:135], v[204:207], v[76:79]
	v_mfma_f32_16x16x32_bf16 v[72:75], v[140:143], v[204:207], v[72:75]
	s_setprio 0
	s_setprio 1
	v_mfma_f32_16x16x32_bf16 v[116:119], v[144:147], v[160:163], v[116:119]
	v_mfma_f32_16x16x32_bf16 v[112:115], v[152:155], v[160:163], v[112:115]
	v_mfma_f32_16x16x32_bf16 v[100:103], v[144:147], v[168:171], v[100:103]
	v_mfma_f32_16x16x32_bf16 v[96:99], v[152:155], v[168:171], v[96:99]
	v_mfma_f32_16x16x32_bf16 v[84:87], v[144:147], v[186:189], v[84:87]
	v_mfma_f32_16x16x32_bf16 v[80:83], v[152:155], v[186:189], v[80:83]
	v_mfma_f32_16x16x32_bf16 v[68:71], v[144:147], v[200:203], v[68:71]
	v_mfma_f32_16x16x32_bf16 v[64:67], v[152:155], v[200:203], v[64:67]
	v_mfma_f32_16x16x32_bf16 v[116:119], v[148:151], v[164:167], v[116:119]
	v_mfma_f32_16x16x32_bf16 v[112:115], v[156:159], v[164:167], v[112:115]
	v_mfma_f32_16x16x32_bf16 v[100:103], v[148:151], v[172:175], v[100:103]
	v_mfma_f32_16x16x32_bf16 v[96:99], v[156:159], v[172:175], v[96:99]
	v_mfma_f32_16x16x32_bf16 v[84:87], v[148:151], v[196:199], v[84:87]
	v_mfma_f32_16x16x32_bf16 v[80:83], v[156:159], v[196:199], v[80:83]
	v_mfma_f32_16x16x32_bf16 v[68:71], v[148:151], v[204:207], v[68:71]
	v_mfma_f32_16x16x32_bf16 v[64:67], v[156:159], v[204:207], v[64:67]
	s_setprio 0
	s_barrier
	s_add_i32 s77, s77, s3
	v_lshl_add_u64 v[192:193], s[72:73], 0, v[178:179]
	s_mov_b32 m0, s77
	ds_read_b128 v[160:163], v195 offset:16384
	ds_read_b128 v[164:167], v195 offset:17408
	ds_read_b128 v[168:171], v195 offset:18432
	ds_read_b128 v[172:175], v195 offset:19456
	ds_read_b128 v[186:189], v195 offset:20480
	ds_read_b128 v[196:199], v195 offset:21504
	ds_read_b128 v[200:203], v195 offset:22528
	ds_read_b128 v[204:207], v195 offset:23552
	global_load_lds_dwordx4 v[192:193], off
	s_add_i32 m0, s77, 0x2000
	v_lshl_add_u64 v[212:213], s[72:73], 0, v[176:177]
	s_add_u32 s72, s72, s42
	s_addc_u32 s73, s73, s43
	s_add_i32 s77, s82, s3
	global_load_lds_dwordx4 v[212:213], off
	v_lshl_add_u64 v[214:215], s[72:73], 0, v[178:179]
	s_mov_b32 m0, s77
	v_lshl_add_u64 v[216:217], s[72:73], 0, v[176:177]
	global_load_lds_dwordx4 v[214:215], off
	s_add_i32 m0, s77, 0x2000
	v_lshl_add_u64 v[218:219], s[34:35], 0, v[178:179]
	global_load_lds_dwordx4 v[216:217], off
	s_mov_b32 m0, s48
	v_lshl_add_u64 v[220:221], s[34:35], 0, v[176:177]
	global_load_lds_dwordx4 v[218:219], off
	s_mov_b32 m0, s56
	s_nop 0
	global_load_lds_dwordx4 v[220:221], off
	s_waitcnt vmcnt(8)
	s_waitcnt lgkmcnt(0)
	s_barrier
	s_setprio 1
	v_mfma_f32_16x16x32_bf16 v[60:63], v[128:131], v[160:163], v[60:63]
	v_mfma_f32_16x16x32_bf16 v[56:59], v[136:139], v[160:163], v[56:59]
	v_mfma_f32_16x16x32_bf16 v[44:47], v[128:131], v[168:171], v[44:47]
	v_mfma_f32_16x16x32_bf16 v[40:43], v[136:139], v[168:171], v[40:43]
	v_mfma_f32_16x16x32_bf16 v[28:31], v[128:131], v[186:189], v[28:31]
	v_mfma_f32_16x16x32_bf16 v[24:27], v[136:139], v[186:189], v[24:27]
	v_mfma_f32_16x16x32_bf16 v[12:15], v[128:131], v[200:203], v[12:15]
	v_mfma_f32_16x16x32_bf16 v[8:11], v[136:139], v[200:203], v[8:11]
	v_mfma_f32_16x16x32_bf16 v[60:63], v[132:135], v[164:167], v[60:63]
	v_mfma_f32_16x16x32_bf16 v[56:59], v[140:143], v[164:167], v[56:59]
	v_mfma_f32_16x16x32_bf16 v[44:47], v[132:135], v[172:175], v[44:47]
	v_mfma_f32_16x16x32_bf16 v[40:43], v[140:143], v[172:175], v[40:43]
	v_mfma_f32_16x16x32_bf16 v[28:31], v[132:135], v[196:199], v[28:31]
	v_mfma_f32_16x16x32_bf16 v[24:27], v[140:143], v[196:199], v[24:27]
	v_mfma_f32_16x16x32_bf16 v[12:15], v[132:135], v[204:207], v[12:15]
	v_mfma_f32_16x16x32_bf16 v[8:11], v[140:143], v[204:207], v[8:11]
	s_setprio 0
	s_setprio 1
	v_mfma_f32_16x16x32_bf16 v[52:55], v[144:147], v[160:163], v[52:55]
	v_mfma_f32_16x16x32_bf16 v[48:51], v[152:155], v[160:163], v[48:51]
	v_mfma_f32_16x16x32_bf16 v[36:39], v[144:147], v[168:171], v[36:39]
	v_mfma_f32_16x16x32_bf16 v[32:35], v[152:155], v[168:171], v[32:35]
	v_mfma_f32_16x16x32_bf16 v[20:23], v[144:147], v[186:189], v[20:23]
	v_mfma_f32_16x16x32_bf16 v[16:19], v[152:155], v[186:189], v[16:19]
	v_mfma_f32_16x16x32_bf16 v[4:7], v[144:147], v[200:203], v[4:7]
	v_mfma_f32_16x16x32_bf16 v[0:3], v[152:155], v[200:203], v[0:3]
	v_mfma_f32_16x16x32_bf16 v[52:55], v[148:151], v[164:167], v[52:55]
	v_mfma_f32_16x16x32_bf16 v[48:51], v[156:159], v[164:167], v[48:51]
	v_mfma_f32_16x16x32_bf16 v[36:39], v[148:151], v[172:175], v[36:39]
	v_mfma_f32_16x16x32_bf16 v[32:35], v[156:159], v[172:175], v[32:35]
	v_mfma_f32_16x16x32_bf16 v[20:23], v[148:151], v[196:199], v[20:23]
	v_mfma_f32_16x16x32_bf16 v[16:19], v[156:159], v[196:199], v[16:19]
	v_mfma_f32_16x16x32_bf16 v[4:7], v[148:151], v[204:207], v[4:7]
	v_mfma_f32_16x16x32_bf16 v[0:3], v[156:159], v[204:207], v[0:3]
	s_setprio 0
	s_barrier
; #define PG8_STAGE(bufoff, gbase, voff) do { _Pragma("unroll") for (int _i = 0; _i < 2; ++_i) \
;         __builtin_amdgcn_global_load_lds((const unsigned*)((const char*)(gbase) + (voff)[_i]), (PG8_LAS unsigned*)(lds + (bufoff) + ldsw + _i * 8192), 16, 0, 0); } while (0)
; #define PG8_LDA(dst, b, h) do { _Pragma("unroll") for (int m = 0; m < 4; ++m) _Pragma("unroll") for (int k = 0; k < 2; ++k) dst[m][k] = *(const PG8_LAS bf16x8*)(lds + PG8_SA(b, h) + aoff + m * 2048 + k * 1024); } while (0)
; #define PG8_LDB(dst, b, h) do { _Pragma("unroll") for (int n = 0; n < 2; ++n) _Pragma("unroll") for (int k = 0; k < 2; ++k) dst[n][k] = *(const PG8_LAS bf16x8*)(lds + PG8_SB(b, h) + boff + n * 2048 + k * 1024); } while (0)
; #define PG8_MMA(ai, bj, At, Bt) do { __builtin_amdgcn_s_setprio(1); _Pragma("unroll") for (int m = 0; m < 4; ++m) _Pragma("unroll") for (int n = 0; n < 2; ++n) _Pragma("unroll") for (int k = 0; k < 2; ++k) \
;         acc[ai][bj][m][n] = mma16<Epi::F16>(Bt[n][k], At[m][k], acc[ai][bj][m][n]); __builtin_amdgcn_s_setprio(0); } while (0)
; #define PG8_WAIT_V(n) asm volatile("s_waitcnt vmcnt(" #n ")" ::: "memory")
; #define PG8_WAIT_L(n) asm volatile("s_waitcnt lgkmcnt(" #n ")" ::: "memory")
; #define PG8_BAR __builtin_amdgcn_s_barrier()
; #define PG8_SCHED __builtin_amdgcn_sched_barrier(0)
; template <class Epi, class Sched, bool ALIGN_EPI = false, bool SP2 = false>
; __device__ __forceinline__ void gemm_phase(PG8_LAS unsigned char* lds, const Gemm g, const Sched& S, const Epi& E) {
;     ...
;             PG8_LDB(B0, 1, 0); PG8_LDB(B1, 1, 1); PG8_SCHED; PG8_LDA(At, 1, 0); PG8_STAGE(PG8_SA(0, 1), a2 + hstep, voffA);
;             PG8_WAIT_V(8); PG8_WAIT_L(0); PG8_BAR; PG8_MMA(0, 0, At, B0); PG8_MMA(0, 1, At, B1); PG8_BAR; PG8_SCHED;
	s_add_i32 s72, 0, 0x18000
	s_add_i32 s73, 0, 0x1c000
	v_add_u32_e32 v140, s72, v191
	v_add_u32_e32 v156, s73, v191
	ds_read_b128 v[128:131], v140
	ds_read_b128 v[132:135], v140 offset:1024
	ds_read_b128 v[136:139], v140 offset:2048
	ds_read_b128 v[140:143], v140 offset:3072
	ds_read_b128 v[144:147], v156
	ds_read_b128 v[148:151], v156 offset:1024
	ds_read_b128 v[152:155], v156 offset:2048
	ds_read_b128 v[156:159], v156 offset:3072
	s_add_u32 s34, s34, s42
	s_addc_u32 s35, s35, s43
	s_mov_b32 m0, s57
	v_lshl_add_u64 v[222:223], s[34:35], 0, v[178:179]
	ds_read_b128 v[160:163], v195 offset:32768
	ds_read_b128 v[164:167], v195 offset:33792
	ds_read_b128 v[168:171], v195 offset:34816
	ds_read_b128 v[172:175], v195 offset:35840
	ds_read_b128 v[186:189], v195 offset:36864
	ds_read_b128 v[196:199], v195 offset:37888
	ds_read_b128 v[200:203], v195 offset:38912
	ds_read_b128 v[204:207], v195 offset:39936
	global_load_lds_dwordx4 v[222:223], off
	v_lshl_add_u64 v[222:223], s[34:35], 0, v[176:177]
	s_mov_b32 m0, s59
	s_nop 0
	global_load_lds_dwordx4 v[222:223], off
	s_waitcnt vmcnt(8)
	s_waitcnt lgkmcnt(0)
	s_barrier
	s_setprio 1
	v_mfma_f32_16x16x32_bf16 v[124:127], v[128:131], v[160:163], v[124:127]
	v_mfma_f32_16x16x32_bf16 v[120:123], v[136:139], v[160:163], v[120:123]
	v_mfma_f32_16x16x32_bf16 v[108:111], v[128:131], v[168:171], v[108:111]
	v_mfma_f32_16x16x32_bf16 v[104:107], v[136:139], v[168:171], v[104:107]
	v_mfma_f32_16x16x32_bf16 v[92:95], v[128:131], v[186:189], v[92:95]
	v_mfma_f32_16x16x32_bf16 v[88:91], v[136:139], v[186:189], v[88:91]
	v_mfma_f32_16x16x32_bf16 v[76:79], v[128:131], v[200:203], v[76:79]
	v_mfma_f32_16x16x32_bf16 v[72:75], v[136:139], v[200:203], v[72:75]
	v_mfma_f32_16x16x32_bf16 v[124:127], v[132:135], v[164:167], v[124:127]
	v_mfma_f32_16x16x32_bf16 v[120:123], v[140:143], v[164:167], v[120:123]
	v_mfma_f32_16x16x32_bf16 v[108:111], v[132:135], v[172:175], v[108:111]
	v_mfma_f32_16x16x32_bf16 v[104:107], v[140:143], v[172:175], v[104:107]
	v_mfma_f32_16x16x32_bf16 v[92:95], v[132:135], v[196:199], v[92:95]
	v_mfma_f32_16x16x32_bf16 v[88:91], v[140:143], v[196:199], v[88:91]
	v_mfma_f32_16x16x32_bf16 v[76:79], v[132:135], v[204:207], v[76:79]
	v_mfma_f32_16x16x32_bf16 v[72:75], v[140:143], v[204:207], v[72:75]
	s_setprio 0
	s_setprio 1
	v_mfma_f32_16x16x32_bf16 v[116:119], v[144:147], v[160:163], v[116:119]
	v_mfma_f32_16x16x32_bf16 v[112:115], v[152:155], v[160:163], v[112:115]
	v_mfma_f32_16x16x32_bf16 v[100:103], v[144:147], v[168:171], v[100:103]
	v_mfma_f32_16x16x32_bf16 v[96:99], v[152:155], v[168:171], v[96:99]
	v_mfma_f32_16x16x32_bf16 v[84:87], v[144:147], v[186:189], v[84:87]
	v_mfma_f32_16x16x32_bf16 v[80:83], v[152:155], v[186:189], v[80:83]
	v_mfma_f32_16x16x32_bf16 v[68:71], v[144:147], v[200:203], v[68:71]
	v_mfma_f32_16x16x32_bf16 v[64:67], v[152:155], v[200:203], v[64:67]
	v_mfma_f32_16x16x32_bf16 v[116:119], v[148:151], v[164:167], v[116:119]
	v_mfma_f32_16x16x32_bf16 v[112:115], v[156:159], v[164:167], v[112:115]
	v_mfma_f32_16x16x32_bf16 v[100:103], v[148:151], v[172:175], v[100:103]
	v_mfma_f32_16x16x32_bf16 v[96:99], v[156:159], v[172:175], v[96:99]
	v_mfma_f32_16x16x32_bf16 v[84:87], v[148:151], v[196:199], v[84:87]
	v_mfma_f32_16x16x32_bf16 v[80:83], v[156:159], v[196:199], v[80:83]
	v_mfma_f32_16x16x32_bf16 v[68:71], v[148:151], v[204:207], v[68:71]
	v_mfma_f32_16x16x32_bf16 v[64:67], v[156:159], v[204:207], v[64:67]
	s_setprio 0
	s_barrier
; #define PG8_STAGE(bufoff, gbase, voff) do { _Pragma("unroll") for (int _i = 0; _i < 2; ++_i) \
;         __builtin_amdgcn_global_load_lds((const unsigned*)((const char*)(gbase) + (voff)[_i]), (PG8_LAS unsigned*)(lds + (bufoff) + ldsw + _i * 8192), 16, 0, 0); } while (0)
; #define PG8_LDA(dst, b, h) do { _Pragma("unroll") for (int m = 0; m < 4; ++m) _Pragma("unroll") for (int k = 0; k < 2; ++k) dst[m][k] = *(const PG8_LAS bf16x8*)(lds + PG8_SA(b, h) + aoff + m * 2048 + k * 1024); } while (0)
; #define PG8_MMA(ai, bj, At, Bt) do { __builtin_amdgcn_s_setprio(1); _Pragma("unroll") for (int m = 0; m < 4; ++m) _Pragma("unroll") for (int n = 0; n < 2; ++n) _Pragma("unroll") for (int k = 0; k < 2; ++k) \
;         acc[ai][bj][m][n] = mma16<Epi::F16>(Bt[n][k], At[m][k], acc[ai][bj][m][n]); __builtin_amdgcn_s_setprio(0); } while (0)
; #define PG8_WAIT_V(n) asm volatile("s_waitcnt vmcnt(" #n ")" ::: "memory")
; #define PG8_WAIT_L(n) asm volatile("s_waitcnt lgkmcnt(" #n ")" ::: "memory")
; #define PG8_BAR __builtin_amdgcn_s_barrier()
; #define PG8_SCHED __builtin_amdgcn_sched_barrier(0)
; template <class Epi, class Sched, bool ALIGN_EPI = false, bool SP2 = false>
; __device__ __forceinline__ void gemm_phase(PG8_LAS unsigned char* lds, const Gemm g, const Sched& S, const Epi& E) {
;     ...
;         for (int t = 0; t < nt; t += 2) {
;             const bool last = (t == nt - 2);
;             const char* a1 = cA + (size_t)(t + 1) * kstep;
;             const char* a2 = last ? nA : cA + (size_t)(t + 2) * kstep; const char* b2 = last ? nB : cB + (size_t)(t + 2) * kstep;
;     ...
;             PG8_LDA(At, 1, 1); PG8_STAGE(PG8_SB(1, 0), b3, voffB); PG8_STAGE(PG8_SB(1, 1), b3 + hstep, voffB); PG8_STAGE(PG8_SA(1, 0), a3, voffA);
;             PG8_WAIT_V(8); PG8_WAIT_L(0); PG8_BAR; PG8_MMA(1, 0, At, B0); PG8_MMA(1, 1, At, B1); PG8_BAR; PG8_SCHED;
	s_add_i32 s34, s72, s3
	v_lshl_add_u64 v[192:193], v[192:193], 0, s[20:21]
	s_mov_b32 m0, s34
	ds_read_b128 v[160:163], v195 offset:49152
	ds_read_b128 v[164:167], v195 offset:50176
	ds_read_b128 v[168:171], v195 offset:51200
	ds_read_b128 v[172:175], v195 offset:52224
	ds_read_b128 v[186:189], v195 offset:53248
	ds_read_b128 v[196:199], v195 offset:54272
	ds_read_b128 v[200:203], v195 offset:55296
	ds_read_b128 v[204:207], v195 offset:56320
	global_load_lds_dwordx4 v[192:193], off
	v_lshl_add_u64 v[192:193], v[212:213], 0, s[20:21]
	s_add_i32 m0, s34, 0x2000
	s_add_i32 s34, s73, s3
	global_load_lds_dwordx4 v[192:193], off
	v_lshl_add_u64 v[192:193], v[214:215], 0, s[20:21]
	s_mov_b32 m0, s34
	s_nop 0
	global_load_lds_dwordx4 v[192:193], off
	v_lshl_add_u64 v[192:193], v[216:217], 0, s[20:21]
	s_add_i32 m0, s34, 0x2000
	s_nop 0
	global_load_lds_dwordx4 v[192:193], off
	v_lshl_add_u64 v[192:193], v[218:219], 0, s[20:21]
	s_mov_b32 m0, s63
	s_nop 0
	global_load_lds_dwordx4 v[192:193], off
	v_lshl_add_u64 v[192:193], v[220:221], 0, s[20:21]
	s_mov_b32 m0, s64
	s_nop 0
	global_load_lds_dwordx4 v[192:193], off
	s_waitcnt vmcnt(8)
	s_waitcnt lgkmcnt(0)
	s_barrier
	s_setprio 1
	v_mfma_f32_16x16x32_bf16 v[60:63], v[128:131], v[160:163], v[60:63]
	v_mfma_f32_16x16x32_bf16 v[56:59], v[136:139], v[160:163], v[56:59]
	v_mfma_f32_16x16x32_bf16 v[44:47], v[128:131], v[168:171], v[44:47]
	v_mfma_f32_16x16x32_bf16 v[40:43], v[136:139], v[168:171], v[40:43]
	v_mfma_f32_16x16x32_bf16 v[28:31], v[128:131], v[186:189], v[28:31]
	v_mfma_f32_16x16x32_bf16 v[24:27], v[136:139], v[186:189], v[24:27]
	v_mfma_f32_16x16x32_bf16 v[12:15], v[128:131], v[200:203], v[12:15]
	v_mfma_f32_16x16x32_bf16 v[8:11], v[136:139], v[200:203], v[8:11]
	v_mfma_f32_16x16x32_bf16 v[60:63], v[132:135], v[164:167], v[60:63]
	v_mfma_f32_16x16x32_bf16 v[56:59], v[140:143], v[164:167], v[56:59]
	v_mfma_f32_16x16x32_bf16 v[44:47], v[132:135], v[172:175], v[44:47]
	v_mfma_f32_16x16x32_bf16 v[40:43], v[140:143], v[172:175], v[40:43]
	v_mfma_f32_16x16x32_bf16 v[28:31], v[132:135], v[196:199], v[28:31]
	v_mfma_f32_16x16x32_bf16 v[24:27], v[140:143], v[196:199], v[24:27]
	v_mfma_f32_16x16x32_bf16 v[12:15], v[132:135], v[204:207], v[12:15]
	v_mfma_f32_16x16x32_bf16 v[8:11], v[140:143], v[204:207], v[8:11]
	s_setprio 0
	s_setprio 1
	v_mfma_f32_16x16x32_bf16 v[52:55], v[144:147], v[160:163], v[52:55]
	v_mfma_f32_16x16x32_bf16 v[48:51], v[152:155], v[160:163], v[48:51]
	v_mfma_f32_16x16x32_bf16 v[36:39], v[144:147], v[168:171], v[36:39]
	v_mfma_f32_16x16x32_bf16 v[32:35], v[152:155], v[168:171], v[32:35]
	v_mfma_f32_16x16x32_bf16 v[20:23], v[144:147], v[186:189], v[20:23]
	v_mfma_f32_16x16x32_bf16 v[16:19], v[152:155], v[186:189], v[16:19]
	v_mfma_f32_16x16x32_bf16 v[4:7], v[144:147], v[200:203], v[4:7]
	v_mfma_f32_16x16x32_bf16 v[0:3], v[152:155], v[200:203], v[0:3]
	v_mfma_f32_16x16x32_bf16 v[52:55], v[148:151], v[164:167], v[52:55]
	v_mfma_f32_16x16x32_bf16 v[48:51], v[156:159], v[164:167], v[48:51]
	v_mfma_f32_16x16x32_bf16 v[36:39], v[148:151], v[172:175], v[36:39]
	v_mfma_f32_16x16x32_bf16 v[32:35], v[156:159], v[172:175], v[32:35]
	v_mfma_f32_16x16x32_bf16 v[20:23], v[148:151], v[196:199], v[20:23]
	v_mfma_f32_16x16x32_bf16 v[16:19], v[156:159], v[196:199], v[16:19]
	v_mfma_f32_16x16x32_bf16 v[4:7], v[148:151], v[204:207], v[4:7]
	v_mfma_f32_16x16x32_bf16 v[0:3], v[156:159], v[204:207], v[0:3]
	s_setprio 0
	s_barrier
	s_add_u32 s30, s30, 0x100
	s_addc_u32 s31, s31, 0
	s_add_u32 s69, s69, 0x100
	s_addc_u32 s70, s70, 0
	s_cmp_ge_i32 s71, s60
	s_mov_b32 s34, s71
	s_cbranch_scc0 .LBB0_1147

; #define PG8_STAGE(bufoff, gbase, voff) do { _Pragma("unroll") for (int _i = 0; _i < 2; ++_i) \
;         __builtin_amdgcn_global_load_lds((const unsigned*)((const char*)(gbase) + (voff)[_i]), (PG8_LAS unsigned*)(lds + (bufoff) + ldsw + _i * 8192), 16, 0, 0); } while (0)
; #define PG8_LDA(dst, b, h) do { _Pragma("unroll") for (int m = 0; m < 4; ++m) _Pragma("unroll") for (int k = 0; k < 2; ++k) dst[m][k] = *(const PG8_LAS bf16x8*)(lds + PG8_SA(b, h) + aoff + m * 2048 + k * 1024); } while (0)
; #define PG8_LDB(dst, b, h) do { _Pragma("unroll") for (int n = 0; n < 2; ++n) _Pragma("unroll") for (int k = 0; k < 2; ++k) dst[n][k] = *(const PG8_LAS bf16x8*)(lds + PG8_SB(b, h) + boff + n * 2048 + k * 1024); } while (0)
; #define PG8_MMA(ai, bj, At, Bt) do { __builtin_amdgcn_s_setprio(1); _Pragma("unroll") for (int m = 0; m < 4; ++m) _Pragma("unroll") for (int n = 0; n < 2; ++n) _Pragma("unroll") for (int k = 0; k < 2; ++k) \
;         acc[ai][bj][m][n] = mma16<Epi::F16>(Bt[n][k], At[m][k], acc[ai][bj][m][n]); __builtin_amdgcn_s_setprio(0); } while (0)
; #define PG8_WAIT_V(n) asm volatile("s_waitcnt vmcnt(" #n ")" ::: "memory")
; #define PG8_WAIT_L(n) asm volatile("s_waitcnt lgkmcnt(" #n ")" ::: "memory")
; #define PG8_BAR __builtin_amdgcn_s_barrier()
; #define PG8_SCHED __builtin_amdgcn_sched_barrier(0)
; template <class Epi, class Sched, bool ALIGN_EPI = false, bool SP2 = false>
; __device__ __forceinline__ void gemm_phase(PG8_LAS unsigned char* lds, const Gemm g, const Sched& S, const Epi& E) {
;     ...
;         for (int t = 0; t < nt; t += 2) {
;             const bool last = (t == nt - 2);
;             const char* a1 = cA + (size_t)(t + 1) * kstep;
;             const char* a2 = last ? nA : cA + (size_t)(t + 2) * kstep; const char* b2 = last ? nB : cB + (size_t)(t + 2) * kstep;
;             const char* a3 = a2 + kstep; const char* b3 = b2 + kstep;
;             if (last && has_next) S.a_ready(nxt);
;             if constexpr (SP2) {
;             PG8_LDB(B0, 0, 0); PG8_LDB(B1, 0, 1); PG8_SCHED; PG8_LDA(At, 0, 0); PG8_STAGE(PG8_SA(1, 1), a1 + hstep, voffA);
;             PG8_WAIT_V(8); PG8_WAIT_L(0); PG8_BAR; PG8_MMA(0, 0, At, B0); PG8_MMA(0, 1, At, B1); PG8_BAR; PG8_SCHED;
;             PG8_LDA(At, 0, 1); PG8_STAGE(PG8_SB(0, 0), b2, voffB); PG8_STAGE(PG8_SB(0, 1), b2 + hstep, voffB); PG8_STAGE(PG8_SA(0, 0), a2, voffA);
.Lpeel_k8:
	s_add_u32 s30, s30, 0x80
	s_addc_u32 s31, s31, 0
	s_add_u32 s40, s34, 0x100
	s_addc_u32 s41, s35, 0
	s_mov_b32 s34, 0
	s_add_i32 s71, s34, 2
	s_add_u32 s72, s30, 0x80
	s_addc_u32 s35, s31, 0
	s_add_i32 s77, 0, 0x10000
	s_cmp_eq_u32 s62, s34
	s_cselect_b32 s35, s1, s35
	s_cselect_b32 s34, s0, s72
	s_cselect_b32 s73, s29, s41
	s_cselect_b32 s72, s28, s40
	s_add_i32 s82, 0, 0x14000
	v_add_u32_e32 v140, s77, v190
	v_add_u32_e32 v156, s82, v190
	ds_read_b128 v[120:123], v140
	ds_read_b128 v[132:135], v140 offset:1024
	ds_read_b128 v[136:139], v140 offset:2048
	ds_read_b128 v[140:143], v140 offset:3072
	ds_read_b128 v[144:147], v156
	ds_read_b128 v[148:151], v156 offset:1024
	ds_read_b128 v[152:155], v156 offset:2048
	ds_read_b128 v[156:159], v156 offset:3072
	v_lshl_add_u64 v[204:205], s[30:31], 0, v[166:167]
	s_add_i32 m0, s8, 0xc000
	ds_read_b128 v[170:173], v191
	ds_read_b128 v[174:177], v191 offset:1024
	ds_read_b128 v[178:181], v191 offset:2048
	ds_read_b128 v[182:185], v191 offset:3072
	ds_read_b128 v[186:189], v191 offset:4096
	ds_read_b128 v[192:195], v191 offset:5120
	ds_read_b128 v[196:199], v191 offset:6144
	ds_read_b128 v[200:203], v191 offset:7168
	global_load_lds_dwordx4 v[204:205], off
	v_lshl_add_u64 v[204:205], s[30:31], 0, v[168:169]
	s_add_i32 m0, s8, 0xe000
	s_nop 0
	global_load_lds_dwordx4 v[204:205], off
	s_waitcnt vmcnt(8)
	s_waitcnt lgkmcnt(0)
	s_barrier
	s_setprio 1
	v_mfma_f32_16x16x32_bf16 v[128:131], v[120:123], v[170:173], 0
	v_mfma_f32_16x16x32_bf16 v[124:127], v[136:139], v[170:173], 0
	v_mfma_f32_16x16x32_bf16 v[108:111], v[120:123], v[178:181], 0
	v_mfma_f32_16x16x32_bf16 v[104:107], v[136:139], v[178:181], 0
	v_mfma_f32_16x16x32_bf16 v[92:95], v[120:123], v[186:189], 0
	v_mfma_f32_16x16x32_bf16 v[88:91], v[136:139], v[186:189], 0
	v_mfma_f32_16x16x32_bf16 v[76:79], v[120:123], v[196:199], 0
	v_mfma_f32_16x16x32_bf16 v[72:75], v[136:139], v[196:199], 0
	v_mfma_f32_16x16x32_bf16 v[128:131], v[132:135], v[174:177], v[128:131]
	v_mfma_f32_16x16x32_bf16 v[124:127], v[140:143], v[174:177], v[124:127]
	v_mfma_f32_16x16x32_bf16 v[108:111], v[132:135], v[182:185], v[108:111]
	v_mfma_f32_16x16x32_bf16 v[104:107], v[140:143], v[182:185], v[104:107]
	v_mfma_f32_16x16x32_bf16 v[92:95], v[132:135], v[192:195], v[92:95]
	v_mfma_f32_16x16x32_bf16 v[88:91], v[140:143], v[192:195], v[88:91]
	v_mfma_f32_16x16x32_bf16 v[76:79], v[132:135], v[200:203], v[76:79]
	v_mfma_f32_16x16x32_bf16 v[72:75], v[140:143], v[200:203], v[72:75]
	s_setprio 0
	s_setprio 1
	v_mfma_f32_16x16x32_bf16 v[116:119], v[144:147], v[170:173], 0
	v_mfma_f32_16x16x32_bf16 v[112:115], v[152:155], v[170:173], 0
	v_mfma_f32_16x16x32_bf16 v[100:103], v[144:147], v[178:181], 0
	v_mfma_f32_16x16x32_bf16 v[96:99], v[152:155], v[178:181], 0
	v_mfma_f32_16x16x32_bf16 v[84:87], v[144:147], v[186:189], 0
	v_mfma_f32_16x16x32_bf16 v[80:83], v[152:155], v[186:189], 0
	v_mfma_f32_16x16x32_bf16 v[68:71], v[144:147], v[196:199], 0
	v_mfma_f32_16x16x32_bf16 v[64:67], v[152:155], v[196:199], 0
	v_mfma_f32_16x16x32_bf16 v[116:119], v[148:151], v[174:177], v[116:119]
	v_mfma_f32_16x16x32_bf16 v[112:115], v[156:159], v[174:177], v[112:115]
	v_mfma_f32_16x16x32_bf16 v[100:103], v[148:151], v[182:185], v[100:103]
	v_mfma_f32_16x16x32_bf16 v[96:99], v[156:159], v[182:185], v[96:99]
	v_mfma_f32_16x16x32_bf16 v[84:87], v[148:151], v[192:195], v[84:87]
	v_mfma_f32_16x16x32_bf16 v[80:83], v[156:159], v[192:195], v[80:83]
	v_mfma_f32_16x16x32_bf16 v[68:71], v[148:151], v[200:203], v[68:71]
	v_mfma_f32_16x16x32_bf16 v[64:67], v[156:159], v[200:203], v[64:67]
	s_setprio 0
	s_barrier
	s_add_i32 s77, s77, s3
	v_lshl_add_u64 v[204:205], s[72:73], 0, v[160:161]
	s_mov_b32 m0, s77
	ds_read_b128 v[170:173], v191 offset:16384
	ds_read_b128 v[174:177], v191 offset:17408
	ds_read_b128 v[178:181], v191 offset:18432
	ds_read_b128 v[182:185], v191 offset:19456
	ds_read_b128 v[186:189], v191 offset:20480
	ds_read_b128 v[192:195], v191 offset:21504
	ds_read_b128 v[196:199], v191 offset:22528
	ds_read_b128 v[200:203], v191 offset:23552
	global_load_lds_dwordx4 v[204:205], off
	s_add_i32 m0, s77, 0x2000
	v_lshl_add_u64 v[206:207], s[72:73], 0, v[162:163]
	s_add_u32 s72, s72, s42
	s_addc_u32 s73, s73, s43
	s_add_i32 s77, s82, s3
	global_load_lds_dwordx4 v[206:207], off
	v_lshl_add_u64 v[212:213], s[72:73], 0, v[160:161]
	s_mov_b32 m0, s77
	v_lshl_add_u64 v[214:215], s[72:73], 0, v[162:163]
	global_load_lds_dwordx4 v[212:213], off
	s_add_i32 m0, s77, 0x2000
	v_lshl_add_u64 v[216:217], s[34:35], 0, v[160:161]
	global_load_lds_dwordx4 v[214:215], off
	s_mov_b32 m0, s8
	v_lshl_add_u64 v[218:219], s[34:35], 0, v[162:163]
	global_load_lds_dwordx4 v[216:217], off
	s_mov_b32 m0, s9
	s_nop 0
	global_load_lds_dwordx4 v[218:219], off
	s_waitcnt vmcnt(8)
	s_waitcnt lgkmcnt(0)
	s_barrier
; #define PG8_STAGE(bufoff, gbase, voff) do { _Pragma("unroll") for (int _i = 0; _i < 2; ++_i) \
;         __builtin_amdgcn_global_load_lds((const unsigned*)((const char*)(gbase) + (voff)[_i]), (PG8_LAS unsigned*)(lds + (bufoff) + ldsw + _i * 8192), 16, 0, 0); } while (0)
; #define PG8_LDA(dst, b, h) do { _Pragma("unroll") for (int m = 0; m < 4; ++m) _Pragma("unroll") for (int k = 0; k < 2; ++k) dst[m][k] = *(const PG8_LAS bf16x8*)(lds + PG8_SA(b, h) + aoff + m * 2048 + k * 1024); } while (0)
; #define PG8_LDB(dst, b, h) do { _Pragma("unroll") for (int n = 0; n < 2; ++n) _Pragma("unroll") for (int k = 0; k < 2; ++k) dst[n][k] = *(const PG8_LAS bf16x8*)(lds + PG8_SB(b, h) + boff + n * 2048 + k * 1024); } while (0)
; #define PG8_MMA(ai, bj, At, Bt) do { __builtin_amdgcn_s_setprio(1); _Pragma("unroll") for (int m = 0; m < 4; ++m) _Pragma("unroll") for (int n = 0; n < 2; ++n) _Pragma("unroll") for (int k = 0; k < 2; ++k) \
;         acc[ai][bj][m][n] = mma16<Epi::F16>(Bt[n][k], At[m][k], acc[ai][bj][m][n]); __builtin_amdgcn_s_setprio(0); } while (0)
; #define PG8_WAIT_V(n) asm volatile("s_waitcnt vmcnt(" #n ")" ::: "memory")
; #define PG8_WAIT_L(n) asm volatile("s_waitcnt lgkmcnt(" #n ")" ::: "memory")
; #define PG8_BAR __builtin_amdgcn_s_barrier()
; #define PG8_SCHED __builtin_amdgcn_sched_barrier(0)
; template <class Epi, class Sched, bool ALIGN_EPI = false, bool SP2 = false>
; __device__ __forceinline__ void gemm_phase(PG8_LAS unsigned char* lds, const Gemm g, const Sched& S, const Epi& E) {
;     ...
;             PG8_WAIT_V(8); PG8_WAIT_L(0); PG8_BAR; PG8_MMA(1, 0, At, B0); PG8_MMA(1, 1, At, B1); PG8_BAR; PG8_SCHED;
;             PG8_LDB(B0, 1, 0); PG8_LDB(B1, 1, 1); PG8_SCHED; PG8_LDA(At, 1, 0); PG8_STAGE(PG8_SA(0, 1), a2 + hstep, voffA);
;             PG8_WAIT_V(8); PG8_WAIT_L(0); PG8_BAR; PG8_MMA(0, 0, At, B0); PG8_MMA(0, 1, At, B1); PG8_BAR; PG8_SCHED;
	s_setprio 1
	v_mfma_f32_16x16x32_bf16 v[60:63], v[120:123], v[170:173], 0
	v_mfma_f32_16x16x32_bf16 v[56:59], v[136:139], v[170:173], 0
	v_mfma_f32_16x16x32_bf16 v[44:47], v[120:123], v[178:181], 0
	v_mfma_f32_16x16x32_bf16 v[40:43], v[136:139], v[178:181], 0
	v_mfma_f32_16x16x32_bf16 v[28:31], v[120:123], v[186:189], 0
	v_mfma_f32_16x16x32_bf16 v[24:27], v[136:139], v[186:189], 0
	v_mfma_f32_16x16x32_bf16 v[12:15], v[120:123], v[196:199], 0
	v_mfma_f32_16x16x32_bf16 v[8:11], v[136:139], v[196:199], 0
	v_mfma_f32_16x16x32_bf16 v[60:63], v[132:135], v[174:177], v[60:63]
	v_mfma_f32_16x16x32_bf16 v[56:59], v[140:143], v[174:177], v[56:59]
	v_mfma_f32_16x16x32_bf16 v[44:47], v[132:135], v[182:185], v[44:47]
	v_mfma_f32_16x16x32_bf16 v[40:43], v[140:143], v[182:185], v[40:43]
	v_mfma_f32_16x16x32_bf16 v[28:31], v[132:135], v[192:195], v[28:31]
	v_mfma_f32_16x16x32_bf16 v[24:27], v[140:143], v[192:195], v[24:27]
	v_mfma_f32_16x16x32_bf16 v[12:15], v[132:135], v[200:203], v[12:15]
	v_mfma_f32_16x16x32_bf16 v[8:11], v[140:143], v[200:203], v[8:11]
	s_setprio 0
	s_setprio 1
	v_mfma_f32_16x16x32_bf16 v[52:55], v[144:147], v[170:173], 0
	v_mfma_f32_16x16x32_bf16 v[48:51], v[152:155], v[170:173], 0
	v_mfma_f32_16x16x32_bf16 v[36:39], v[144:147], v[178:181], 0
	v_mfma_f32_16x16x32_bf16 v[32:35], v[152:155], v[178:181], 0
	v_mfma_f32_16x16x32_bf16 v[20:23], v[144:147], v[186:189], 0
	v_mfma_f32_16x16x32_bf16 v[16:19], v[152:155], v[186:189], 0
	v_mfma_f32_16x16x32_bf16 v[4:7], v[144:147], v[196:199], 0
	v_mfma_f32_16x16x32_bf16 v[0:3], v[152:155], v[196:199], 0
	v_mfma_f32_16x16x32_bf16 v[52:55], v[148:151], v[174:177], v[52:55]
	v_mfma_f32_16x16x32_bf16 v[48:51], v[156:159], v[174:177], v[48:51]
	v_mfma_f32_16x16x32_bf16 v[36:39], v[148:151], v[182:185], v[36:39]
	v_mfma_f32_16x16x32_bf16 v[32:35], v[156:159], v[182:185], v[32:35]
	v_mfma_f32_16x16x32_bf16 v[20:23], v[148:151], v[192:195], v[20:23]
	v_mfma_f32_16x16x32_bf16 v[16:19], v[156:159], v[192:195], v[16:19]
	v_mfma_f32_16x16x32_bf16 v[4:7], v[148:151], v[200:203], v[4:7]
	v_mfma_f32_16x16x32_bf16 v[0:3], v[156:159], v[200:203], v[0:3]
	s_setprio 0
	s_barrier
	s_add_i32 s72, 0, 0x18000
	s_add_i32 s73, 0, 0x1c000
	v_add_u32_e32 v140, s72, v190
	v_add_u32_e32 v156, s73, v190
	ds_read_b128 v[120:123], v140
	ds_read_b128 v[132:135], v140 offset:1024
	ds_read_b128 v[136:139], v140 offset:2048
	ds_read_b128 v[140:143], v140 offset:3072
	ds_read_b128 v[144:147], v156
	ds_read_b128 v[148:151], v156 offset:1024
	ds_read_b128 v[152:155], v156 offset:2048
	ds_read_b128 v[156:159], v156 offset:3072
	s_add_u32 s34, s34, s42
	s_addc_u32 s35, s35, s43
	s_mov_b32 m0, s11
	v_lshl_add_u64 v[220:221], s[34:35], 0, v[160:161]
	ds_read_b128 v[170:173], v191 offset:32768
	ds_read_b128 v[174:177], v191 offset:33792
	ds_read_b128 v[178:181], v191 offset:34816
	ds_read_b128 v[182:185], v191 offset:35840
	ds_read_b128 v[186:189], v191 offset:36864
	ds_read_b128 v[192:195], v191 offset:37888
	ds_read_b128 v[196:199], v191 offset:38912
	ds_read_b128 v[200:203], v191 offset:39936
	global_load_lds_dwordx4 v[220:221], off
	v_lshl_add_u64 v[220:221], s[34:35], 0, v[162:163]
	s_mov_b32 m0, s36
	s_nop 0
	global_load_lds_dwordx4 v[220:221], off
	s_waitcnt vmcnt(8)
	s_waitcnt lgkmcnt(0)
	s_barrier
	s_setprio 1
	v_mfma_f32_16x16x32_bf16 v[128:131], v[120:123], v[170:173], v[128:131]
	v_mfma_f32_16x16x32_bf16 v[124:127], v[136:139], v[170:173], v[124:127]
	v_mfma_f32_16x16x32_bf16 v[108:111], v[120:123], v[178:181], v[108:111]
	v_mfma_f32_16x16x32_bf16 v[104:107], v[136:139], v[178:181], v[104:107]
	v_mfma_f32_16x16x32_bf16 v[92:95], v[120:123], v[186:189], v[92:95]
	v_mfma_f32_16x16x32_bf16 v[88:91], v[136:139], v[186:189], v[88:91]
	v_mfma_f32_16x16x32_bf16 v[76:79], v[120:123], v[196:199], v[76:79]
	v_mfma_f32_16x16x32_bf16 v[72:75], v[136:139], v[196:199], v[72:75]
	v_mfma_f32_16x16x32_bf16 v[128:131], v[132:135], v[174:177], v[128:131]
	v_mfma_f32_16x16x32_bf16 v[124:127], v[140:143], v[174:177], v[124:127]
	v_mfma_f32_16x16x32_bf16 v[108:111], v[132:135], v[182:185], v[108:111]
	v_mfma_f32_16x16x32_bf16 v[104:107], v[140:143], v[182:185], v[104:107]
	v_mfma_f32_16x16x32_bf16 v[92:95], v[132:135], v[192:195], v[92:95]
	v_mfma_f32_16x16x32_bf16 v[88:91], v[140:143], v[192:195], v[88:91]
	v_mfma_f32_16x16x32_bf16 v[76:79], v[132:135], v[200:203], v[76:79]
	v_mfma_f32_16x16x32_bf16 v[72:75], v[140:143], v[200:203], v[72:75]
	s_setprio 0
	s_setprio 1
	v_mfma_f32_16x16x32_bf16 v[116:119], v[144:147], v[170:173], v[116:119]
	v_mfma_f32_16x16x32_bf16 v[112:115], v[152:155], v[170:173], v[112:115]
	v_mfma_f32_16x16x32_bf16 v[100:103], v[144:147], v[178:181], v[100:103]
	v_mfma_f32_16x16x32_bf16 v[96:99], v[152:155], v[178:181], v[96:99]
	v_mfma_f32_16x16x32_bf16 v[84:87], v[144:147], v[186:189], v[84:87]
	v_mfma_f32_16x16x32_bf16 v[80:83], v[152:155], v[186:189], v[80:83]
	v_mfma_f32_16x16x32_bf16 v[68:71], v[144:147], v[196:199], v[68:71]
	v_mfma_f32_16x16x32_bf16 v[64:67], v[152:155], v[196:199], v[64:67]
	v_mfma_f32_16x16x32_bf16 v[116:119], v[148:151], v[174:177], v[116:119]
	v_mfma_f32_16x16x32_bf16 v[112:115], v[156:159], v[174:177], v[112:115]
	v_mfma_f32_16x16x32_bf16 v[100:103], v[148:151], v[182:185], v[100:103]
	v_mfma_f32_16x16x32_bf16 v[96:99], v[156:159], v[182:185], v[96:99]
	v_mfma_f32_16x16x32_bf16 v[84:87], v[148:151], v[192:195], v[84:87]
	v_mfma_f32_16x16x32_bf16 v[80:83], v[156:159], v[192:195], v[80:83]
	v_mfma_f32_16x16x32_bf16 v[68:71], v[148:151], v[200:203], v[68:71]
	v_mfma_f32_16x16x32_bf16 v[64:67], v[156:159], v[200:203], v[64:67]
	s_setprio 0
	s_barrier
; #define PG8_STAGE(bufoff, gbase, voff) do { _Pragma("unroll") for (int _i = 0; _i < 2; ++_i) \
;         __builtin_amdgcn_global_load_lds((const unsigned*)((const char*)(gbase) + (voff)[_i]), (PG8_LAS unsigned*)(lds + (bufoff) + ldsw + _i * 8192), 16, 0, 0); } while (0)
; #define PG8_LDA(dst, b, h) do { _Pragma("unroll") for (int m = 0; m < 4; ++m) _Pragma("unroll") for (int k = 0; k < 2; ++k) dst[m][k] = *(const PG8_LAS bf16x8*)(lds + PG8_SA(b, h) + aoff + m * 2048 + k * 1024); } while (0)
; #define PG8_LDB(dst, b, h) do { _Pragma("unroll") for (int n = 0; n < 2; ++n) _Pragma("unroll") for (int k = 0; k < 2; ++k) dst[n][k] = *(const PG8_LAS bf16x8*)(lds + PG8_SB(b, h) + boff + n * 2048 + k * 1024); } while (0)
; #define PG8_MMA(ai, bj, At, Bt) do { __builtin_amdgcn_s_setprio(1); _Pragma("unroll") for (int m = 0; m < 4; ++m) _Pragma("unroll") for (int n = 0; n < 2; ++n) _Pragma("unroll") for (int k = 0; k < 2; ++k) \
;         acc[ai][bj][m][n] = mma16<Epi::F16>(Bt[n][k], At[m][k], acc[ai][bj][m][n]); __builtin_amdgcn_s_setprio(0); } while (0)
; #define PG8_WAIT_V(n) asm volatile("s_waitcnt vmcnt(" #n ")" ::: "memory")
; #define PG8_WAIT_L(n) asm volatile("s_waitcnt lgkmcnt(" #n ")" ::: "memory")
; template <class Epi, class Sched, bool ALIGN_EPI = false, bool SP2 = false>
; __device__ __forceinline__ void gemm_phase(PG8_LAS unsigned char* lds, const Gemm g, const Sched& S, const Epi& E) {
;     ...
;         for (int t = 0; t < nt; t += 2) {
;             const bool last = (t == nt - 2);
;             const char* a1 = cA + (size_t)(t + 1) * kstep;
;             const char* a2 = last ? nA : cA + (size_t)(t + 2) * kstep; const char* b2 = last ? nB : cB + (size_t)(t + 2) * kstep;
;             const char* a3 = a2 + kstep; const char* b3 = b2 + kstep;
;             if (last && has_next) S.a_ready(nxt);
;             if constexpr (SP2) {
;             PG8_LDB(B0, 0, 0); PG8_LDB(B1, 0, 1); PG8_SCHED; PG8_LDA(At, 0, 0); PG8_STAGE(PG8_SA(1, 1), a1 + hstep, voffA);
;             PG8_WAIT_V(8); PG8_WAIT_L(0); PG8_BAR; PG8_MMA(0, 0, At, B0); PG8_MMA(0, 1, At, B1); PG8_BAR; PG8_SCHED;
;     ...
;             PG8_LDA(At, 1, 1); PG8_STAGE(PG8_SB(1, 0), b3, voffB); PG8_STAGE(PG8_SB(1, 1), b3 + hstep, voffB); PG8_STAGE(PG8_SA(1, 0), a3, voffA);
;             PG8_WAIT_V(8); PG8_WAIT_L(0); PG8_BAR; PG8_MMA(1, 0, At, B0); PG8_MMA(1, 1, At, B1); PG8_BAR; PG8_SCHED;
	s_add_i32 s34, s72, s3
	v_lshl_add_u64 v[204:205], v[204:205], 0, s[20:21]
	s_mov_b32 m0, s34
	ds_read_b128 v[170:173], v191 offset:49152
	ds_read_b128 v[174:177], v191 offset:50176
	ds_read_b128 v[178:181], v191 offset:51200
	ds_read_b128 v[182:185], v191 offset:52224
	ds_read_b128 v[186:189], v191 offset:53248
	ds_read_b128 v[192:195], v191 offset:54272
	ds_read_b128 v[196:199], v191 offset:55296
	ds_read_b128 v[200:203], v191 offset:56320
	global_load_lds_dwordx4 v[204:205], off
	v_lshl_add_u64 v[204:205], v[206:207], 0, s[20:21]
	s_add_i32 m0, s34, 0x2000
	s_add_i32 s34, s73, s3
	global_load_lds_dwordx4 v[204:205], off
	v_lshl_add_u64 v[204:205], v[212:213], 0, s[20:21]
	s_mov_b32 m0, s34
	s_nop 0
	global_load_lds_dwordx4 v[204:205], off
	v_lshl_add_u64 v[204:205], v[214:215], 0, s[20:21]
	s_add_i32 m0, s34, 0x2000
	s_nop 0
	global_load_lds_dwordx4 v[204:205], off
	v_lshl_add_u64 v[204:205], v[216:217], 0, s[20:21]
	s_mov_b32 m0, s60
	s_nop 0
	global_load_lds_dwordx4 v[204:205], off
	v_lshl_add_u64 v[204:205], v[218:219], 0, s[20:21]
	s_mov_b32 m0, s61
	s_nop 0
	global_load_lds_dwordx4 v[204:205], off
	s_waitcnt vmcnt(8)
	s_waitcnt lgkmcnt(0)
	s_barrier
	s_setprio 1
	v_mfma_f32_16x16x32_bf16 v[60:63], v[120:123], v[170:173], v[60:63]
	v_mfma_f32_16x16x32_bf16 v[56:59], v[136:139], v[170:173], v[56:59]
	v_mfma_f32_16x16x32_bf16 v[44:47], v[120:123], v[178:181], v[44:47]
	v_mfma_f32_16x16x32_bf16 v[40:43], v[136:139], v[178:181], v[40:43]
	v_mfma_f32_16x16x32_bf16 v[28:31], v[120:123], v[186:189], v[28:31]
	v_mfma_f32_16x16x32_bf16 v[24:27], v[136:139], v[186:189], v[24:27]
	v_mfma_f32_16x16x32_bf16 v[12:15], v[120:123], v[196:199], v[12:15]
	v_mfma_f32_16x16x32_bf16 v[8:11], v[136:139], v[196:199], v[8:11]
	v_mfma_f32_16x16x32_bf16 v[60:63], v[132:135], v[174:177], v[60:63]
	v_mfma_f32_16x16x32_bf16 v[56:59], v[140:143], v[174:177], v[56:59]
	v_mfma_f32_16x16x32_bf16 v[44:47], v[132:135], v[182:185], v[44:47]
	v_mfma_f32_16x16x32_bf16 v[40:43], v[140:143], v[182:185], v[40:43]
	v_mfma_f32_16x16x32_bf16 v[28:31], v[132:135], v[192:195], v[28:31]
	v_mfma_f32_16x16x32_bf16 v[24:27], v[140:143], v[192:195], v[24:27]
	v_mfma_f32_16x16x32_bf16 v[12:15], v[132:135], v[200:203], v[12:15]
	v_mfma_f32_16x16x32_bf16 v[8:11], v[140:143], v[200:203], v[8:11]
	s_setprio 0
	s_setprio 1
	v_mfma_f32_16x16x32_bf16 v[52:55], v[144:147], v[170:173], v[52:55]
	v_mfma_f32_16x16x32_bf16 v[48:51], v[152:155], v[170:173], v[48:51]
	v_mfma_f32_16x16x32_bf16 v[36:39], v[144:147], v[178:181], v[36:39]
	v_mfma_f32_16x16x32_bf16 v[32:35], v[152:155], v[178:181], v[32:35]
	v_mfma_f32_16x16x32_bf16 v[20:23], v[144:147], v[186:189], v[20:23]
	v_mfma_f32_16x16x32_bf16 v[16:19], v[152:155], v[186:189], v[16:19]
	v_mfma_f32_16x16x32_bf16 v[4:7], v[144:147], v[196:199], v[4:7]
	v_mfma_f32_16x16x32_bf16 v[0:3], v[152:155], v[196:199], v[0:3]
	v_mfma_f32_16x16x32_bf16 v[52:55], v[148:151], v[174:177], v[52:55]
	v_mfma_f32_16x16x32_bf16 v[48:51], v[156:159], v[174:177], v[48:51]
	v_mfma_f32_16x16x32_bf16 v[36:39], v[148:151], v[182:185], v[36:39]
	v_mfma_f32_16x16x32_bf16 v[32:35], v[156:159], v[182:185], v[32:35]
	v_mfma_f32_16x16x32_bf16 v[20:23], v[148:151], v[192:195], v[20:23]
	v_mfma_f32_16x16x32_bf16 v[16:19], v[156:159], v[192:195], v[16:19]
	v_mfma_f32_16x16x32_bf16 v[4:7], v[148:151], v[200:203], v[4:7]
	v_mfma_f32_16x16x32_bf16 v[0:3], v[156:159], v[200:203], v[0:3]
	s_setprio 0
	s_barrier
	s_add_u32 s30, s30, 0x100
	s_addc_u32 s31, s31, 0
	s_add_u32 s40, s40, 0x100
	s_addc_u32 s41, s41, 0
	s_cmp_ge_i32 s71, s48
	s_mov_b32 s34, s71
	s_cbranch_scc0 .LBB0_1170
	s_branch .LBB0_1171
.LBB0_1170:
	s_add_i32 s71, s34, 2
	s_add_u32 s72, s30, 0x80
	s_addc_u32 s35, s31, 0
	s_add_i32 s77, 0, 0x10000
	s_cmp_eq_u32 s62, s34
	s_cselect_b32 s35, s1, s35
	s_cselect_b32 s34, s0, s72
	s_cselect_b32 s73, s29, s41
	s_cselect_b32 s72, s28, s40
	s_add_i32 s82, 0, 0x14000
	v_add_u32_e32 v140, s77, v190
	v_add_u32_e32 v156, s82, v190
	ds_read_b128 v[120:123], v140
	ds_read_b128 v[132:135], v140 offset:1024
	ds_read_b128 v[136:139], v140 offset:2048
	ds_read_b128 v[140:143], v140 offset:3072
	ds_read_b128 v[144:147], v156
	ds_read_b128 v[148:151], v156 offset:1024
	ds_read_b128 v[152:155], v156 offset:2048
	ds_read_b128 v[156:159], v156 offset:3072
	v_lshl_add_u64 v[204:205], s[30:31], 0, v[166:167]
	s_add_i32 m0, s8, 0xc000
	ds_read_b128 v[170:173], v191
	ds_read_b128 v[174:177], v191 offset:1024
	ds_read_b128 v[178:181], v191 offset:2048
	ds_read_b128 v[182:185], v191 offset:3072
	ds_read_b128 v[186:189], v191 offset:4096
	ds_read_b128 v[192:195], v191 offset:5120
	ds_read_b128 v[196:199], v191 offset:6144
	ds_read_b128 v[200:203], v191 offset:7168
	global_load_lds_dwordx4 v[204:205], off
	v_lshl_add_u64 v[204:205], s[30:31], 0, v[168:169]
	s_add_i32 m0, s8, 0xe000
	s_nop 0
	global_load_lds_dwordx4 v[204:205], off
	s_waitcnt vmcnt(8)
	s_waitcnt lgkmcnt(0)
	s_barrier
; #define PG8_STAGE(bufoff, gbase, voff) do { _Pragma("unroll") for (int _i = 0; _i < 2; ++_i) \
;         __builtin_amdgcn_global_load_lds((const unsigned*)((const char*)(gbase) + (voff)[_i]), (PG8_LAS unsigned*)(lds + (bufoff) + ldsw + _i * 8192), 16, 0, 0); } while (0)
; #define PG8_LDA(dst, b, h) do { _Pragma("unroll") for (int m = 0; m < 4; ++m) _Pragma("unroll") for (int k = 0; k < 2; ++k) dst[m][k] = *(const PG8_LAS bf16x8*)(lds + PG8_SA(b, h) + aoff + m * 2048 + k * 1024); } while (0)
; #define PG8_LDB(dst, b, h) do { _Pragma("unroll") for (int n = 0; n < 2; ++n) _Pragma("unroll") for (int k = 0; k < 2; ++k) dst[n][k] = *(const PG8_LAS bf16x8*)(lds + PG8_SB(b, h) + boff + n * 2048 + k * 1024); } while (0)
; #define PG8_MMA(ai, bj, At, Bt) do { __builtin_amdgcn_s_setprio(1); _Pragma("unroll") for (int m = 0; m < 4; ++m) _Pragma("unroll") for (int n = 0; n < 2; ++n) _Pragma("unroll") for (int k = 0; k < 2; ++k) \
;         acc[ai][bj][m][n] = mma16<Epi::F16>(Bt[n][k], At[m][k], acc[ai][bj][m][n]); __builtin_amdgcn_s_setprio(0); } while (0)
; #define PG8_WAIT_V(n) asm volatile("s_waitcnt vmcnt(" #n ")" ::: "memory")
; #define PG8_WAIT_L(n) asm volatile("s_waitcnt lgkmcnt(" #n ")" ::: "memory")
; #define PG8_BAR __builtin_amdgcn_s_barrier()
; #define PG8_SCHED __builtin_amdgcn_sched_barrier(0)
; template <class Epi, class Sched, bool ALIGN_EPI = false, bool SP2 = false>
; __device__ __forceinline__ void gemm_phase(PG8_LAS unsigned char* lds, const Gemm g, const Sched& S, const Epi& E) {
;     ...
;             PG8_WAIT_V(8); PG8_WAIT_L(0); PG8_BAR; PG8_MMA(0, 0, At, B0); PG8_MMA(0, 1, At, B1); PG8_BAR; PG8_SCHED;
;             PG8_LDA(At, 0, 1); PG8_STAGE(PG8_SB(0, 0), b2, voffB); PG8_STAGE(PG8_SB(0, 1), b2 + hstep, voffB); PG8_STAGE(PG8_SA(0, 0), a2, voffA);
;             PG8_WAIT_V(8); PG8_WAIT_L(0); PG8_BAR; PG8_MMA(1, 0, At, B0); PG8_MMA(1, 1, At, B1); PG8_BAR; PG8_SCHED;
;             PG8_LDB(B0, 1, 0); PG8_LDB(B1, 1, 1); PG8_SCHED; PG8_LDA(At, 1, 0); PG8_STAGE(PG8_SA(0, 1), a2 + hstep, voffA);
;             PG8_WAIT_V(8); PG8_WAIT_L(0); PG8_BAR; PG8_MMA(0, 0, At, B0); PG8_MMA(0, 1, At, B1); PG8_BAR; PG8_SCHED;
;             PG8_LDA(At, 1, 1); PG8_STAGE(PG8_SB(1, 0), b3, voffB); PG8_STAGE(PG8_SB(1, 1), b3 + hstep, voffB); PG8_STAGE(PG8_SA(1, 0), a3, voffA);
	s_setprio 1
	v_mfma_f32_16x16x32_bf16 v[128:131], v[120:123], v[170:173], v[128:131]
	v_mfma_f32_16x16x32_bf16 v[124:127], v[136:139], v[170:173], v[124:127]
	v_mfma_f32_16x16x32_bf16 v[108:111], v[120:123], v[178:181], v[108:111]
	v_mfma_f32_16x16x32_bf16 v[104:107], v[136:139], v[178:181], v[104:107]
	v_mfma_f32_16x16x32_bf16 v[92:95], v[120:123], v[186:189], v[92:95]
	v_mfma_f32_16x16x32_bf16 v[88:91], v[136:139], v[186:189], v[88:91]
	v_mfma_f32_16x16x32_bf16 v[76:79], v[120:123], v[196:199], v[76:79]
	v_mfma_f32_16x16x32_bf16 v[72:75], v[136:139], v[196:199], v[72:75]
	v_mfma_f32_16x16x32_bf16 v[128:131], v[132:135], v[174:177], v[128:131]
	v_mfma_f32_16x16x32_bf16 v[124:127], v[140:143], v[174:177], v[124:127]
	v_mfma_f32_16x16x32_bf16 v[108:111], v[132:135], v[182:185], v[108:111]
	v_mfma_f32_16x16x32_bf16 v[104:107], v[140:143], v[182:185], v[104:107]
	v_mfma_f32_16x16x32_bf16 v[92:95], v[132:135], v[192:195], v[92:95]
	v_mfma_f32_16x16x32_bf16 v[88:91], v[140:143], v[192:195], v[88:91]
	v_mfma_f32_16x16x32_bf16 v[76:79], v[132:135], v[200:203], v[76:79]
	v_mfma_f32_16x16x32_bf16 v[72:75], v[140:143], v[200:203], v[72:75]
	s_setprio 0
	s_setprio 1
	v_mfma_f32_16x16x32_bf16 v[116:119], v[144:147], v[170:173], v[116:119]
	v_mfma_f32_16x16x32_bf16 v[112:115], v[152:155], v[170:173], v[112:115]
	v_mfma_f32_16x16x32_bf16 v[100:103], v[144:147], v[178:181], v[100:103]
	v_mfma_f32_16x16x32_bf16 v[96:99], v[152:155], v[178:181], v[96:99]
	v_mfma_f32_16x16x32_bf16 v[84:87], v[144:147], v[186:189], v[84:87]
	v_mfma_f32_16x16x32_bf16 v[80:83], v[152:155], v[186:189], v[80:83]
	v_mfma_f32_16x16x32_bf16 v[68:71], v[144:147], v[196:199], v[68:71]
	v_mfma_f32_16x16x32_bf16 v[64:67], v[152:155], v[196:199], v[64:67]
	v_mfma_f32_16x16x32_bf16 v[116:119], v[148:151], v[174:177], v[116:119]
	v_mfma_f32_16x16x32_bf16 v[112:115], v[156:159], v[174:177], v[112:115]
	v_mfma_f32_16x16x32_bf16 v[100:103], v[148:151], v[182:185], v[100:103]
	v_mfma_f32_16x16x32_bf16 v[96:99], v[156:159], v[182:185], v[96:99]
	v_mfma_f32_16x16x32_bf16 v[84:87], v[148:151], v[192:195], v[84:87]
	v_mfma_f32_16x16x32_bf16 v[80:83], v[156:159], v[192:195], v[80:83]
	v_mfma_f32_16x16x32_bf16 v[68:71], v[148:151], v[200:203], v[68:71]
	v_mfma_f32_16x16x32_bf16 v[64:67], v[156:159], v[200:203], v[64:67]
	s_setprio 0
	s_barrier
	s_add_i32 s77, s77, s3
	v_lshl_add_u64 v[204:205], s[72:73], 0, v[160:161]
	s_mov_b32 m0, s77
	ds_read_b128 v[170:173], v191 offset:16384
	ds_read_b128 v[174:177], v191 offset:17408
	ds_read_b128 v[178:181], v191 offset:18432
	ds_read_b128 v[182:185], v191 offset:19456
	ds_read_b128 v[186:189], v191 offset:20480
	ds_read_b128 v[192:195], v191 offset:21504
	ds_read_b128 v[196:199], v191 offset:22528
	ds_read_b128 v[200:203], v191 offset:23552
	global_load_lds_dwordx4 v[204:205], off
	s_add_i32 m0, s77, 0x2000
	v_lshl_add_u64 v[206:207], s[72:73], 0, v[162:163]
	s_add_u32 s72, s72, s42
	s_addc_u32 s73, s73, s43
	s_add_i32 s77, s82, s3
	global_load_lds_dwordx4 v[206:207], off
	v_lshl_add_u64 v[212:213], s[72:73], 0, v[160:161]
	s_mov_b32 m0, s77
	v_lshl_add_u64 v[214:215], s[72:73], 0, v[162:163]
	global_load_lds_dwordx4 v[212:213], off
	s_add_i32 m0, s77, 0x2000
	v_lshl_add_u64 v[216:217], s[34:35], 0, v[160:161]
	global_load_lds_dwordx4 v[214:215], off
	s_mov_b32 m0, s8
	v_lshl_add_u64 v[218:219], s[34:35], 0, v[162:163]
	global_load_lds_dwordx4 v[216:217], off
	s_mov_b32 m0, s9
	s_nop 0
	global_load_lds_dwordx4 v[218:219], off
	s_waitcnt vmcnt(8)
	s_waitcnt lgkmcnt(0)
	s_barrier
	s_setprio 1
	v_mfma_f32_16x16x32_bf16 v[60:63], v[120:123], v[170:173], v[60:63]
	v_mfma_f32_16x16x32_bf16 v[56:59], v[136:139], v[170:173], v[56:59]
	v_mfma_f32_16x16x32_bf16 v[44:47], v[120:123], v[178:181], v[44:47]
	v_mfma_f32_16x16x32_bf16 v[40:43], v[136:139], v[178:181], v[40:43]
	v_mfma_f32_16x16x32_bf16 v[28:31], v[120:123], v[186:189], v[28:31]
	v_mfma_f32_16x16x32_bf16 v[24:27], v[136:139], v[186:189], v[24:27]
	v_mfma_f32_16x16x32_bf16 v[12:15], v[120:123], v[196:199], v[12:15]
	v_mfma_f32_16x16x32_bf16 v[8:11], v[136:139], v[196:199], v[8:11]
	v_mfma_f32_16x16x32_bf16 v[60:63], v[132:135], v[174:177], v[60:63]
	v_mfma_f32_16x16x32_bf16 v[56:59], v[140:143], v[174:177], v[56:59]
	v_mfma_f32_16x16x32_bf16 v[44:47], v[132:135], v[182:185], v[44:47]
	v_mfma_f32_16x16x32_bf16 v[40:43], v[140:143], v[182:185], v[40:43]
	v_mfma_f32_16x16x32_bf16 v[28:31], v[132:135], v[192:195], v[28:31]
	v_mfma_f32_16x16x32_bf16 v[24:27], v[140:143], v[192:195], v[24:27]
	v_mfma_f32_16x16x32_bf16 v[12:15], v[132:135], v[200:203], v[12:15]
	v_mfma_f32_16x16x32_bf16 v[8:11], v[140:143], v[200:203], v[8:11]
	s_setprio 0
	s_setprio 1
	v_mfma_f32_16x16x32_bf16 v[52:55], v[144:147], v[170:173], v[52:55]
	v_mfma_f32_16x16x32_bf16 v[48:51], v[152:155], v[170:173], v[48:51]
	v_mfma_f32_16x16x32_bf16 v[36:39], v[144:147], v[178:181], v[36:39]
	v_mfma_f32_16x16x32_bf16 v[32:35], v[152:155], v[178:181], v[32:35]
	v_mfma_f32_16x16x32_bf16 v[20:23], v[144:147], v[186:189], v[20:23]
	v_mfma_f32_16x16x32_bf16 v[16:19], v[152:155], v[186:189], v[16:19]
	v_mfma_f32_16x16x32_bf16 v[4:7], v[144:147], v[196:199], v[4:7]
	v_mfma_f32_16x16x32_bf16 v[0:3], v[152:155], v[196:199], v[0:3]
	v_mfma_f32_16x16x32_bf16 v[52:55], v[148:151], v[174:177], v[52:55]
	v_mfma_f32_16x16x32_bf16 v[48:51], v[156:159], v[174:177], v[48:51]
	v_mfma_f32_16x16x32_bf16 v[36:39], v[148:151], v[182:185], v[36:39]
	v_mfma_f32_16x16x32_bf16 v[32:35], v[156:159], v[182:185], v[32:35]
	v_mfma_f32_16x16x32_bf16 v[20:23], v[148:151], v[192:195], v[20:23]
	v_mfma_f32_16x16x32_bf16 v[16:19], v[156:159], v[192:195], v[16:19]
	v_mfma_f32_16x16x32_bf16 v[4:7], v[148:151], v[200:203], v[4:7]
	v_mfma_f32_16x16x32_bf16 v[0:3], v[156:159], v[200:203], v[0:3]
	s_setprio 0
	s_barrier
; #define PG8_STAGE(bufoff, gbase, voff) do { _Pragma("unroll") for (int _i = 0; _i < 2; ++_i) \
;         __builtin_amdgcn_global_load_lds((const unsigned*)((const char*)(gbase) + (voff)[_i]), (PG8_LAS unsigned*)(lds + (bufoff) + ldsw + _i * 8192), 16, 0, 0); } while (0)
; #define PG8_LDA(dst, b, h) do { _Pragma("unroll") for (int m = 0; m < 4; ++m) _Pragma("unroll") for (int k = 0; k < 2; ++k) dst[m][k] = *(const PG8_LAS bf16x8*)(lds + PG8_SA(b, h) + aoff + m * 2048 + k * 1024); } while (0)
; #define PG8_LDB(dst, b, h) do { _Pragma("unroll") for (int n = 0; n < 2; ++n) _Pragma("unroll") for (int k = 0; k < 2; ++k) dst[n][k] = *(const PG8_LAS bf16x8*)(lds + PG8_SB(b, h) + boff + n * 2048 + k * 1024); } while (0)
; #define PG8_MMA(ai, bj, At, Bt) do { __builtin_amdgcn_s_setprio(1); _Pragma("unroll") for (int m = 0; m < 4; ++m) _Pragma("unroll") for (int n = 0; n < 2; ++n) _Pragma("unroll") for (int k = 0; k < 2; ++k) \
;         acc[ai][bj][m][n] = mma16<Epi::F16>(Bt[n][k], At[m][k], acc[ai][bj][m][n]); __builtin_amdgcn_s_setprio(0); } while (0)
; #define PG8_WAIT_V(n) asm volatile("s_waitcnt vmcnt(" #n ")" ::: "memory")
; #define PG8_WAIT_L(n) asm volatile("s_waitcnt lgkmcnt(" #n ")" ::: "memory")
; #define PG8_BAR __builtin_amdgcn_s_barrier()
; #define PG8_SCHED __builtin_amdgcn_sched_barrier(0)
; template <class Epi, class Sched, bool ALIGN_EPI = false, bool SP2 = false>
; __device__ __forceinline__ void gemm_phase(PG8_LAS unsigned char* lds, const Gemm g, const Sched& S, const Epi& E) {
;     ...
;             PG8_LDB(B0, 1, 0); PG8_LDB(B1, 1, 1); PG8_SCHED; PG8_LDA(At, 1, 0); PG8_STAGE(PG8_SA(0, 1), a2 + hstep, voffA);
;             PG8_WAIT_V(8); PG8_WAIT_L(0); PG8_BAR; PG8_MMA(0, 0, At, B0); PG8_MMA(0, 1, At, B1); PG8_BAR; PG8_SCHED;
	s_add_i32 s72, 0, 0x18000
	s_add_i32 s73, 0, 0x1c000
	v_add_u32_e32 v140, s72, v190
	v_add_u32_e32 v156, s73, v190
	ds_read_b128 v[120:123], v140
	ds_read_b128 v[132:135], v140 offset:1024
	ds_read_b128 v[136:139], v140 offset:2048
	ds_read_b128 v[140:143], v140 offset:3072
	ds_read_b128 v[144:147], v156
	ds_read_b128 v[148:151], v156 offset:1024
	ds_read_b128 v[152:155], v156 offset:2048
	ds_read_b128 v[156:159], v156 offset:3072
	s_add_u32 s34, s34, s42
	s_addc_u32 s35, s35, s43
	s_mov_b32 m0, s11
	v_lshl_add_u64 v[220:221], s[34:35], 0, v[160:161]
	ds_read_b128 v[170:173], v191 offset:32768
	ds_read_b128 v[174:177], v191 offset:33792
	ds_read_b128 v[178:181], v191 offset:34816
	ds_read_b128 v[182:185], v191 offset:35840
	ds_read_b128 v[186:189], v191 offset:36864
	ds_read_b128 v[192:195], v191 offset:37888
	ds_read_b128 v[196:199], v191 offset:38912
	ds_read_b128 v[200:203], v191 offset:39936
	global_load_lds_dwordx4 v[220:221], off
	v_lshl_add_u64 v[220:221], s[34:35], 0, v[162:163]
	s_mov_b32 m0, s36
	s_nop 0
	global_load_lds_dwordx4 v[220:221], off
	s_waitcnt vmcnt(8)
	s_waitcnt lgkmcnt(0)
	s_barrier
	s_setprio 1
	v_mfma_f32_16x16x32_bf16 v[128:131], v[120:123], v[170:173], v[128:131]
	v_mfma_f32_16x16x32_bf16 v[124:127], v[136:139], v[170:173], v[124:127]
	v_mfma_f32_16x16x32_bf16 v[108:111], v[120:123], v[178:181], v[108:111]
	v_mfma_f32_16x16x32_bf16 v[104:107], v[136:139], v[178:181], v[104:107]
	v_mfma_f32_16x16x32_bf16 v[92:95], v[120:123], v[186:189], v[92:95]
	v_mfma_f32_16x16x32_bf16 v[88:91], v[136:139], v[186:189], v[88:91]
	v_mfma_f32_16x16x32_bf16 v[76:79], v[120:123], v[196:199], v[76:79]
	v_mfma_f32_16x16x32_bf16 v[72:75], v[136:139], v[196:199], v[72:75]
	v_mfma_f32_16x16x32_bf16 v[128:131], v[132:135], v[174:177], v[128:131]
	v_mfma_f32_16x16x32_bf16 v[124:127], v[140:143], v[174:177], v[124:127]
	v_mfma_f32_16x16x32_bf16 v[108:111], v[132:135], v[182:185], v[108:111]
	v_mfma_f32_16x16x32_bf16 v[104:107], v[140:143], v[182:185], v[104:107]
	v_mfma_f32_16x16x32_bf16 v[92:95], v[132:135], v[192:195], v[92:95]
	v_mfma_f32_16x16x32_bf16 v[88:91], v[140:143], v[192:195], v[88:91]
	v_mfma_f32_16x16x32_bf16 v[76:79], v[132:135], v[200:203], v[76:79]
	v_mfma_f32_16x16x32_bf16 v[72:75], v[140:143], v[200:203], v[72:75]
	s_setprio 0
	s_setprio 1
	v_mfma_f32_16x16x32_bf16 v[116:119], v[144:147], v[170:173], v[116:119]
	v_mfma_f32_16x16x32_bf16 v[112:115], v[152:155], v[170:173], v[112:115]
	v_mfma_f32_16x16x32_bf16 v[100:103], v[144:147], v[178:181], v[100:103]
	v_mfma_f32_16x16x32_bf16 v[96:99], v[152:155], v[178:181], v[96:99]
	v_mfma_f32_16x16x32_bf16 v[84:87], v[144:147], v[186:189], v[84:87]
	v_mfma_f32_16x16x32_bf16 v[80:83], v[152:155], v[186:189], v[80:83]
	v_mfma_f32_16x16x32_bf16 v[68:71], v[144:147], v[196:199], v[68:71]
	v_mfma_f32_16x16x32_bf16 v[64:67], v[152:155], v[196:199], v[64:67]
	v_mfma_f32_16x16x32_bf16 v[116:119], v[148:151], v[174:177], v[116:119]
	v_mfma_f32_16x16x32_bf16 v[112:115], v[156:159], v[174:177], v[112:115]
	v_mfma_f32_16x16x32_bf16 v[100:103], v[148:151], v[182:185], v[100:103]
	v_mfma_f32_16x16x32_bf16 v[96:99], v[156:159], v[182:185], v[96:99]
	v_mfma_f32_16x16x32_bf16 v[84:87], v[148:151], v[192:195], v[84:87]
	v_mfma_f32_16x16x32_bf16 v[80:83], v[156:159], v[192:195], v[80:83]
	v_mfma_f32_16x16x32_bf16 v[68:71], v[148:151], v[200:203], v[68:71]
	v_mfma_f32_16x16x32_bf16 v[64:67], v[156:159], v[200:203], v[64:67]
	s_setprio 0
	s_barrier
; #define PG8_STAGE(bufoff, gbase, voff) do { _Pragma("unroll") for (int _i = 0; _i < 2; ++_i) \
;         __builtin_amdgcn_global_load_lds((const unsigned*)((const char*)(gbase) + (voff)[_i]), (PG8_LAS unsigned*)(lds + (bufoff) + ldsw + _i * 8192), 16, 0, 0); } while (0)
; #define PG8_LDA(dst, b, h) do { _Pragma("unroll") for (int m = 0; m < 4; ++m) _Pragma("unroll") for (int k = 0; k < 2; ++k) dst[m][k] = *(const PG8_LAS bf16x8*)(lds + PG8_SA(b, h) + aoff + m * 2048 + k * 1024); } while (0)
; #define PG8_MMA(ai, bj, At, Bt) do { __builtin_amdgcn_s_setprio(1); _Pragma("unroll") for (int m = 0; m < 4; ++m) _Pragma("unroll") for (int n = 0; n < 2; ++n) _Pragma("unroll") for (int k = 0; k < 2; ++k) \
;         acc[ai][bj][m][n] = mma16<Epi::F16>(Bt[n][k], At[m][k], acc[ai][bj][m][n]); __builtin_amdgcn_s_setprio(0); } while (0)
; #define PG8_WAIT_V(n) asm volatile("s_waitcnt vmcnt(" #n ")" ::: "memory")
; #define PG8_WAIT_L(n) asm volatile("s_waitcnt lgkmcnt(" #n ")" ::: "memory")
; #define PG8_BAR __builtin_amdgcn_s_barrier()
; #define PG8_SCHED __builtin_amdgcn_sched_barrier(0)
; template <class Epi, class Sched, bool ALIGN_EPI = false, bool SP2 = false>
; __device__ __forceinline__ void gemm_phase(PG8_LAS unsigned char* lds, const Gemm g, const Sched& S, const Epi& E) {
;     ...
;         for (int t = 0; t < nt; t += 2) {
;             const bool last = (t == nt - 2);
;             const char* a1 = cA + (size_t)(t + 1) * kstep;
;             const char* a2 = last ? nA : cA + (size_t)(t + 2) * kstep; const char* b2 = last ? nB : cB + (size_t)(t + 2) * kstep;
;     ...
;             PG8_LDA(At, 1, 1); PG8_STAGE(PG8_SB(1, 0), b3, voffB); PG8_STAGE(PG8_SB(1, 1), b3 + hstep, voffB); PG8_STAGE(PG8_SA(1, 0), a3, voffA);
;             PG8_WAIT_V(8); PG8_WAIT_L(0); PG8_BAR; PG8_MMA(1, 0, At, B0); PG8_MMA(1, 1, At, B1); PG8_BAR; PG8_SCHED;
	s_add_i32 s34, s72, s3
	v_lshl_add_u64 v[204:205], v[204:205], 0, s[20:21]
	s_mov_b32 m0, s34
	ds_read_b128 v[170:173], v191 offset:49152
	ds_read_b128 v[174:177], v191 offset:50176
	ds_read_b128 v[178:181], v191 offset:51200
	ds_read_b128 v[182:185], v191 offset:52224
	ds_read_b128 v[186:189], v191 offset:53248
	ds_read_b128 v[192:195], v191 offset:54272
	ds_read_b128 v[196:199], v191 offset:55296
	ds_read_b128 v[200:203], v191 offset:56320
	global_load_lds_dwordx4 v[204:205], off
	v_lshl_add_u64 v[204:205], v[206:207], 0, s[20:21]
	s_add_i32 m0, s34, 0x2000
	s_add_i32 s34, s73, s3
	global_load_lds_dwordx4 v[204:205], off
	v_lshl_add_u64 v[204:205], v[212:213], 0, s[20:21]
	s_mov_b32 m0, s34
	s_nop 0
	global_load_lds_dwordx4 v[204:205], off
	v_lshl_add_u64 v[204:205], v[214:215], 0, s[20:21]
	s_add_i32 m0, s34, 0x2000
	s_nop 0
	global_load_lds_dwordx4 v[204:205], off
	v_lshl_add_u64 v[204:205], v[216:217], 0, s[20:21]
	s_mov_b32 m0, s60
	s_nop 0
	global_load_lds_dwordx4 v[204:205], off
	v_lshl_add_u64 v[204:205], v[218:219], 0, s[20:21]
	s_mov_b32 m0, s61
	s_nop 0
	global_load_lds_dwordx4 v[204:205], off
	s_waitcnt vmcnt(8)
	s_waitcnt lgkmcnt(0)
	s_barrier
	s_setprio 1
	v_mfma_f32_16x16x32_bf16 v[60:63], v[120:123], v[170:173], v[60:63]
	v_mfma_f32_16x16x32_bf16 v[56:59], v[136:139], v[170:173], v[56:59]
	v_mfma_f32_16x16x32_bf16 v[44:47], v[120:123], v[178:181], v[44:47]
	v_mfma_f32_16x16x32_bf16 v[40:43], v[136:139], v[178:181], v[40:43]
	v_mfma_f32_16x16x32_bf16 v[28:31], v[120:123], v[186:189], v[28:31]
	v_mfma_f32_16x16x32_bf16 v[24:27], v[136:139], v[186:189], v[24:27]
	v_mfma_f32_16x16x32_bf16 v[12:15], v[120:123], v[196:199], v[12:15]
	v_mfma_f32_16x16x32_bf16 v[8:11], v[136:139], v[196:199], v[8:11]
	v_mfma_f32_16x16x32_bf16 v[60:63], v[132:135], v[174:177], v[60:63]
	v_mfma_f32_16x16x32_bf16 v[56:59], v[140:143], v[174:177], v[56:59]
	v_mfma_f32_16x16x32_bf16 v[44:47], v[132:135], v[182:185], v[44:47]
	v_mfma_f32_16x16x32_bf16 v[40:43], v[140:143], v[182:185], v[40:43]
	v_mfma_f32_16x16x32_bf16 v[28:31], v[132:135], v[192:195], v[28:31]
	v_mfma_f32_16x16x32_bf16 v[24:27], v[140:143], v[192:195], v[24:27]
	v_mfma_f32_16x16x32_bf16 v[12:15], v[132:135], v[200:203], v[12:15]
	v_mfma_f32_16x16x32_bf16 v[8:11], v[140:143], v[200:203], v[8:11]
	s_setprio 0
	s_setprio 1
	v_mfma_f32_16x16x32_bf16 v[52:55], v[144:147], v[170:173], v[52:55]
	v_mfma_f32_16x16x32_bf16 v[48:51], v[152:155], v[170:173], v[48:51]
	v_mfma_f32_16x16x32_bf16 v[36:39], v[144:147], v[178:181], v[36:39]
	v_mfma_f32_16x16x32_bf16 v[32:35], v[152:155], v[178:181], v[32:35]
	v_mfma_f32_16x16x32_bf16 v[20:23], v[144:147], v[186:189], v[20:23]
	v_mfma_f32_16x16x32_bf16 v[16:19], v[152:155], v[186:189], v[16:19]
	v_mfma_f32_16x16x32_bf16 v[4:7], v[144:147], v[196:199], v[4:7]
	v_mfma_f32_16x16x32_bf16 v[0:3], v[152:155], v[196:199], v[0:3]
	v_mfma_f32_16x16x32_bf16 v[52:55], v[148:151], v[174:177], v[52:55]
	v_mfma_f32_16x16x32_bf16 v[48:51], v[156:159], v[174:177], v[48:51]
	v_mfma_f32_16x16x32_bf16 v[36:39], v[148:151], v[182:185], v[36:39]
	v_mfma_f32_16x16x32_bf16 v[32:35], v[156:159], v[182:185], v[32:35]
	v_mfma_f32_16x16x32_bf16 v[20:23], v[148:151], v[192:195], v[20:23]
	v_mfma_f32_16x16x32_bf16 v[16:19], v[156:159], v[192:195], v[16:19]
	v_mfma_f32_16x16x32_bf16 v[4:7], v[148:151], v[200:203], v[4:7]
	v_mfma_f32_16x16x32_bf16 v[0:3], v[156:159], v[200:203], v[0:3]
	s_setprio 0
	s_barrier
	s_add_u32 s30, s30, 0x100
	s_addc_u32 s31, s31, 0
	s_add_u32 s40, s40, 0x100
	s_addc_u32 s41, s41, 0
	s_cmp_ge_i32 s71, s48
	s_mov_b32 s34, s71
	s_cbranch_scc0 .LBB0_1170

; #define PG8_STAGE(bufoff, gbase, voff) do { _Pragma("unroll") for (int _i = 0; _i < 2; ++_i) \
;         __builtin_amdgcn_global_load_lds((const unsigned*)((const char*)(gbase) + (voff)[_i]), (PG8_LAS unsigned*)(lds + (bufoff) + ldsw + _i * 8192), 16, 0, 0); } while (0)
; #define PG8_LDA(dst, b, h) do { _Pragma("unroll") for (int m = 0; m < 4; ++m) _Pragma("unroll") for (int k = 0; k < 2; ++k) dst[m][k] = *(const PG8_LAS bf16x8*)(lds + PG8_SA(b, h) + aoff + m * 2048 + k * 1024); } while (0)
; #define PG8_LDB(dst, b, h) do { _Pragma("unroll") for (int n = 0; n < 2; ++n) _Pragma("unroll") for (int k = 0; k < 2; ++k) dst[n][k] = *(const PG8_LAS bf16x8*)(lds + PG8_SB(b, h) + boff + n * 2048 + k * 1024); } while (0)
; #define PG8_MMA(ai, bj, At, Bt) do { __builtin_amdgcn_s_setprio(1); _Pragma("unroll") for (int m = 0; m < 4; ++m) _Pragma("unroll") for (int n = 0; n < 2; ++n) _Pragma("unroll") for (int k = 0; k < 2; ++k) \
;         acc[ai][bj][m][n] = mma16<Epi::F16>(Bt[n][k], At[m][k], acc[ai][bj][m][n]); __builtin_amdgcn_s_setprio(0); } while (0)
; #define PG8_WAIT_V(n) asm volatile("s_waitcnt vmcnt(" #n ")" ::: "memory")
; #define PG8_WAIT_L(n) asm volatile("s_waitcnt lgkmcnt(" #n ")" ::: "memory")
; #define PG8_BAR __builtin_amdgcn_s_barrier()
; #define PG8_SCHED __builtin_amdgcn_sched_barrier(0)
; template <class Epi, class Sched, bool ALIGN_EPI = false, bool SP2 = false>
; __device__ __forceinline__ void gemm_phase(PG8_LAS unsigned char* lds, const Gemm g, const Sched& S, const Epi& E) {
;     ...
;         for (int t = 0; t < nt; t += 2) {
;             const bool last = (t == nt - 2);
;             const char* a1 = cA + (size_t)(t + 1) * kstep;
;             const char* a2 = last ? nA : cA + (size_t)(t + 2) * kstep; const char* b2 = last ? nB : cB + (size_t)(t + 2) * kstep;
;             const char* a3 = a2 + kstep; const char* b3 = b2 + kstep;
;             if (last && has_next) S.a_ready(nxt);
;             if constexpr (SP2) {
;             PG8_LDB(B0, 0, 0); PG8_LDB(B1, 0, 1); PG8_SCHED; PG8_LDA(At, 0, 0); PG8_STAGE(PG8_SA(1, 1), a1 + hstep, voffA);
;             PG8_WAIT_V(8); PG8_WAIT_L(0); PG8_BAR; PG8_MMA(0, 0, At, B0); PG8_MMA(0, 1, At, B1); PG8_BAR; PG8_SCHED;
;             PG8_LDA(At, 0, 1); PG8_STAGE(PG8_SB(0, 0), b2, voffB); PG8_STAGE(PG8_SB(0, 1), b2 + hstep, voffB); PG8_STAGE(PG8_SA(0, 0), a2, voffA);
.Lpeel_k9:
	s_add_u32 s30, s30, 0x80
	s_addc_u32 s31, s31, 0
	s_add_u32 s29, s34, 0x100
	s_addc_u32 s71, s35, 0
	s_mov_b32 s34, 0
	s_add_i32 s72, s34, 2
	s_add_u32 s73, s30, 0x80
	s_addc_u32 s35, s31, 0
	s_add_i32 s77, 0, 0x10000
	s_cmp_eq_u32 s59, s34
	s_cselect_b32 s35, s1, s35
	s_cselect_b32 s34, s0, s73
	v_add_u32_e32 v131, s77, v133
	s_cselect_b32 s85, s57, s71
	s_cselect_b32 s84, s56, s29
	s_add_i32 s73, 0, 0x14000
	ds_read_b128 v[140:143], v131
	ds_read_b128 v[144:147], v131 offset:1024
	ds_read_b128 v[148:151], v131 offset:2048
	ds_read_b128 v[152:155], v131 offset:3072
	v_add_u32_e32 v131, s73, v133
	ds_read_b128 v[156:159], v131
	ds_read_b128 v[160:163], v131 offset:1024
	ds_read_b128 v[164:167], v131 offset:2048
	ds_read_b128 v[168:171], v131 offset:3072
	v_lshl_add_u64 v[212:213], s[30:31], 0, v[136:137]
	s_add_i32 m0, s9, 0xc000
	ds_read_b128 v[172:175], v199
	ds_read_b128 v[176:179], v199 offset:1024
	ds_read_b128 v[180:183], v199 offset:2048
	ds_read_b128 v[184:187], v199 offset:3072
	ds_read_b128 v[188:191], v199 offset:4096
	ds_read_b128 v[192:195], v199 offset:5120
	ds_read_b128 v[200:203], v199 offset:6144
	ds_read_b128 v[204:207], v199 offset:7168
	global_load_lds_dwordx4 v[212:213], off
	v_lshl_add_u64 v[212:213], s[30:31], 0, v[138:139]
	s_add_i32 m0, s9, 0xe000
	s_nop 0
	global_load_lds_dwordx4 v[212:213], off
	s_waitcnt vmcnt(8)
	s_waitcnt lgkmcnt(0)
	s_barrier
	s_setprio 1
	v_mfma_f32_16x16x32_bf16 v[120:123], v[140:143], v[172:175], 0
	v_mfma_f32_16x16x32_bf16 v[124:127], v[148:151], v[172:175], 0
	v_mfma_f32_16x16x32_bf16 v[108:111], v[140:143], v[180:183], 0
	v_mfma_f32_16x16x32_bf16 v[104:107], v[148:151], v[180:183], 0
	v_mfma_f32_16x16x32_bf16 v[92:95], v[140:143], v[188:191], 0
	v_mfma_f32_16x16x32_bf16 v[88:91], v[148:151], v[188:191], 0
	v_mfma_f32_16x16x32_bf16 v[76:79], v[140:143], v[200:203], 0
	v_mfma_f32_16x16x32_bf16 v[72:75], v[148:151], v[200:203], 0
	v_mfma_f32_16x16x32_bf16 v[120:123], v[144:147], v[176:179], v[120:123]
	v_mfma_f32_16x16x32_bf16 v[124:127], v[152:155], v[176:179], v[124:127]
	v_mfma_f32_16x16x32_bf16 v[108:111], v[144:147], v[184:187], v[108:111]
	v_mfma_f32_16x16x32_bf16 v[104:107], v[152:155], v[184:187], v[104:107]
	v_mfma_f32_16x16x32_bf16 v[92:95], v[144:147], v[192:195], v[92:95]
	v_mfma_f32_16x16x32_bf16 v[88:91], v[152:155], v[192:195], v[88:91]
	v_mfma_f32_16x16x32_bf16 v[76:79], v[144:147], v[204:207], v[76:79]
	v_mfma_f32_16x16x32_bf16 v[72:75], v[152:155], v[204:207], v[72:75]
	s_setprio 0
	s_setprio 1
	v_mfma_f32_16x16x32_bf16 v[116:119], v[156:159], v[172:175], 0
	v_mfma_f32_16x16x32_bf16 v[112:115], v[164:167], v[172:175], 0
	v_mfma_f32_16x16x32_bf16 v[100:103], v[156:159], v[180:183], 0
	v_mfma_f32_16x16x32_bf16 v[96:99], v[164:167], v[180:183], 0
	v_mfma_f32_16x16x32_bf16 v[84:87], v[156:159], v[188:191], 0
	v_mfma_f32_16x16x32_bf16 v[80:83], v[164:167], v[188:191], 0
	v_mfma_f32_16x16x32_bf16 v[68:71], v[156:159], v[200:203], 0
	v_mfma_f32_16x16x32_bf16 v[64:67], v[164:167], v[200:203], 0
	v_mfma_f32_16x16x32_bf16 v[116:119], v[160:163], v[176:179], v[116:119]
	v_mfma_f32_16x16x32_bf16 v[112:115], v[168:171], v[176:179], v[112:115]
	v_mfma_f32_16x16x32_bf16 v[100:103], v[160:163], v[184:187], v[100:103]
	v_mfma_f32_16x16x32_bf16 v[96:99], v[168:171], v[184:187], v[96:99]
	v_mfma_f32_16x16x32_bf16 v[84:87], v[160:163], v[192:195], v[84:87]
	v_mfma_f32_16x16x32_bf16 v[80:83], v[168:171], v[192:195], v[80:83]
	v_mfma_f32_16x16x32_bf16 v[68:71], v[160:163], v[204:207], v[68:71]
	v_mfma_f32_16x16x32_bf16 v[64:67], v[168:171], v[204:207], v[64:67]
	s_setprio 0
	s_barrier
	s_add_i32 s77, s77, s8
	v_lshl_add_u64 v[212:213], s[84:85], 0, v[208:209]
	s_mov_b32 m0, s77
	ds_read_b128 v[172:175], v199 offset:16384
	ds_read_b128 v[176:179], v199 offset:17408
	ds_read_b128 v[180:183], v199 offset:18432
	ds_read_b128 v[184:187], v199 offset:19456
	ds_read_b128 v[188:191], v199 offset:20480
	ds_read_b128 v[192:195], v199 offset:21504
	ds_read_b128 v[200:203], v199 offset:22528
	ds_read_b128 v[204:207], v199 offset:23552
	global_load_lds_dwordx4 v[212:213], off
	s_add_i32 m0, s77, 0x2000
	v_lshl_add_u64 v[214:215], s[84:85], 0, v[128:129]
	s_add_u32 s84, s84, s42
	s_addc_u32 s85, s85, s43
	s_add_i32 s73, s73, s8
	global_load_lds_dwordx4 v[214:215], off
	v_lshl_add_u64 v[216:217], s[84:85], 0, v[208:209]
	s_mov_b32 m0, s73
	v_lshl_add_u64 v[218:219], s[84:85], 0, v[128:129]
	global_load_lds_dwordx4 v[216:217], off
	s_add_i32 m0, s73, 0x2000
	v_lshl_add_u64 v[220:221], s[34:35], 0, v[208:209]
	global_load_lds_dwordx4 v[218:219], off
	s_mov_b32 m0, s9
	v_lshl_add_u64 v[222:223], s[34:35], 0, v[128:129]
	global_load_lds_dwordx4 v[220:221], off
	s_mov_b32 m0, s11
	s_nop 0
	global_load_lds_dwordx4 v[222:223], off
	s_waitcnt vmcnt(8)
	s_waitcnt lgkmcnt(0)
	s_barrier
; #define PG8_STAGE(bufoff, gbase, voff) do { _Pragma("unroll") for (int _i = 0; _i < 2; ++_i) \
;         __builtin_amdgcn_global_load_lds((const unsigned*)((const char*)(gbase) + (voff)[_i]), (PG8_LAS unsigned*)(lds + (bufoff) + ldsw + _i * 8192), 16, 0, 0); } while (0)
; #define PG8_LDA(dst, b, h) do { _Pragma("unroll") for (int m = 0; m < 4; ++m) _Pragma("unroll") for (int k = 0; k < 2; ++k) dst[m][k] = *(const PG8_LAS bf16x8*)(lds + PG8_SA(b, h) + aoff + m * 2048 + k * 1024); } while (0)
; #define PG8_LDB(dst, b, h) do { _Pragma("unroll") for (int n = 0; n < 2; ++n) _Pragma("unroll") for (int k = 0; k < 2; ++k) dst[n][k] = *(const PG8_LAS bf16x8*)(lds + PG8_SB(b, h) + boff + n * 2048 + k * 1024); } while (0)
; #define PG8_MMA(ai, bj, At, Bt) do { __builtin_amdgcn_s_setprio(1); _Pragma("unroll") for (int m = 0; m < 4; ++m) _Pragma("unroll") for (int n = 0; n < 2; ++n) _Pragma("unroll") for (int k = 0; k < 2; ++k) \
;         acc[ai][bj][m][n] = mma16<Epi::F16>(Bt[n][k], At[m][k], acc[ai][bj][m][n]); __builtin_amdgcn_s_setprio(0); } while (0)
; #define PG8_WAIT_V(n) asm volatile("s_waitcnt vmcnt(" #n ")" ::: "memory")
; #define PG8_WAIT_L(n) asm volatile("s_waitcnt lgkmcnt(" #n ")" ::: "memory")
; #define PG8_BAR __builtin_amdgcn_s_barrier()
; #define PG8_SCHED __builtin_amdgcn_sched_barrier(0)
; template <class Epi, class Sched, bool ALIGN_EPI = false, bool SP2 = false>
; __device__ __forceinline__ void gemm_phase(PG8_LAS unsigned char* lds, const Gemm g, const Sched& S, const Epi& E) {
;     ...
;             PG8_WAIT_V(8); PG8_WAIT_L(0); PG8_BAR; PG8_MMA(1, 0, At, B0); PG8_MMA(1, 1, At, B1); PG8_BAR; PG8_SCHED;
;             PG8_LDB(B0, 1, 0); PG8_LDB(B1, 1, 1); PG8_SCHED; PG8_LDA(At, 1, 0); PG8_STAGE(PG8_SA(0, 1), a2 + hstep, voffA);
;             PG8_WAIT_V(8); PG8_WAIT_L(0); PG8_BAR; PG8_MMA(0, 0, At, B0); PG8_MMA(0, 1, At, B1); PG8_BAR; PG8_SCHED;
	s_setprio 1
	v_mfma_f32_16x16x32_bf16 v[60:63], v[140:143], v[172:175], 0
	v_mfma_f32_16x16x32_bf16 v[56:59], v[148:151], v[172:175], 0
	v_mfma_f32_16x16x32_bf16 v[44:47], v[140:143], v[180:183], 0
	v_mfma_f32_16x16x32_bf16 v[40:43], v[148:151], v[180:183], 0
	v_mfma_f32_16x16x32_bf16 v[28:31], v[140:143], v[188:191], 0
	v_mfma_f32_16x16x32_bf16 v[24:27], v[148:151], v[188:191], 0
	v_mfma_f32_16x16x32_bf16 v[12:15], v[140:143], v[200:203], 0
	v_mfma_f32_16x16x32_bf16 v[8:11], v[148:151], v[200:203], 0
	v_mfma_f32_16x16x32_bf16 v[60:63], v[144:147], v[176:179], v[60:63]
	v_mfma_f32_16x16x32_bf16 v[56:59], v[152:155], v[176:179], v[56:59]
	v_mfma_f32_16x16x32_bf16 v[44:47], v[144:147], v[184:187], v[44:47]
	v_mfma_f32_16x16x32_bf16 v[40:43], v[152:155], v[184:187], v[40:43]
	v_mfma_f32_16x16x32_bf16 v[28:31], v[144:147], v[192:195], v[28:31]
	v_mfma_f32_16x16x32_bf16 v[24:27], v[152:155], v[192:195], v[24:27]
	v_mfma_f32_16x16x32_bf16 v[12:15], v[144:147], v[204:207], v[12:15]
	v_mfma_f32_16x16x32_bf16 v[8:11], v[152:155], v[204:207], v[8:11]
	s_setprio 0
	s_setprio 1
	v_mfma_f32_16x16x32_bf16 v[52:55], v[156:159], v[172:175], 0
	v_mfma_f32_16x16x32_bf16 v[48:51], v[164:167], v[172:175], 0
	v_mfma_f32_16x16x32_bf16 v[36:39], v[156:159], v[180:183], 0
	v_mfma_f32_16x16x32_bf16 v[32:35], v[164:167], v[180:183], 0
	v_mfma_f32_16x16x32_bf16 v[20:23], v[156:159], v[188:191], 0
	v_mfma_f32_16x16x32_bf16 v[16:19], v[164:167], v[188:191], 0
	v_mfma_f32_16x16x32_bf16 v[4:7], v[156:159], v[200:203], 0
	v_mfma_f32_16x16x32_bf16 v[0:3], v[164:167], v[200:203], 0
	v_mfma_f32_16x16x32_bf16 v[52:55], v[160:163], v[176:179], v[52:55]
	v_mfma_f32_16x16x32_bf16 v[48:51], v[168:171], v[176:179], v[48:51]
	v_mfma_f32_16x16x32_bf16 v[36:39], v[160:163], v[184:187], v[36:39]
	v_mfma_f32_16x16x32_bf16 v[32:35], v[168:171], v[184:187], v[32:35]
	v_mfma_f32_16x16x32_bf16 v[20:23], v[160:163], v[192:195], v[20:23]
	v_mfma_f32_16x16x32_bf16 v[16:19], v[168:171], v[192:195], v[16:19]
	v_mfma_f32_16x16x32_bf16 v[4:7], v[160:163], v[204:207], v[4:7]
	v_mfma_f32_16x16x32_bf16 v[0:3], v[168:171], v[204:207], v[0:3]
	s_setprio 0
	s_barrier
	s_add_i32 s73, 0, 0x18000
	v_add_u32_e32 v131, s73, v133
	s_add_i32 s77, 0, 0x1c000
	ds_read_b128 v[140:143], v131
	ds_read_b128 v[144:147], v131 offset:1024
	ds_read_b128 v[148:151], v131 offset:2048
	ds_read_b128 v[152:155], v131 offset:3072
	v_add_u32_e32 v131, s77, v133
	ds_read_b128 v[156:159], v131
	ds_read_b128 v[160:163], v131 offset:1024
	ds_read_b128 v[164:167], v131 offset:2048
	ds_read_b128 v[168:171], v131 offset:3072
	s_add_u32 s34, s34, s42
	s_addc_u32 s35, s35, s43
	s_mov_b32 m0, s18
	v_lshl_add_u64 v[224:225], s[34:35], 0, v[208:209]
	ds_read_b128 v[172:175], v199 offset:32768
	ds_read_b128 v[176:179], v199 offset:33792
	ds_read_b128 v[180:183], v199 offset:34816
	ds_read_b128 v[184:187], v199 offset:35840
	ds_read_b128 v[188:191], v199 offset:36864
	ds_read_b128 v[192:195], v199 offset:37888
	ds_read_b128 v[200:203], v199 offset:38912
	ds_read_b128 v[204:207], v199 offset:39936
	global_load_lds_dwordx4 v[224:225], off
	v_lshl_add_u64 v[224:225], s[34:35], 0, v[128:129]
	s_mov_b32 m0, s36
	s_nop 0
	global_load_lds_dwordx4 v[224:225], off
	s_waitcnt vmcnt(8)
	s_waitcnt lgkmcnt(0)
	s_barrier
	s_setprio 1
	v_mfma_f32_16x16x32_bf16 v[120:123], v[140:143], v[172:175], v[120:123]
	v_mfma_f32_16x16x32_bf16 v[124:127], v[148:151], v[172:175], v[124:127]
	v_mfma_f32_16x16x32_bf16 v[108:111], v[140:143], v[180:183], v[108:111]
	v_mfma_f32_16x16x32_bf16 v[104:107], v[148:151], v[180:183], v[104:107]
	v_mfma_f32_16x16x32_bf16 v[92:95], v[140:143], v[188:191], v[92:95]
	v_mfma_f32_16x16x32_bf16 v[88:91], v[148:151], v[188:191], v[88:91]
	v_mfma_f32_16x16x32_bf16 v[76:79], v[140:143], v[200:203], v[76:79]
	v_mfma_f32_16x16x32_bf16 v[72:75], v[148:151], v[200:203], v[72:75]
	v_mfma_f32_16x16x32_bf16 v[120:123], v[144:147], v[176:179], v[120:123]
	v_mfma_f32_16x16x32_bf16 v[124:127], v[152:155], v[176:179], v[124:127]
	v_mfma_f32_16x16x32_bf16 v[108:111], v[144:147], v[184:187], v[108:111]
	v_mfma_f32_16x16x32_bf16 v[104:107], v[152:155], v[184:187], v[104:107]
	v_mfma_f32_16x16x32_bf16 v[92:95], v[144:147], v[192:195], v[92:95]
	v_mfma_f32_16x16x32_bf16 v[88:91], v[152:155], v[192:195], v[88:91]
	v_mfma_f32_16x16x32_bf16 v[76:79], v[144:147], v[204:207], v[76:79]
	v_mfma_f32_16x16x32_bf16 v[72:75], v[152:155], v[204:207], v[72:75]
	s_setprio 0
	s_setprio 1
	v_mfma_f32_16x16x32_bf16 v[116:119], v[156:159], v[172:175], v[116:119]
	v_mfma_f32_16x16x32_bf16 v[112:115], v[164:167], v[172:175], v[112:115]
	v_mfma_f32_16x16x32_bf16 v[100:103], v[156:159], v[180:183], v[100:103]
	v_mfma_f32_16x16x32_bf16 v[96:99], v[164:167], v[180:183], v[96:99]
	v_mfma_f32_16x16x32_bf16 v[84:87], v[156:159], v[188:191], v[84:87]
	v_mfma_f32_16x16x32_bf16 v[80:83], v[164:167], v[188:191], v[80:83]
	v_mfma_f32_16x16x32_bf16 v[68:71], v[156:159], v[200:203], v[68:71]
	v_mfma_f32_16x16x32_bf16 v[64:67], v[164:167], v[200:203], v[64:67]
	v_mfma_f32_16x16x32_bf16 v[116:119], v[160:163], v[176:179], v[116:119]
	v_mfma_f32_16x16x32_bf16 v[112:115], v[168:171], v[176:179], v[112:115]
	v_mfma_f32_16x16x32_bf16 v[100:103], v[160:163], v[184:187], v[100:103]
	v_mfma_f32_16x16x32_bf16 v[96:99], v[168:171], v[184:187], v[96:99]
	v_mfma_f32_16x16x32_bf16 v[84:87], v[160:163], v[192:195], v[84:87]
	v_mfma_f32_16x16x32_bf16 v[80:83], v[168:171], v[192:195], v[80:83]
	v_mfma_f32_16x16x32_bf16 v[68:71], v[160:163], v[204:207], v[68:71]
	v_mfma_f32_16x16x32_bf16 v[64:67], v[168:171], v[204:207], v[64:67]
	s_setprio 0
	s_barrier
; #define PG8_STAGE(bufoff, gbase, voff) do { _Pragma("unroll") for (int _i = 0; _i < 2; ++_i) \
;         __builtin_amdgcn_global_load_lds((const unsigned*)((const char*)(gbase) + (voff)[_i]), (PG8_LAS unsigned*)(lds + (bufoff) + ldsw + _i * 8192), 16, 0, 0); } while (0)
; #define PG8_LDA(dst, b, h) do { _Pragma("unroll") for (int m = 0; m < 4; ++m) _Pragma("unroll") for (int k = 0; k < 2; ++k) dst[m][k] = *(const PG8_LAS bf16x8*)(lds + PG8_SA(b, h) + aoff + m * 2048 + k * 1024); } while (0)
; #define PG8_LDB(dst, b, h) do { _Pragma("unroll") for (int n = 0; n < 2; ++n) _Pragma("unroll") for (int k = 0; k < 2; ++k) dst[n][k] = *(const PG8_LAS bf16x8*)(lds + PG8_SB(b, h) + boff + n * 2048 + k * 1024); } while (0)
; #define PG8_MMA(ai, bj, At, Bt) do { __builtin_amdgcn_s_setprio(1); _Pragma("unroll") for (int m = 0; m < 4; ++m) _Pragma("unroll") for (int n = 0; n < 2; ++n) _Pragma("unroll") for (int k = 0; k < 2; ++k) \
;         acc[ai][bj][m][n] = mma16<Epi::F16>(Bt[n][k], At[m][k], acc[ai][bj][m][n]); __builtin_amdgcn_s_setprio(0); } while (0)
; #define PG8_WAIT_V(n) asm volatile("s_waitcnt vmcnt(" #n ")" ::: "memory")
; #define PG8_WAIT_L(n) asm volatile("s_waitcnt lgkmcnt(" #n ")" ::: "memory")
; template <class Epi, class Sched, bool ALIGN_EPI = false, bool SP2 = false>
; __device__ __forceinline__ void gemm_phase(PG8_LAS unsigned char* lds, const Gemm g, const Sched& S, const Epi& E) {
;     ...
;         for (int t = 0; t < nt; t += 2) {
;             const bool last = (t == nt - 2);
;             const char* a1 = cA + (size_t)(t + 1) * kstep;
;             const char* a2 = last ? nA : cA + (size_t)(t + 2) * kstep; const char* b2 = last ? nB : cB + (size_t)(t + 2) * kstep;
;             const char* a3 = a2 + kstep; const char* b3 = b2 + kstep;
;             if (last && has_next) S.a_ready(nxt);
;             if constexpr (SP2) {
;             PG8_LDB(B0, 0, 0); PG8_LDB(B1, 0, 1); PG8_SCHED; PG8_LDA(At, 0, 0); PG8_STAGE(PG8_SA(1, 1), a1 + hstep, voffA);
;             PG8_WAIT_V(8); PG8_WAIT_L(0); PG8_BAR; PG8_MMA(0, 0, At, B0); PG8_MMA(0, 1, At, B1); PG8_BAR; PG8_SCHED;
;     ...
;             PG8_LDA(At, 1, 1); PG8_STAGE(PG8_SB(1, 0), b3, voffB); PG8_STAGE(PG8_SB(1, 1), b3 + hstep, voffB); PG8_STAGE(PG8_SA(1, 0), a3, voffA);
;             PG8_WAIT_V(8); PG8_WAIT_L(0); PG8_BAR; PG8_MMA(1, 0, At, B0); PG8_MMA(1, 1, At, B1); PG8_BAR; PG8_SCHED;
	s_add_i32 s34, s73, s8
	v_lshl_add_u64 v[212:213], v[212:213], 0, s[20:21]
	s_mov_b32 m0, s34
	ds_read_b128 v[172:175], v199 offset:49152
	ds_read_b128 v[176:179], v199 offset:50176
	ds_read_b128 v[180:183], v199 offset:51200
	ds_read_b128 v[184:187], v199 offset:52224
	ds_read_b128 v[188:191], v199 offset:53248
	ds_read_b128 v[192:195], v199 offset:54272
	ds_read_b128 v[200:203], v199 offset:55296
	ds_read_b128 v[204:207], v199 offset:56320
	global_load_lds_dwordx4 v[212:213], off
	v_lshl_add_u64 v[212:213], v[214:215], 0, s[20:21]
	s_add_i32 m0, s34, 0x2000
	s_add_i32 s34, s77, s8
	global_load_lds_dwordx4 v[212:213], off
	v_lshl_add_u64 v[212:213], v[216:217], 0, s[20:21]
	s_mov_b32 m0, s34
	s_nop 0
	global_load_lds_dwordx4 v[212:213], off
	v_lshl_add_u64 v[212:213], v[218:219], 0, s[20:21]
	s_add_i32 m0, s34, 0x2000
	s_nop 0
	global_load_lds_dwordx4 v[212:213], off
	v_lshl_add_u64 v[212:213], v[220:221], 0, s[20:21]
	s_mov_b32 m0, s37
	s_nop 0
	global_load_lds_dwordx4 v[212:213], off
	v_lshl_add_u64 v[212:213], v[222:223], 0, s[20:21]
	s_mov_b32 m0, s48
	s_nop 0
	global_load_lds_dwordx4 v[212:213], off
	s_waitcnt vmcnt(8)
	s_waitcnt lgkmcnt(0)
	s_barrier
	s_setprio 1
	v_mfma_f32_16x16x32_bf16 v[60:63], v[140:143], v[172:175], v[60:63]
	v_mfma_f32_16x16x32_bf16 v[56:59], v[148:151], v[172:175], v[56:59]
	v_mfma_f32_16x16x32_bf16 v[44:47], v[140:143], v[180:183], v[44:47]
	v_mfma_f32_16x16x32_bf16 v[40:43], v[148:151], v[180:183], v[40:43]
	v_mfma_f32_16x16x32_bf16 v[28:31], v[140:143], v[188:191], v[28:31]
	v_mfma_f32_16x16x32_bf16 v[24:27], v[148:151], v[188:191], v[24:27]
	v_mfma_f32_16x16x32_bf16 v[12:15], v[140:143], v[200:203], v[12:15]
	v_mfma_f32_16x16x32_bf16 v[8:11], v[148:151], v[200:203], v[8:11]
	v_mfma_f32_16x16x32_bf16 v[60:63], v[144:147], v[176:179], v[60:63]
	v_mfma_f32_16x16x32_bf16 v[56:59], v[152:155], v[176:179], v[56:59]
	v_mfma_f32_16x16x32_bf16 v[44:47], v[144:147], v[184:187], v[44:47]
	v_mfma_f32_16x16x32_bf16 v[40:43], v[152:155], v[184:187], v[40:43]
	v_mfma_f32_16x16x32_bf16 v[28:31], v[144:147], v[192:195], v[28:31]
	v_mfma_f32_16x16x32_bf16 v[24:27], v[152:155], v[192:195], v[24:27]
	v_mfma_f32_16x16x32_bf16 v[12:15], v[144:147], v[204:207], v[12:15]
	v_mfma_f32_16x16x32_bf16 v[8:11], v[152:155], v[204:207], v[8:11]
	s_setprio 0
	s_setprio 1
	v_mfma_f32_16x16x32_bf16 v[52:55], v[156:159], v[172:175], v[52:55]
	v_mfma_f32_16x16x32_bf16 v[48:51], v[164:167], v[172:175], v[48:51]
	v_mfma_f32_16x16x32_bf16 v[36:39], v[156:159], v[180:183], v[36:39]
	v_mfma_f32_16x16x32_bf16 v[32:35], v[164:167], v[180:183], v[32:35]
	v_mfma_f32_16x16x32_bf16 v[20:23], v[156:159], v[188:191], v[20:23]
	v_mfma_f32_16x16x32_bf16 v[16:19], v[164:167], v[188:191], v[16:19]
	v_mfma_f32_16x16x32_bf16 v[4:7], v[156:159], v[200:203], v[4:7]
	v_mfma_f32_16x16x32_bf16 v[0:3], v[164:167], v[200:203], v[0:3]
	v_mfma_f32_16x16x32_bf16 v[52:55], v[160:163], v[176:179], v[52:55]
	v_mfma_f32_16x16x32_bf16 v[48:51], v[168:171], v[176:179], v[48:51]
	v_mfma_f32_16x16x32_bf16 v[36:39], v[160:163], v[184:187], v[36:39]
	v_mfma_f32_16x16x32_bf16 v[32:35], v[168:171], v[184:187], v[32:35]
	v_mfma_f32_16x16x32_bf16 v[20:23], v[160:163], v[192:195], v[20:23]
	v_mfma_f32_16x16x32_bf16 v[16:19], v[168:171], v[192:195], v[16:19]
	v_mfma_f32_16x16x32_bf16 v[4:7], v[160:163], v[204:207], v[4:7]
	v_mfma_f32_16x16x32_bf16 v[0:3], v[168:171], v[204:207], v[0:3]
	s_setprio 0
	s_barrier
	s_add_u32 s30, s30, 0x100
	s_addc_u32 s31, s31, 0
	s_add_u32 s29, s29, 0x100
	s_addc_u32 s71, s71, 0
	s_cmp_ge_i32 s72, s58
	s_mov_b32 s34, s72
	s_cbranch_scc0 .LBB0_1480
	s_branch .LBB0_1481
.LBB0_1480:
	s_add_i32 s72, s34, 2
	s_add_u32 s73, s30, 0x80
	s_addc_u32 s35, s31, 0
	s_add_i32 s77, 0, 0x10000
	s_cmp_eq_u32 s59, s34
	s_cselect_b32 s35, s1, s35
	s_cselect_b32 s34, s0, s73
	v_add_u32_e32 v131, s77, v133
	s_cselect_b32 s85, s57, s71
	s_cselect_b32 s84, s56, s29
	s_add_i32 s73, 0, 0x14000
	ds_read_b128 v[140:143], v131
	ds_read_b128 v[144:147], v131 offset:1024
	ds_read_b128 v[148:151], v131 offset:2048
	ds_read_b128 v[152:155], v131 offset:3072
	v_add_u32_e32 v131, s73, v133
	ds_read_b128 v[156:159], v131
	ds_read_b128 v[160:163], v131 offset:1024
	ds_read_b128 v[164:167], v131 offset:2048
	ds_read_b128 v[168:171], v131 offset:3072
	v_lshl_add_u64 v[212:213], s[30:31], 0, v[136:137]
	s_add_i32 m0, s9, 0xc000
	ds_read_b128 v[172:175], v199
	ds_read_b128 v[176:179], v199 offset:1024
	ds_read_b128 v[180:183], v199 offset:2048
	ds_read_b128 v[184:187], v199 offset:3072
	ds_read_b128 v[188:191], v199 offset:4096
	ds_read_b128 v[192:195], v199 offset:5120
	ds_read_b128 v[200:203], v199 offset:6144
	ds_read_b128 v[204:207], v199 offset:7168
	global_load_lds_dwordx4 v[212:213], off
	v_lshl_add_u64 v[212:213], s[30:31], 0, v[138:139]
	s_add_i32 m0, s9, 0xe000
	s_nop 0
	global_load_lds_dwordx4 v[212:213], off
	s_waitcnt vmcnt(8)
	s_waitcnt lgkmcnt(0)
	s_barrier
; #define PG8_STAGE(bufoff, gbase, voff) do { _Pragma("unroll") for (int _i = 0; _i < 2; ++_i) \
;         __builtin_amdgcn_global_load_lds((const unsigned*)((const char*)(gbase) + (voff)[_i]), (PG8_LAS unsigned*)(lds + (bufoff) + ldsw + _i * 8192), 16, 0, 0); } while (0)
; #define PG8_LDA(dst, b, h) do { _Pragma("unroll") for (int m = 0; m < 4; ++m) _Pragma("unroll") for (int k = 0; k < 2; ++k) dst[m][k] = *(const PG8_LAS bf16x8*)(lds + PG8_SA(b, h) + aoff + m * 2048 + k * 1024); } while (0)
; #define PG8_LDB(dst, b, h) do { _Pragma("unroll") for (int n = 0; n < 2; ++n) _Pragma("unroll") for (int k = 0; k < 2; ++k) dst[n][k] = *(const PG8_LAS bf16x8*)(lds + PG8_SB(b, h) + boff + n * 2048 + k * 1024); } while (0)
; #define PG8_MMA(ai, bj, At, Bt) do { __builtin_amdgcn_s_setprio(1); _Pragma("unroll") for (int m = 0; m < 4; ++m) _Pragma("unroll") for (int n = 0; n < 2; ++n) _Pragma("unroll") for (int k = 0; k < 2; ++k) \
;         acc[ai][bj][m][n] = mma16<Epi::F16>(Bt[n][k], At[m][k], acc[ai][bj][m][n]); __builtin_amdgcn_s_setprio(0); } while (0)
; #define PG8_WAIT_V(n) asm volatile("s_waitcnt vmcnt(" #n ")" ::: "memory")
; #define PG8_WAIT_L(n) asm volatile("s_waitcnt lgkmcnt(" #n ")" ::: "memory")
; #define PG8_BAR __builtin_amdgcn_s_barrier()
; #define PG8_SCHED __builtin_amdgcn_sched_barrier(0)
; template <class Epi, class Sched, bool ALIGN_EPI = false, bool SP2 = false>
; __device__ __forceinline__ void gemm_phase(PG8_LAS unsigned char* lds, const Gemm g, const Sched& S, const Epi& E) {
;     ...
;             PG8_WAIT_V(8); PG8_WAIT_L(0); PG8_BAR; PG8_MMA(0, 0, At, B0); PG8_MMA(0, 1, At, B1); PG8_BAR; PG8_SCHED;
;             PG8_LDA(At, 0, 1); PG8_STAGE(PG8_SB(0, 0), b2, voffB); PG8_STAGE(PG8_SB(0, 1), b2 + hstep, voffB); PG8_STAGE(PG8_SA(0, 0), a2, voffA);
;             PG8_WAIT_V(8); PG8_WAIT_L(0); PG8_BAR; PG8_MMA(1, 0, At, B0); PG8_MMA(1, 1, At, B1); PG8_BAR; PG8_SCHED;
;             PG8_LDB(B0, 1, 0); PG8_LDB(B1, 1, 1); PG8_SCHED; PG8_LDA(At, 1, 0); PG8_STAGE(PG8_SA(0, 1), a2 + hstep, voffA);
;             PG8_WAIT_V(8); PG8_WAIT_L(0); PG8_BAR; PG8_MMA(0, 0, At, B0); PG8_MMA(0, 1, At, B1); PG8_BAR; PG8_SCHED;
;             PG8_LDA(At, 1, 1); PG8_STAGE(PG8_SB(1, 0), b3, voffB); PG8_STAGE(PG8_SB(1, 1), b3 + hstep, voffB); PG8_STAGE(PG8_SA(1, 0), a3, voffA);
	s_setprio 1
	v_mfma_f32_16x16x32_bf16 v[120:123], v[140:143], v[172:175], v[120:123]
	v_mfma_f32_16x16x32_bf16 v[124:127], v[148:151], v[172:175], v[124:127]
	v_mfma_f32_16x16x32_bf16 v[108:111], v[140:143], v[180:183], v[108:111]
	v_mfma_f32_16x16x32_bf16 v[104:107], v[148:151], v[180:183], v[104:107]
	v_mfma_f32_16x16x32_bf16 v[92:95], v[140:143], v[188:191], v[92:95]
	v_mfma_f32_16x16x32_bf16 v[88:91], v[148:151], v[188:191], v[88:91]
	v_mfma_f32_16x16x32_bf16 v[76:79], v[140:143], v[200:203], v[76:79]
	v_mfma_f32_16x16x32_bf16 v[72:75], v[148:151], v[200:203], v[72:75]
	v_mfma_f32_16x16x32_bf16 v[120:123], v[144:147], v[176:179], v[120:123]
	v_mfma_f32_16x16x32_bf16 v[124:127], v[152:155], v[176:179], v[124:127]
	v_mfma_f32_16x16x32_bf16 v[108:111], v[144:147], v[184:187], v[108:111]
	v_mfma_f32_16x16x32_bf16 v[104:107], v[152:155], v[184:187], v[104:107]
	v_mfma_f32_16x16x32_bf16 v[92:95], v[144:147], v[192:195], v[92:95]
	v_mfma_f32_16x16x32_bf16 v[88:91], v[152:155], v[192:195], v[88:91]
	v_mfma_f32_16x16x32_bf16 v[76:79], v[144:147], v[204:207], v[76:79]
	v_mfma_f32_16x16x32_bf16 v[72:75], v[152:155], v[204:207], v[72:75]
	s_setprio 0
	s_setprio 1
	v_mfma_f32_16x16x32_bf16 v[116:119], v[156:159], v[172:175], v[116:119]
	v_mfma_f32_16x16x32_bf16 v[112:115], v[164:167], v[172:175], v[112:115]
	v_mfma_f32_16x16x32_bf16 v[100:103], v[156:159], v[180:183], v[100:103]
	v_mfma_f32_16x16x32_bf16 v[96:99], v[164:167], v[180:183], v[96:99]
	v_mfma_f32_16x16x32_bf16 v[84:87], v[156:159], v[188:191], v[84:87]
	v_mfma_f32_16x16x32_bf16 v[80:83], v[164:167], v[188:191], v[80:83]
	v_mfma_f32_16x16x32_bf16 v[68:71], v[156:159], v[200:203], v[68:71]
	v_mfma_f32_16x16x32_bf16 v[64:67], v[164:167], v[200:203], v[64:67]
	v_mfma_f32_16x16x32_bf16 v[116:119], v[160:163], v[176:179], v[116:119]
	v_mfma_f32_16x16x32_bf16 v[112:115], v[168:171], v[176:179], v[112:115]
	v_mfma_f32_16x16x32_bf16 v[100:103], v[160:163], v[184:187], v[100:103]
	v_mfma_f32_16x16x32_bf16 v[96:99], v[168:171], v[184:187], v[96:99]
	v_mfma_f32_16x16x32_bf16 v[84:87], v[160:163], v[192:195], v[84:87]
	v_mfma_f32_16x16x32_bf16 v[80:83], v[168:171], v[192:195], v[80:83]
	v_mfma_f32_16x16x32_bf16 v[68:71], v[160:163], v[204:207], v[68:71]
	v_mfma_f32_16x16x32_bf16 v[64:67], v[168:171], v[204:207], v[64:67]
	s_setprio 0
	s_barrier
	s_add_i32 s77, s77, s8
	v_lshl_add_u64 v[212:213], s[84:85], 0, v[208:209]
	s_mov_b32 m0, s77
	ds_read_b128 v[172:175], v199 offset:16384
	ds_read_b128 v[176:179], v199 offset:17408
	ds_read_b128 v[180:183], v199 offset:18432
	ds_read_b128 v[184:187], v199 offset:19456
	ds_read_b128 v[188:191], v199 offset:20480
	ds_read_b128 v[192:195], v199 offset:21504
	ds_read_b128 v[200:203], v199 offset:22528
	ds_read_b128 v[204:207], v199 offset:23552
	global_load_lds_dwordx4 v[212:213], off
	s_add_i32 m0, s77, 0x2000
	v_lshl_add_u64 v[214:215], s[84:85], 0, v[128:129]
	s_add_u32 s84, s84, s42
	s_addc_u32 s85, s85, s43
	s_add_i32 s73, s73, s8
	global_load_lds_dwordx4 v[214:215], off
	v_lshl_add_u64 v[216:217], s[84:85], 0, v[208:209]
	s_mov_b32 m0, s73
	v_lshl_add_u64 v[218:219], s[84:85], 0, v[128:129]
	global_load_lds_dwordx4 v[216:217], off
	s_add_i32 m0, s73, 0x2000
	v_lshl_add_u64 v[220:221], s[34:35], 0, v[208:209]
	global_load_lds_dwordx4 v[218:219], off
	s_mov_b32 m0, s9
	v_lshl_add_u64 v[222:223], s[34:35], 0, v[128:129]
	global_load_lds_dwordx4 v[220:221], off
	s_mov_b32 m0, s11
	s_nop 0
	global_load_lds_dwordx4 v[222:223], off
	s_waitcnt vmcnt(8)
	s_waitcnt lgkmcnt(0)
	s_barrier
	s_setprio 1
	v_mfma_f32_16x16x32_bf16 v[60:63], v[140:143], v[172:175], v[60:63]
	v_mfma_f32_16x16x32_bf16 v[56:59], v[148:151], v[172:175], v[56:59]
	v_mfma_f32_16x16x32_bf16 v[44:47], v[140:143], v[180:183], v[44:47]
	v_mfma_f32_16x16x32_bf16 v[40:43], v[148:151], v[180:183], v[40:43]
	v_mfma_f32_16x16x32_bf16 v[28:31], v[140:143], v[188:191], v[28:31]
	v_mfma_f32_16x16x32_bf16 v[24:27], v[148:151], v[188:191], v[24:27]
	v_mfma_f32_16x16x32_bf16 v[12:15], v[140:143], v[200:203], v[12:15]
	v_mfma_f32_16x16x32_bf16 v[8:11], v[148:151], v[200:203], v[8:11]
	v_mfma_f32_16x16x32_bf16 v[60:63], v[144:147], v[176:179], v[60:63]
	v_mfma_f32_16x16x32_bf16 v[56:59], v[152:155], v[176:179], v[56:59]
	v_mfma_f32_16x16x32_bf16 v[44:47], v[144:147], v[184:187], v[44:47]
	v_mfma_f32_16x16x32_bf16 v[40:43], v[152:155], v[184:187], v[40:43]
	v_mfma_f32_16x16x32_bf16 v[28:31], v[144:147], v[192:195], v[28:31]
	v_mfma_f32_16x16x32_bf16 v[24:27], v[152:155], v[192:195], v[24:27]
	v_mfma_f32_16x16x32_bf16 v[12:15], v[144:147], v[204:207], v[12:15]
	v_mfma_f32_16x16x32_bf16 v[8:11], v[152:155], v[204:207], v[8:11]
	s_setprio 0
	s_setprio 1
	v_mfma_f32_16x16x32_bf16 v[52:55], v[156:159], v[172:175], v[52:55]
	v_mfma_f32_16x16x32_bf16 v[48:51], v[164:167], v[172:175], v[48:51]
	v_mfma_f32_16x16x32_bf16 v[36:39], v[156:159], v[180:183], v[36:39]
	v_mfma_f32_16x16x32_bf16 v[32:35], v[164:167], v[180:183], v[32:35]
	v_mfma_f32_16x16x32_bf16 v[20:23], v[156:159], v[188:191], v[20:23]
	v_mfma_f32_16x16x32_bf16 v[16:19], v[164:167], v[188:191], v[16:19]
	v_mfma_f32_16x16x32_bf16 v[4:7], v[156:159], v[200:203], v[4:7]
	v_mfma_f32_16x16x32_bf16 v[0:3], v[164:167], v[200:203], v[0:3]
	v_mfma_f32_16x16x32_bf16 v[52:55], v[160:163], v[176:179], v[52:55]
	v_mfma_f32_16x16x32_bf16 v[48:51], v[168:171], v[176:179], v[48:51]
	v_mfma_f32_16x16x32_bf16 v[36:39], v[160:163], v[184:187], v[36:39]
	v_mfma_f32_16x16x32_bf16 v[32:35], v[168:171], v[184:187], v[32:35]
	v_mfma_f32_16x16x32_bf16 v[20:23], v[160:163], v[192:195], v[20:23]
	v_mfma_f32_16x16x32_bf16 v[16:19], v[168:171], v[192:195], v[16:19]
	v_mfma_f32_16x16x32_bf16 v[4:7], v[160:163], v[204:207], v[4:7]
	v_mfma_f32_16x16x32_bf16 v[0:3], v[168:171], v[204:207], v[0:3]
	s_setprio 0
	s_barrier
; #define PG8_STAGE(bufoff, gbase, voff) do { _Pragma("unroll") for (int _i = 0; _i < 2; ++_i) \
;         __builtin_amdgcn_global_load_lds((const unsigned*)((const char*)(gbase) + (voff)[_i]), (PG8_LAS unsigned*)(lds + (bufoff) + ldsw + _i * 8192), 16, 0, 0); } while (0)
; #define PG8_LDA(dst, b, h) do { _Pragma("unroll") for (int m = 0; m < 4; ++m) _Pragma("unroll") for (int k = 0; k < 2; ++k) dst[m][k] = *(const PG8_LAS bf16x8*)(lds + PG8_SA(b, h) + aoff + m * 2048 + k * 1024); } while (0)
; #define PG8_LDB(dst, b, h) do { _Pragma("unroll") for (int n = 0; n < 2; ++n) _Pragma("unroll") for (int k = 0; k < 2; ++k) dst[n][k] = *(const PG8_LAS bf16x8*)(lds + PG8_SB(b, h) + boff + n * 2048 + k * 1024); } while (0)
; #define PG8_MMA(ai, bj, At, Bt) do { __builtin_amdgcn_s_setprio(1); _Pragma("unroll") for (int m = 0; m < 4; ++m) _Pragma("unroll") for (int n = 0; n < 2; ++n) _Pragma("unroll") for (int k = 0; k < 2; ++k) \
;         acc[ai][bj][m][n] = mma16<Epi::F16>(Bt[n][k], At[m][k], acc[ai][bj][m][n]); __builtin_amdgcn_s_setprio(0); } while (0)
; #define PG8_WAIT_V(n) asm volatile("s_waitcnt vmcnt(" #n ")" ::: "memory")
; #define PG8_WAIT_L(n) asm volatile("s_waitcnt lgkmcnt(" #n ")" ::: "memory")
; #define PG8_BAR __builtin_amdgcn_s_barrier()
; #define PG8_SCHED __builtin_amdgcn_sched_barrier(0)
; template <class Epi, class Sched, bool ALIGN_EPI = false, bool SP2 = false>
; __device__ __forceinline__ void gemm_phase(PG8_LAS unsigned char* lds, const Gemm g, const Sched& S, const Epi& E) {
;     ...
;             PG8_LDB(B0, 1, 0); PG8_LDB(B1, 1, 1); PG8_SCHED; PG8_LDA(At, 1, 0); PG8_STAGE(PG8_SA(0, 1), a2 + hstep, voffA);
;             PG8_WAIT_V(8); PG8_WAIT_L(0); PG8_BAR; PG8_MMA(0, 0, At, B0); PG8_MMA(0, 1, At, B1); PG8_BAR; PG8_SCHED;
	s_add_i32 s73, 0, 0x18000
	v_add_u32_e32 v131, s73, v133
	s_add_i32 s77, 0, 0x1c000
	ds_read_b128 v[140:143], v131
	ds_read_b128 v[144:147], v131 offset:1024
	ds_read_b128 v[148:151], v131 offset:2048
	ds_read_b128 v[152:155], v131 offset:3072
	v_add_u32_e32 v131, s77, v133
	ds_read_b128 v[156:159], v131
	ds_read_b128 v[160:163], v131 offset:1024
	ds_read_b128 v[164:167], v131 offset:2048
	ds_read_b128 v[168:171], v131 offset:3072
	s_add_u32 s34, s34, s42
	s_addc_u32 s35, s35, s43
	s_mov_b32 m0, s18
	v_lshl_add_u64 v[224:225], s[34:35], 0, v[208:209]
	ds_read_b128 v[172:175], v199 offset:32768
	ds_read_b128 v[176:179], v199 offset:33792
	ds_read_b128 v[180:183], v199 offset:34816
	ds_read_b128 v[184:187], v199 offset:35840
	ds_read_b128 v[188:191], v199 offset:36864
	ds_read_b128 v[192:195], v199 offset:37888
	ds_read_b128 v[200:203], v199 offset:38912
	ds_read_b128 v[204:207], v199 offset:39936
	global_load_lds_dwordx4 v[224:225], off
	v_lshl_add_u64 v[224:225], s[34:35], 0, v[128:129]
	s_mov_b32 m0, s36
	s_nop 0
	global_load_lds_dwordx4 v[224:225], off
	s_waitcnt vmcnt(8)
	s_waitcnt lgkmcnt(0)
	s_barrier
	s_setprio 1
	v_mfma_f32_16x16x32_bf16 v[120:123], v[140:143], v[172:175], v[120:123]
	v_mfma_f32_16x16x32_bf16 v[124:127], v[148:151], v[172:175], v[124:127]
	v_mfma_f32_16x16x32_bf16 v[108:111], v[140:143], v[180:183], v[108:111]
	v_mfma_f32_16x16x32_bf16 v[104:107], v[148:151], v[180:183], v[104:107]
	v_mfma_f32_16x16x32_bf16 v[92:95], v[140:143], v[188:191], v[92:95]
	v_mfma_f32_16x16x32_bf16 v[88:91], v[148:151], v[188:191], v[88:91]
	v_mfma_f32_16x16x32_bf16 v[76:79], v[140:143], v[200:203], v[76:79]
	v_mfma_f32_16x16x32_bf16 v[72:75], v[148:151], v[200:203], v[72:75]
	v_mfma_f32_16x16x32_bf16 v[120:123], v[144:147], v[176:179], v[120:123]
	v_mfma_f32_16x16x32_bf16 v[124:127], v[152:155], v[176:179], v[124:127]
	v_mfma_f32_16x16x32_bf16 v[108:111], v[144:147], v[184:187], v[108:111]
	v_mfma_f32_16x16x32_bf16 v[104:107], v[152:155], v[184:187], v[104:107]
	v_mfma_f32_16x16x32_bf16 v[92:95], v[144:147], v[192:195], v[92:95]
	v_mfma_f32_16x16x32_bf16 v[88:91], v[152:155], v[192:195], v[88:91]
	v_mfma_f32_16x16x32_bf16 v[76:79], v[144:147], v[204:207], v[76:79]
	v_mfma_f32_16x16x32_bf16 v[72:75], v[152:155], v[204:207], v[72:75]
	s_setprio 0
	s_setprio 1
	v_mfma_f32_16x16x32_bf16 v[116:119], v[156:159], v[172:175], v[116:119]
	v_mfma_f32_16x16x32_bf16 v[112:115], v[164:167], v[172:175], v[112:115]
	v_mfma_f32_16x16x32_bf16 v[100:103], v[156:159], v[180:183], v[100:103]
	v_mfma_f32_16x16x32_bf16 v[96:99], v[164:167], v[180:183], v[96:99]
	v_mfma_f32_16x16x32_bf16 v[84:87], v[156:159], v[188:191], v[84:87]
	v_mfma_f32_16x16x32_bf16 v[80:83], v[164:167], v[188:191], v[80:83]
	v_mfma_f32_16x16x32_bf16 v[68:71], v[156:159], v[200:203], v[68:71]
	v_mfma_f32_16x16x32_bf16 v[64:67], v[164:167], v[200:203], v[64:67]
	v_mfma_f32_16x16x32_bf16 v[116:119], v[160:163], v[176:179], v[116:119]
	v_mfma_f32_16x16x32_bf16 v[112:115], v[168:171], v[176:179], v[112:115]
	v_mfma_f32_16x16x32_bf16 v[100:103], v[160:163], v[184:187], v[100:103]
	v_mfma_f32_16x16x32_bf16 v[96:99], v[168:171], v[184:187], v[96:99]
	v_mfma_f32_16x16x32_bf16 v[84:87], v[160:163], v[192:195], v[84:87]
	v_mfma_f32_16x16x32_bf16 v[80:83], v[168:171], v[192:195], v[80:83]
	v_mfma_f32_16x16x32_bf16 v[68:71], v[160:163], v[204:207], v[68:71]
	v_mfma_f32_16x16x32_bf16 v[64:67], v[168:171], v[204:207], v[64:67]
	s_setprio 0
	s_barrier
; #define PG8_STAGE(bufoff, gbase, voff) do { _Pragma("unroll") for (int _i = 0; _i < 2; ++_i) \
;         __builtin_amdgcn_global_load_lds((const unsigned*)((const char*)(gbase) + (voff)[_i]), (PG8_LAS unsigned*)(lds + (bufoff) + ldsw + _i * 8192), 16, 0, 0); } while (0)
; #define PG8_LDA(dst, b, h) do { _Pragma("unroll") for (int m = 0; m < 4; ++m) _Pragma("unroll") for (int k = 0; k < 2; ++k) dst[m][k] = *(const PG8_LAS bf16x8*)(lds + PG8_SA(b, h) + aoff + m * 2048 + k * 1024); } while (0)
; #define PG8_MMA(ai, bj, At, Bt) do { __builtin_amdgcn_s_setprio(1); _Pragma("unroll") for (int m = 0; m < 4; ++m) _Pragma("unroll") for (int n = 0; n < 2; ++n) _Pragma("unroll") for (int k = 0; k < 2; ++k) \
;         acc[ai][bj][m][n] = mma16<Epi::F16>(Bt[n][k], At[m][k], acc[ai][bj][m][n]); __builtin_amdgcn_s_setprio(0); } while (0)
; #define PG8_WAIT_V(n) asm volatile("s_waitcnt vmcnt(" #n ")" ::: "memory")
; #define PG8_WAIT_L(n) asm volatile("s_waitcnt lgkmcnt(" #n ")" ::: "memory")
; #define PG8_BAR __builtin_amdgcn_s_barrier()
; #define PG8_SCHED __builtin_amdgcn_sched_barrier(0)
; template <class Epi, class Sched, bool ALIGN_EPI = false, bool SP2 = false>
; __device__ __forceinline__ void gemm_phase(PG8_LAS unsigned char* lds, const Gemm g, const Sched& S, const Epi& E) {
;     ...
;             PG8_LDA(At, 1, 1); PG8_STAGE(PG8_SB(1, 0), b3, voffB); PG8_STAGE(PG8_SB(1, 1), b3 + hstep, voffB); PG8_STAGE(PG8_SA(1, 0), a3, voffA);
;             PG8_WAIT_V(8); PG8_WAIT_L(0); PG8_BAR; PG8_MMA(1, 0, At, B0); PG8_MMA(1, 1, At, B1); PG8_BAR; PG8_SCHED;
	s_add_i32 s34, s73, s8
	v_lshl_add_u64 v[212:213], v[212:213], 0, s[20:21]
	s_mov_b32 m0, s34
	ds_read_b128 v[172:175], v199 offset:49152
	ds_read_b128 v[176:179], v199 offset:50176
	ds_read_b128 v[180:183], v199 offset:51200
	ds_read_b128 v[184:187], v199 offset:52224
	ds_read_b128 v[188:191], v199 offset:53248
	ds_read_b128 v[192:195], v199 offset:54272
	ds_read_b128 v[200:203], v199 offset:55296
	ds_read_b128 v[204:207], v199 offset:56320
	global_load_lds_dwordx4 v[212:213], off
	v_lshl_add_u64 v[212:213], v[214:215], 0, s[20:21]
	s_add_i32 m0, s34, 0x2000
	s_add_i32 s34, s77, s8
	global_load_lds_dwordx4 v[212:213], off
	v_lshl_add_u64 v[212:213], v[216:217], 0, s[20:21]
	s_mov_b32 m0, s34
	s_nop 0
	global_load_lds_dwordx4 v[212:213], off
	v_lshl_add_u64 v[212:213], v[218:219], 0, s[20:21]
	s_add_i32 m0, s34, 0x2000
	s_nop 0
	global_load_lds_dwordx4 v[212:213], off
	v_lshl_add_u64 v[212:213], v[220:221], 0, s[20:21]
	s_mov_b32 m0, s37
	s_nop 0
	global_load_lds_dwordx4 v[212:213], off
	v_lshl_add_u64 v[212:213], v[222:223], 0, s[20:21]
	s_mov_b32 m0, s48
	s_nop 0
	global_load_lds_dwordx4 v[212:213], off
	s_waitcnt vmcnt(8)
	s_waitcnt lgkmcnt(0)
	s_barrier
	s_setprio 1
	v_mfma_f32_16x16x32_bf16 v[60:63], v[140:143], v[172:175], v[60:63]
	v_mfma_f32_16x16x32_bf16 v[56:59], v[148:151], v[172:175], v[56:59]
	v_mfma_f32_16x16x32_bf16 v[44:47], v[140:143], v[180:183], v[44:47]
	v_mfma_f32_16x16x32_bf16 v[40:43], v[148:151], v[180:183], v[40:43]
	v_mfma_f32_16x16x32_bf16 v[28:31], v[140:143], v[188:191], v[28:31]
	v_mfma_f32_16x16x32_bf16 v[24:27], v[148:151], v[188:191], v[24:27]
	v_mfma_f32_16x16x32_bf16 v[12:15], v[140:143], v[200:203], v[12:15]
	v_mfma_f32_16x16x32_bf16 v[8:11], v[148:151], v[200:203], v[8:11]
	v_mfma_f32_16x16x32_bf16 v[60:63], v[144:147], v[176:179], v[60:63]
	v_mfma_f32_16x16x32_bf16 v[56:59], v[152:155], v[176:179], v[56:59]
	v_mfma_f32_16x16x32_bf16 v[44:47], v[144:147], v[184:187], v[44:47]
	v_mfma_f32_16x16x32_bf16 v[40:43], v[152:155], v[184:187], v[40:43]
	v_mfma_f32_16x16x32_bf16 v[28:31], v[144:147], v[192:195], v[28:31]
	v_mfma_f32_16x16x32_bf16 v[24:27], v[152:155], v[192:195], v[24:27]
	v_mfma_f32_16x16x32_bf16 v[12:15], v[144:147], v[204:207], v[12:15]
	v_mfma_f32_16x16x32_bf16 v[8:11], v[152:155], v[204:207], v[8:11]
	s_setprio 0
	s_setprio 1
	v_mfma_f32_16x16x32_bf16 v[52:55], v[156:159], v[172:175], v[52:55]
	v_mfma_f32_16x16x32_bf16 v[48:51], v[164:167], v[172:175], v[48:51]
	v_mfma_f32_16x16x32_bf16 v[36:39], v[156:159], v[180:183], v[36:39]
	v_mfma_f32_16x16x32_bf16 v[32:35], v[164:167], v[180:183], v[32:35]
	v_mfma_f32_16x16x32_bf16 v[20:23], v[156:159], v[188:191], v[20:23]
	v_mfma_f32_16x16x32_bf16 v[16:19], v[164:167], v[188:191], v[16:19]
	v_mfma_f32_16x16x32_bf16 v[4:7], v[156:159], v[200:203], v[4:7]
	v_mfma_f32_16x16x32_bf16 v[0:3], v[164:167], v[200:203], v[0:3]
	v_mfma_f32_16x16x32_bf16 v[52:55], v[160:163], v[176:179], v[52:55]
	v_mfma_f32_16x16x32_bf16 v[48:51], v[168:171], v[176:179], v[48:51]
	v_mfma_f32_16x16x32_bf16 v[36:39], v[160:163], v[184:187], v[36:39]
	v_mfma_f32_16x16x32_bf16 v[32:35], v[168:171], v[184:187], v[32:35]
	v_mfma_f32_16x16x32_bf16 v[20:23], v[160:163], v[192:195], v[20:23]
	v_mfma_f32_16x16x32_bf16 v[16:19], v[168:171], v[192:195], v[16:19]
	v_mfma_f32_16x16x32_bf16 v[4:7], v[160:163], v[204:207], v[4:7]
	v_mfma_f32_16x16x32_bf16 v[0:3], v[168:171], v[204:207], v[0:3]
	s_setprio 0
	s_barrier
	s_add_u32 s30, s30, 0x100
	s_addc_u32 s31, s31, 0
	s_add_u32 s29, s29, 0x100
	s_addc_u32 s71, s71, 0
	s_cmp_ge_i32 s72, s58
	s_mov_b32 s34, s72
	s_cbranch_scc0 .LBB0_1480
